# v93 stack + v_pk_*_f32 split into scalar ops in all mixer phases (GLA, attention, RG-LRU)
# baseline (speedup 1.0000x reference)
.LBB0_464:
	ds_read_b128 v[94:97], v149 offset:6144
	ds_read_b128 v[98:101], v149 offset:6160
	s_waitcnt vmcnt(5)
	v_lshlrev_b32_e32 v102, 16, v22
	v_and_b32_e32 v103, 0xffff0000, v22
	s_add_i32 s46, s47, s46
	s_waitcnt lgkmcnt(1)
	v_mul_f32_e32 v94, 0xbfb8aa3b, v94
	v_mul_f32_e32 v95, 0xbfb8aa3b, v95
	v_exp_f32_e32 v94, v94
	v_exp_f32_e32 v95, v95
	v_mul_f32_e32 v22, 0xbfb8aa3b, v96
	v_exp_f32_e32 v96, v22
	v_mul_f32_e32 v22, 0xbfb8aa3b, v97
	v_exp_f32_e32 v97, v22
	v_mul_f32_e64 v94, v94, v102
	v_mul_f32_e64 v95, v95, v103
	s_add_i32 s83, s83, 1
	v_cvt_pk_bf16_f32 v22, v94, v95
	v_lshlrev_b32_e32 v94, 16, v23
	v_and_b32_e32 v95, 0xffff0000, v23
	s_waitcnt lgkmcnt(0)
	v_mul_f32_e32 v23, 0xbfb8aa3b, v98
	v_mul_f32_e64 v94, v96, v94
	v_mul_f32_e64 v95, v97, v95
	v_exp_f32_e32 v96, v23
	v_mul_f32_e32 v23, 0xbfb8aa3b, v99
	v_exp_f32_e32 v97, v23
	v_cvt_pk_bf16_f32 v23, v94, v95
	v_lshlrev_b32_e32 v94, 16, v24
	v_and_b32_e32 v95, 0xffff0000, v24
	v_mul_f32_e32 v24, 0xbfb8aa3b, v100
	v_mul_f32_e64 v94, v96, v94
	v_mul_f32_e64 v95, v97, v95
	v_exp_f32_e32 v96, v24
	v_mul_f32_e32 v24, 0xbfb8aa3b, v101
	v_exp_f32_e32 v97, v24
	v_cvt_pk_bf16_f32 v24, v94, v95
	v_lshlrev_b32_e32 v94, 16, v25
	v_and_b32_e32 v95, 0xffff0000, v25
	v_mul_f32_e64 v94, v96, v94
	v_mul_f32_e64 v95, v97, v95
	s_waitcnt vmcnt(4)
	v_lshlrev_b32_e32 v98, 16, v6
	v_cvt_pk_bf16_f32 v25, v94, v95
	ds_write_b128 v150, v[22:25] offset:56320
	ds_read_b128 v[22:25], v151 offset:6144
	ds_read_b128 v[94:97], v151 offset:6160
	v_and_b32_e32 v99, 0xffff0000, v6
	s_mul_i32 s53, s46, 0x1800
	s_mul_hi_i32 s52, s46, 0x1800
	s_waitcnt lgkmcnt(1)
	v_mul_f32_e32 v22, 0xbfb8aa3b, v22
	v_mul_f32_e32 v23, 0xbfb8aa3b, v23
	v_exp_f32_e32 v22, v22
	v_exp_f32_e32 v23, v23
	v_mul_f32_e32 v6, 0xbfb8aa3b, v24
	v_exp_f32_e32 v24, v6
	v_mul_f32_e32 v6, 0xbfb8aa3b, v25
	v_exp_f32_e32 v25, v6
	v_mul_f32_e64 v22, v22, v98
	v_mul_f32_e64 v23, v23, v99
	s_add_u32 s50, s80, s53
	v_cvt_pk_bf16_f32 v6, v22, v23
	v_lshlrev_b32_e32 v22, 16, v7
	v_and_b32_e32 v23, 0xffff0000, v7
	s_waitcnt lgkmcnt(0)
	v_mul_f32_e32 v7, 0xbfb8aa3b, v94
	v_mul_f32_e64 v22, v24, v22
	v_mul_f32_e64 v23, v25, v23
	v_exp_f32_e32 v24, v7
	v_mul_f32_e32 v7, 0xbfb8aa3b, v95
	v_exp_f32_e32 v25, v7
	v_cvt_pk_bf16_f32 v7, v22, v23
	v_lshlrev_b32_e32 v22, 16, v8
	v_and_b32_e32 v23, 0xffff0000, v8
	v_mul_f32_e32 v8, 0xbfb8aa3b, v96
	v_mul_f32_e64 v22, v24, v22
	v_mul_f32_e64 v23, v25, v23
	v_exp_f32_e32 v24, v8
	v_mul_f32_e32 v8, 0xbfb8aa3b, v97
	v_exp_f32_e32 v25, v8
	v_cvt_pk_bf16_f32 v8, v22, v23
	v_lshlrev_b32_e32 v22, 16, v9
	v_and_b32_e32 v23, 0xffff0000, v9
	v_mul_f32_e64 v22, v24, v22
	v_mul_f32_e64 v23, v25, v23
	s_addc_u32 s51, s81, s52
	v_cvt_pk_bf16_f32 v9, v22, v23
	ds_write_b128 v152, v[6:9] offset:56320
	s_waitcnt vmcnt(3)
	ds_write_b128 v153, v[2:5]
	s_waitcnt vmcnt(2)
	ds_write_b128 v155, v[10:13]
	s_waitcnt vmcnt(1)
	ds_write_b128 v153, v[14:17] offset:16896
	s_waitcnt vmcnt(0)
	ds_write_b128 v156, v[18:21]
	v_lshl_add_u64 v[2:3], s[50:51], 0, v[112:113]
	s_add_u32 s50, s38, s53
	s_addc_u32 s51, s39, s52
	s_add_u32 s50, s50, s76
	s_addc_u32 s51, s51, 0
	s_add_u32 s50, s50, 0xad20800
	global_load_dwordx4 v[22:25], v[2:3], off offset:1024
	v_add_co_u32_e32 v2, vcc, s63, v2
	s_addc_u32 s51, s51, 0
	s_nop 0
	v_addc_co_u32_e32 v3, vcc, 0, v3, vcc
	v_lshl_add_u64 v[18:19], s[50:51], 0, v[114:115]
	v_add_co_u32_e32 v10, vcc, s64, v18
	global_load_dwordx4 v[6:9], v[2:3], off offset:1024
	s_nop 0
	v_addc_co_u32_e32 v11, vcc, 0, v19, vcc
	v_add_co_u32_e32 v14, vcc, s63, v18
	global_load_dwordx4 v[2:5], v[18:19], off
	s_nop 0
	v_addc_co_u32_e32 v15, vcc, 0, v19, vcc
	v_add_co_u32_e32 v18, vcc, s65, v18
	global_load_dwordx4 v[10:13], v[10:11], off
	s_nop 0
	v_addc_co_u32_e32 v19, vcc, 0, v19, vcc
	global_load_dwordx4 v[14:17], v[14:15], off
	v_lshl_add_u32 v167, s87, 9, v128
	global_load_dwordx4 v[18:21], v[18:19], off
	s_waitcnt lgkmcnt(0)
	s_barrier
	ds_read_b64_tr_b16 v[96:97], v158 offset:57408
	ds_read_b64_tr_b16 v[94:95], v158 offset:56320
	ds_read_b64_tr_b16 v[108:109], v157 offset:2112
	ds_read_b64_tr_b16 v[106:107], v157
	ds_read_b64_tr_b16 v[102:103], v157 offset:32
	ds_read_b64_tr_b16 v[104:105], v157 offset:2144
	s_waitcnt lgkmcnt(2)
	v_mfma_f32_16x16x32_bf16 v[70:73], v[94:97], v[106:109], v[70:73]
	ds_read_b64_tr_b16 v[168:169], v158 offset:65024
	ds_read_b64_tr_b16 v[170:171], v159 offset:57408
	ds_read_b64_tr_b16 v[98:99], v157 offset:16896
	s_cmp_eq_u32 s43, s83
	s_waitcnt lgkmcnt(3)
	v_mfma_f32_16x16x32_bf16 v[74:77], v[94:97], v[102:105], v[74:77]
	ds_read_b64_tr_b16 v[100:101], v157 offset:19008
	ds_read_b64_tr_b16 v[94:95], v157 offset:16928
	ds_read_b64_tr_b16 v[96:97], v157 offset:19040
	ds_read_b64_tr_b16 v[172:173], v158 offset:56352
	ds_read_b64_tr_b16 v[174:175], v158 offset:57440
	s_waitcnt lgkmcnt(4)
	v_mfma_f32_16x16x32_bf16 v[70:73], v[168:171], v[98:101], v[70:73]
	s_waitcnt lgkmcnt(2)
	v_mfma_f32_16x16x32_bf16 v[74:77], v[168:171], v[94:97], v[74:77]
	ds_read_b64_tr_b16 v[170:171], v159 offset:57440
	ds_read_b64_tr_b16 v[168:169], v158 offset:65056
	s_waitcnt lgkmcnt(2)
	v_mfma_f32_16x16x32_bf16 v[58:61], v[172:175], v[106:109], v[58:61]
	v_mfma_f32_16x16x32_bf16 v[82:85], v[172:175], v[102:105], v[82:85]
	s_waitcnt lgkmcnt(0)
	v_mfma_f32_16x16x32_bf16 v[58:61], v[168:171], v[98:101], v[58:61]
	v_mfma_f32_16x16x32_bf16 v[82:85], v[168:171], v[94:97], v[82:85]
	ds_read_b64_tr_b16 v[168:169], v158 offset:56384
	ds_read_b64_tr_b16 v[170:171], v158 offset:57472
	s_waitcnt lgkmcnt(0)
	v_mfma_f32_16x16x32_bf16 v[66:69], v[168:171], v[106:109], v[66:69]
	v_mfma_f32_16x16x32_bf16 v[78:81], v[168:171], v[102:105], v[78:81]
	ds_read_b64_tr_b16 v[168:169], v158 offset:65088
	ds_read_b64_tr_b16 v[170:171], v159 offset:57472
	s_waitcnt lgkmcnt(0)
	v_mfma_f32_16x16x32_bf16 v[66:69], v[168:171], v[98:101], v[66:69]
	v_mfma_f32_16x16x32_bf16 v[78:81], v[168:171], v[94:97], v[78:81]
	ds_read_b64_tr_b16 v[168:169], v158 offset:56416
	ds_read_b64_tr_b16 v[170:171], v158 offset:57504
	s_waitcnt lgkmcnt(0)
	v_mfma_f32_16x16x32_bf16 v[62:65], v[168:171], v[106:109], v[62:65]
	v_mfma_f32_16x16x32_bf16 v[86:89], v[168:171], v[102:105], v[86:89]
	ds_read_b64_tr_b16 v[168:169], v158 offset:65120
	ds_read_b64_tr_b16 v[170:171], v159 offset:57504
	s_waitcnt lgkmcnt(0)
	v_mfma_f32_16x16x32_bf16 v[62:65], v[168:171], v[98:101], v[62:65]
	v_mfma_f32_16x16x32_bf16 v[86:89], v[168:171], v[94:97], v[86:89]
	ds_read_b64_tr_b16 v[168:169], v158 offset:56448
	ds_read_b64_tr_b16 v[170:171], v158 offset:57536
	s_waitcnt lgkmcnt(0)
	v_mfma_f32_16x16x32_bf16 v[38:41], v[168:171], v[106:109], v[38:41]
	v_mfma_f32_16x16x32_bf16 v[50:53], v[168:171], v[102:105], v[50:53]
	ds_read_b64_tr_b16 v[168:169], v158 offset:65152
	ds_read_b64_tr_b16 v[170:171], v159 offset:57536
	s_waitcnt lgkmcnt(0)
	v_mfma_f32_16x16x32_bf16 v[38:41], v[168:171], v[98:101], v[38:41]
	v_mfma_f32_16x16x32_bf16 v[50:53], v[168:171], v[94:97], v[50:53]
	ds_read_b64_tr_b16 v[168:169], v158 offset:56480
	ds_read_b64_tr_b16 v[170:171], v158 offset:57568
	s_waitcnt lgkmcnt(0)
	v_mfma_f32_16x16x32_bf16 v[30:33], v[168:171], v[106:109], v[30:33]
	v_mfma_f32_16x16x32_bf16 v[54:57], v[168:171], v[102:105], v[54:57]
	ds_read_b64_tr_b16 v[168:169], v158 offset:65184
	ds_read_b64_tr_b16 v[170:171], v159 offset:57568
	s_waitcnt lgkmcnt(0)
	v_mfma_f32_16x16x32_bf16 v[30:33], v[168:171], v[98:101], v[30:33]
	v_mfma_f32_16x16x32_bf16 v[54:57], v[168:171], v[94:97], v[54:57]
	ds_read_b64_tr_b16 v[168:169], v158 offset:56512
	ds_read_b64_tr_b16 v[170:171], v158 offset:57600
	s_waitcnt lgkmcnt(0)
	v_mfma_f32_16x16x32_bf16 v[42:45], v[168:171], v[106:109], v[42:45]
	v_mfma_f32_16x16x32_bf16 v[46:49], v[168:171], v[102:105], v[46:49]
	ds_read_b64_tr_b16 v[168:169], v158 offset:65216
	ds_read_b64_tr_b16 v[170:171], v159 offset:57600
	s_waitcnt lgkmcnt(0)
	v_mfma_f32_16x16x32_bf16 v[42:45], v[168:171], v[98:101], v[42:45]
	v_mfma_f32_16x16x32_bf16 v[46:49], v[168:171], v[94:97], v[46:49]
	ds_read_b64_tr_b16 v[168:169], v158 offset:56544
	ds_read_b64_tr_b16 v[170:171], v158 offset:57632
	s_waitcnt lgkmcnt(0)
	v_mfma_f32_16x16x32_bf16 v[34:37], v[168:171], v[106:109], v[34:37]
	ds_read_b64_tr_b16 v[106:107], v158 offset:65248
	ds_read_b64_tr_b16 v[108:109], v159 offset:57632
	v_mfma_f32_16x16x32_bf16 v[102:105], v[168:171], v[102:105], v[26:29]
	ds_read_b128 v[168:171], v167 offset:4096
	s_waitcnt lgkmcnt(1)
	v_mfma_f32_16x16x32_bf16 v[26:29], v[106:109], v[98:101], v[34:37]
	s_waitcnt lgkmcnt(0)
	s_nop 1
	s_nop 0
	v_mov_b32_e32 v98, v168
	s_nop 0
	v_mov_b32_e32 v99, v169
	s_nop 0
	v_mov_b32_e32 v100, v170
	s_nop 0
	v_mov_b32_e32 v101, v171
	ds_read_b128 v[34:37], v167 offset:4160
	v_mfma_f32_16x16x32_bf16 v[94:97], v[106:109], v[94:97], v[102:105]
	v_mul_f32_e64 v70, v70, v98
	v_mul_f32_e64 v71, v71, v99
	v_mul_f32_e64 v74, v74, v98
	v_mul_f32_e64 v75, v75, v99
	v_mul_f32_e64 v72, v72, v100
	v_mul_f32_e64 v73, v73, v101
	s_waitcnt lgkmcnt(0)
	s_nop 0
	v_mov_b32_e32 v102, v34
	s_nop 0
	v_mov_b32_e32 v103, v35
	s_nop 0
	v_mov_b32_e32 v104, v36
	s_nop 0
	v_mov_b32_e32 v105, v37
	ds_read_b128 v[34:37], v167 offset:4224
	v_mul_f32_e64 v76, v76, v100
	v_mul_f32_e64 v77, v77, v101
	v_mul_f32_e64 v58, v58, v102
	v_mul_f32_e64 v59, v59, v103
	v_mul_f32_e64 v82, v82, v102
	v_mul_f32_e64 v83, v83, v103
	v_mul_f32_e64 v60, v60, v104
	v_mul_f32_e64 v61, v61, v105
	s_waitcnt lgkmcnt(0)
	s_nop 0
	v_mov_b32_e32 v98, v34
	s_nop 0
	v_mov_b32_e32 v99, v35
	s_nop 0
	v_mov_b32_e32 v100, v36
	s_nop 0
	v_mov_b32_e32 v101, v37
	ds_read_b128 v[34:37], v167 offset:4288
	v_mul_f32_e64 v84, v84, v104
	v_mul_f32_e64 v85, v85, v105
	v_mul_f32_e64 v66, v66, v98
	v_mul_f32_e64 v67, v67, v99
	v_mul_f32_e64 v78, v78, v98
	v_mul_f32_e64 v79, v79, v99
	v_mul_f32_e64 v68, v68, v100
	v_mul_f32_e64 v69, v69, v101
	s_waitcnt lgkmcnt(0)
	s_nop 0
	v_mov_b32_e32 v102, v34
	s_nop 0
	v_mov_b32_e32 v103, v35
	s_nop 0
	v_mov_b32_e32 v104, v36
	s_nop 0
	v_mov_b32_e32 v105, v37
	ds_read_b128 v[34:37], v167 offset:4352
	v_mul_f32_e64 v80, v80, v100
	v_mul_f32_e64 v81, v81, v101
	v_mul_f32_e64 v62, v62, v102
	v_mul_f32_e64 v63, v63, v103
	v_mul_f32_e64 v86, v86, v102
	v_mul_f32_e64 v87, v87, v103
	v_mul_f32_e64 v64, v64, v104
	v_mul_f32_e64 v65, v65, v105
	s_waitcnt lgkmcnt(0)
	s_nop 0
	v_mov_b32_e32 v98, v34
	s_nop 0
	v_mov_b32_e32 v99, v35
	s_nop 0
	v_mov_b32_e32 v100, v36
	s_nop 0
	v_mov_b32_e32 v101, v37
	ds_read_b128 v[34:37], v167 offset:4416
	v_mul_f32_e64 v88, v88, v104
	v_mul_f32_e64 v89, v89, v105
	v_mul_f32_e64 v38, v38, v98
	v_mul_f32_e64 v39, v39, v99
	v_mul_f32_e64 v50, v50, v98
	v_mul_f32_e64 v51, v51, v99
	v_mul_f32_e64 v40, v40, v100
	v_mul_f32_e64 v41, v41, v101
	s_waitcnt lgkmcnt(0)
	s_nop 0
	v_mov_b32_e32 v102, v34
	s_nop 0
	v_mov_b32_e32 v103, v35
	s_nop 0
	v_mov_b32_e32 v104, v36
	s_nop 0
	v_mov_b32_e32 v105, v37
	ds_read_b128 v[34:37], v167 offset:4480
	v_mul_f32_e64 v52, v52, v100
	v_mul_f32_e64 v53, v53, v101
	v_mul_f32_e64 v30, v30, v102
	v_mul_f32_e64 v31, v31, v103
	v_mul_f32_e64 v54, v54, v102
	v_mul_f32_e64 v55, v55, v103
	v_mul_f32_e64 v32, v32, v104
	v_mul_f32_e64 v33, v33, v105
	s_waitcnt lgkmcnt(0)
	s_nop 0
	v_mov_b32_e32 v98, v34
	s_nop 0
	v_mov_b32_e32 v99, v35
	s_nop 0
	v_mov_b32_e32 v100, v36
	s_nop 0
	v_mov_b32_e32 v101, v37
	ds_read_b128 v[34:37], v167 offset:4544
	v_mul_f32_e64 v56, v56, v104
	v_mul_f32_e64 v57, v57, v105
	v_mul_f32_e64 v42, v42, v98
	v_mul_f32_e64 v43, v43, v99
	v_mul_f32_e64 v44, v44, v100
	v_mul_f32_e64 v45, v45, v101
	v_mul_f32_e64 v48, v48, v100
	v_mul_f32_e64 v49, v49, v101
	s_waitcnt lgkmcnt(0)
	s_nop 0
	v_mov_b32_e32 v102, v34
	v_mov_b32_e32 v34, v35
	v_mov_b32_e32 v35, v36
	v_mov_b32_e32 v104, v35
	s_nop 0
	v_mov_b32_e32 v105, v37
	v_mov_b32_e32 v103, v34
	v_mul_f32_e64 v46, v46, v98
	v_mul_f32_e64 v47, v47, v99
	v_mul_f32_e64 v36, v28, v104
	v_mul_f32_e64 v37, v29, v105
	v_mul_f32_e64 v34, v26, v102
	v_mul_f32_e64 v35, v27, v103
	v_mul_f32_e64 v28, v96, v104
	v_mul_f32_e64 v29, v97, v105
	v_mul_f32_e64 v26, v94, v102
	v_mul_f32_e64 v27, v95, v103
	s_cbranch_scc1 .LBB0_480

.LBB0_490:
	s_or_b64 exec, exec, s[30:31]
	ds_read_b128 v[90:93], v149 offset:6144
	ds_read_b128 v[94:97], v149 offset:6160
	s_waitcnt vmcnt(5)
	v_lshlrev_b32_e32 v98, 16, v22
	v_and_b32_e32 v99, 0xffff0000, v22
	s_waitcnt lgkmcnt(1)
	v_mul_f32_e32 v90, 0xbfb8aa3b, v90
	v_mul_f32_e32 v91, 0xbfb8aa3b, v91
	v_exp_f32_e32 v90, v90
	v_exp_f32_e32 v91, v91
	v_mul_f32_e32 v22, 0xbfb8aa3b, v92
	v_exp_f32_e32 v92, v22
	v_mul_f32_e32 v22, 0xbfb8aa3b, v93
	v_exp_f32_e32 v93, v22
	v_mul_f32_e64 v90, v90, v98
	v_mul_f32_e64 v91, v91, v99
	s_nop 0
	v_cvt_pk_bf16_f32 v22, v90, v91
	v_lshlrev_b32_e32 v90, 16, v23
	v_and_b32_e32 v91, 0xffff0000, v23
	s_waitcnt lgkmcnt(0)
	v_mul_f32_e32 v23, 0xbfb8aa3b, v94
	v_mul_f32_e64 v90, v92, v90
	v_mul_f32_e64 v91, v93, v91
	v_exp_f32_e32 v92, v23
	v_mul_f32_e32 v23, 0xbfb8aa3b, v95
	v_exp_f32_e32 v93, v23
	v_cvt_pk_bf16_f32 v23, v90, v91
	v_lshlrev_b32_e32 v90, 16, v24
	v_and_b32_e32 v91, 0xffff0000, v24
	v_mul_f32_e32 v24, 0xbfb8aa3b, v96
	v_mul_f32_e64 v90, v92, v90
	v_mul_f32_e64 v91, v93, v91
	v_exp_f32_e32 v92, v24
	v_mul_f32_e32 v24, 0xbfb8aa3b, v97
	v_exp_f32_e32 v93, v24
	v_cvt_pk_bf16_f32 v24, v90, v91
	v_lshlrev_b32_e32 v90, 16, v25
	v_and_b32_e32 v91, 0xffff0000, v25
	v_mul_f32_e64 v90, v92, v90
	v_mul_f32_e64 v91, v93, v91
	s_waitcnt vmcnt(4)
	v_lshlrev_b32_e32 v94, 16, v6
	v_cvt_pk_bf16_f32 v25, v90, v91
	ds_write_b128 v150, v[22:25] offset:56320
	ds_read_b128 v[22:25], v151 offset:6144
	ds_read_b128 v[90:93], v151 offset:6160
	v_and_b32_e32 v95, 0xffff0000, v6
	s_waitcnt lgkmcnt(1)
	v_mul_f32_e32 v22, 0xbfb8aa3b, v22
	v_mul_f32_e32 v23, 0xbfb8aa3b, v23
	v_exp_f32_e32 v22, v22
	v_exp_f32_e32 v23, v23
	v_mul_f32_e32 v6, 0xbfb8aa3b, v24
	v_exp_f32_e32 v24, v6
	v_mul_f32_e32 v6, 0xbfb8aa3b, v25
	v_exp_f32_e32 v25, v6
	v_mul_f32_e64 v22, v22, v94
	v_mul_f32_e64 v23, v23, v95
	s_nop 0
	v_cvt_pk_bf16_f32 v6, v22, v23
	v_lshlrev_b32_e32 v22, 16, v7
	v_and_b32_e32 v23, 0xffff0000, v7
	s_waitcnt lgkmcnt(0)
	v_mul_f32_e32 v7, 0xbfb8aa3b, v90
	v_mul_f32_e64 v22, v24, v22
	v_mul_f32_e64 v23, v25, v23
	v_exp_f32_e32 v24, v7
	v_mul_f32_e32 v7, 0xbfb8aa3b, v91
	v_exp_f32_e32 v25, v7
	v_cvt_pk_bf16_f32 v7, v22, v23
	v_lshlrev_b32_e32 v22, 16, v8
	v_and_b32_e32 v23, 0xffff0000, v8
	v_mul_f32_e32 v8, 0xbfb8aa3b, v92
	v_mul_f32_e64 v22, v24, v22
	v_mul_f32_e64 v23, v25, v23
	v_exp_f32_e32 v24, v8
	v_mul_f32_e32 v8, 0xbfb8aa3b, v93
	v_exp_f32_e32 v25, v8
	v_cvt_pk_bf16_f32 v8, v22, v23
	v_lshlrev_b32_e32 v22, 16, v9
	v_and_b32_e32 v23, 0xffff0000, v9
	v_mul_f32_e64 v22, v24, v22
	v_mul_f32_e64 v23, v25, v23
	s_nop 0
	v_cvt_pk_bf16_f32 v9, v22, v23
	ds_write_b128 v152, v[6:9] offset:56320
	s_waitcnt vmcnt(3)
	ds_write_b128 v153, v[2:5]
	s_waitcnt vmcnt(2)
	ds_write_b128 v155, v[10:13]
	s_waitcnt vmcnt(1)
	ds_write_b128 v153, v[14:17] offset:16896
	s_waitcnt vmcnt(0)
	ds_write_b128 v156, v[18:21]
	s_waitcnt lgkmcnt(0)
	s_barrier
	ds_read_b64_tr_b16 v[4:5], v158 offset:57408
	ds_read_b64_tr_b16 v[2:3], v158 offset:56320
	ds_read_b64_tr_b16 v[8:9], v157 offset:2112
	ds_read_b64_tr_b16 v[6:7], v157
	ds_read_b64_tr_b16 v[12:13], v157 offset:2144
	ds_read_b64_tr_b16 v[10:11], v157 offset:32
	ds_read_b64_tr_b16 v[14:15], v158 offset:56352
	ds_read_b64_tr_b16 v[18:19], v158 offset:56384
	ds_read_b64_tr_b16 v[22:23], v158 offset:56416
	ds_read_b64_tr_b16 v[16:17], v158 offset:57440
	ds_read_b64_tr_b16 v[20:21], v158 offset:57472
	ds_read_b64_tr_b16 v[24:25], v158 offset:57504
	ds_read_b64_tr_b16 v[90:91], v158 offset:65024
	ds_read_b64_tr_b16 v[92:93], v159 offset:57408
	ds_read_b64_tr_b16 v[94:95], v157 offset:16896
	ds_read_b64_tr_b16 v[96:97], v157 offset:19008
	ds_read_b64_tr_b16 v[100:101], v157 offset:19040
	ds_read_b64_tr_b16 v[98:99], v157 offset:16928
	s_waitcnt lgkmcnt(8)
	v_mfma_f32_16x16x32_bf16 v[58:61], v[14:17], v[6:9], v[58:61]
	v_mfma_f32_16x16x32_bf16 v[14:17], v[14:17], v[10:13], v[82:85]
	v_mfma_f32_16x16x32_bf16 v[70:73], v[2:5], v[6:9], v[70:73]
	v_mfma_f32_16x16x32_bf16 v[2:5], v[2:5], v[10:13], v[74:77]
	s_nop 2
	ds_read_b64_tr_b16 v[74:75], v158 offset:65056
	ds_read_b64_tr_b16 v[102:103], v158 offset:65088
	ds_read_b64_tr_b16 v[106:107], v158 offset:65120
	ds_read_b64_tr_b16 v[76:77], v159 offset:57440
	ds_read_b64_tr_b16 v[104:105], v159 offset:57472
	ds_read_b64_tr_b16 v[108:109], v159 offset:57504
	s_waitcnt lgkmcnt(2)
	v_mfma_f32_16x16x32_bf16 v[58:61], v[74:77], v[94:97], v[58:61]
	v_mfma_f32_16x16x32_bf16 v[14:17], v[74:77], v[98:101], v[14:17]
	ds_read_b64_tr_b16 v[74:75], v158 offset:56448
	ds_read_b64_tr_b16 v[76:77], v158 offset:57536
	v_mfma_f32_16x16x32_bf16 v[66:69], v[18:21], v[6:9], v[66:69]
	v_mfma_f32_16x16x32_bf16 v[18:21], v[18:21], v[10:13], v[78:81]
	v_mfma_f32_16x16x32_bf16 v[62:65], v[22:25], v[6:9], v[62:65]
	v_mfma_f32_16x16x32_bf16 v[22:25], v[22:25], v[10:13], v[86:89]
	s_nop 0
	ds_read_b64_tr_b16 v[78:79], v158 offset:56480
	ds_read_b64_tr_b16 v[82:83], v158 offset:56512
	ds_read_b64_tr_b16 v[86:87], v158 offset:56544
	ds_read_b64_tr_b16 v[80:81], v158 offset:57568
	ds_read_b64_tr_b16 v[84:85], v158 offset:57600
	ds_read_b64_tr_b16 v[88:89], v158 offset:57632
	s_waitcnt lgkmcnt(1)
	v_mfma_f32_16x16x32_bf16 v[42:45], v[82:85], v[6:9], v[42:45]
	v_mfma_f32_16x16x32_bf16 v[46:49], v[82:85], v[10:13], v[46:49]
	v_add_u32_e32 v82, s43, v128
	s_ashr_i32 s43, s42, 31
	s_lshl_b64 s[30:31], s[42:43], 17
	v_mfma_f32_16x16x32_bf16 v[70:73], v[90:93], v[94:97], v[70:73]
	v_mfma_f32_16x16x32_bf16 v[2:5], v[90:93], v[98:101], v[2:5]
	ds_read_b64_tr_b16 v[90:91], v158 offset:65152
	ds_read_b64_tr_b16 v[92:93], v159 offset:57536
	v_mfma_f32_16x16x32_bf16 v[66:69], v[102:105], v[94:97], v[66:69]
	v_mfma_f32_16x16x32_bf16 v[18:21], v[102:105], v[98:101], v[18:21]
	v_mfma_f32_16x16x32_bf16 v[62:65], v[106:109], v[94:97], v[62:65]
	v_mfma_f32_16x16x32_bf16 v[22:25], v[106:109], v[98:101], v[22:25]
	v_mfma_f32_16x16x32_bf16 v[38:41], v[74:77], v[6:9], v[38:41]
	v_mfma_f32_16x16x32_bf16 v[50:53], v[74:77], v[10:13], v[50:53]
	ds_read_b64_tr_b16 v[74:75], v158 offset:65184
	ds_read_b64_tr_b16 v[102:103], v158 offset:65216
	ds_read_b64_tr_b16 v[106:107], v158 offset:65248
	ds_read_b64_tr_b16 v[76:77], v159 offset:57568
	ds_read_b64_tr_b16 v[104:105], v159 offset:57600
	ds_read_b64_tr_b16 v[108:109], v159 offset:57632
	v_mfma_f32_16x16x32_bf16 v[54:57], v[78:81], v[10:13], v[54:57]
	s_waitcnt lgkmcnt(8)
	v_mfma_f32_16x16x32_bf16 v[10:13], v[86:89], v[10:13], v[26:29]
	s_nop 2
	ds_read_b128 v[26:29], v82 offset:4096
	v_mfma_f32_16x16x32_bf16 v[30:33], v[78:81], v[6:9], v[30:33]
	v_mfma_f32_16x16x32_bf16 v[6:9], v[86:89], v[6:9], v[34:37]
	s_nop 2
	ds_read_b128 v[34:37], v82 offset:4160
	s_waitcnt lgkmcnt(1)
	s_nop 0
	v_mfma_f32_16x16x32_bf16 v[30:33], v[74:77], v[94:97], v[30:33]
	s_waitcnt lgkmcnt(0)
	s_nop 0
	v_mfma_f32_16x16x32_bf16 v[54:57], v[74:77], v[98:101], v[54:57]
	v_mov_b32_e32 v74, v26
	v_mov_b32_e32 v26, v27
	v_mov_b32_e32 v27, v28
	v_mov_b32_e32 v76, v27
	s_nop 0
	v_mov_b32_e32 v77, v29
	v_mov_b32_e32 v75, v26
	v_mfma_f32_16x16x32_bf16 v[38:41], v[90:93], v[94:97], v[38:41]
	v_mul_f32_e64 v28, v72, v76
	v_mul_f32_e64 v29, v73, v77
	v_mul_f32_e64 v4, v4, v76
	v_mul_f32_e64 v5, v5, v77
	v_mov_b32_e32 v76, v34
	v_mov_b32_e32 v34, v35
	v_mov_b32_e32 v35, v36
	v_mov_b32_e32 v78, v35
	s_nop 0
	v_mov_b32_e32 v79, v37
	v_mov_b32_e32 v77, v34
	ds_read_b128 v[34:37], v82 offset:4224
	v_mul_f32_e64 v26, v70, v74
	v_mul_f32_e64 v27, v71, v75
	ds_read_b128 v[70:73], v82 offset:4288
	v_mul_f32_e64 v2, v2, v74
	v_mul_f32_e64 v3, v3, v75
	v_mul_f32_e64 v60, v60, v78
	v_mul_f32_e64 v61, v61, v79
	s_waitcnt lgkmcnt(1)
	s_nop 0
	v_mov_b32_e32 v74, v34
	v_mov_b32_e32 v34, v35
	v_mov_b32_e32 v35, v36
	v_mov_b32_e32 v75, v34
	v_mov_b32_e32 v80, v35
	s_nop 0
	v_mov_b32_e32 v81, v37
	v_mul_f32_e64 v34, v66, v74
	v_mul_f32_e64 v35, v67, v75
	s_waitcnt lgkmcnt(0)
	v_mov_b32_e32 v66, v70
	v_mov_b32_e32 v67, v72
	v_mul_f32_e64 v58, v58, v76
	v_mul_f32_e64 v59, v59, v77
	v_mul_f32_e64 v16, v16, v78
	v_mul_f32_e64 v17, v17, v79
	v_mul_f32_e64 v14, v14, v76
	v_mul_f32_e64 v15, v15, v77
	v_mov_b32_e32 v76, v66
	v_mov_b32_e32 v66, v71
	v_mov_b32_e32 v78, v67
	v_mov_b32_e32 v67, v73
	v_mul_f32_e64 v36, v68, v80
	v_mul_f32_e64 v37, v69, v81
	v_mov_b32_e32 v79, v67
	v_mov_b32_e32 v77, v66
	ds_read_b128 v[66:69], v82 offset:4352
	ds_read_b128 v[70:73], v82 offset:4416
	v_mul_f32_e64 v18, v18, v74
	v_mul_f32_e64 v19, v19, v75
	v_mfma_f32_16x16x32_bf16 v[50:53], v[90:93], v[98:101], v[50:53]
	v_mul_f32_e64 v64, v64, v78
	v_mul_f32_e64 v65, v65, v79
	s_waitcnt lgkmcnt(1)
	s_nop 0
	v_mov_b32_e32 v74, v66
	v_mov_b32_e32 v75, v67
	v_mov_b32_e32 v66, v68
	v_mov_b32_e32 v67, v69
	s_nop 0
	s_nop 0
	v_mul_f32_e64 v62, v62, v76
	v_mul_f32_e64 v63, v63, v77
	v_mul_f32_e64 v24, v24, v78
	v_mul_f32_e64 v25, v25, v79
	v_mul_f32_e64 v22, v22, v76
	v_mul_f32_e64 v23, v23, v77
	v_mul_f32_e64 v40, v40, v66
	v_mul_f32_e64 v41, v41, v67
	v_mul_f32_e64 v52, v52, v66
	v_mul_f32_e64 v53, v53, v67
	s_waitcnt lgkmcnt(0)
	v_mov_b32_e32 v66, v70
	v_mov_b32_e32 v67, v72
	v_mov_b32_e32 v76, v66
	v_mov_b32_e32 v66, v71
	v_mov_b32_e32 v78, v67
	s_nop 0
	v_mov_b32_e32 v79, v73
	v_mov_b32_e32 v77, v66
	ds_read_b128 v[66:69], v82 offset:4480
	ds_read_b128 v[70:73], v82 offset:4544
	v_mfma_f32_16x16x32_bf16 v[42:45], v[102:105], v[94:97], v[42:45]
	v_mul_f32_e64 v20, v20, v80
	v_mul_f32_e64 v21, v21, v81
	s_nop 0
	s_waitcnt lgkmcnt(1)
	s_nop 0
	s_nop 0
	v_mfma_f32_16x16x32_bf16 v[46:49], v[102:105], v[98:101], v[46:49]
	s_nop 0
	s_nop 0
	v_mul_f32_e64 v38, v38, v74
	v_mul_f32_e64 v39, v39, v75
	v_mul_f32_e64 v50, v50, v74
	v_mul_f32_e64 v51, v51, v75
	s_nop 0
	v_mul_f32_e64 v42, v42, v66
	v_mul_f32_e64 v43, v43, v67
	s_nop 1
	v_mul_f32_e64 v46, v46, v66
	v_mul_f32_e64 v47, v47, v67
	v_lshl_add_u64 v[66:67], v[120:121], 0, s[30:31]
	s_movk_i32 s30, 0x2000
	global_store_dwordx4 v[66:67], v[26:29], off
	s_nop 0
	v_mul_f32_e64 v32, v32, v78
	v_mul_f32_e64 v33, v33, v79
	v_add_co_u32_e32 v26, vcc, s30, v66
	s_movk_i32 s30, 0x4000
	s_nop 0
	v_addc_co_u32_e32 v27, vcc, 0, v67, vcc
	global_store_dwordx4 v[26:27], v[2:5], off
	v_mul_f32_e64 v30, v30, v76
	v_mul_f32_e64 v31, v31, v77
	s_nop 0
	v_add_co_u32_e32 v2, vcc, s30, v66
	s_movk_i32 s30, 0x6000
	s_nop 0
	v_addc_co_u32_e32 v3, vcc, 0, v67, vcc
	global_store_dwordx4 v[2:3], v[58:61], off
	v_add_co_u32_e32 v2, vcc, s30, v66
	s_nop 0
	s_nop 0
	v_addc_co_u32_e32 v3, vcc, 0, v67, vcc
	global_store_dwordx4 v[2:3], v[14:17], off
	v_add_co_u32_e32 v2, vcc, s62, v66
	v_mul_f32_e64 v56, v56, v78
	v_mul_f32_e64 v57, v57, v79
	s_nop 0
	v_addc_co_u32_e32 v3, vcc, 0, v67, vcc
	global_store_dwordx4 v[2:3], v[34:37], off
	v_add_co_u32_e32 v2, vcc, s69, v66
	v_mul_f32_e64 v54, v54, v76
	v_mul_f32_e64 v55, v55, v77
	s_nop 0
	v_addc_co_u32_e32 v3, vcc, 0, v67, vcc
	global_store_dwordx4 v[2:3], v[18:21], off
	v_add_co_u32_e32 v2, vcc, s70, v66
	s_waitcnt lgkmcnt(0)
	s_nop 0
	v_addc_co_u32_e32 v3, vcc, 0, v67, vcc
	global_store_dwordx4 v[2:3], v[62:65], off
	v_add_co_u32_e32 v2, vcc, s71, v66
	s_nop 0
	s_nop 0
	v_addc_co_u32_e32 v3, vcc, 0, v67, vcc
	global_store_dwordx4 v[2:3], v[22:25], off
	v_add_co_u32_e32 v2, vcc, s72, v66
	s_nop 0
	s_nop 0
	v_addc_co_u32_e32 v3, vcc, 0, v67, vcc
	global_store_dwordx4 v[2:3], v[38:41], off
	v_add_co_u32_e32 v2, vcc, s66, v66
	s_nop 0
	s_nop 0
	v_addc_co_u32_e32 v3, vcc, 0, v67, vcc
	global_store_dwordx4 v[2:3], v[50:53], off
	v_add_co_u32_e32 v2, vcc, s73, v66
	v_mfma_f32_16x16x32_bf16 v[6:9], v[106:109], v[94:97], v[6:9]
	s_nop 0
	v_addc_co_u32_e32 v3, vcc, 0, v67, vcc
	global_store_dwordx4 v[2:3], v[30:33], off
	v_add_co_u32_e32 v2, vcc, s74, v66
	v_mul_f32_e64 v44, v44, v68
	v_mul_f32_e64 v45, v45, v69
	s_nop 0
	v_addc_co_u32_e32 v3, vcc, 0, v67, vcc
	global_store_dwordx4 v[2:3], v[54:57], off
	v_add_co_u32_e32 v2, vcc, s64, v66
	s_nop 0
	s_nop 0
	s_nop 0
	s_nop 0
	v_addc_co_u32_e32 v3, vcc, 0, v67, vcc
	global_store_dwordx4 v[2:3], v[42:45], off
	v_add_co_u32_e32 v2, vcc, s75, v66
	v_mfma_f32_16x16x32_bf16 v[10:13], v[106:109], v[98:101], v[10:13]
	v_mul_f32_e64 v48, v48, v68
	v_mul_f32_e64 v49, v49, v69
	v_addc_co_u32_e32 v3, vcc, 0, v67, vcc
	global_store_dwordx4 v[2:3], v[46:49], off
	v_add_co_u32_e32 v2, vcc, 0x1c000, v66
	v_mul_f32_e64 v8, v8, v72
	v_mul_f32_e64 v9, v9, v73
	v_mul_f32_e64 v6, v6, v70
	v_mul_f32_e64 v7, v7, v71
	v_addc_co_u32_e32 v3, vcc, 0, v67, vcc
	global_store_dwordx4 v[2:3], v[6:9], off
	v_add_co_u32_e32 v2, vcc, 0x1e000, v66
	v_mul_f32_e64 v12, v12, v72
	v_mul_f32_e64 v13, v13, v73
	v_mul_f32_e64 v10, v10, v70
	v_mul_f32_e64 v11, v11, v71
	v_addc_co_u32_e32 v3, vcc, 0, v67, vcc
	global_store_dwordx4 v[2:3], v[10:13], off
	s_and_saveexec_b64 s[30:31], s[4:5]
	s_cbranch_execz .LBB0_450
	v_mul_f32_e32 v1, 0x3fb8aa3b, v1
	v_exp_f32_e32 v1, v1
	s_lshl_b64 s[46:47], s[42:43], 9
	v_lshl_add_u64 v[2:3], v[118:119], 0, s[46:47]
	global_store_dword v[2:3], v1, off
	s_branch .LBB0_450

.LBB0_501:
	ds_read_b128 v[160:163], v149 offset:6144
	ds_read_b128 v[164:167], v149 offset:6160
	s_waitcnt vmcnt(6)
	v_lshlrev_b32_e32 v108, 16, v98
	v_and_b32_e32 v109, 0xffff0000, v98
	v_cvt_pk_bf16_f32 v180, v34, v35
	s_waitcnt lgkmcnt(1)
	v_mul_f32_e32 v1, 0xbfb8aa3b, v160
	v_mul_f32_e32 v107, 0xbfb8aa3b, v161
	v_exp_f32_e32 v168, v1
	v_exp_f32_e32 v169, v107
	v_mul_f32_e32 v1, 0xbfb8aa3b, v162
	v_exp_f32_e32 v170, v1
	v_mul_f32_e32 v1, 0xbfb8aa3b, v163
	v_exp_f32_e32 v171, v1
	s_waitcnt lgkmcnt(0)
	v_mul_f32_e32 v1, 0xbfb8aa3b, v164
	v_mul_f32_e64 v108, v168, v108
	v_mul_f32_e64 v109, v169, v109
	v_exp_f32_e32 v168, v1
	v_mul_f32_e32 v1, 0xbfb8aa3b, v165
	v_exp_f32_e32 v169, v1
	v_cvt_pk_bf16_f32 v98, v108, v109
	v_lshlrev_b32_e32 v108, 16, v99
	v_and_b32_e32 v109, 0xffff0000, v99
	v_mul_f32_e64 v108, v170, v108
	v_mul_f32_e64 v109, v171, v109
	v_mul_f32_e32 v1, 0xbfb8aa3b, v166
	v_cvt_pk_bf16_f32 v99, v108, v109
	v_lshlrev_b32_e32 v108, 16, v100
	v_and_b32_e32 v109, 0xffff0000, v100
	v_mul_f32_e64 v108, v168, v108
	v_mul_f32_e64 v109, v169, v109
	v_exp_f32_e32 v168, v1
	v_mul_f32_e32 v1, 0xbfb8aa3b, v167
	v_exp_f32_e32 v169, v1
	v_cvt_pk_bf16_f32 v100, v108, v109
	v_lshlrev_b32_e32 v108, 16, v101
	v_and_b32_e32 v109, 0xffff0000, v101
	v_mul_f32_e64 v108, v168, v108
	v_mul_f32_e64 v109, v169, v109
	v_mul_f32_e32 v1, 0x3fb8aa3b, v160
	v_cvt_pk_bf16_f32 v101, v108, v109
	v_exp_f32_e32 v108, v1
	v_mul_f32_e32 v1, 0x3fb8aa3b, v161
	v_exp_f32_e32 v109, v1
	ds_write_b128 v135, v[98:101] offset:56320
	v_lshlrev_b32_e32 v98, 16, v94
	v_and_b32_e32 v99, 0xffff0000, v94
	v_mul_f32_e64 v100, v108, s40
	v_mul_f32_e64 v101, v109, s40
	v_mul_f32_e32 v1, 0x3fb8aa3b, v162
	v_mul_f32_e64 v98, v100, v98
	v_mul_f32_e64 v99, v101, v99
	v_exp_f32_e32 v100, v1
	v_mul_f32_e32 v1, 0x3fb8aa3b, v163
	v_exp_f32_e32 v101, v1
	v_cvt_pk_bf16_f32 v94, v98, v99
	v_lshlrev_b32_e32 v98, 16, v95
	v_and_b32_e32 v99, 0xffff0000, v95
	v_mul_f32_e64 v100, v100, s40
	v_mul_f32_e64 v101, v101, s40
	v_mul_f32_e32 v1, 0x3fb8aa3b, v164
	v_mul_f32_e64 v98, v100, v98
	v_mul_f32_e64 v99, v101, v99
	v_exp_f32_e32 v100, v1
	v_mul_f32_e32 v1, 0x3fb8aa3b, v165
	v_exp_f32_e32 v101, v1
	v_cvt_pk_bf16_f32 v95, v98, v99
	v_lshlrev_b32_e32 v98, 16, v96
	v_and_b32_e32 v99, 0xffff0000, v96
	v_mul_f32_e64 v100, v100, s40
	v_mul_f32_e64 v101, v101, s40
	v_mul_f32_e32 v1, 0x3fb8aa3b, v166
	v_mul_f32_e64 v98, v100, v98
	v_mul_f32_e64 v99, v101, v99
	v_exp_f32_e32 v100, v1
	v_mul_f32_e32 v1, 0x3fb8aa3b, v167
	v_exp_f32_e32 v101, v1
	v_cvt_pk_bf16_f32 v96, v98, v99
	v_lshlrev_b32_e32 v98, 16, v97
	v_and_b32_e32 v99, 0xffff0000, v97
	v_mul_f32_e64 v100, v100, s40
	v_mul_f32_e64 v101, v101, s40
	s_waitcnt vmcnt(4)
	v_lshlrev_b32_e32 v160, 16, v90
	v_mul_f32_e64 v98, v100, v98
	v_mul_f32_e64 v99, v101, v99
	v_and_b32_e32 v161, 0xffff0000, v90
	v_cvt_pk_bf16_f32 v97, v98, v99
	ds_write_b128 v135, v[94:97] offset:38912
	ds_read_b128 v[94:97], v151 offset:6144
	ds_read_b128 v[98:101], v151 offset:6160
	v_cvt_pk_bf16_f32 v181, v36, v37
	v_cvt_pk_bf16_f32 v182, v30, v31
	v_cvt_pk_bf16_f32 v183, v32, v33
	s_waitcnt lgkmcnt(1)
	v_mul_f32_e32 v1, 0xbfb8aa3b, v94
	v_exp_f32_e32 v108, v1
	v_mul_f32_e32 v1, 0xbfb8aa3b, v95
	v_exp_f32_e32 v109, v1
	v_mul_f32_e32 v1, 0xbfb8aa3b, v96
	v_add_u32_e32 v107, 0xa800, v147
	s_add_u32 s46, s46, 0x60000
	v_mul_f32_e64 v108, v108, v160
	v_mul_f32_e64 v109, v109, v161
	v_exp_f32_e32 v160, v1
	v_mul_f32_e32 v1, 0xbfb8aa3b, v97
	v_exp_f32_e32 v161, v1
	v_cvt_pk_bf16_f32 v90, v108, v109
	v_lshlrev_b32_e32 v108, 16, v91
	v_and_b32_e32 v109, 0xffff0000, v91
	s_waitcnt lgkmcnt(0)
	v_mul_f32_e32 v1, 0xbfb8aa3b, v98
	v_mul_f32_e64 v108, v160, v108
	v_mul_f32_e64 v109, v161, v109
	v_exp_f32_e32 v160, v1
	v_mul_f32_e32 v1, 0xbfb8aa3b, v99
	v_exp_f32_e32 v161, v1
	v_cvt_pk_bf16_f32 v91, v108, v109
	v_lshlrev_b32_e32 v108, 16, v92
	v_and_b32_e32 v109, 0xffff0000, v92
	v_mul_f32_e32 v1, 0xbfb8aa3b, v100
	v_mul_f32_e64 v108, v160, v108
	v_mul_f32_e64 v109, v161, v109
	v_exp_f32_e32 v160, v1
	v_mul_f32_e32 v1, 0xbfb8aa3b, v101
	v_exp_f32_e32 v161, v1
	v_mul_f32_e32 v1, 0x3fb8aa3b, v94
	v_exp_f32_e32 v94, v1
	v_mul_f32_e32 v1, 0x3fb8aa3b, v95
	v_exp_f32_e32 v95, v1
	v_cvt_pk_bf16_f32 v92, v108, v109
	v_lshlrev_b32_e32 v108, 16, v93
	v_and_b32_e32 v109, 0xffff0000, v93
	v_mul_f32_e64 v108, v160, v108
	v_mul_f32_e64 v109, v161, v109
	v_mul_f32_e32 v1, 0x3fb8aa3b, v96
	v_cvt_pk_bf16_f32 v93, v108, v109
	ds_write_b128 v136, v[90:93] offset:56320
	v_lshlrev_b32_e32 v90, 16, v86
	v_and_b32_e32 v91, 0xffff0000, v86
	v_mul_f32_e64 v92, v94, s40
	v_mul_f32_e64 v93, v95, s40
	v_add_u32_e32 v108, 0xb800, v147
	v_mul_f32_e64 v90, v92, v90
	v_mul_f32_e64 v91, v93, v91
	v_exp_f32_e32 v92, v1
	v_mul_f32_e32 v1, 0x3fb8aa3b, v97
	v_exp_f32_e32 v93, v1
	v_cvt_pk_bf16_f32 v86, v90, v91
	v_lshlrev_b32_e32 v90, 16, v87
	v_and_b32_e32 v91, 0xffff0000, v87
	v_mul_f32_e64 v92, v92, s40
	v_mul_f32_e64 v93, v93, s40
	v_mul_f32_e32 v1, 0x3fb8aa3b, v98
	v_mul_f32_e64 v90, v92, v90
	v_mul_f32_e64 v91, v93, v91
	v_exp_f32_e32 v92, v1
	v_mul_f32_e32 v1, 0x3fb8aa3b, v99
	v_exp_f32_e32 v93, v1
	v_cvt_pk_bf16_f32 v87, v90, v91
	v_lshlrev_b32_e32 v90, 16, v88
	v_and_b32_e32 v91, 0xffff0000, v88
	v_mul_f32_e64 v92, v92, s40
	v_mul_f32_e64 v93, v93, s40
	v_mul_f32_e32 v1, 0x3fb8aa3b, v100
	v_mul_f32_e64 v90, v92, v90
	v_mul_f32_e64 v91, v93, v91
	v_exp_f32_e32 v92, v1
	v_mul_f32_e32 v1, 0x3fb8aa3b, v101
	v_exp_f32_e32 v93, v1
	v_cvt_pk_bf16_f32 v88, v90, v91
	v_lshlrev_b32_e32 v90, 16, v89
	v_and_b32_e32 v91, 0xffff0000, v89
	v_mul_f32_e64 v92, v92, s40
	v_mul_f32_e64 v93, v93, s40
	v_add_u32_e32 v109, 0xc800, v147
	v_mul_f32_e64 v90, v92, v90
	v_mul_f32_e64 v91, v93, v91
	s_addc_u32 s47, s47, 0
	v_cvt_pk_bf16_f32 v89, v90, v91
	ds_write_b128 v136, v[86:89] offset:38912
	s_waitcnt vmcnt(3)
	ds_write_b128 v153, v[70:73]
	s_waitcnt vmcnt(2)
	ds_write_b128 v155, v[74:77]
	s_waitcnt vmcnt(1)
	ds_write_b128 v153, v[78:81] offset:16896
	s_waitcnt vmcnt(0)
	ds_write_b128 v156, v[82:85]
	s_waitcnt lgkmcnt(0)
	s_barrier
	ds_read_b128 v[70:73], v142 offset:56320
	ds_read_b128 v[74:77], v142 offset:56384
	ds_read_b128 v[78:81], v134 offset:38912
	ds_read_b128 v[82:85], v134 offset:38976
	ds_read_b128 v[86:89], v142 offset:56448
	s_waitcnt lgkmcnt(2)
	v_mfma_f32_16x16x32_bf16 v[70:73], v[70:73], v[78:81], 0
	s_add_i32 s30, s30, 64
	s_waitcnt lgkmcnt(1)
	v_mfma_f32_16x16x32_bf16 v[70:73], v[74:77], v[82:85], v[70:73]
	ds_read_b128 v[74:77], v142 offset:56512
	ds_read_b128 v[90:93], v134 offset:39040
	ds_read_b128 v[94:97], v134 offset:39104
	s_waitcnt lgkmcnt(1)
	v_mfma_f32_16x16x32_bf16 v[70:73], v[86:89], v[90:93], v[70:73]
	s_waitcnt lgkmcnt(0)
	v_mfma_f32_16x16x32_bf16 v[70:73], v[74:77], v[94:97], v[70:73]
	v_mov_b32_e32 v74, s59
	s_nop 6
	v_cndmask_b32_e64 v1, v70, v74, s[14:15]
	v_cndmask_b32_e64 v1, v1, v70, s[16:17]
	v_cndmask_b32_e64 v70, 0, v71, s[16:17]
	v_cndmask_b32_e64 v71, v72, 0, s[18:19]
	v_cndmask_b32_e64 v72, v73, 0, s[20:21]
	v_cvt_pk_bf16_f32 v70, v1, v70
	v_cvt_pk_bf16_f32 v71, v71, v72
	ds_write_b64 v143, v[70:71]
	ds_read_b128 v[70:73], v144 offset:56320
	ds_read_b128 v[74:77], v144 offset:56384
	s_waitcnt lgkmcnt(1)
	v_mfma_f32_16x16x32_bf16 v[70:73], v[70:73], v[78:81], 0
	ds_read_b128 v[78:81], v144 offset:56448
	s_waitcnt lgkmcnt(1)
	v_mfma_f32_16x16x32_bf16 v[70:73], v[74:77], v[82:85], v[70:73]
	ds_read_b128 v[74:77], v144 offset:56512
	s_waitcnt lgkmcnt(1)
	v_mfma_f32_16x16x32_bf16 v[70:73], v[78:81], v[90:93], v[70:73]
	s_waitcnt lgkmcnt(0)
	v_mfma_f32_16x16x32_bf16 v[70:73], v[74:77], v[94:97], v[70:73]
	v_mov_b32_e32 v74, s59
	s_nop 6
	v_cndmask_b32_e64 v1, v70, v74, s[22:23]
	v_cndmask_b32_e64 v1, v1, v70, s[24:25]
	v_cndmask_b32_e64 v70, 0, v71, s[24:25]
	v_cndmask_b32_e64 v71, v72, 0, s[26:27]
	v_cndmask_b32_e64 v72, v73, 0, s[28:29]
	v_cvt_pk_bf16_f32 v70, v1, v70
	v_cvt_pk_bf16_f32 v71, v71, v72
	ds_write_b64 v145, v[70:71]
	s_waitcnt lgkmcnt(0)
	s_barrier
	ds_read_b64_tr_b16 v[76:77], v157 offset:2112
	ds_read_b64_tr_b16 v[74:75], v157
	ds_read_b64_tr_b16 v[80:81], v157 offset:2144
	ds_read_b64_tr_b16 v[78:79], v157 offset:32
	ds_read_b128 v[70:73], v146
	ds_read_b128 v[86:89], v146 offset:64
	s_waitcnt lgkmcnt(1)
	v_mfma_f32_16x16x32_bf16 v[90:93], v[74:77], v[70:73], 0
	ds_read_b64_tr_b16 v[82:83], v157 offset:16896
	ds_read_b64_tr_b16 v[84:85], v157 offset:19008
	v_add_u32_e32 v1, 0x9800, v147
	v_mfma_f32_16x16x32_bf16 v[94:97], v[78:81], v[70:73], 0
	ds_read_b64_tr_b16 v[72:73], v157 offset:19040
	ds_read_b64_tr_b16 v[70:71], v157 offset:16928
	s_waitcnt lgkmcnt(2)
	v_mfma_f32_16x16x32_bf16 v[90:93], v[82:85], v[86:89], v[90:93]
	s_waitcnt lgkmcnt(0)
	v_mfma_f32_16x16x32_bf16 v[86:89], v[70:73], v[86:89], v[94:97]
	s_nop 2
	ds_read_b128 v[94:97], v146 offset:2304
	ds_read_b128 v[98:101], v146 offset:2368
	s_waitcnt lgkmcnt(1)
	v_mfma_f32_16x16x32_bf16 v[160:163], v[74:77], v[94:97], 0
	v_mfma_f32_16x16x32_bf16 v[94:97], v[78:81], v[94:97], 0
	s_waitcnt lgkmcnt(0)
	v_mfma_f32_16x16x32_bf16 v[160:163], v[82:85], v[98:101], v[160:163]
	v_mfma_f32_16x16x32_bf16 v[94:97], v[70:73], v[98:101], v[94:97]
	ds_read_b128 v[98:101], v146 offset:4608
	ds_read_b128 v[164:167], v146 offset:4672
	s_waitcnt lgkmcnt(1)
	v_mfma_f32_16x16x32_bf16 v[168:171], v[74:77], v[98:101], 0
	v_mfma_f32_16x16x32_bf16 v[98:101], v[78:81], v[98:101], 0
	s_waitcnt lgkmcnt(0)
	v_mfma_f32_16x16x32_bf16 v[168:171], v[82:85], v[164:167], v[168:171]
	v_mfma_f32_16x16x32_bf16 v[98:101], v[70:73], v[164:167], v[98:101]
	ds_read_b128 v[164:167], v146 offset:6912
	ds_read_b128 v[172:175], v146 offset:6976
	ds_read2_b64 v[184:187], v1 offset1:4
	ds_read2_b64 v[188:191], v1 offset0:8 offset1:12
	s_waitcnt lgkmcnt(3)
	v_mfma_f32_16x16x32_bf16 v[176:179], v[74:77], v[164:167], 0
	v_mfma_f32_16x16x32_bf16 v[164:167], v[78:81], v[164:167], 0
	s_waitcnt lgkmcnt(2)
	v_mfma_f32_16x16x32_bf16 v[176:179], v[82:85], v[172:175], v[176:179]
	v_mfma_f32_16x16x32_bf16 v[164:167], v[70:73], v[172:175], v[164:167]
	v_cvt_pk_bf16_f32 v172, v14, v15
	v_cvt_pk_bf16_f32 v173, v16, v17
	v_cvt_pk_bf16_f32 v174, v58, v59
	v_cvt_pk_bf16_f32 v175, v60, v61
	s_waitcnt lgkmcnt(1)
	v_mfma_f32_16x16x32_bf16 v[90:93], v[180:183], v[184:187], v[90:93]
	v_mfma_f32_16x16x32_bf16 v[86:89], v[172:175], v[184:187], v[86:89]
	ds_read2_b64 v[184:187], v107 offset0:32 offset1:36
	s_waitcnt lgkmcnt(0)
	v_mfma_f32_16x16x32_bf16 v[160:163], v[180:183], v[184:187], v[160:163]
	v_mfma_f32_16x16x32_bf16 v[94:97], v[172:175], v[184:187], v[94:97]
	ds_read2_b64 v[184:187], v108 offset0:64 offset1:68
	s_waitcnt lgkmcnt(0)
	v_mfma_f32_16x16x32_bf16 v[168:171], v[180:183], v[184:187], v[168:171]
	v_mfma_f32_16x16x32_bf16 v[98:101], v[172:175], v[184:187], v[98:101]
	ds_read2_b64 v[184:187], v109 offset0:96 offset1:100
	s_waitcnt lgkmcnt(0)
	v_mfma_f32_16x16x32_bf16 v[176:179], v[180:183], v[184:187], v[176:179]
	v_cvt_pk_bf16_f32 v180, v54, v55
	v_cvt_pk_bf16_f32 v181, v56, v57
	v_cvt_pk_bf16_f32 v182, v62, v63
	v_cvt_pk_bf16_f32 v183, v64, v65
	v_mfma_f32_16x16x32_bf16 v[164:167], v[172:175], v[184:187], v[164:167]
	v_cvt_pk_bf16_f32 v172, v46, v47
	v_cvt_pk_bf16_f32 v173, v48, v49
	v_cvt_pk_bf16_f32 v174, v66, v67
	v_cvt_pk_bf16_f32 v175, v68, v69
	ds_read2_b64 v[184:187], v107 offset0:40 offset1:44
	s_waitcnt lgkmcnt(0)
	v_mfma_f32_16x16x32_bf16 v[160:163], v[180:183], v[184:187], v[160:163]
	v_mfma_f32_16x16x32_bf16 v[94:97], v[172:175], v[184:187], v[94:97]
	ds_read2_b64 v[184:187], v108 offset0:72 offset1:76
	s_waitcnt lgkmcnt(0)
	v_mfma_f32_16x16x32_bf16 v[168:171], v[180:183], v[184:187], v[168:171]
	v_mfma_f32_16x16x32_bf16 v[98:101], v[172:175], v[184:187], v[98:101]
	ds_read2_b64 v[184:187], v109 offset0:104 offset1:108
	v_mfma_f32_16x16x32_bf16 v[90:93], v[180:183], v[188:191], v[90:93]
	v_mfma_f32_16x16x32_bf16 v[86:89], v[172:175], v[188:191], v[86:89]
	ds_read2_b64 v[188:191], v1 offset0:16 offset1:20
	s_waitcnt lgkmcnt(1)
	v_mfma_f32_16x16x32_bf16 v[176:179], v[180:183], v[184:187], v[176:179]
	v_cvt_pk_bf16_f32 v180, v22, v23
	v_cvt_pk_bf16_f32 v181, v24, v25
	v_cvt_pk_bf16_f32 v182, v18, v19
	v_cvt_pk_bf16_f32 v183, v20, v21
	v_mfma_f32_16x16x32_bf16 v[164:167], v[172:175], v[184:187], v[164:167]
	v_cvt_pk_bf16_f32 v172, v10, v11
	v_cvt_pk_bf16_f32 v173, v12, v13
	v_cvt_pk_bf16_f32 v174, v50, v51
	v_cvt_pk_bf16_f32 v175, v52, v53
	ds_read2_b64 v[184:187], v107 offset0:48 offset1:52
	s_waitcnt lgkmcnt(0)
	v_mfma_f32_16x16x32_bf16 v[160:163], v[180:183], v[184:187], v[160:163]
	v_mfma_f32_16x16x32_bf16 v[94:97], v[172:175], v[184:187], v[94:97]
	ds_read2_b64 v[184:187], v108 offset0:80 offset1:84
	s_waitcnt lgkmcnt(0)
	v_mfma_f32_16x16x32_bf16 v[168:171], v[180:183], v[184:187], v[168:171]
	v_mfma_f32_16x16x32_bf16 v[98:101], v[172:175], v[184:187], v[98:101]
	ds_read2_b64 v[184:187], v109 offset0:112 offset1:116
	v_mfma_f32_16x16x32_bf16 v[90:93], v[180:183], v[188:191], v[90:93]
	v_mfma_f32_16x16x32_bf16 v[86:89], v[172:175], v[188:191], v[86:89]
	ds_read2_b64 v[188:191], v1 offset0:24 offset1:28
	v_lshl_add_u32 v1, s79, 9, v128
	s_waitcnt lgkmcnt(1)
	v_mfma_f32_16x16x32_bf16 v[176:179], v[180:183], v[184:187], v[176:179]
	v_cvt_pk_bf16_f32 v180, v38, v39
	v_cvt_pk_bf16_f32 v181, v40, v41
	v_cvt_pk_bf16_f32 v182, v26, v27
	v_cvt_pk_bf16_f32 v183, v28, v29
	v_mfma_f32_16x16x32_bf16 v[164:167], v[172:175], v[184:187], v[164:167]
	v_cvt_pk_bf16_f32 v172, v42, v43
	v_cvt_pk_bf16_f32 v173, v44, v45
	v_cvt_pk_bf16_f32 v174, v6, v7
	v_cvt_pk_bf16_f32 v175, v8, v9
	ds_read2_b64 v[184:187], v107 offset0:56 offset1:60
	s_waitcnt lgkmcnt(0)
	v_mfma_f32_16x16x32_bf16 v[160:163], v[180:183], v[184:187], v[160:163]
	v_mfma_f32_16x16x32_bf16 v[94:97], v[172:175], v[184:187], v[94:97]
	ds_read2_b64 v[184:187], v108 offset0:88 offset1:92
	s_waitcnt lgkmcnt(0)
	v_mfma_f32_16x16x32_bf16 v[168:171], v[180:183], v[184:187], v[168:171]
	v_mfma_f32_16x16x32_bf16 v[98:101], v[172:175], v[184:187], v[98:101]
	ds_read2_b64 v[184:187], v109 offset0:120 offset1:124
	v_mfma_f32_16x16x32_bf16 v[90:93], v[180:183], v[188:191], v[90:93]
	s_waitcnt lgkmcnt(0)
	v_mfma_f32_16x16x32_bf16 v[176:179], v[180:183], v[184:187], v[176:179]
	ds_read_b64_tr_b16 v[182:183], v158 offset:57408
	ds_read_b64_tr_b16 v[180:181], v158 offset:56320
	s_nop 3
	v_cvt_pk_bf16_f32 v90, v90, v91
	v_cvt_pk_bf16_f32 v91, v92, v93
	v_mfma_f32_16x16x32_bf16 v[86:89], v[172:175], v[188:191], v[86:89]
	v_lshl_add_u64 v[92:93], s[44:45], 0, v[116:117]
	s_add_u32 s44, s44, 0x20000
	s_addc_u32 s45, s45, 0
	v_mfma_f32_16x16x32_bf16 v[164:167], v[172:175], v[184:187], v[164:167]
	ds_read_b64_tr_b16 v[172:173], v158 offset:56352
	ds_read_b64_tr_b16 v[184:185], v158 offset:56384
	ds_read_b64_tr_b16 v[188:189], v158 offset:56416
	ds_read_b64_tr_b16 v[174:175], v158 offset:57440
	ds_read_b64_tr_b16 v[186:187], v158 offset:57472
	ds_read_b64_tr_b16 v[190:191], v158 offset:57504
	ds_read_b64_tr_b16 v[192:193], v158 offset:65024
	ds_read_b64_tr_b16 v[194:195], v159 offset:57408
	v_cvt_pk_bf16_f32 v86, v86, v87
	s_waitcnt lgkmcnt(4)
	v_mfma_f32_16x16x32_bf16 v[30:33], v[172:175], v[74:77], v[30:33]
	v_cvt_pk_bf16_f32 v87, v88, v89
	v_add_co_u32_e32 v88, vcc, s62, v92
	v_mfma_f32_16x16x32_bf16 v[58:61], v[172:175], v[78:81], v[58:61]
	s_nop 0
	v_addc_co_u32_e32 v89, vcc, 0, v93, vcc
	s_add_i32 s78, s78, 1
	v_mfma_f32_16x16x32_bf16 v[34:37], v[180:183], v[74:77], v[34:37]
	s_cmp_lg_u32 s46, 0x180000
	v_mfma_f32_16x16x32_bf16 v[14:17], v[180:183], v[78:81], v[14:17]
	ds_read_b64_tr_b16 v[180:181], v158 offset:65056
	ds_read_b64_tr_b16 v[196:197], v158 offset:65088
	ds_read_b64_tr_b16 v[200:201], v158 offset:65120
	ds_read_b64_tr_b16 v[182:183], v159 offset:57440
	ds_read_b64_tr_b16 v[198:199], v159 offset:57472
	ds_read_b64_tr_b16 v[202:203], v159 offset:57504
	ds_read_b64_tr_b16 v[172:173], v158 offset:56448
	ds_read_b64_tr_b16 v[174:175], v158 offset:57536
	s_waitcnt lgkmcnt(4)
	v_mfma_f32_16x16x32_bf16 v[30:33], v[180:183], v[82:85], v[30:33]
	v_mfma_f32_16x16x32_bf16 v[58:61], v[180:183], v[70:73], v[58:61]
	v_mfma_f32_16x16x32_bf16 v[54:57], v[184:187], v[74:77], v[54:57]
	v_mfma_f32_16x16x32_bf16 v[46:49], v[184:187], v[78:81], v[46:49]
	v_mfma_f32_16x16x32_bf16 v[62:65], v[188:191], v[74:77], v[62:65]
	v_mfma_f32_16x16x32_bf16 v[66:69], v[188:191], v[78:81], v[66:69]
	ds_read_b64_tr_b16 v[180:181], v158 offset:56480
	ds_read_b64_tr_b16 v[184:185], v158 offset:56512
	ds_read_b64_tr_b16 v[188:189], v158 offset:56544
	ds_read_b64_tr_b16 v[182:183], v158 offset:57568
	ds_read_b64_tr_b16 v[186:187], v158 offset:57600
	ds_read_b64_tr_b16 v[190:191], v158 offset:57632
	v_mfma_f32_16x16x32_bf16 v[34:37], v[192:195], v[82:85], v[34:37]
	v_mfma_f32_16x16x32_bf16 v[14:17], v[192:195], v[70:73], v[14:17]
	ds_read_b64_tr_b16 v[192:193], v158 offset:65152
	ds_read_b64_tr_b16 v[194:195], v159 offset:57536
	s_waitcnt lgkmcnt(11)
	v_mfma_f32_16x16x32_bf16 v[54:57], v[196:199], v[82:85], v[54:57]
	v_mfma_f32_16x16x32_bf16 v[46:49], v[196:199], v[70:73], v[46:49]
	s_waitcnt lgkmcnt(10)
	v_mfma_f32_16x16x32_bf16 v[62:65], v[200:203], v[82:85], v[62:65]
	v_mfma_f32_16x16x32_bf16 v[66:69], v[200:203], v[70:73], v[66:69]
	s_waitcnt lgkmcnt(8)
	v_mfma_f32_16x16x32_bf16 v[22:25], v[172:175], v[74:77], v[22:25]
	v_mfma_f32_16x16x32_bf16 v[10:13], v[172:175], v[78:81], v[10:13]
	ds_read_b64_tr_b16 v[172:173], v158 offset:65184
	ds_read_b64_tr_b16 v[196:197], v158 offset:65216
	ds_read_b64_tr_b16 v[200:201], v158 offset:65248
	ds_read_b64_tr_b16 v[174:175], v159 offset:57568
	ds_read_b64_tr_b16 v[198:199], v159 offset:57600
	ds_read_b64_tr_b16 v[202:203], v159 offset:57632
	global_store_dwordx2 v[92:93], v[86:87], off offset:32
	v_cvt_pk_bf16_f32 v86, v160, v161
	s_waitcnt lgkmcnt(10)
	v_mfma_f32_16x16x32_bf16 v[18:21], v[180:183], v[74:77], v[18:21]
	v_cvt_pk_bf16_f32 v87, v162, v163
	global_store_dwordx2 v[88:89], v[86:87], off
	v_cvt_pk_bf16_f32 v86, v94, v95
	v_mfma_f32_16x16x32_bf16 v[50:53], v[180:183], v[78:81], v[50:53]
	v_cvt_pk_bf16_f32 v87, v96, v97
	global_store_dwordx2 v[88:89], v[86:87], off offset:32
	v_add_co_u32_e32 v88, vcc, s72, v92
	s_waitcnt lgkmcnt(9)
	v_mfma_f32_16x16x32_bf16 v[38:41], v[184:187], v[74:77], v[38:41]
	v_cvt_pk_bf16_f32 v86, v168, v169
	v_cvt_pk_bf16_f32 v87, v170, v171
	v_addc_co_u32_e32 v89, vcc, 0, v93, vcc
	v_mfma_f32_16x16x32_bf16 v[42:45], v[184:187], v[78:81], v[42:45]
	global_store_dwordx2 v[88:89], v[86:87], off
	v_cvt_pk_bf16_f32 v86, v98, v99
	v_cvt_pk_bf16_f32 v87, v100, v101
	s_waitcnt lgkmcnt(8)
	v_mfma_f32_16x16x32_bf16 v[26:29], v[188:191], v[74:77], v[26:29]
	ds_read_b128 v[74:77], v1 offset:4096
	global_store_dwordx2 v[88:89], v[86:87], off offset:32
	v_add_co_u32_e32 v88, vcc, s64, v92
	v_mfma_f32_16x16x32_bf16 v[6:9], v[188:191], v[78:81], v[6:9]
	ds_read_b128 v[78:81], v1 offset:4160
	s_waitcnt lgkmcnt(1)
	s_nop 0
	s_nop 0
	v_mfma_f32_16x16x32_bf16 v[10:13], v[192:195], v[70:73], v[10:13]
	s_nop 0
	s_nop 0
	s_nop 0
	v_mfma_f32_16x16x32_bf16 v[50:53], v[172:175], v[70:73], v[50:53]
	s_nop 0
	s_nop 0
	s_nop 0
	v_mfma_f32_16x16x32_bf16 v[42:45], v[196:199], v[70:73], v[42:45]
	v_cvt_pk_bf16_f32 v86, v176, v177
	v_mul_f32_e64 v36, v36, v76
	v_mul_f32_e64 v37, v37, v77
	v_mul_f32_e64 v34, v34, v74
	v_mul_f32_e64 v35, v35, v75
	v_mfma_f32_16x16x32_bf16 v[6:9], v[200:203], v[70:73], v[6:9]
	s_waitcnt lgkmcnt(0)
	v_mov_b32_e32 v70, v78
	v_mov_b32_e32 v71, v80
	v_mov_b32_e32 v78, v70
	v_mov_b32_e32 v70, v79
	v_mov_b32_e32 v80, v71
	s_nop 0
	v_mov_b32_e32 v81, v81
	v_mov_b32_e32 v79, v70
	ds_read_b128 v[70:73], v1 offset:4224
	v_mul_f32_e64 v16, v16, v76
	v_mul_f32_e64 v17, v17, v77
	v_mul_f32_e64 v14, v14, v74
	v_mul_f32_e64 v15, v15, v75
	ds_read_b128 v[74:77], v1 offset:4288
	v_mfma_f32_16x16x32_bf16 v[22:25], v[192:195], v[82:85], v[22:25]
	s_waitcnt lgkmcnt(1)
	s_nop 0
	v_mul_f32_e64 v32, v32, v80
	v_mul_f32_e64 v33, v33, v81
	v_mul_f32_e64 v30, v30, v78
	v_mul_f32_e64 v31, v31, v79
	v_mfma_f32_16x16x32_bf16 v[18:21], v[172:175], v[82:85], v[18:21]
	v_mul_f32_e64 v60, v60, v80
	v_mul_f32_e64 v61, v61, v81
	v_mul_f32_e64 v58, v58, v78
	v_mul_f32_e64 v59, v59, v79
	v_cvt_pk_bf16_f32 v87, v178, v179
	v_mfma_f32_16x16x32_bf16 v[38:41], v[196:199], v[82:85], v[38:41]
	v_addc_co_u32_e32 v89, vcc, 0, v93, vcc
	global_store_dwordx2 v[88:89], v[86:87], off
	v_mfma_f32_16x16x32_bf16 v[26:29], v[200:203], v[82:85], v[26:29]
	v_mov_b32_e32 v82, v70
	v_mov_b32_e32 v83, v71
	v_mov_b32_e32 v70, v72
	v_mov_b32_e32 v71, v73
	s_nop 0
	s_nop 0
	s_nop 0
	v_cvt_pk_bf16_f32 v86, v164, v165
	v_cvt_pk_bf16_f32 v87, v166, v167
	v_mul_f32_e64 v56, v56, v70
	v_mul_f32_e64 v57, v57, v71
	v_mul_f32_e64 v48, v48, v70
	v_mul_f32_e64 v49, v49, v71
	s_waitcnt lgkmcnt(0)
	v_mov_b32_e32 v70, v74
	v_mov_b32_e32 v71, v76
	v_mov_b32_e32 v78, v70
	v_mov_b32_e32 v70, v75
	v_mov_b32_e32 v80, v71
	s_nop 0
	v_mov_b32_e32 v81, v77
	v_mov_b32_e32 v79, v70
	ds_read_b128 v[70:73], v1 offset:4352
	ds_read_b128 v[74:77], v1 offset:4416
	v_mul_f32_e64 v54, v54, v82
	v_mul_f32_e64 v55, v55, v83
	v_mul_f32_e64 v46, v46, v82
	v_mul_f32_e64 v47, v47, v83
	v_mul_f32_e64 v64, v64, v80
	v_mul_f32_e64 v65, v65, v81
	s_waitcnt lgkmcnt(1)
	s_nop 0
	v_mov_b32_e32 v82, v70
	v_mov_b32_e32 v83, v71
	v_mov_b32_e32 v70, v72
	v_mov_b32_e32 v71, v73
	s_nop 0
	s_nop 0
	v_mul_f32_e64 v62, v62, v78
	v_mul_f32_e64 v63, v63, v79
	v_mul_f32_e64 v68, v68, v80
	v_mul_f32_e64 v69, v69, v81
	v_mul_f32_e64 v66, v66, v78
	v_mul_f32_e64 v67, v67, v79
	v_mul_f32_e64 v24, v24, v70
	v_mul_f32_e64 v25, v25, v71
	v_mul_f32_e64 v12, v12, v70
	v_mul_f32_e64 v13, v13, v71
	s_waitcnt lgkmcnt(0)
	v_mov_b32_e32 v70, v74
	v_mov_b32_e32 v71, v76
	v_mov_b32_e32 v78, v70
	v_mov_b32_e32 v70, v75
	v_mov_b32_e32 v80, v71
	s_nop 0
	v_mov_b32_e32 v81, v77
	v_mov_b32_e32 v79, v70
	ds_read_b128 v[70:73], v1 offset:4480
	ds_read_b128 v[74:77], v1 offset:4544
	s_nop 0
	v_mul_f32_e64 v20, v20, v80
	v_mul_f32_e64 v21, v21, v81
	v_mul_f32_e64 v18, v18, v78
	v_mul_f32_e64 v19, v19, v79
	s_waitcnt lgkmcnt(1)
	s_nop 0
	v_mov_b32_e32 v70, v70
	v_mov_b32_e32 v1, v71
	v_mov_b32_e32 v71, v72
	v_mov_b32_e32 v72, v71
	s_nop 0
	v_mov_b32_e32 v73, v73
	v_mov_b32_e32 v71, v1
	s_waitcnt lgkmcnt(0)
	s_nop 0
	v_mov_b32_e32 v74, v74
	v_mov_b32_e32 v1, v75
	v_mov_b32_e32 v75, v76
	v_mov_b32_e32 v76, v75
	s_nop 0
	v_mov_b32_e32 v77, v77
	v_mov_b32_e32 v75, v1
	v_mul_f32_e64 v22, v22, v82
	v_mul_f32_e64 v23, v23, v83
	v_mul_f32_e64 v10, v10, v82
	v_mul_f32_e64 v11, v11, v83
	v_mul_f32_e64 v52, v52, v80
	v_mul_f32_e64 v53, v53, v81
	v_mul_f32_e64 v50, v50, v78
	v_mul_f32_e64 v51, v51, v79
	v_mul_f32_e64 v40, v40, v72
	v_mul_f32_e64 v41, v41, v73
	v_mul_f32_e64 v38, v38, v70
	v_mul_f32_e64 v39, v39, v71
	v_mul_f32_e64 v44, v44, v72
	v_mul_f32_e64 v45, v45, v73
	v_mul_f32_e64 v42, v42, v70
	v_mul_f32_e64 v43, v43, v71
	v_mul_f32_e64 v28, v28, v76
	v_mul_f32_e64 v29, v29, v77
	v_mul_f32_e64 v26, v26, v74
	v_mul_f32_e64 v27, v27, v75
	v_mul_f32_e64 v8, v8, v76
	v_mul_f32_e64 v9, v9, v77
	v_mul_f32_e64 v6, v6, v74
	v_mul_f32_e64 v7, v7, v75
	global_store_dwordx2 v[92:93], v[90:91], off
	global_store_dwordx2 v[88:89], v[86:87], off offset:32
	s_cbranch_scc0 .LBB0_451

.LBB0_579:
	s_or_b64 exec, exec, s[0:1]
	s_waitcnt lgkmcnt(0)
	s_barrier
	ds_read_b128 v[132:135], v180
	ds_read_b128 v[138:141], v180 offset:16
	s_add_i32 s58, s58, 1
	s_add_u32 s38, s38, 0xfffa0000
	s_addc_u32 s39, s39, -1
	s_waitcnt lgkmcnt(1)
	v_mov_b32_e32 v78, v133
	v_mov_b32_e32 v79, v134
	v_mov_b32_e32 v133, v135
	s_waitcnt vmcnt(9)
	v_lshlrev_b32_e32 v134, 16, v162
	v_and_b32_e32 v135, 0xffff0000, v162
	v_add_f32_e64 v78, v78, v132
	v_add_f32_e64 v79, v79, v133
	s_waitcnt lgkmcnt(0)
	v_mov_b32_e32 v132, v140
	v_mov_b32_e32 v133, v138
	v_mov_b32_e32 v138, v141
	v_mul_f32_e32 v140, 0xbfb8aa3b, v134
	v_mul_f32_e32 v141, 0xbfb8aa3b, v135
	v_exp_f32_e32 v140, v140
	v_exp_f32_e32 v141, v141
	v_add_f32_e64 v144, v132, v138
	v_add_f32_e64 v145, v133, v139
	v_lshlrev_b32_e32 v138, 16, v163
	v_and_b32_e32 v139, 0xffff0000, v163
	v_add_f32_e32 v132, 1.0, v140
	v_add_f32_e32 v133, 1.0, v141
	v_mul_f32_e32 v140, 0xbfb8aa3b, v138
	v_mul_f32_e32 v141, 0xbfb8aa3b, v139
	v_rcp_f32_e32 v132, v132
	v_rcp_f32_e32 v133, v133
	v_exp_f32_e32 v140, v140
	v_exp_f32_e32 v141, v141
	s_waitcnt vmcnt(8)
	v_lshlrev_b32_e32 v162, 16, v152
	v_mul_f32_e64 v146, v132, v134
	v_mul_f32_e64 v147, v133, v135
	v_add_f32_e32 v132, 1.0, v140
	v_add_f32_e32 v133, 1.0, v141
	v_and_b32_e32 v163, 0xffff0000, v152
	v_mul_f32_e32 v134, 0xbfb8aa3b, v162
	v_rcp_f32_e32 v132, v132
	v_rcp_f32_e32 v133, v133
	v_exp_f32_e32 v134, v134
	v_mul_f32_e32 v135, 0xbfb8aa3b, v163
	v_exp_f32_e32 v135, v135
	v_mul_f32_e64 v200, v132, v138
	v_mul_f32_e64 v201, v133, v139
	v_add_f32_e32 v132, 1.0, v134
	v_rcp_f32_e32 v202, v132
	v_add_f32_e32 v132, 1.0, v135
	v_lshlrev_b32_e32 v152, 16, v153
	v_and_b32_e32 v153, 0xffff0000, v153
	v_rcp_f32_e32 v203, v132
	v_mul_f32_e32 v132, 0xbfb8aa3b, v152
	v_mul_f32_e32 v133, 0xbfb8aa3b, v153
	v_exp_f32_e32 v132, v132
	v_exp_f32_e32 v138, v133
	s_sub_i32 s30, s30, 64
	v_add_f32_e32 v139, 1.0, v132
	ds_read_b128 v[132:135], v180 offset:512
	v_add_f32_e32 v138, 1.0, v138
	v_rcp_f32_e32 v204, v139
	v_rcp_f32_e32 v205, v138
	ds_read_b128 v[138:141], v180 offset:528
	s_waitcnt lgkmcnt(1)
	v_mov_b32_e32 v206, v133
	v_mov_b32_e32 v207, v134
	v_mov_b32_e32 v133, v135
	v_add_f32_e64 v132, v206, v132
	v_add_f32_e64 v133, v207, v133
	s_waitcnt lgkmcnt(0)
	v_mov_b32_e32 v134, v140
	v_mov_b32_e32 v135, v138
	v_mov_b32_e32 v138, v141
	v_add_f32_e64 v134, v134, v138
	v_add_f32_e64 v135, v135, v139
	v_mov_b32_e32 v138, v132
	v_mov_b32_e32 v139, v78
	v_mov_b32_e32 v78, v133
	v_add_f32_e64 v78, v138, v78
	v_add_f32_e64 v79, v139, v79
	v_mov_b32_e32 v132, v135
	v_mov_b32_e32 v133, v145
	v_add_f32_e64 v78, v78, v132
	v_add_f32_e64 v79, v79, v133
	v_mov_b32_e32 v135, v144
	v_add_f32_e64 v132, v134, v78
	v_add_f32_e64 v133, v135, v79
	v_mov_b64_e32 v[78:79], s[42:43]
	v_fma_f32 v132, v132, s40, v78
	v_fma_f32 v133, v133, s40, v78
	v_mul_f32_e64 v138, v202, v162
	v_mul_f32_e64 v139, v203, v163
	v_mul_f32_e32 v134, 0x4b800000, v133
	v_cmp_gt_f32_e64 s[0:1], s57, v133
	v_mul_f32_e64 v140, v204, v152
	v_mul_f32_e64 v141, v205, v153
	v_lshl_add_u64 v[152:153], s[34:35], 0, v[116:117]
	v_cndmask_b32_e64 v133, v133, v134, s[0:1]
	v_rsq_f32_e32 v133, v133
	v_lshl_add_u64 v[134:135], s[34:35], 0, v[106:107]
	v_mul_f32_e32 v144, 0x45800000, v133
	v_cndmask_b32_e64 v144, v133, v144, s[0:1]
	v_mul_f32_e64 v148, v148, v144
	v_mul_f32_e64 v149, v149, v144
	v_mul_f32_e32 v133, 0x4b800000, v132
	s_waitcnt vmcnt(1)
	v_mul_f32_e64 v148, v72, v148
	v_mul_f32_e64 v149, v73, v149
	v_cmp_gt_f32_e64 s[0:1], s57, v132
	v_mul_f32_e64 v146, v146, v148
	v_mul_f32_e64 v147, v147, v149
	v_mul_f32_e64 v148, v150, v144
	v_mul_f32_e64 v149, v151, v144
	v_cvt_pk_bf16_f32 v146, v146, v147
	v_mul_f32_e64 v148, v74, v148
	v_mul_f32_e64 v149, v75, v149
	v_cndmask_b32_e64 v132, v132, v133, s[0:1]
	v_mul_f32_e64 v148, v200, v148
	v_mul_f32_e64 v149, v201, v149
	v_rsq_f32_e32 v133, v132
	v_cvt_pk_bf16_f32 v147, v148, v149
	global_store_dwordx2 v[134:135], v[146:147], off
	v_mul_f32_e64 v146, v156, v144
	v_mul_f32_e64 v147, v157, v144
	v_mul_f32_e64 v145, v159, v144
	v_mul_f32_e64 v144, v158, v144
	s_waitcnt vmcnt(1)
	v_mul_f32_e64 v146, v68, v146
	v_mul_f32_e64 v147, v69, v147
	v_mul_f32_e64 v144, v70, v144
	v_mul_f32_e64 v145, v71, v145
	v_mul_f32_e64 v138, v138, v146
	v_mul_f32_e64 v139, v139, v147
	v_mul_f32_e64 v140, v140, v144
	v_mul_f32_e64 v141, v141, v145
	v_cvt_pk_bf16_f32 v138, v138, v139
	v_cvt_pk_bf16_f32 v139, v140, v141
	v_lshlrev_b32_e32 v132, 16, v142
	global_store_dwordx2 v[134:135], v[138:139], off offset:32
	v_mul_f32_e32 v134, 0xbfb8aa3b, v132
	v_exp_f32_e32 v135, v134
	v_mul_f32_e32 v134, 0x45800000, v133
	v_cndmask_b32_e64 v134, v133, v134, s[0:1]
	v_and_b32_e32 v133, 0xffff0000, v142
	v_mul_f32_e32 v138, 0xbfb8aa3b, v133
	v_exp_f32_e32 v139, v138
	v_add_f32_e32 v135, 1.0, v135
	v_rcp_f32_e32 v138, v135
	v_mul_f32_e64 v140, v160, v134
	v_mul_f32_e64 v141, v161, v134
	v_add_f32_e32 v135, 1.0, v139
	v_lshlrev_b32_e32 v142, 16, v143
	v_rcp_f32_e32 v139, v135
	v_and_b32_e32 v143, 0xffff0000, v143
	v_mul_f32_e32 v135, 0xbfb8aa3b, v142
	v_exp_f32_e32 v135, v135
	v_mul_f32_e32 v144, 0xbfb8aa3b, v143
	v_exp_f32_e32 v144, v144
	v_mul_f32_e64 v132, v138, v132
	v_mul_f32_e64 v133, v139, v133
	v_add_f32_e32 v135, 1.0, v135
	v_rcp_f32_e32 v138, v135
	v_add_f32_e32 v135, 1.0, v144
	v_rcp_f32_e32 v139, v135
	v_mul_f32_e64 v98, v98, v134
	v_mul_f32_e64 v99, v99, v134
	v_mul_f32_e64 v140, v72, v140
	v_mul_f32_e64 v141, v73, v141
	v_mul_f32_e64 v98, v74, v98
	v_mul_f32_e64 v99, v75, v99
	v_mul_f32_e64 v138, v138, v142
	v_mul_f32_e64 v139, v139, v143
	v_mul_f32_e64 v132, v132, v140
	v_mul_f32_e64 v133, v133, v141
	v_mul_f32_e64 v98, v138, v98
	v_mul_f32_e64 v99, v139, v99
	v_cvt_pk_bf16_f32 v132, v132, v133
	v_cvt_pk_bf16_f32 v133, v98, v99
	v_lshlrev_b32_e32 v98, 16, v136
	v_mul_f32_e32 v99, 0xbfb8aa3b, v98
	v_exp_f32_e32 v135, v99
	v_lshl_add_u64 v[138:139], s[34:35], 0, v[110:111]
	v_and_b32_e32 v99, 0xffff0000, v136
	global_store_dwordx2 v[138:139], v[132:133], off
	v_mul_f32_e32 v133, 0xbfb8aa3b, v99
	v_exp_f32_e32 v133, v133
	v_lshlrev_b32_e32 v136, 16, v137
	v_and_b32_e32 v137, 0xffff0000, v137
	v_add_f32_e32 v132, 1.0, v135
	v_mul_f32_e64 v96, v96, v134
	v_mul_f32_e64 v97, v97, v134
	v_add_f32_e32 v133, 1.0, v133
	v_mul_f32_e32 v135, 0xbfb8aa3b, v136
	v_mul_f32_e32 v138, 0xbfb8aa3b, v137
	v_rcp_f32_e32 v132, v132
	v_rcp_f32_e32 v133, v133
	v_exp_f32_e32 v135, v135
	v_exp_f32_e32 v138, v138
	v_mul_f32_e64 v96, v68, v96
	v_mul_f32_e64 v97, v69, v97
	v_mul_f32_e64 v98, v132, v98
	v_mul_f32_e64 v99, v133, v99
	v_add_f32_e32 v132, 1.0, v135
	v_add_f32_e32 v133, 1.0, v138
	v_rcp_f32_e32 v132, v132
	v_rcp_f32_e32 v133, v133
	v_mul_f32_e64 v94, v94, v134
	v_mul_f32_e64 v95, v95, v134
	v_mul_f32_e64 v96, v98, v96
	v_mul_f32_e64 v97, v99, v97
	v_mul_f32_e64 v94, v70, v94
	v_mul_f32_e64 v95, v71, v95
	v_mul_f32_e64 v98, v132, v136
	v_mul_f32_e64 v99, v133, v137
	v_cvt_pk_bf16_f32 v132, v96, v97
	v_mul_f32_e64 v98, v98, v94
	v_mul_f32_e64 v99, v99, v95
	ds_read_b128 v[94:97], v180 offset:1024
	v_cvt_pk_bf16_f32 v133, v98, v99
	v_lshl_add_u64 v[98:99], s[34:35], 0, v[112:113]
	global_store_dwordx2 v[98:99], v[132:133], off
	ds_read_b128 v[132:135], v180 offset:1040
	s_waitcnt lgkmcnt(1)
	v_mov_b32_e32 v98, v95
	v_mov_b32_e32 v99, v96
	v_mov_b32_e32 v95, v97
	v_lshlrev_b32_e32 v96, 16, v130
	v_add_f32_e64 v98, v98, v94
	v_add_f32_e64 v99, v99, v95
	v_and_b32_e32 v97, 0xffff0000, v130
	v_mul_f32_e32 v95, 0xbfb8aa3b, v96
	v_exp_f32_e32 v130, v95
	v_mul_f32_e32 v95, 0xbfb8aa3b, v97
	s_waitcnt lgkmcnt(0)
	v_mov_b32_e32 v94, v134
	v_exp_f32_e32 v134, v95
	v_lshlrev_b32_e32 v136, 16, v131
	v_and_b32_e32 v137, 0xffff0000, v131
	v_mul_f32_e32 v131, 0xbfb8aa3b, v136
	v_mov_b32_e32 v95, v132
	v_add_f32_e32 v132, 1.0, v134
	v_exp_f32_e32 v134, v131
	v_mul_f32_e32 v131, 0xbfb8aa3b, v137
	v_exp_f32_e32 v139, v131
	v_rcp_f32_e32 v131, v132
	v_add_f32_e32 v132, 1.0, v134
	v_rcp_f32_e32 v138, v132
	v_add_f32_e32 v132, 1.0, v139
	v_rcp_f32_e32 v139, v132
	v_mov_b32_e32 v132, v135
	v_add_f32_e64 v132, v94, v132
	v_add_f32_e64 v133, v95, v133
	v_lshlrev_b32_e32 v144, 16, v129
	v_mul_f32_e64 v136, v138, v136
	v_mul_f32_e64 v137, v139, v137
	v_lshlrev_b32_e32 v138, 16, v128
	v_and_b32_e32 v139, 0xffff0000, v128
	v_mul_f32_e32 v94, 0xbfb8aa3b, v138
	v_exp_f32_e32 v94, v94
	v_mul_f32_e32 v95, 0xbfb8aa3b, v139
	v_exp_f32_e32 v95, v95
	v_and_b32_e32 v145, 0xffff0000, v129
	v_add_f32_e32 v94, 1.0, v94
	v_rcp_f32_e32 v142, v94
	v_add_f32_e32 v94, 1.0, v95
	v_add_f32_e32 v130, 1.0, v130
	v_rcp_f32_e32 v143, v94
	v_mul_f32_e32 v94, 0xbfb8aa3b, v144
	v_mul_f32_e32 v95, 0xbfb8aa3b, v145
	v_rcp_f32_e32 v130, v130
	v_exp_f32_e32 v94, v94
	v_exp_f32_e32 v128, v95
	v_lshl_add_u64 v[140:141], s[34:35], 0, v[114:115]
	v_mul_f32_e64 v134, v130, v96
	v_mul_f32_e64 v135, v131, v97
	v_add_f32_e32 v129, 1.0, v94
	ds_read_b128 v[94:97], v180 offset:1536
	v_add_f32_e32 v128, 1.0, v128
	v_rcp_f32_e32 v146, v129
	v_rcp_f32_e32 v147, v128
	ds_read_b128 v[128:131], v180 offset:1552
	s_waitcnt lgkmcnt(1)
	v_mov_b32_e32 v148, v95
	v_mov_b32_e32 v149, v96
	v_mov_b32_e32 v95, v97
	v_add_f32_e64 v94, v148, v94
	v_add_f32_e64 v95, v149, v95
	s_waitcnt lgkmcnt(0)
	v_mov_b32_e32 v96, v130
	v_mov_b32_e32 v97, v128
	v_mov_b32_e32 v128, v131
	v_add_f32_e64 v96, v96, v128
	v_add_f32_e64 v97, v97, v129
	v_mov_b32_e32 v128, v94
	v_mov_b32_e32 v129, v98
	v_mov_b32_e32 v98, v95
	v_add_f32_e64 v94, v128, v98
	v_add_f32_e64 v95, v129, v99
	v_mov_b32_e32 v98, v97
	v_mov_b32_e32 v99, v133
	v_add_f32_e64 v94, v94, v98
	v_add_f32_e64 v95, v95, v99
	v_mov_b32_e32 v97, v132
	v_add_f32_e64 v94, v96, v94
	v_add_f32_e64 v95, v97, v95
	v_mul_f32_e64 v98, v146, v144
	v_mul_f32_e64 v99, v147, v145
	v_fma_f32 v79, v95, s40, v78
	v_fma_f32 v78, v94, s40, v78
	s_nop 0
	v_mul_f32_e32 v94, 0x4b800000, v79
	v_cmp_gt_f32_e64 s[0:1], s57, v79
	s_nop 1
	v_cndmask_b32_e64 v79, v79, v94, s[0:1]
	v_rsq_f32_e32 v79, v79
	v_mul_f32_e64 v94, v142, v138
	v_mul_f32_e64 v95, v143, v139
	v_mul_f32_e32 v96, 0x45800000, v79
	v_cndmask_b32_e64 v96, v79, v96, s[0:1]
	v_mul_f32_e64 v88, v88, v96
	v_mul_f32_e64 v89, v89, v96
	v_mul_f32_e64 v92, v92, v96
	v_mul_f32_e64 v93, v93, v96
	v_mul_f32_e64 v88, v72, v88
	v_mul_f32_e64 v89, v73, v89
	v_mul_f32_e64 v92, v74, v92
	v_mul_f32_e64 v93, v75, v93
	v_mul_f32_e64 v88, v134, v88
	v_mul_f32_e64 v89, v135, v89
	v_mul_f32_e64 v92, v136, v92
	v_mul_f32_e64 v93, v137, v93
	v_cvt_pk_bf16_f32 v88, v88, v89
	v_cvt_pk_bf16_f32 v89, v92, v93
	global_store_dwordx2 v[140:141], v[88:89], off
	v_mul_f32_e64 v88, v90, v96
	v_mul_f32_e64 v89, v91, v96
	v_mul_f32_e32 v79, 0x4b800000, v78
	v_cmp_gt_f32_e64 s[0:1], s57, v78
	v_mul_f32_e64 v88, v68, v88
	v_mul_f32_e64 v89, v69, v89
	v_mul_f32_e64 v86, v86, v96
	v_mul_f32_e64 v87, v87, v96
	v_cndmask_b32_e64 v78, v78, v79, s[0:1]
	v_mul_f32_e64 v200, v94, v88
	v_mul_f32_e64 v201, v95, v89
	v_mul_f32_e64 v202, v70, v86
	v_mul_f32_e64 v203, v71, v87
	ds_read_b64_tr_b16 v[88:89], v196 offset:57408
	ds_read_b64_tr_b16 v[86:87], v196 offset:56320
	ds_read_b64_tr_b16 v[92:93], v198 offset:2112
	ds_read_b64_tr_b16 v[90:91], v198
	ds_read_b64_tr_b16 v[96:97], v198 offset:2144
	ds_read_b64_tr_b16 v[94:95], v198 offset:32
	ds_read_b64_tr_b16 v[128:129], v196 offset:56352
	ds_read_b64_tr_b16 v[132:133], v196 offset:56384
	ds_read_b64_tr_b16 v[136:137], v196 offset:56416
	ds_read_b64_tr_b16 v[130:131], v196 offset:57440
	ds_read_b64_tr_b16 v[134:135], v196 offset:57472
	ds_read_b64_tr_b16 v[138:139], v196 offset:57504
	v_rsq_f32_e32 v78, v78
	ds_read_b64_tr_b16 v[140:141], v196 offset:65024
	ds_read_b64_tr_b16 v[142:143], v197 offset:57408
	ds_read_b64_tr_b16 v[144:145], v198 offset:16896
	ds_read_b64_tr_b16 v[146:147], v198 offset:19008
	ds_read_b64_tr_b16 v[150:151], v198 offset:19040
	ds_read_b64_tr_b16 v[148:149], v198 offset:16928
	v_mul_f32_e64 v98, v98, v202
	v_mul_f32_e64 v99, v99, v203
	s_waitcnt lgkmcnt(8)
	v_mfma_f32_16x16x32_bf16 v[12:15], v[128:131], v[90:93], v[12:15]
	v_cvt_pk_bf16_f32 v200, v200, v201
	v_cvt_pk_bf16_f32 v201, v98, v99
	v_mul_f32_e32 v79, 0x45800000, v78
	v_mfma_f32_16x16x32_bf16 v[36:39], v[128:131], v[94:97], v[36:39]
	v_lshlrev_b32_e32 v98, 16, v126
	v_cndmask_b32_e64 v78, v78, v79, s[0:1]
	v_and_b32_e32 v99, 0xffff0000, v126
	v_mfma_f32_16x16x32_bf16 v[8:11], v[86:89], v[90:93], v[8:11]
	v_mul_f32_e32 v79, 0xbfb8aa3b, v98
	v_exp_f32_e32 v79, v79
	v_mul_f32_e32 v126, 0xbfb8aa3b, v99
	v_mfma_f32_16x16x32_bf16 v[4:7], v[86:89], v[94:97], v[4:7]
	ds_read_b64_tr_b16 v[86:87], v196 offset:65056
	ds_read_b64_tr_b16 v[156:157], v196 offset:65088
	ds_read_b64_tr_b16 v[160:161], v196 offset:65120
	ds_read_b64_tr_b16 v[88:89], v197 offset:57440
	ds_read_b64_tr_b16 v[158:159], v197 offset:57472
	ds_read_b64_tr_b16 v[162:163], v197 offset:57504
	v_add_f32_e32 v79, 1.0, v79
	global_store_dwordx2 v[152:153], v[200:201], off
	s_waitcnt lgkmcnt(2)
	v_mfma_f32_16x16x32_bf16 v[12:15], v[86:89], v[144:147], v[12:15]
	v_mfma_f32_16x16x32_bf16 v[36:39], v[86:89], v[148:151], v[36:39]
	v_exp_f32_e32 v87, v126
	v_rcp_f32_e32 v86, v79
	v_add_f32_e32 v79, 1.0, v87
	v_rcp_f32_e32 v87, v79
	v_mul_f32_e64 v84, v84, v78
	v_mul_f32_e64 v85, v85, v78
	v_mfma_f32_16x16x32_bf16 v[24:27], v[132:135], v[90:93], v[24:27]
	v_mul_f32_e64 v72, v72, v84
	v_mul_f32_e64 v73, v73, v85
	v_mul_f32_e64 v84, v86, v98
	v_mul_f32_e64 v85, v87, v99
	v_lshlrev_b32_e32 v86, 16, v127
	v_mul_f32_e32 v79, 0xbfb8aa3b, v86
	v_exp_f32_e32 v79, v79
	v_mul_f32_e64 v98, v84, v72
	v_mul_f32_e64 v99, v85, v73
	v_and_b32_e32 v87, 0xffff0000, v127
	v_mfma_f32_16x16x32_bf16 v[32:35], v[132:135], v[94:97], v[32:35]
	v_add_f32_e32 v72, 1.0, v79
	v_rcp_f32_e32 v84, v72
	v_mul_f32_e32 v72, 0xbfb8aa3b, v87
	v_exp_f32_e32 v79, v72
	v_mfma_f32_16x16x32_bf16 v[40:43], v[136:139], v[90:93], v[40:43]
	v_cvt_pk_bf16_f32 v98, v98, v99
	v_mul_f32_e64 v72, v82, v78
	v_mul_f32_e64 v73, v83, v78
	s_nop 0
	v_mul_f32_e64 v134, v74, v72
	v_mul_f32_e64 v135, v75, v73
	v_add_f32_e32 v72, 1.0, v79
	v_rcp_f32_e32 v85, v72
	ds_read_b64_tr_b16 v[72:73], v196 offset:56448
	ds_read_b64_tr_b16 v[74:75], v196 offset:57536
	v_mfma_f32_16x16x32_bf16 v[64:67], v[136:139], v[94:97], v[64:67]
	v_mul_f32_e64 v136, v84, v86
	v_mul_f32_e64 v137, v85, v87
	ds_read_b64_tr_b16 v[82:83], v196 offset:56480
	ds_read_b64_tr_b16 v[86:87], v196 offset:56512
	ds_read_b64_tr_b16 v[126:127], v196 offset:56544
	ds_read_b64_tr_b16 v[84:85], v196 offset:57568
	ds_read_b64_tr_b16 v[88:89], v196 offset:57600
	ds_read_b64_tr_b16 v[128:129], v196 offset:57632
	v_mfma_f32_16x16x32_bf16 v[8:11], v[140:143], v[144:147], v[8:11]
	ds_read_b64_tr_b16 v[130:131], v196 offset:65152
	ds_read_b64_tr_b16 v[132:133], v197 offset:57536
	v_mfma_f32_16x16x32_bf16 v[4:7], v[140:143], v[148:151], v[4:7]
	v_mul_f32_e64 v142, v136, v134
	v_mul_f32_e64 v143, v137, v135
	v_cvt_pk_bf16_f32 v99, v142, v143
	v_lshl_add_u64 v[142:143], s[34:35], 0, v[118:119]
	s_waitcnt lgkmcnt(8)
	v_mfma_f32_16x16x32_bf16 v[16:19], v[72:75], v[90:93], v[16:19]
	v_mfma_f32_16x16x32_bf16 v[20:23], v[72:75], v[94:97], v[20:23]
	ds_read_b64_tr_b16 v[72:73], v196 offset:65184
	ds_read_b64_tr_b16 v[134:135], v196 offset:65216
	ds_read_b64_tr_b16 v[138:139], v196 offset:65248
	ds_read_b64_tr_b16 v[74:75], v197 offset:57568
	ds_read_b64_tr_b16 v[136:137], v197 offset:57600
	ds_read_b64_tr_b16 v[140:141], v197 offset:57632
	global_store_dwordx2 v[142:143], v[98:99], off
	v_lshlrev_b32_e32 v98, 16, v124
	v_and_b32_e32 v99, 0xffff0000, v124
	v_mul_f32_e32 v79, 0xbfb8aa3b, v98
	v_exp_f32_e32 v79, v79
	v_mul_f32_e32 v124, 0xbfb8aa3b, v99
	s_waitcnt lgkmcnt(10)
	v_mfma_f32_16x16x32_bf16 v[28:31], v[82:85], v[90:93], v[28:31]
	v_add_f32_e32 v79, 1.0, v79
	v_mfma_f32_16x16x32_bf16 v[48:51], v[82:85], v[94:97], v[48:51]
	v_exp_f32_e32 v83, v124
	v_rcp_f32_e32 v82, v79
	v_add_f32_e32 v79, 1.0, v83
	v_rcp_f32_e32 v83, v79
	v_mul_f32_e64 v80, v80, v78
	v_mul_f32_e64 v81, v81, v78
	s_waitcnt lgkmcnt(2)
	v_mfma_f32_16x16x32_bf16 v[28:31], v[72:75], v[144:147], v[28:31]
	v_mul_f32_e64 v68, v68, v80
	v_mul_f32_e64 v69, v69, v81
	v_mul_f32_e64 v76, v76, v78
	v_mul_f32_e64 v77, v77, v78
	v_lshl_add_u64 v[78:79], s[34:35], 0, v[120:121]
	v_mfma_f32_16x16x32_bf16 v[48:51], v[72:75], v[148:151], v[48:51]
	v_mul_f32_e64 v72, v82, v98
	v_mul_f32_e64 v73, v83, v99
	v_mul_f32_e64 v70, v70, v76
	v_mul_f32_e64 v71, v71, v77
	v_mul_f32_e64 v68, v72, v68
	v_mul_f32_e64 v69, v73, v69
	v_lshlrev_b32_e32 v72, 16, v125
	v_and_b32_e32 v73, 0xffff0000, v125
	v_mul_f32_e32 v74, 0xbfb8aa3b, v72
	v_mul_f32_e32 v75, 0xbfb8aa3b, v73
	v_exp_f32_e32 v74, v74
	v_exp_f32_e32 v75, v75
	v_lshl_add_u32 v82, s59, 9, v176
	v_cvt_pk_bf16_f32 v76, v68, v69
	v_add_f32_e32 v74, 1.0, v74
	v_add_f32_e32 v75, 1.0, v75
	v_rcp_f32_e32 v74, v74
	v_rcp_f32_e32 v75, v75
	v_mfma_f32_16x16x32_bf16 v[24:27], v[156:159], v[144:147], v[24:27]
	s_add_u32 s34, s34, 0xfffe0000
	s_addc_u32 s35, s35, -1
	v_mul_f32_e64 v72, v74, v72
	v_mul_f32_e64 v73, v75, v73
	v_mfma_f32_16x16x32_bf16 v[32:35], v[156:159], v[148:151], v[32:35]
	v_mul_f32_e64 v72, v72, v70
	v_mul_f32_e64 v73, v73, v71
	ds_read_b128 v[68:71], v82 offset:4096
	v_cvt_pk_bf16_f32 v77, v72, v73
	ds_read_b128 v[72:75], v82 offset:4160
	global_store_dwordx2 v[78:79], v[76:77], off
	v_mfma_f32_16x16x32_bf16 v[16:19], v[130:133], v[144:147], v[16:19]
	s_waitcnt lgkmcnt(1)
	s_nop 0
	v_mov_b32_e32 v80, v68
	v_mov_b32_e32 v81, v69
	v_mov_b32_e32 v68, v70
	v_mov_b32_e32 v69, v71
	s_nop 0
	s_nop 0
	s_nop 0
	v_mfma_f32_16x16x32_bf16 v[20:23], v[130:133], v[148:151], v[20:23]
	s_add_u32 s36, s36, 0xfffe0000
	v_mul_f32_e64 v10, v10, v68
	v_mul_f32_e64 v11, v11, v69
	v_mul_f32_e64 v6, v6, v68
	v_mul_f32_e64 v7, v7, v69
	s_waitcnt lgkmcnt(0)
	v_mov_b32_e32 v68, v72
	v_mov_b32_e32 v69, v74
	v_mov_b32_e32 v76, v68
	v_mov_b32_e32 v68, v73
	v_mov_b32_e32 v78, v69
	s_nop 0
	v_mov_b32_e32 v79, v75
	v_mov_b32_e32 v77, v68
	ds_read_b128 v[68:71], v82 offset:4224
	ds_read_b128 v[72:75], v82 offset:4288
	v_mul_f32_e64 v8, v8, v80
	v_mul_f32_e64 v9, v9, v81
	v_mul_f32_e64 v4, v4, v80
	v_mul_f32_e64 v5, v5, v81
	v_mul_f32_e64 v14, v14, v78
	v_mul_f32_e64 v15, v15, v79
	s_waitcnt lgkmcnt(1)
	s_nop 0
	v_mov_b32_e32 v80, v68
	v_mov_b32_e32 v81, v69
	v_mov_b32_e32 v68, v70
	v_mov_b32_e32 v69, v71
	s_nop 0
	s_nop 0
	v_mul_f32_e64 v12, v12, v76
	v_mul_f32_e64 v13, v13, v77
	v_mul_f32_e64 v38, v38, v78
	v_mul_f32_e64 v39, v39, v79
	v_mul_f32_e64 v36, v36, v76
	v_mul_f32_e64 v37, v37, v77
	v_mul_f32_e64 v26, v26, v68
	v_mul_f32_e64 v27, v27, v69
	v_mul_f32_e64 v34, v34, v68
	v_mul_f32_e64 v35, v35, v69
	s_waitcnt lgkmcnt(0)
	v_mov_b32_e32 v68, v72
	v_mov_b32_e32 v69, v74
	v_mov_b32_e32 v76, v68
	v_mov_b32_e32 v68, v73
	v_mov_b32_e32 v78, v69
	s_nop 0
	v_mov_b32_e32 v79, v75
	v_mov_b32_e32 v77, v68
	ds_read_b128 v[68:71], v82 offset:4352
	ds_read_b128 v[72:75], v82 offset:4416
	s_nop 0
	v_mfma_f32_16x16x32_bf16 v[40:43], v[160:163], v[144:147], v[40:43]
	s_addc_u32 s37, s37, -1
	s_waitcnt lgkmcnt(1)
	s_nop 0
	v_mul_f32_e64 v24, v24, v80
	v_mul_f32_e64 v25, v25, v81
	v_mul_f32_e64 v32, v32, v80
	v_mul_f32_e64 v33, v33, v81
	v_mov_b32_e32 v80, v68
	v_mov_b32_e32 v81, v69
	v_mov_b32_e32 v68, v70
	v_mov_b32_e32 v69, v71
	s_nop 0
	s_nop 0
	v_mfma_f32_16x16x32_bf16 v[64:67], v[160:163], v[148:151], v[64:67]
	v_mul_f32_e64 v42, v42, v78
	v_mul_f32_e64 v43, v43, v79
	v_mul_f32_e64 v40, v40, v76
	v_mul_f32_e64 v41, v41, v77
	v_mul_f32_e64 v18, v18, v68
	v_mul_f32_e64 v19, v19, v69
	v_mul_f32_e64 v22, v22, v68
	v_mul_f32_e64 v23, v23, v69
	s_waitcnt lgkmcnt(0)
	v_mov_b32_e32 v68, v72
	v_mov_b32_e32 v69, v74
	v_mul_f32_e64 v66, v66, v78
	v_mul_f32_e64 v67, v67, v79
	v_mul_f32_e64 v64, v64, v76
	v_mul_f32_e64 v65, v65, v77
	v_mov_b32_e32 v76, v68
	v_mov_b32_e32 v68, v73
	v_mov_b32_e32 v78, v69
	s_nop 0
	v_mov_b32_e32 v79, v75
	v_mov_b32_e32 v77, v68
	ds_read_b128 v[68:71], v82 offset:4480
	ds_read_b128 v[72:75], v82 offset:4544
	v_mfma_f32_16x16x32_bf16 v[44:47], v[86:89], v[90:93], v[44:47]
	s_nop 0
	v_mul_f32_e64 v30, v30, v78
	v_mul_f32_e64 v31, v31, v79
	s_waitcnt lgkmcnt(1)
	s_nop 0
	v_mfma_f32_16x16x32_bf16 v[56:59], v[86:89], v[94:97], v[56:59]
	s_nop 0
	s_nop 0
	s_nop 0
	v_mfma_f32_16x16x32_bf16 v[52:55], v[126:129], v[90:93], v[52:55]
	s_waitcnt lgkmcnt(0)
	s_nop 0
	s_nop 0
	s_nop 0
	v_mfma_f32_16x16x32_bf16 v[60:63], v[126:129], v[94:97], v[60:63]
	s_nop 0
	s_nop 0
	s_nop 0
	v_mfma_f32_16x16x32_bf16 v[44:47], v[134:137], v[144:147], v[44:47]
	s_nop 0
	s_nop 0
	s_nop 0
	v_mfma_f32_16x16x32_bf16 v[56:59], v[134:137], v[148:151], v[56:59]
	s_nop 0
	s_nop 0
	s_nop 0
	v_mfma_f32_16x16x32_bf16 v[52:55], v[138:141], v[144:147], v[52:55]
	v_mul_f32_e64 v16, v16, v80
	v_mul_f32_e64 v17, v17, v81
	v_mul_f32_e64 v20, v20, v80
	v_mul_f32_e64 v21, v21, v81
	v_mul_f32_e64 v28, v28, v76
	v_mul_f32_e64 v29, v29, v77
	v_mfma_f32_16x16x32_bf16 v[60:63], v[138:141], v[148:151], v[60:63]
	v_mul_f32_e64 v50, v50, v78
	v_mul_f32_e64 v51, v51, v79
	v_mul_f32_e64 v48, v48, v76
	v_mul_f32_e64 v49, v49, v77
	v_mul_f32_e64 v46, v46, v70
	v_mul_f32_e64 v47, v47, v71
	v_mul_f32_e64 v44, v44, v68
	v_mul_f32_e64 v45, v45, v69
	v_mul_f32_e64 v58, v58, v70
	v_mul_f32_e64 v59, v59, v71
	v_mul_f32_e64 v56, v56, v68
	v_mul_f32_e64 v57, v57, v69
	v_mul_f32_e64 v54, v54, v74
	v_mul_f32_e64 v55, v55, v75
	v_mul_f32_e64 v52, v52, v72
	v_mul_f32_e64 v53, v53, v73
	v_mul_f32_e64 v62, v62, v74
	v_mul_f32_e64 v63, v63, v75
	s_cmp_eq_u32 s58, 4
	v_mul_f32_e64 v60, v60, v72
	v_mul_f32_e64 v61, v61, v73
	s_cbranch_scc1 .LBB0_597

.LBB0_591:
	s_or_b64 exec, exec, s[0:1]
	s_waitcnt vmcnt(15)
	v_lshlrev_b32_e32 v160, 16, v146
	s_waitcnt lgkmcnt(0)
	v_and_b32_e32 v161, 0xffff0000, v146
	v_add_f32_e64 v160, v96, v160
	v_add_f32_e64 v161, v97, v161
	v_lshlrev_b32_e32 v96, 16, v147
	v_and_b32_e32 v97, 0xffff0000, v147
	v_add_f32_e64 v98, v98, v96
	v_add_f32_e64 v99, v99, v97
	v_mul_f32_e64 v146, v160, v160
	v_mul_f32_e64 v147, v161, v161
	v_mul_f32_e64 v200, v98, v98
	v_mul_f32_e64 v201, v99, v99
	s_waitcnt vmcnt(14)
	v_lshlrev_b32_e32 v96, 16, v144
	v_and_b32_e32 v97, 0xffff0000, v144
	v_add_f32_e32 v146, v146, v147
	v_add_f32_e64 v96, v92, v96
	v_add_f32_e64 v97, v93, v97
	v_lshlrev_b32_e32 v92, 16, v145
	v_and_b32_e32 v93, 0xffff0000, v145
	v_add_f32_e32 v146, v200, v146
	v_add_f32_e64 v94, v94, v92
	v_add_f32_e64 v95, v95, v93
	v_mul_f32_e64 v92, v96, v96
	v_mul_f32_e64 v93, v97, v97
	v_add_f32_e32 v146, v201, v146
	v_add_f32_e32 v92, v92, v146
	v_mul_f32_e64 v144, v94, v94
	v_mul_f32_e64 v145, v95, v95
	v_add_f32_e32 v92, v93, v92
	v_add_f32_e32 v92, v144, v92
	v_add_f32_e32 v92, v145, v92
	v_mov_b32_e32 v93, v92
	s_nop 1
	v_permlane16_swap_b32_e32 v93, v92
	s_waitcnt lgkmcnt(0)
	v_add_f32_e32 v92, v92, v93
	v_mov_b32_e32 v93, v92
	s_nop 1
	v_permlane32_swap_b32_e32 v93, v92
	s_and_saveexec_b64 s[0:1], s[6:7]
	s_cbranch_execz .LBB0_593
	s_waitcnt lgkmcnt(0)
	v_add_f32_e32 v92, v92, v93
	ds_write_b32 v181, v92 offset:512
.LBB0_593:
	s_or_b64 exec, exec, s[0:1]
	s_waitcnt vmcnt(13)
	v_lshlrev_b32_e32 v92, 16, v140
	s_waitcnt lgkmcnt(0)
	v_and_b32_e32 v93, 0xffff0000, v140
	v_add_f32_e64 v88, v88, v92
	v_add_f32_e64 v89, v89, v93
	v_lshlrev_b32_e32 v92, 16, v141
	v_and_b32_e32 v93, 0xffff0000, v141
	v_add_f32_e64 v92, v90, v92
	v_add_f32_e64 v93, v91, v93
	v_mul_f32_e64 v140, v88, v88
	v_mul_f32_e64 v141, v89, v89
	v_mul_f32_e64 v144, v92, v92
	v_mul_f32_e64 v145, v93, v93
	s_waitcnt vmcnt(12)
	v_lshlrev_b32_e32 v90, 16, v138
	v_and_b32_e32 v91, 0xffff0000, v138
	v_add_f32_e32 v140, v140, v141
	v_add_f32_e64 v90, v84, v90
	v_add_f32_e64 v91, v85, v91
	v_lshlrev_b32_e32 v84, 16, v139
	v_and_b32_e32 v85, 0xffff0000, v139
	v_add_f32_e32 v140, v144, v140
	v_add_f32_e64 v86, v86, v84
	v_add_f32_e64 v87, v87, v85
	v_mul_f32_e64 v84, v90, v90
	v_mul_f32_e64 v85, v91, v91
	v_add_f32_e32 v140, v145, v140
	v_add_f32_e32 v84, v84, v140
	v_mul_f32_e64 v138, v86, v86
	v_mul_f32_e64 v139, v87, v87
	v_add_f32_e32 v84, v85, v84
	v_add_f32_e32 v84, v138, v84
	v_add_f32_e32 v84, v139, v84
	v_mov_b32_e32 v85, v84
	s_nop 1
	v_permlane16_swap_b32_e32 v85, v84
	s_waitcnt lgkmcnt(0)
	v_add_f32_e32 v84, v84, v85
	v_mov_b32_e32 v85, v84
	s_nop 1
	v_permlane32_swap_b32_e32 v85, v84
	s_and_saveexec_b64 s[0:1], s[6:7]
	s_cbranch_execz .LBB0_595
	s_waitcnt lgkmcnt(0)
	v_add_f32_e32 v84, v84, v85
	ds_write_b32 v181, v84 offset:1024
.LBB0_595:
	s_or_b64 exec, exec, s[0:1]
	s_waitcnt vmcnt(11)
	v_lshlrev_b32_e32 v84, 16, v134
	s_waitcnt lgkmcnt(0)
	v_and_b32_e32 v85, 0xffff0000, v134
	v_add_f32_e64 v84, v80, v84
	v_add_f32_e64 v85, v81, v85
	v_lshlrev_b32_e32 v80, 16, v135
	v_and_b32_e32 v81, 0xffff0000, v135
	v_add_f32_e64 v82, v82, v80
	v_add_f32_e64 v83, v83, v81
	v_mul_f32_e64 v134, v84, v84
	v_mul_f32_e64 v135, v85, v85
	v_mul_f32_e64 v138, v82, v82
	v_mul_f32_e64 v139, v83, v83
	s_waitcnt vmcnt(10)
	v_lshlrev_b32_e32 v80, 16, v132
	v_and_b32_e32 v81, 0xffff0000, v132
	v_add_f32_e32 v134, v134, v135
	v_add_f32_e64 v80, v76, v80
	v_add_f32_e64 v81, v77, v81
	v_lshlrev_b32_e32 v76, 16, v133
	v_and_b32_e32 v77, 0xffff0000, v133
	v_add_f32_e32 v134, v138, v134
	v_add_f32_e64 v76, v78, v76
	v_add_f32_e64 v77, v79, v77
	v_mul_f32_e64 v78, v80, v80
	v_mul_f32_e64 v79, v81, v81
	v_add_f32_e32 v134, v139, v134
	v_add_f32_e32 v78, v78, v134
	v_mul_f32_e64 v132, v76, v76
	v_mul_f32_e64 v133, v77, v77
	v_add_f32_e32 v78, v79, v78
	v_add_f32_e32 v78, v132, v78
	v_add_f32_e32 v78, v133, v78
	v_mov_b32_e32 v79, v78
	s_nop 1
	v_permlane16_swap_b32_e32 v79, v78
	s_waitcnt lgkmcnt(0)
	v_add_f32_e32 v78, v78, v79
	v_mov_b32_e32 v79, v78
	s_nop 1
	v_permlane32_swap_b32_e32 v79, v78
	s_and_saveexec_b64 s[0:1], s[6:7]
	s_cbranch_execz .LBB0_579
	s_waitcnt lgkmcnt(0)
	v_add_f32_e32 v78, v78, v79
	ds_write_b32 v181, v78 offset:1536
	s_branch .LBB0_579

.LBB0_663:
	ds_read_b128 v[134:137], v201 offset:6144
	ds_read_b128 v[138:141], v201 offset:6160
	s_waitcnt vmcnt(6)
	v_lshlrev_b32_e32 v144, 16, v98
	v_and_b32_e32 v145, 0xffff0000, v98
	v_add_u32_e32 v215, 0x9800, v212
	s_waitcnt lgkmcnt(1)
	v_mul_f32_e32 v109, 0xbfb8aa3b, v134
	v_exp_f32_e32 v142, v109
	v_mul_f32_e32 v109, 0xbfb8aa3b, v135
	v_exp_f32_e32 v143, v109
	v_mul_f32_e32 v109, 0xbfb8aa3b, v136
	v_cvt_pk_bf16_f32 v156, v10, v11
	v_cvt_pk_bf16_f32 v157, v12, v13
	v_mul_f32_e64 v142, v142, v144
	v_mul_f32_e64 v143, v143, v145
	v_lshlrev_b32_e32 v144, 16, v99
	v_cvt_pk_bf16_f32 v98, v142, v143
	v_exp_f32_e32 v142, v109
	v_mul_f32_e32 v109, 0xbfb8aa3b, v137
	v_exp_f32_e32 v143, v109
	v_and_b32_e32 v145, 0xffff0000, v99
	s_waitcnt lgkmcnt(0)
	v_mul_f32_e32 v109, 0xbfb8aa3b, v138
	v_cvt_pk_bf16_f32 v158, v26, v27
	v_mul_f32_e64 v142, v142, v144
	v_mul_f32_e64 v143, v143, v145
	v_lshlrev_b32_e32 v144, 16, v100
	v_cvt_pk_bf16_f32 v99, v142, v143
	v_exp_f32_e32 v142, v109
	v_mul_f32_e32 v109, 0xbfb8aa3b, v139
	v_exp_f32_e32 v143, v109
	v_and_b32_e32 v145, 0xffff0000, v100
	v_mul_f32_e32 v109, 0xbfb8aa3b, v140
	v_cvt_pk_bf16_f32 v159, v28, v29
	v_mul_f32_e64 v142, v142, v144
	v_mul_f32_e64 v143, v143, v145
	v_lshlrev_b32_e32 v144, 16, v101
	v_cvt_pk_bf16_f32 v100, v142, v143
	v_exp_f32_e32 v142, v109
	v_mul_f32_e32 v109, 0xbfb8aa3b, v141
	v_exp_f32_e32 v143, v109
	v_and_b32_e32 v145, 0xffff0000, v101
	v_add_u32_e32 v216, 0xa800, v212
	v_add_u32_e32 v217, 0xb800, v212
	v_mul_f32_e64 v142, v142, v144
	v_mul_f32_e64 v143, v143, v145
	v_add_u32_e32 v218, 0xc800, v212
	v_cvt_pk_bf16_f32 v101, v142, v143
	ds_write_b128 v181, v[98:101] offset:56320
	v_mul_f32_e32 v98, 0x3fb8aa3b, v134
	v_mul_f32_e32 v99, 0x3fb8aa3b, v135
	v_exp_f32_e32 v98, v98
	v_exp_f32_e32 v99, v99
	v_lshlrev_b32_e32 v100, 16, v94
	v_and_b32_e32 v101, 0xffff0000, v94
	s_mov_b32 s62, 0x8000
	v_mul_f32_e64 v98, v98, s50
	v_mul_f32_e64 v99, v99, s50
	s_add_u32 s76, s76, 0x60000
	v_mul_f32_e64 v98, v98, v100
	v_mul_f32_e64 v99, v99, v101
	v_lshlrev_b32_e32 v100, 16, v95
	v_cvt_pk_bf16_f32 v94, v98, v99
	v_mul_f32_e32 v98, 0x3fb8aa3b, v136
	v_mul_f32_e32 v99, 0x3fb8aa3b, v137
	v_exp_f32_e32 v98, v98
	v_exp_f32_e32 v99, v99
	v_and_b32_e32 v101, 0xffff0000, v95
	s_waitcnt vmcnt(4)
	v_lshlrev_b32_e32 v136, 16, v90
	v_and_b32_e32 v137, 0xffff0000, v90
	v_mul_f32_e64 v98, v98, s50
	v_mul_f32_e64 v99, v99, s50
	s_addc_u32 s77, s77, 0
	v_mul_f32_e64 v98, v98, v100
	v_mul_f32_e64 v99, v99, v101
	v_lshlrev_b32_e32 v100, 16, v96
	v_cvt_pk_bf16_f32 v95, v98, v99
	v_mul_f32_e32 v98, 0x3fb8aa3b, v138
	v_mul_f32_e32 v99, 0x3fb8aa3b, v139
	v_exp_f32_e32 v98, v98
	v_exp_f32_e32 v99, v99
	v_and_b32_e32 v101, 0xffff0000, v96
	s_add_i32 s64, s64, 64
	v_mul_f32_e64 v98, v98, s50
	v_mul_f32_e64 v99, v99, s50
	s_nop 0
	v_mul_f32_e64 v98, v98, v100
	v_mul_f32_e64 v99, v99, v101
	v_lshlrev_b32_e32 v100, 16, v97
	v_cvt_pk_bf16_f32 v96, v98, v99
	v_mul_f32_e32 v98, 0x3fb8aa3b, v140
	v_mul_f32_e32 v99, 0x3fb8aa3b, v141
	v_exp_f32_e32 v98, v98
	v_exp_f32_e32 v99, v99
	v_and_b32_e32 v101, 0xffff0000, v97
	v_mul_f32_e64 v98, v98, s50
	v_mul_f32_e64 v99, v99, s50
	s_nop 0
	v_mul_f32_e64 v98, v98, v100
	v_mul_f32_e64 v99, v99, v101
	s_nop 0
	v_cvt_pk_bf16_f32 v97, v98, v99
	ds_write_b128 v181, v[94:97] offset:38912
	ds_read_b128 v[94:97], v202 offset:6144
	ds_read_b128 v[98:101], v202 offset:6160
	s_waitcnt lgkmcnt(1)
	v_mul_f32_e32 v109, 0xbfb8aa3b, v94
	v_exp_f32_e32 v134, v109
	v_mul_f32_e32 v109, 0xbfb8aa3b, v95
	v_exp_f32_e32 v135, v109
	v_mul_f32_e32 v109, 0xbfb8aa3b, v96
	v_mul_f32_e64 v134, v134, v136
	v_mul_f32_e64 v135, v135, v137
	s_nop 0
	v_cvt_pk_bf16_f32 v90, v134, v135
	v_exp_f32_e32 v134, v109
	v_mul_f32_e32 v109, 0xbfb8aa3b, v97
	v_exp_f32_e32 v135, v109
	v_lshlrev_b32_e32 v136, 16, v91
	v_and_b32_e32 v137, 0xffff0000, v91
	s_waitcnt lgkmcnt(0)
	v_mul_f32_e32 v109, 0xbfb8aa3b, v98
	v_mul_f32_e64 v134, v134, v136
	v_mul_f32_e64 v135, v135, v137
	v_lshlrev_b32_e32 v136, 16, v92
	v_cvt_pk_bf16_f32 v91, v134, v135
	v_exp_f32_e32 v134, v109
	v_mul_f32_e32 v109, 0xbfb8aa3b, v99
	v_exp_f32_e32 v135, v109
	v_and_b32_e32 v137, 0xffff0000, v92
	v_mul_f32_e32 v109, 0xbfb8aa3b, v100
	v_mul_f32_e64 v134, v134, v136
	v_mul_f32_e64 v135, v135, v137
	s_nop 0
	v_cvt_pk_bf16_f32 v92, v134, v135
	v_exp_f32_e32 v134, v109
	v_mul_f32_e32 v109, 0xbfb8aa3b, v101
	v_exp_f32_e32 v135, v109
	v_lshlrev_b32_e32 v136, 16, v93
	v_and_b32_e32 v137, 0xffff0000, v93
	v_mul_f32_e64 v134, v134, v136
	v_mul_f32_e64 v135, v135, v137
	s_nop 0
	v_cvt_pk_bf16_f32 v93, v134, v135
	ds_write_b128 v182, v[90:93] offset:56320
	v_mul_f32_e32 v90, 0x3fb8aa3b, v94
	v_mul_f32_e32 v91, 0x3fb8aa3b, v95
	v_exp_f32_e32 v90, v90
	v_exp_f32_e32 v91, v91
	v_lshlrev_b32_e32 v92, 16, v70
	v_and_b32_e32 v93, 0xffff0000, v70
	v_mul_f32_e64 v90, v90, s50
	v_mul_f32_e64 v91, v91, s50
	s_nop 0
	v_mul_f32_e64 v90, v90, v92
	v_mul_f32_e64 v91, v91, v93
	v_lshlrev_b32_e32 v92, 16, v71
	v_cvt_pk_bf16_f32 v70, v90, v91
	v_mul_f32_e32 v90, 0x3fb8aa3b, v96
	v_mul_f32_e32 v91, 0x3fb8aa3b, v97
	v_exp_f32_e32 v90, v90
	v_exp_f32_e32 v91, v91
	v_and_b32_e32 v93, 0xffff0000, v71
	v_mul_f32_e64 v90, v90, s50
	v_mul_f32_e64 v91, v91, s50
	s_nop 0
	v_mul_f32_e64 v90, v90, v92
	v_mul_f32_e64 v91, v91, v93
	v_lshlrev_b32_e32 v92, 16, v72
	v_cvt_pk_bf16_f32 v71, v90, v91
	v_mul_f32_e32 v90, 0x3fb8aa3b, v98
	v_mul_f32_e32 v91, 0x3fb8aa3b, v99
	v_exp_f32_e32 v90, v90
	v_exp_f32_e32 v91, v91
	v_and_b32_e32 v93, 0xffff0000, v72
	v_mul_f32_e64 v90, v90, s50
	v_mul_f32_e64 v91, v91, s50
	s_nop 0
	v_mul_f32_e64 v90, v90, v92
	v_mul_f32_e64 v91, v91, v93
	v_lshlrev_b32_e32 v92, 16, v73
	v_cvt_pk_bf16_f32 v72, v90, v91
	v_mul_f32_e32 v90, 0x3fb8aa3b, v100
	v_mul_f32_e32 v91, 0x3fb8aa3b, v101
	v_exp_f32_e32 v90, v90
	v_exp_f32_e32 v91, v91
	v_and_b32_e32 v93, 0xffff0000, v73
	v_mul_f32_e64 v90, v90, s50
	v_mul_f32_e64 v91, v91, s50
	s_nop 0
	v_mul_f32_e64 v90, v90, v92
	v_mul_f32_e64 v91, v91, v93
	s_nop 0
	v_cvt_pk_bf16_f32 v73, v90, v91
	ds_write_b128 v182, v[70:73] offset:38912
	s_waitcnt vmcnt(3)
	ds_write_b128 v203, v[74:77]
	s_waitcnt vmcnt(2)
	ds_write_b128 v204, v[78:81]
	s_waitcnt vmcnt(1)
	ds_write_b128 v203, v[82:85] offset:16896
	s_waitcnt vmcnt(0)
	ds_write_b128 v205, v[86:89]
	s_waitcnt lgkmcnt(0)
	s_barrier
	ds_read_b128 v[70:73], v206 offset:56320
	ds_read_b128 v[74:77], v180 offset:38912
	ds_read_b128 v[78:81], v206 offset:56384
	ds_read_b128 v[82:85], v180 offset:38976
	s_waitcnt lgkmcnt(2)
	v_mfma_f32_16x16x32_bf16 v[70:73], v[70:73], v[74:77], 0
	s_waitcnt lgkmcnt(0)
	v_mfma_f32_16x16x32_bf16 v[70:73], v[78:81], v[82:85], v[70:73]
	ds_read_b128 v[78:81], v206 offset:56448
	ds_read_b128 v[86:89], v180 offset:39040
	s_waitcnt lgkmcnt(0)
	v_mfma_f32_16x16x32_bf16 v[70:73], v[78:81], v[86:89], v[70:73]
	ds_read_b128 v[78:81], v206 offset:56512
	ds_read_b128 v[90:93], v180 offset:39104
	s_waitcnt lgkmcnt(0)
	v_mfma_f32_16x16x32_bf16 v[70:73], v[78:81], v[90:93], v[70:73]
	v_mov_b32_e32 v78, s49
	s_nop 6
	v_cndmask_b32_e64 v78, v70, v78, s[12:13]
	v_cndmask_b32_e64 v70, v78, v70, s[14:15]
	v_cndmask_b32_e64 v71, 0, v71, s[14:15]
	v_cndmask_b32_e64 v72, v72, 0, s[16:17]
	v_cndmask_b32_e64 v73, v73, 0, s[18:19]
	v_cvt_pk_bf16_f32 v70, v70, v71
	v_cvt_pk_bf16_f32 v71, v72, v73
	ds_write_b64 v207, v[70:71]
	ds_read_b128 v[70:73], v208 offset:56320
	s_waitcnt lgkmcnt(0)
	v_mfma_f32_16x16x32_bf16 v[70:73], v[70:73], v[74:77], 0
	ds_read_b128 v[74:77], v208 offset:56384
	s_waitcnt lgkmcnt(0)
	v_mfma_f32_16x16x32_bf16 v[70:73], v[74:77], v[82:85], v[70:73]
	ds_read_b128 v[74:77], v208 offset:56448
	s_waitcnt lgkmcnt(0)
	v_mfma_f32_16x16x32_bf16 v[70:73], v[74:77], v[86:89], v[70:73]
	ds_read_b128 v[74:77], v208 offset:56512
	s_waitcnt lgkmcnt(0)
	v_mfma_f32_16x16x32_bf16 v[70:73], v[74:77], v[90:93], v[70:73]
	v_mov_b32_e32 v74, s49
	s_nop 6
	v_cndmask_b32_e64 v74, v70, v74, s[20:21]
	v_cndmask_b32_e64 v70, v74, v70, s[22:23]
	v_cndmask_b32_e64 v71, 0, v71, s[22:23]
	v_cndmask_b32_e64 v72, v72, 0, s[24:25]
	v_cndmask_b32_e64 v73, v73, 0, s[26:27]
	v_cvt_pk_bf16_f32 v70, v70, v71
	v_cvt_pk_bf16_f32 v71, v72, v73
	ds_write_b64 v209, v[70:71]
	s_waitcnt lgkmcnt(0)
	s_barrier
	ds_read_b64_tr_b16 v[80:81], v210 offset:2112
	ds_read_b64_tr_b16 v[78:79], v210
	ds_read_b64_tr_b16 v[82:83], v210 offset:32
	ds_read_b64_tr_b16 v[70:71], v210 offset:16896
	ds_read_b64_tr_b16 v[72:73], v210 offset:19008
	ds_read_b64_tr_b16 v[84:85], v210 offset:2144
	ds_read_b64_tr_b16 v[74:75], v210 offset:16928
	ds_read_b64_tr_b16 v[76:77], v210 offset:19040
	ds_read_b128 v[86:89], v211
	ds_read_b128 v[94:97], v211 offset:64
	ds_read_b128 v[134:137], v211 offset:2368
	s_waitcnt lgkmcnt(2)
	v_mfma_f32_16x16x32_bf16 v[90:93], v[78:81], v[86:89], 0
	ds_read_b128 v[142:145], v211 offset:4672
	ds_read_b128 v[150:153], v211 offset:6976
	ds_read2_b64 v[160:163], v215 offset1:4
	v_mfma_f32_16x16x32_bf16 v[86:89], v[82:85], v[86:89], 0
	s_waitcnt lgkmcnt(4)
	v_mfma_f32_16x16x32_bf16 v[90:93], v[70:73], v[94:97], v[90:93]
	v_mfma_f32_16x16x32_bf16 v[86:89], v[74:77], v[94:97], v[86:89]
	ds_read_b128 v[94:97], v211 offset:2304
	s_waitcnt lgkmcnt(0)
	v_mfma_f32_16x16x32_bf16 v[98:101], v[78:81], v[94:97], 0
	v_mfma_f32_16x16x32_bf16 v[94:97], v[82:85], v[94:97], 0
	v_mfma_f32_16x16x32_bf16 v[98:101], v[70:73], v[134:137], v[98:101]
	v_mfma_f32_16x16x32_bf16 v[94:97], v[74:77], v[134:137], v[94:97]
	ds_read_b128 v[134:137], v211 offset:4608
	s_waitcnt lgkmcnt(0)
	v_mfma_f32_16x16x32_bf16 v[138:141], v[78:81], v[134:137], 0
	v_mfma_f32_16x16x32_bf16 v[134:137], v[82:85], v[134:137], 0
	v_mfma_f32_16x16x32_bf16 v[138:141], v[70:73], v[142:145], v[138:141]
	v_mfma_f32_16x16x32_bf16 v[134:137], v[74:77], v[142:145], v[134:137]
	ds_read_b128 v[142:145], v211 offset:6912
	s_waitcnt lgkmcnt(0)
	v_mfma_f32_16x16x32_bf16 v[146:149], v[78:81], v[142:145], 0
	v_mfma_f32_16x16x32_bf16 v[142:145], v[82:85], v[142:145], 0
	v_mfma_f32_16x16x32_bf16 v[146:149], v[70:73], v[150:153], v[146:149]
	v_mfma_f32_16x16x32_bf16 v[142:145], v[74:77], v[150:153], v[142:145]
	v_cvt_pk_bf16_f32 v150, v6, v7
	v_cvt_pk_bf16_f32 v151, v8, v9
	v_cvt_pk_bf16_f32 v152, v22, v23
	v_cvt_pk_bf16_f32 v153, v24, v25
	v_mfma_f32_16x16x32_bf16 v[86:89], v[156:159], v[160:163], v[86:89]
	s_nop 0
	v_mfma_f32_16x16x32_bf16 v[90:93], v[150:153], v[160:163], v[90:93]
	ds_read2_b64 v[160:163], v216 offset0:32 offset1:36
	s_waitcnt lgkmcnt(0)
	v_mfma_f32_16x16x32_bf16 v[98:101], v[150:153], v[160:163], v[98:101]
	v_mfma_f32_16x16x32_bf16 v[94:97], v[156:159], v[160:163], v[94:97]
	ds_read2_b64 v[160:163], v217 offset0:64 offset1:68
	s_waitcnt lgkmcnt(0)
	v_mfma_f32_16x16x32_bf16 v[138:141], v[150:153], v[160:163], v[138:141]
	v_mfma_f32_16x16x32_bf16 v[134:137], v[156:159], v[160:163], v[134:137]
	ds_read2_b64 v[160:163], v218 offset0:96 offset1:100
	s_waitcnt lgkmcnt(0)
	v_mfma_f32_16x16x32_bf16 v[146:149], v[150:153], v[160:163], v[146:149]
	v_cvt_pk_bf16_f32 v150, v14, v15
	v_cvt_pk_bf16_f32 v151, v16, v17
	v_cvt_pk_bf16_f32 v152, v38, v39
	v_mfma_f32_16x16x32_bf16 v[142:145], v[156:159], v[160:163], v[142:145]
	v_cvt_pk_bf16_f32 v153, v40, v41
	v_cvt_pk_bf16_f32 v156, v18, v19
	v_cvt_pk_bf16_f32 v157, v20, v21
	v_cvt_pk_bf16_f32 v158, v42, v43
	v_cvt_pk_bf16_f32 v159, v44, v45
	ds_read2_b64 v[160:163], v215 offset0:8 offset1:12
	s_waitcnt lgkmcnt(0)
	v_mfma_f32_16x16x32_bf16 v[90:93], v[150:153], v[160:163], v[90:93]
	v_mfma_f32_16x16x32_bf16 v[86:89], v[156:159], v[160:163], v[86:89]
	ds_read2_b64 v[160:163], v216 offset0:40 offset1:44
	s_waitcnt lgkmcnt(0)
	v_mfma_f32_16x16x32_bf16 v[98:101], v[150:153], v[160:163], v[98:101]
	v_mfma_f32_16x16x32_bf16 v[94:97], v[156:159], v[160:163], v[94:97]
	ds_read2_b64 v[160:163], v217 offset0:72 offset1:76
	s_waitcnt lgkmcnt(0)
	v_mfma_f32_16x16x32_bf16 v[138:141], v[150:153], v[160:163], v[138:141]
	v_mfma_f32_16x16x32_bf16 v[134:137], v[156:159], v[160:163], v[134:137]
	ds_read2_b64 v[160:163], v218 offset0:104 offset1:108
	s_waitcnt lgkmcnt(0)
	v_mfma_f32_16x16x32_bf16 v[146:149], v[150:153], v[160:163], v[146:149]
	v_cvt_pk_bf16_f32 v150, v30, v31
	v_cvt_pk_bf16_f32 v151, v32, v33
	v_cvt_pk_bf16_f32 v152, v46, v47
	v_mfma_f32_16x16x32_bf16 v[142:145], v[156:159], v[160:163], v[142:145]
	v_cvt_pk_bf16_f32 v153, v48, v49
	v_cvt_pk_bf16_f32 v156, v34, v35
	v_cvt_pk_bf16_f32 v157, v36, v37
	v_cvt_pk_bf16_f32 v158, v54, v55
	v_cvt_pk_bf16_f32 v159, v56, v57
	ds_read2_b64 v[160:163], v215 offset0:16 offset1:20
	s_waitcnt lgkmcnt(0)
	v_mfma_f32_16x16x32_bf16 v[90:93], v[150:153], v[160:163], v[90:93]
	v_mfma_f32_16x16x32_bf16 v[86:89], v[156:159], v[160:163], v[86:89]
	ds_read2_b64 v[160:163], v216 offset0:48 offset1:52
	s_waitcnt lgkmcnt(0)
	v_mfma_f32_16x16x32_bf16 v[98:101], v[150:153], v[160:163], v[98:101]
	v_mfma_f32_16x16x32_bf16 v[94:97], v[156:159], v[160:163], v[94:97]
	ds_read2_b64 v[160:163], v217 offset0:80 offset1:84
	s_waitcnt lgkmcnt(0)
	v_mfma_f32_16x16x32_bf16 v[138:141], v[150:153], v[160:163], v[138:141]
	v_mfma_f32_16x16x32_bf16 v[134:137], v[156:159], v[160:163], v[134:137]
	ds_read2_b64 v[160:163], v218 offset0:112 offset1:116
	s_waitcnt lgkmcnt(0)
	v_mfma_f32_16x16x32_bf16 v[146:149], v[150:153], v[160:163], v[146:149]
	v_cvt_pk_bf16_f32 v150, v50, v51
	v_cvt_pk_bf16_f32 v151, v52, v53
	v_cvt_pk_bf16_f32 v152, v62, v63
	v_mfma_f32_16x16x32_bf16 v[142:145], v[156:159], v[160:163], v[142:145]
	v_cvt_pk_bf16_f32 v153, v64, v65
	v_cvt_pk_bf16_f32 v156, v58, v59
	v_cvt_pk_bf16_f32 v157, v60, v61
	v_cvt_pk_bf16_f32 v158, v66, v67
	v_cvt_pk_bf16_f32 v159, v68, v69
	ds_read2_b64 v[160:163], v215 offset0:24 offset1:28
	s_waitcnt lgkmcnt(0)
	v_mfma_f32_16x16x32_bf16 v[90:93], v[150:153], v[160:163], v[90:93]
	v_mfma_f32_16x16x32_bf16 v[86:89], v[156:159], v[160:163], v[86:89]
	ds_read2_b64 v[160:163], v216 offset0:56 offset1:60
	s_nop 5
	v_cvt_pk_bf16_f32 v90, v90, v91
	v_cvt_pk_bf16_f32 v91, v92, v93
	s_waitcnt lgkmcnt(0)
	v_mfma_f32_16x16x32_bf16 v[98:101], v[150:153], v[160:163], v[98:101]
	v_lshl_add_u64 v[92:93], s[74:75], 0, v[116:117]
	v_cvt_pk_bf16_f32 v86, v86, v87
	v_cvt_pk_bf16_f32 v87, v88, v89
	v_mfma_f32_16x16x32_bf16 v[94:97], v[156:159], v[160:163], v[94:97]
	ds_read2_b64 v[160:163], v217 offset0:88 offset1:92
	v_add_co_u32_e32 v88, vcc, s62, v92
	s_waitcnt lgkmcnt(0)
	v_mfma_f32_16x16x32_bf16 v[138:141], v[150:153], v[160:163], v[138:141]
	global_store_dwordx2 v[92:93], v[86:87], off offset:32
	v_cvt_pk_bf16_f32 v86, v98, v99
	v_cvt_pk_bf16_f32 v87, v100, v101
	v_mfma_f32_16x16x32_bf16 v[134:137], v[156:159], v[160:163], v[134:137]
	ds_read2_b64 v[160:163], v218 offset0:120 offset1:124
	v_addc_co_u32_e32 v89, vcc, 0, v93, vcc
	global_store_dwordx2 v[88:89], v[86:87], off
	v_cvt_pk_bf16_f32 v86, v94, v95
	v_cvt_pk_bf16_f32 v87, v96, v97
	s_mov_b32 s62, 0x10000
	s_waitcnt lgkmcnt(0)
	v_mfma_f32_16x16x32_bf16 v[146:149], v[150:153], v[160:163], v[146:149]
	global_store_dwordx2 v[88:89], v[86:87], off offset:32
	v_add_co_u32_e32 v88, vcc, s62, v92
	v_mfma_f32_16x16x32_bf16 v[142:145], v[156:159], v[160:163], v[142:145]
	v_cvt_pk_bf16_f32 v86, v138, v139
	v_cvt_pk_bf16_f32 v87, v140, v141
	v_addc_co_u32_e32 v89, vcc, 0, v93, vcc
	global_store_dwordx2 v[88:89], v[86:87], off
	v_cvt_pk_bf16_f32 v86, v134, v135
	v_cvt_pk_bf16_f32 v87, v136, v137
	global_store_dwordx2 v[88:89], v[86:87], off offset:32
	v_add_co_u32_e32 v88, vcc, s81, v92
	v_cvt_pk_bf16_f32 v86, v146, v147
	v_cvt_pk_bf16_f32 v87, v148, v149
	v_addc_co_u32_e32 v89, vcc, 0, v93, vcc
	global_store_dwordx2 v[88:89], v[86:87], off
	v_cvt_pk_bf16_f32 v86, v142, v143
	v_cvt_pk_bf16_f32 v87, v144, v145
	global_store_dwordx2 v[92:93], v[90:91], off
	global_store_dwordx2 v[88:89], v[86:87], off offset:32
	ds_read_b64_tr_b16 v[88:89], v213 offset:57408
	ds_read_b64_tr_b16 v[86:87], v213 offset:56320
	ds_read_b64_tr_b16 v[90:91], v213 offset:56352
	s_waitcnt lgkmcnt(1)
	v_mfma_f32_16x16x32_bf16 v[6:9], v[86:89], v[78:81], v[6:9]
	s_add_u32 s74, s74, 0x20000
	s_addc_u32 s75, s75, 0
	s_add_i32 s92, s92, 1
	v_mfma_f32_16x16x32_bf16 v[10:13], v[86:89], v[82:85], v[10:13]
	ds_read_b64_tr_b16 v[86:87], v213 offset:65024
	ds_read_b64_tr_b16 v[88:89], v214 offset:57408
	ds_read_b64_tr_b16 v[94:95], v214 offset:57440
	ds_read_b64_tr_b16 v[92:93], v213 offset:57440
	s_cmp_lg_u32 s76, 0x300000
	s_waitcnt lgkmcnt(2)
	v_mfma_f32_16x16x32_bf16 v[6:9], v[86:89], v[70:73], v[6:9]
	v_mfma_f32_16x16x32_bf16 v[10:13], v[86:89], v[74:77], v[10:13]
	s_waitcnt lgkmcnt(0)
	v_mfma_f32_16x16x32_bf16 v[22:25], v[90:93], v[78:81], v[22:25]
	v_mfma_f32_16x16x32_bf16 v[26:29], v[90:93], v[82:85], v[26:29]
	ds_read_b64_tr_b16 v[92:93], v213 offset:65056
	ds_read_b64_tr_b16 v[86:87], v213 offset:56384
	ds_read_b64_tr_b16 v[88:89], v213 offset:57472
	s_waitcnt lgkmcnt(0)
	v_mfma_f32_16x16x32_bf16 v[14:17], v[86:89], v[78:81], v[14:17]
	v_mfma_f32_16x16x32_bf16 v[18:21], v[86:89], v[82:85], v[18:21]
	ds_read_b64_tr_b16 v[86:87], v213 offset:65088
	ds_read_b64_tr_b16 v[88:89], v214 offset:57472
	s_waitcnt lgkmcnt(0)
	v_mfma_f32_16x16x32_bf16 v[14:17], v[86:89], v[70:73], v[14:17]
	v_mfma_f32_16x16x32_bf16 v[18:21], v[86:89], v[74:77], v[18:21]
	ds_read_b64_tr_b16 v[86:87], v213 offset:56416
	ds_read_b64_tr_b16 v[88:89], v213 offset:57504
	s_waitcnt lgkmcnt(0)
	v_mfma_f32_16x16x32_bf16 v[38:41], v[86:89], v[78:81], v[38:41]
	v_mfma_f32_16x16x32_bf16 v[42:45], v[86:89], v[82:85], v[42:45]
	ds_read_b64_tr_b16 v[86:87], v213 offset:65120
	ds_read_b64_tr_b16 v[88:89], v214 offset:57504
	s_waitcnt lgkmcnt(0)
	v_mfma_f32_16x16x32_bf16 v[38:41], v[86:89], v[70:73], v[38:41]
	v_mfma_f32_16x16x32_bf16 v[42:45], v[86:89], v[74:77], v[42:45]
	ds_read_b64_tr_b16 v[86:87], v213 offset:56448
	ds_read_b64_tr_b16 v[88:89], v213 offset:57536
	s_waitcnt lgkmcnt(0)
	v_mfma_f32_16x16x32_bf16 v[30:33], v[86:89], v[78:81], v[30:33]
	v_mfma_f32_16x16x32_bf16 v[34:37], v[86:89], v[82:85], v[34:37]
	ds_read_b64_tr_b16 v[86:87], v213 offset:65152
	ds_read_b64_tr_b16 v[88:89], v214 offset:57536
	s_waitcnt lgkmcnt(0)
	v_mfma_f32_16x16x32_bf16 v[30:33], v[86:89], v[70:73], v[30:33]
	v_mfma_f32_16x16x32_bf16 v[34:37], v[86:89], v[74:77], v[34:37]
	ds_read_b64_tr_b16 v[86:87], v213 offset:56480
	ds_read_b64_tr_b16 v[88:89], v213 offset:57568
	s_waitcnt lgkmcnt(0)
	v_mfma_f32_16x16x32_bf16 v[46:49], v[86:89], v[78:81], v[46:49]
	v_mfma_f32_16x16x32_bf16 v[54:57], v[86:89], v[82:85], v[54:57]
	ds_read_b64_tr_b16 v[86:87], v213 offset:65184
	ds_read_b64_tr_b16 v[88:89], v214 offset:57568
	s_waitcnt lgkmcnt(0)
	v_mfma_f32_16x16x32_bf16 v[46:49], v[86:89], v[70:73], v[46:49]
	v_mfma_f32_16x16x32_bf16 v[54:57], v[86:89], v[74:77], v[54:57]
	ds_read_b64_tr_b16 v[86:87], v213 offset:56512
	ds_read_b64_tr_b16 v[88:89], v213 offset:57600
	s_waitcnt lgkmcnt(0)
	v_mfma_f32_16x16x32_bf16 v[50:53], v[86:89], v[78:81], v[50:53]
	v_mfma_f32_16x16x32_bf16 v[58:61], v[86:89], v[82:85], v[58:61]
	ds_read_b64_tr_b16 v[86:87], v213 offset:65216
	ds_read_b64_tr_b16 v[88:89], v214 offset:57600
	s_waitcnt lgkmcnt(0)
	v_mfma_f32_16x16x32_bf16 v[50:53], v[86:89], v[70:73], v[50:53]
	v_mfma_f32_16x16x32_bf16 v[58:61], v[86:89], v[74:77], v[58:61]
	ds_read_b64_tr_b16 v[86:87], v213 offset:56544
	ds_read_b64_tr_b16 v[88:89], v213 offset:57632
	s_waitcnt lgkmcnt(0)
	v_mfma_f32_16x16x32_bf16 v[62:65], v[86:89], v[78:81], v[62:65]
	ds_read_b64_tr_b16 v[78:79], v213 offset:65248
	ds_read_b64_tr_b16 v[80:81], v214 offset:57632
	v_mfma_f32_16x16x32_bf16 v[66:69], v[86:89], v[82:85], v[66:69]
	v_mfma_f32_16x16x32_bf16 v[22:25], v[92:95], v[70:73], v[22:25]
	s_waitcnt lgkmcnt(0)
	v_mfma_f32_16x16x32_bf16 v[62:65], v[78:81], v[70:73], v[62:65]
	v_lshl_add_u32 v70, s93, 9, v179
	v_mfma_f32_16x16x32_bf16 v[26:29], v[92:95], v[74:77], v[26:29]
	v_mfma_f32_16x16x32_bf16 v[66:69], v[78:81], v[74:77], v[66:69]
	ds_read_b128 v[72:75], v70 offset:4096
	s_waitcnt lgkmcnt(0)
	s_nop 0
	v_mov_b32_e32 v72, v72
	s_nop 0
	v_mov_b32_e32 v73, v73
	s_nop 0
	v_mov_b32_e32 v74, v74
	s_nop 0
	v_mov_b32_e32 v75, v75
	v_mul_f32_e64 v6, v6, v72
	v_mul_f32_e64 v7, v7, v73
	v_mul_f32_e64 v10, v10, v72
	v_mul_f32_e64 v11, v11, v73
	v_mul_f32_e64 v8, v8, v74
	v_mul_f32_e64 v9, v9, v75
	v_mul_f32_e64 v12, v12, v74
	v_mul_f32_e64 v13, v13, v75
	ds_read_b128 v[72:75], v70 offset:4160
	s_waitcnt lgkmcnt(0)
	s_nop 0
	v_mov_b32_e32 v72, v72
	s_nop 0
	v_mov_b32_e32 v73, v73
	s_nop 0
	v_mov_b32_e32 v74, v74
	s_nop 0
	v_mov_b32_e32 v75, v75
	v_mul_f32_e64 v22, v22, v72
	v_mul_f32_e64 v23, v23, v73
	v_mul_f32_e64 v26, v26, v72
	v_mul_f32_e64 v27, v27, v73
	v_mul_f32_e64 v24, v24, v74
	v_mul_f32_e64 v25, v25, v75
	v_mul_f32_e64 v28, v28, v74
	v_mul_f32_e64 v29, v29, v75
	ds_read_b128 v[72:75], v70 offset:4224
	s_waitcnt lgkmcnt(0)
	s_nop 0
	v_mov_b32_e32 v72, v72
	s_nop 0
	v_mov_b32_e32 v73, v73
	s_nop 0
	v_mov_b32_e32 v74, v74
	s_nop 0
	v_mov_b32_e32 v75, v75
	v_mul_f32_e64 v14, v14, v72
	v_mul_f32_e64 v15, v15, v73
	v_mul_f32_e64 v18, v18, v72
	v_mul_f32_e64 v19, v19, v73
	v_mul_f32_e64 v16, v16, v74
	v_mul_f32_e64 v17, v17, v75
	v_mul_f32_e64 v20, v20, v74
	v_mul_f32_e64 v21, v21, v75
	ds_read_b128 v[72:75], v70 offset:4288
	s_waitcnt lgkmcnt(0)
	s_nop 0
	v_mov_b32_e32 v72, v72
	s_nop 0
	v_mov_b32_e32 v73, v73
	s_nop 0
	v_mov_b32_e32 v74, v74
	s_nop 0
	v_mov_b32_e32 v75, v75
	v_mul_f32_e64 v38, v38, v72
	v_mul_f32_e64 v39, v39, v73
	v_mul_f32_e64 v42, v42, v72
	v_mul_f32_e64 v43, v43, v73
	v_mul_f32_e64 v40, v40, v74
	v_mul_f32_e64 v41, v41, v75
	v_mul_f32_e64 v44, v44, v74
	v_mul_f32_e64 v45, v45, v75
	ds_read_b128 v[72:75], v70 offset:4352
	s_waitcnt lgkmcnt(0)
	s_nop 0
	v_mov_b32_e32 v72, v72
	s_nop 0
	v_mov_b32_e32 v73, v73
	s_nop 0
	v_mov_b32_e32 v74, v74
	s_nop 0
	v_mov_b32_e32 v75, v75
	v_mul_f32_e64 v30, v30, v72
	v_mul_f32_e64 v31, v31, v73
	v_mul_f32_e64 v34, v34, v72
	v_mul_f32_e64 v35, v35, v73
	v_mul_f32_e64 v32, v32, v74
	v_mul_f32_e64 v33, v33, v75
	v_mul_f32_e64 v36, v36, v74
	v_mul_f32_e64 v37, v37, v75
	ds_read_b128 v[72:75], v70 offset:4416
	s_waitcnt lgkmcnt(0)
	s_nop 0
	v_mov_b32_e32 v72, v72
	s_nop 0
	v_mov_b32_e32 v73, v73
	s_nop 0
	v_mov_b32_e32 v74, v74
	s_nop 0
	v_mov_b32_e32 v75, v75
	v_mul_f32_e64 v46, v46, v72
	v_mul_f32_e64 v47, v47, v73
	v_mul_f32_e64 v54, v54, v72
	v_mul_f32_e64 v55, v55, v73
	v_mul_f32_e64 v48, v48, v74
	v_mul_f32_e64 v49, v49, v75
	v_mul_f32_e64 v56, v56, v74
	v_mul_f32_e64 v57, v57, v75
	ds_read_b128 v[72:75], v70 offset:4480
	s_waitcnt lgkmcnt(0)
	s_nop 0
	v_mov_b32_e32 v72, v72
	s_nop 0
	v_mov_b32_e32 v73, v73
	s_nop 0
	v_mov_b32_e32 v74, v74
	s_nop 0
	v_mov_b32_e32 v75, v75
	v_mul_f32_e64 v50, v50, v72
	v_mul_f32_e64 v51, v51, v73
	v_mul_f32_e64 v58, v58, v72
	v_mul_f32_e64 v59, v59, v73
	ds_read_b128 v[70:73], v70 offset:4544
	v_mul_f32_e64 v52, v52, v74
	v_mul_f32_e64 v53, v53, v75
	v_mul_f32_e64 v60, v60, v74
	v_mul_f32_e64 v61, v61, v75
	s_waitcnt lgkmcnt(0)
	s_nop 0
	s_nop 0
	s_nop 0
	s_nop 0
	s_nop 0
	s_nop 0
	s_nop 0
	s_nop 0
	v_mul_f32_e64 v62, v62, v70
	v_mul_f32_e64 v63, v63, v71
	v_mul_f32_e64 v66, v66, v70
	v_mul_f32_e64 v67, v67, v71
	v_mul_f32_e64 v64, v64, v72
	v_mul_f32_e64 v65, v65, v73
	v_mul_f32_e64 v68, v68, v72
	v_mul_f32_e64 v69, v69, v73
	s_cbranch_scc0 .LBB0_672

.LBB0_679:
	s_or_b64 exec, exec, s[62:63]
	s_waitcnt lgkmcnt(0)
	s_barrier
	ds_read_b128 v[136:139], v184
	ds_read_b128 v[142:145], v184 offset:16
	s_waitcnt vmcnt(8)
	v_lshlrev_b32_e32 v156, 16, v166
	v_and_b32_e32 v157, 0xffff0000, v166
	v_lshlrev_b32_e32 v166, 16, v167
	s_waitcnt lgkmcnt(1)
	v_mov_b32_e32 v81, v138
	v_lshlrev_b32_e32 v138, 16, v168
	v_mov_b32_e32 v80, v137
	v_mov_b32_e32 v137, v139
	v_and_b32_e32 v139, 0xffff0000, v168
	v_mul_f32_e32 v0, 0xbfb8aa3b, v138
	v_add_f32_e64 v80, v80, v136
	v_add_f32_e64 v81, v81, v137
	s_waitcnt lgkmcnt(0)
	v_mov_b32_e32 v136, v144
	v_exp_f32_e32 v0, v0
	v_mul_f32_e32 v144, 0xbfb8aa3b, v139
	v_exp_f32_e32 v144, v144
	v_mov_b32_e32 v137, v142
	v_mov_b32_e32 v142, v145
	v_add_f32_e32 v0, 1.0, v0
	v_add_f32_e64 v146, v136, v142
	v_add_f32_e64 v147, v137, v143
	v_rcp_f32_e32 v136, v0
	v_add_f32_e32 v0, 1.0, v144
	v_lshlrev_b32_e32 v142, 16, v169
	v_rcp_f32_e32 v137, v0
	v_and_b32_e32 v143, 0xffff0000, v169
	v_mul_f32_e32 v0, 0xbfb8aa3b, v142
	v_exp_f32_e32 v0, v0
	v_mul_f32_e32 v144, 0xbfb8aa3b, v143
	v_exp_f32_e32 v144, v144
	v_mul_f32_e64 v148, v136, v138
	v_mul_f32_e64 v149, v137, v139
	v_add_f32_e32 v0, 1.0, v0
	v_rcp_f32_e32 v136, v0
	v_add_f32_e32 v0, 1.0, v144
	v_rcp_f32_e32 v137, v0
	v_mul_f32_e32 v0, 0xbfb8aa3b, v156
	v_exp_f32_e32 v0, v0
	v_mul_f32_e32 v138, 0xbfb8aa3b, v157
	v_exp_f32_e32 v138, v138
	v_and_b32_e32 v167, 0xffff0000, v167
	v_add_f32_e32 v0, 1.0, v0
	v_rcp_f32_e32 v224, v0
	v_add_f32_e32 v0, 1.0, v138
	v_rcp_f32_e32 v225, v0
	v_mul_f32_e32 v0, 0xbfb8aa3b, v166
	v_mul_f32_e64 v168, v136, v142
	v_mul_f32_e64 v169, v137, v143
	v_exp_f32_e32 v0, v0
	v_mul_f32_e32 v136, 0xbfb8aa3b, v167
	v_exp_f32_e32 v142, v136
	ds_read_b128 v[136:139], v184 offset:512
	v_add_f32_e32 v0, 1.0, v0
	v_rcp_f32_e32 v226, v0
	v_add_f32_e32 v0, 1.0, v142
	ds_read_b128 v[142:145], v184 offset:528
	s_waitcnt lgkmcnt(1)
	v_mov_b32_e32 v228, v137
	v_mov_b32_e32 v229, v138
	v_mov_b32_e32 v137, v139
	v_add_f32_e64 v136, v228, v136
	v_add_f32_e64 v137, v229, v137
	s_waitcnt lgkmcnt(0)
	v_mov_b32_e32 v138, v144
	v_mov_b32_e32 v139, v142
	v_mov_b32_e32 v142, v145
	v_add_f32_e64 v138, v138, v142
	v_add_f32_e64 v139, v139, v143
	v_mov_b32_e32 v142, v136
	v_mov_b32_e32 v143, v80
	v_mov_b32_e32 v80, v137
	v_add_f32_e64 v80, v142, v80
	v_add_f32_e64 v81, v143, v81
	v_mov_b32_e32 v136, v139
	v_mov_b32_e32 v137, v147
	v_add_f32_e64 v80, v80, v136
	v_add_f32_e64 v81, v81, v137
	v_mov_b32_e32 v139, v146
	s_mov_b32 s62, 0x358637bd
	v_add_f32_e64 v136, v138, v80
	v_add_f32_e64 v137, v139, v81
	v_mov_b64_e32 v[80:81], s[62:63]
	v_fma_f32 v136, v136, s52, v80
	v_fma_f32 v137, v137, s52, v80
	v_rcp_f32_e32 v227, v0
	v_mul_f32_e32 v0, 0x4b800000, v137
	v_cmp_gt_f32_e32 vcc, s1, v137
	v_mul_f32_e64 v142, v224, v156
	v_mul_f32_e64 v143, v225, v157
	v_mul_f32_e64 v144, v226, v166
	v_mul_f32_e64 v145, v227, v167
	v_cndmask_b32_e32 v0, v137, v0, vcc
	v_rsq_f32_e32 v0, v0
	v_lshl_add_u64 v[138:139], s[56:57], 0, v[116:117]
	s_waitcnt vmcnt(4)
	v_lshlrev_b32_e32 v146, 16, v159
	v_and_b32_e32 v147, 0xffff0000, v159
	v_mul_f32_e32 v137, 0x45800000, v0
	v_cndmask_b32_e32 v0, v0, v137, vcc
	v_mul_f32_e64 v106, v106, v0
	v_mul_f32_e64 v107, v107, v0
	v_mul_f32_e64 v108, v108, v0
	v_mul_f32_e64 v109, v109, v0
	v_mul_f32_e64 v102, v102, v0
	v_mul_f32_e64 v103, v103, v0
	v_mul_f32_e64 v104, v104, v0
	v_mul_f32_e64 v105, v105, v0
	v_mul_f32_e32 v0, 0x4b800000, v136
	v_cmp_gt_f32_e32 vcc, s1, v136
	s_waitcnt vmcnt(0)
	v_mul_f32_e64 v102, v70, v102
	v_mul_f32_e64 v103, v71, v103
	v_mul_f32_e64 v104, v72, v104
	v_mul_f32_e64 v105, v73, v105
	v_cndmask_b32_e32 v0, v136, v0, vcc
	v_mul_f32_e64 v102, v142, v102
	v_mul_f32_e64 v103, v143, v103
	v_mul_f32_e64 v104, v144, v104
	v_mul_f32_e64 v105, v145, v105
	v_rsq_f32_e32 v0, v0
	v_cvt_pk_bf16_f32 v102, v102, v103
	v_cvt_pk_bf16_f32 v103, v104, v105
	global_store_dwordx2 v[138:139], v[102:103], off offset:32
	v_lshlrev_b32_e32 v102, 16, v164
	v_mul_f32_e32 v103, 0xbfb8aa3b, v102
	v_exp_f32_e32 v104, v103
	v_mul_f32_e32 v103, 0x45800000, v0
	v_cndmask_b32_e32 v0, v0, v103, vcc
	v_and_b32_e32 v103, 0xffff0000, v164
	v_mul_f32_e32 v105, 0xbfb8aa3b, v103
	v_exp_f32_e32 v105, v105
	v_mul_f32_e64 v106, v74, v106
	v_mul_f32_e64 v107, v75, v107
	v_mul_f32_e64 v108, v76, v108
	v_mul_f32_e64 v109, v77, v109
	v_mul_f32_e64 v106, v148, v106
	v_mul_f32_e64 v107, v149, v107
	v_mul_f32_e64 v108, v168, v108
	v_mul_f32_e64 v109, v169, v109
	v_cvt_pk_bf16_f32 v106, v106, v107
	v_cvt_pk_bf16_f32 v107, v108, v109
	v_lshlrev_b32_e32 v108, 16, v165
	v_and_b32_e32 v109, 0xffff0000, v165
	v_add_f32_e32 v104, 1.0, v104
	v_add_f32_e32 v105, 1.0, v105
	v_mul_f32_e32 v136, 0xbfb8aa3b, v108
	v_mul_f32_e32 v137, 0xbfb8aa3b, v109
	v_rcp_f32_e32 v104, v104
	v_rcp_f32_e32 v105, v105
	v_exp_f32_e32 v136, v136
	v_exp_f32_e32 v137, v137
	global_store_dwordx2 v[138:139], v[106:107], off
	v_mul_f32_e64 v102, v104, v102
	v_mul_f32_e64 v103, v105, v103
	v_add_f32_e32 v104, 1.0, v136
	v_add_f32_e32 v105, 1.0, v137
	v_rcp_f32_e32 v104, v104
	v_rcp_f32_e32 v105, v105
	v_mul_f32_e64 v106, v152, v0
	v_mul_f32_e64 v107, v153, v0
	v_mul_f32_e64 v100, v100, v0
	v_mul_f32_e64 v101, v101, v0
	v_mul_f32_e64 v106, v74, v106
	v_mul_f32_e64 v107, v75, v107
	v_mul_f32_e64 v100, v76, v100
	v_mul_f32_e64 v101, v77, v101
	v_mul_f32_e64 v104, v104, v108
	v_mul_f32_e64 v105, v105, v109
	v_mul_f32_e64 v102, v102, v106
	v_mul_f32_e64 v103, v103, v107
	v_mul_f32_e64 v100, v104, v100
	v_mul_f32_e64 v101, v105, v101
	v_cvt_pk_bf16_f32 v102, v102, v103
	v_cvt_pk_bf16_f32 v103, v100, v101
	v_lshlrev_b32_e32 v100, 16, v162
	v_mul_f32_e32 v101, 0xbfb8aa3b, v100
	v_exp_f32_e32 v106, v101
	v_lshl_add_u64 v[104:105], s[56:57], 0, v[120:121]
	v_and_b32_e32 v101, 0xffff0000, v162
	global_store_dwordx2 v[104:105], v[102:103], off
	v_mul_f32_e32 v103, 0xbfb8aa3b, v101
	v_exp_f32_e32 v103, v103
	v_lshlrev_b32_e32 v104, 16, v163
	v_and_b32_e32 v105, 0xffff0000, v163
	v_add_f32_e32 v102, 1.0, v106
	v_add_f32_e32 v103, 1.0, v103
	v_mul_f32_e32 v106, 0xbfb8aa3b, v104
	v_mul_f32_e32 v107, 0xbfb8aa3b, v105
	v_rcp_f32_e32 v102, v102
	v_rcp_f32_e32 v103, v103
	v_exp_f32_e32 v106, v106
	v_exp_f32_e32 v107, v107
	v_mul_f32_e64 v98, v98, v0
	v_mul_f32_e64 v99, v99, v0
	v_mul_f32_e64 v100, v102, v100
	v_mul_f32_e64 v101, v103, v101
	v_add_f32_e32 v102, 1.0, v106
	v_add_f32_e32 v103, 1.0, v107
	v_rcp_f32_e32 v102, v102
	v_rcp_f32_e32 v103, v103
	v_mul_f32_e64 v98, v70, v98
	v_mul_f32_e64 v99, v71, v99
	v_mul_f32_e64 v96, v96, v0
	v_mul_f32_e64 v97, v97, v0
	v_mul_f32_e64 v98, v100, v98
	v_mul_f32_e64 v99, v101, v99
	v_mul_f32_e64 v96, v72, v96
	v_mul_f32_e64 v97, v73, v97
	v_mul_f32_e64 v100, v102, v104
	v_mul_f32_e64 v101, v103, v105
	v_cvt_pk_bf16_f32 v102, v98, v99
	v_mul_f32_e64 v100, v100, v96
	v_mul_f32_e64 v101, v101, v97
	ds_read_b128 v[96:99], v184 offset:1024
	v_cvt_pk_bf16_f32 v103, v100, v101
	v_lshl_add_u64 v[100:101], s[56:57], 0, v[122:123]
	global_store_dwordx2 v[100:101], v[102:103], off
	ds_read_b128 v[100:103], v184 offset:1040
	s_waitcnt lgkmcnt(1)
	v_mov_b32_e32 v105, v98
	v_lshlrev_b32_e32 v98, 16, v160
	v_mov_b32_e32 v104, v97
	v_mov_b32_e32 v97, v99
	v_and_b32_e32 v99, 0xffff0000, v160
	v_mul_f32_e32 v0, 0xbfb8aa3b, v98
	v_add_f32_e64 v104, v104, v96
	v_add_f32_e64 v105, v105, v97
	v_exp_f32_e32 v0, v0
	v_mul_f32_e32 v97, 0xbfb8aa3b, v99
	s_waitcnt lgkmcnt(0)
	v_mov_b32_e32 v96, v102
	v_exp_f32_e32 v102, v97
	v_lshlrev_b32_e32 v108, 16, v161
	v_mov_b32_e32 v97, v100
	v_add_f32_e32 v0, 1.0, v0
	v_and_b32_e32 v109, 0xffff0000, v161
	v_mul_f32_e32 v100, 0xbfb8aa3b, v108
	v_rcp_f32_e32 v106, v0
	v_add_f32_e32 v0, 1.0, v102
	v_exp_f32_e32 v100, v100
	v_mul_f32_e32 v102, 0xbfb8aa3b, v109
	v_exp_f32_e32 v102, v102
	v_rcp_f32_e32 v107, v0
	v_add_f32_e32 v0, 1.0, v100
	v_rcp_f32_e32 v136, v0
	v_add_f32_e32 v0, 1.0, v102
	v_rcp_f32_e32 v137, v0
	v_mov_b32_e32 v100, v103
	v_add_f32_e64 v138, v96, v100
	v_add_f32_e64 v139, v97, v101
	v_mul_f32_e64 v106, v106, v98
	v_mul_f32_e64 v107, v107, v99
	v_mul_f32_e64 v108, v136, v108
	v_mul_f32_e64 v109, v137, v109
	v_lshlrev_b32_e32 v136, 16, v158
	v_and_b32_e32 v137, 0xffff0000, v158
	v_mul_f32_e32 v0, 0xbfb8aa3b, v136
	v_exp_f32_e32 v0, v0
	v_mul_f32_e32 v96, 0xbfb8aa3b, v137
	v_exp_f32_e32 v96, v96
	v_lshl_add_u64 v[142:143], s[56:57], 0, v[124:125]
	v_add_f32_e32 v0, 1.0, v0
	v_rcp_f32_e32 v144, v0
	v_add_f32_e32 v0, 1.0, v96
	v_rcp_f32_e32 v145, v0
	v_mul_f32_e32 v0, 0xbfb8aa3b, v146
	v_exp_f32_e32 v0, v0
	v_mul_f32_e32 v96, 0xbfb8aa3b, v147
	v_exp_f32_e32 v100, v96
	ds_read_b128 v[96:99], v184 offset:1536
	v_add_f32_e32 v0, 1.0, v0
	v_rcp_f32_e32 v148, v0
	v_add_f32_e32 v0, 1.0, v100
	ds_read_b128 v[100:103], v184 offset:1552
	s_waitcnt lgkmcnt(1)
	v_mov_b32_e32 v152, v97
	v_mov_b32_e32 v153, v98
	v_mov_b32_e32 v97, v99
	v_add_f32_e64 v96, v152, v96
	v_add_f32_e64 v97, v153, v97
	s_waitcnt lgkmcnt(0)
	v_mov_b32_e32 v98, v102
	v_mov_b32_e32 v99, v100
	v_mov_b32_e32 v100, v103
	v_add_f32_e64 v98, v98, v100
	v_add_f32_e64 v99, v99, v101
	v_mov_b32_e32 v100, v96
	v_mov_b32_e32 v101, v104
	v_mov_b32_e32 v104, v97
	v_add_f32_e64 v96, v100, v104
	v_add_f32_e64 v97, v101, v105
	v_mov_b32_e32 v100, v99
	v_mov_b32_e32 v101, v139
	v_add_f32_e64 v96, v96, v100
	v_add_f32_e64 v97, v97, v101
	v_mov_b32_e32 v99, v138
	v_add_f32_e64 v96, v98, v96
	v_add_f32_e64 v97, v99, v97
	v_rcp_f32_e32 v149, v0
	v_fma_f32 v81, v97, s52, v80
	v_fma_f32 v80, v96, s52, v80
	v_mul_f32_e64 v96, v144, v136
	v_mul_f32_e64 v97, v145, v137
	v_mul_f32_e32 v0, 0x4b800000, v81
	v_cmp_gt_f32_e32 vcc, s1, v81
	v_mul_f32_e64 v152, v148, v146
	v_mul_f32_e64 v153, v149, v147
	v_lshl_add_u64 v[168:169], s[56:57], 0, v[126:127]
	v_cndmask_b32_e32 v0, v81, v0, vcc
	v_rsq_f32_e32 v0, v0
	s_add_i32 s75, s75, 1
	s_add_u32 s60, s60, 0xfffa0000
	s_addc_u32 s61, s61, -1
	v_mul_f32_e32 v81, 0x45800000, v0
	v_cndmask_b32_e32 v0, v0, v81, vcc
	v_mul_f32_e64 v90, v90, v0
	v_mul_f32_e64 v91, v91, v0
	v_mul_f32_e64 v94, v94, v0
	v_mul_f32_e64 v95, v95, v0
	v_mul_f32_e64 v90, v74, v90
	v_mul_f32_e64 v91, v75, v91
	v_mul_f32_e64 v94, v76, v94
	v_mul_f32_e64 v95, v77, v95
	v_mul_f32_e64 v90, v106, v90
	v_mul_f32_e64 v91, v107, v91
	v_mul_f32_e64 v94, v108, v94
	v_mul_f32_e64 v95, v109, v95
	v_cvt_pk_bf16_f32 v90, v90, v91
	v_cvt_pk_bf16_f32 v91, v94, v95
	global_store_dwordx2 v[142:143], v[90:91], off
	v_mul_f32_e64 v90, v92, v0
	v_mul_f32_e64 v91, v93, v0
	v_mul_f32_e64 v88, v88, v0
	v_mul_f32_e64 v89, v89, v0
	v_mul_f32_e32 v0, 0x4b800000, v80
	v_cmp_gt_f32_e32 vcc, s1, v80
	v_mul_f32_e64 v90, v70, v90
	v_mul_f32_e64 v91, v71, v91
	v_mul_f32_e64 v224, v72, v88
	v_mul_f32_e64 v225, v73, v89
	v_cndmask_b32_e32 v0, v80, v0, vcc
	v_mul_f32_e64 v108, v96, v90
	v_mul_f32_e64 v109, v97, v91
	ds_read_b64_tr_b16 v[90:91], v213 offset:57408
	ds_read_b64_tr_b16 v[88:89], v213 offset:56320
	ds_read_b64_tr_b16 v[94:95], v210 offset:2112
	ds_read_b64_tr_b16 v[92:93], v210
	ds_read_b64_tr_b16 v[98:99], v210 offset:2144
	ds_read_b64_tr_b16 v[96:97], v210 offset:32
	ds_read_b64_tr_b16 v[100:101], v213 offset:56352
	ds_read_b64_tr_b16 v[104:105], v213 offset:56384
	ds_read_b64_tr_b16 v[136:137], v213 offset:56416
	ds_read_b64_tr_b16 v[102:103], v213 offset:57440
	ds_read_b64_tr_b16 v[106:107], v213 offset:57472
	ds_read_b64_tr_b16 v[138:139], v213 offset:57504
	v_rsq_f32_e32 v0, v0
	ds_read_b64_tr_b16 v[142:143], v213 offset:65024
	ds_read_b64_tr_b16 v[144:145], v214 offset:57408
	ds_read_b64_tr_b16 v[146:147], v210 offset:16896
	ds_read_b64_tr_b16 v[148:149], v210 offset:19008
	ds_read_b64_tr_b16 v[158:159], v210 offset:19040
	ds_read_b64_tr_b16 v[156:157], v210 offset:16928
	s_waitcnt lgkmcnt(8)
	v_mfma_f32_16x16x32_bf16 v[10:13], v[100:103], v[92:95], v[10:13]
	v_and_b32_e32 v81, 0xffff0000, v150
	v_mul_f32_e32 v80, 0x45800000, v0
	v_cndmask_b32_e32 v0, v0, v80, vcc
	v_mfma_f32_16x16x32_bf16 v[18:21], v[100:103], v[96:99], v[18:21]
	v_lshlrev_b32_e32 v80, 16, v150
	v_mul_f32_e32 v100, 0xbfb8aa3b, v80
	v_mul_f32_e32 v101, 0xbfb8aa3b, v81
	v_mfma_f32_16x16x32_bf16 v[30:33], v[88:91], v[92:95], v[30:33]
	v_exp_f32_e32 v100, v100
	v_mul_f32_e64 v86, v86, v0
	v_mul_f32_e64 v87, v87, v0
	v_mul_f32_e64 v152, v152, v224
	v_mul_f32_e64 v153, v153, v225
	v_mfma_f32_16x16x32_bf16 v[6:9], v[88:91], v[96:99], v[6:9]
	ds_read_b64_tr_b16 v[88:89], v213 offset:65056
	ds_read_b64_tr_b16 v[160:161], v213 offset:65088
	ds_read_b64_tr_b16 v[164:165], v213 offset:65120
	ds_read_b64_tr_b16 v[90:91], v214 offset:57440
	ds_read_b64_tr_b16 v[162:163], v214 offset:57472
	ds_read_b64_tr_b16 v[166:167], v214 offset:57504
	v_mul_f32_e64 v74, v74, v86
	v_mul_f32_e64 v75, v75, v87
	v_lshlrev_b32_e32 v86, 16, v151
	s_waitcnt lgkmcnt(2)
	v_mfma_f32_16x16x32_bf16 v[10:13], v[88:91], v[146:149], v[10:13]
	v_mul_f32_e32 v87, 0xbfb8aa3b, v86
	v_cvt_pk_bf16_f32 v108, v108, v109
	v_cvt_pk_bf16_f32 v109, v152, v153
	v_mfma_f32_16x16x32_bf16 v[18:21], v[88:91], v[156:159], v[18:21]
	v_exp_f32_e32 v89, v101
	v_add_f32_e32 v88, 1.0, v100
	v_rcp_f32_e32 v88, v88
	global_store_dwordx2 v[168:169], v[108:109], off
	v_add_f32_e32 v89, 1.0, v89
	v_rcp_f32_e32 v89, v89
	v_mfma_f32_16x16x32_bf16 v[14:17], v[104:107], v[92:95], v[14:17]
	v_mul_f32_e64 v82, v82, v0
	v_mul_f32_e64 v83, v83, v0
	v_mul_f32_e64 v78, v78, v0
	v_mul_f32_e64 v79, v79, v0
	v_mul_f32_e64 v80, v88, v80
	v_mul_f32_e64 v81, v89, v81
	v_exp_f32_e32 v88, v87
	v_mul_f32_e64 v80, v80, v74
	v_mul_f32_e64 v81, v81, v75
	v_and_b32_e32 v87, 0xffff0000, v151
	v_mfma_f32_16x16x32_bf16 v[26:29], v[104:107], v[96:99], v[26:29]
	v_add_f32_e32 v74, 1.0, v88
	v_rcp_f32_e32 v88, v74
	v_mul_f32_e32 v74, 0xbfb8aa3b, v87
	v_exp_f32_e32 v89, v74
	v_mul_f32_e64 v74, v84, v0
	v_mul_f32_e64 v75, v85, v0
	v_mfma_f32_16x16x32_bf16 v[38:41], v[136:139], v[92:95], v[38:41]
	v_mul_f32_e64 v108, v76, v74
	v_mul_f32_e64 v109, v77, v75
	v_add_f32_e32 v74, 1.0, v89
	v_rcp_f32_e32 v89, v74
	ds_read_b64_tr_b16 v[74:75], v213 offset:56448
	ds_read_b64_tr_b16 v[76:77], v213 offset:57536
	v_mfma_f32_16x16x32_bf16 v[50:53], v[136:139], v[96:99], v[50:53]
	v_cvt_pk_bf16_f32 v80, v80, v81
	v_mul_f32_e64 v136, v88, v86
	v_mul_f32_e64 v137, v89, v87
	ds_read_b64_tr_b16 v[84:85], v213 offset:56480
	ds_read_b64_tr_b16 v[88:89], v213 offset:56512
	ds_read_b64_tr_b16 v[100:101], v213 offset:56544
	ds_read_b64_tr_b16 v[86:87], v213 offset:57568
	ds_read_b64_tr_b16 v[90:91], v213 offset:57600
	ds_read_b64_tr_b16 v[102:103], v213 offset:57632
	ds_read_b64_tr_b16 v[104:105], v213 offset:65152
	ds_read_b64_tr_b16 v[106:107], v214 offset:57536
	s_waitcnt lgkmcnt(8)
	v_mfma_f32_16x16x32_bf16 v[22:25], v[74:77], v[92:95], v[22:25]
	v_mul_f32_e64 v108, v136, v108
	v_mul_f32_e64 v109, v137, v109
	v_mul_f32_e64 v70, v70, v82
	v_mul_f32_e64 v71, v71, v83
	v_cvt_pk_bf16_f32 v81, v108, v109
	v_mfma_f32_16x16x32_bf16 v[34:37], v[74:77], v[96:99], v[34:37]
	v_lshl_add_u64 v[108:109], s[56:57], 0, v[128:129]
	v_mul_f32_e64 v72, v72, v78
	v_mul_f32_e64 v73, v73, v79
	v_lshl_add_u32 v0, s67, 9, v179
	v_mfma_f32_16x16x32_bf16 v[30:33], v[142:145], v[146:149], v[30:33]
	s_sub_i32 s54, s54, 64
	v_mfma_f32_16x16x32_bf16 v[6:9], v[142:145], v[156:159], v[6:9]
	ds_read_b64_tr_b16 v[74:75], v213 offset:65184
	ds_read_b64_tr_b16 v[136:137], v213 offset:65216
	ds_read_b64_tr_b16 v[142:143], v213 offset:65248
	ds_read_b64_tr_b16 v[76:77], v214 offset:57568
	ds_read_b64_tr_b16 v[138:139], v214 offset:57600
	ds_read_b64_tr_b16 v[144:145], v214 offset:57632
	global_store_dwordx2 v[108:109], v[80:81], off
	v_lshlrev_b32_e32 v80, 16, v140
	v_and_b32_e32 v81, 0xffff0000, v140
	s_waitcnt lgkmcnt(6)
	v_mfma_f32_16x16x32_bf16 v[22:25], v[104:107], v[146:149], v[22:25]
	v_mfma_f32_16x16x32_bf16 v[34:37], v[104:107], v[156:159], v[34:37]
	v_mul_f32_e32 v104, 0xbfb8aa3b, v80
	v_mul_f32_e32 v105, 0xbfb8aa3b, v81
	v_exp_f32_e32 v104, v104
	v_mfma_f32_16x16x32_bf16 v[42:45], v[84:87], v[92:95], v[42:45]
	v_mfma_f32_16x16x32_bf16 v[54:57], v[84:87], v[96:99], v[54:57]
	v_exp_f32_e32 v85, v105
	v_add_f32_e32 v84, 1.0, v104
	v_rcp_f32_e32 v84, v84
	s_waitcnt lgkmcnt(2)
	v_mfma_f32_16x16x32_bf16 v[42:45], v[74:77], v[146:149], v[42:45]
	v_add_f32_e32 v85, 1.0, v85
	v_rcp_f32_e32 v85, v85
	v_mfma_f32_16x16x32_bf16 v[54:57], v[74:77], v[156:159], v[54:57]
	v_mul_f32_e64 v74, v84, v80
	v_mul_f32_e64 v75, v85, v81
	v_mul_f32_e64 v70, v74, v70
	v_mul_f32_e64 v71, v75, v71
	v_lshlrev_b32_e32 v74, 16, v141
	v_and_b32_e32 v75, 0xffff0000, v141
	v_mul_f32_e32 v76, 0xbfb8aa3b, v74
	v_mul_f32_e32 v77, 0xbfb8aa3b, v75
	v_exp_f32_e32 v76, v76
	v_exp_f32_e32 v77, v77
	v_cvt_pk_bf16_f32 v78, v70, v71
	v_lshl_add_u64 v[80:81], s[56:57], 0, v[130:131]
	v_add_f32_e32 v76, 1.0, v76
	v_add_f32_e32 v77, 1.0, v77
	v_rcp_f32_e32 v76, v76
	v_rcp_f32_e32 v77, v77
	v_mfma_f32_16x16x32_bf16 v[14:17], v[160:163], v[146:149], v[14:17]
	s_add_u32 s56, s56, 0xfffe0000
	s_addc_u32 s57, s57, -1
	v_mul_f32_e64 v74, v76, v74
	v_mul_f32_e64 v75, v77, v75
	v_mfma_f32_16x16x32_bf16 v[26:29], v[160:163], v[156:159], v[26:29]
	v_mul_f32_e64 v74, v74, v72
	v_mul_f32_e64 v75, v75, v73
	ds_read_b128 v[70:73], v0 offset:4096
	v_cvt_pk_bf16_f32 v79, v74, v75
	ds_read_b128 v[74:77], v0 offset:4160
	global_store_dwordx2 v[80:81], v[78:79], off
	v_mfma_f32_16x16x32_bf16 v[38:41], v[164:167], v[146:149], v[38:41]
	s_waitcnt lgkmcnt(1)
	s_nop 0
	v_mov_b32_e32 v82, v70
	v_mov_b32_e32 v83, v71
	v_mov_b32_e32 v70, v72
	v_mov_b32_e32 v71, v73
	s_nop 0
	s_nop 0
	s_nop 0
	v_mfma_f32_16x16x32_bf16 v[50:53], v[164:167], v[156:159], v[50:53]
	s_add_u32 s58, s58, 0xfffe0000
	v_mul_f32_e64 v32, v32, v70
	v_mul_f32_e64 v33, v33, v71
	v_mul_f32_e64 v8, v8, v70
	v_mul_f32_e64 v9, v9, v71
	s_waitcnt lgkmcnt(0)
	v_mov_b32_e32 v70, v74
	v_mov_b32_e32 v71, v76
	v_mov_b32_e32 v78, v70
	v_mov_b32_e32 v70, v75
	v_mov_b32_e32 v80, v71
	s_nop 0
	v_mov_b32_e32 v81, v77
	v_mov_b32_e32 v79, v70
	ds_read_b128 v[70:73], v0 offset:4224
	ds_read_b128 v[74:77], v0 offset:4288
	v_mul_f32_e64 v30, v30, v82
	v_mul_f32_e64 v31, v31, v83
	v_mul_f32_e64 v6, v6, v82
	v_mul_f32_e64 v7, v7, v83
	v_mul_f32_e64 v12, v12, v80
	v_mul_f32_e64 v13, v13, v81
	s_waitcnt lgkmcnt(1)
	s_nop 0
	v_mov_b32_e32 v82, v70
	v_mov_b32_e32 v83, v71
	v_mov_b32_e32 v70, v72
	v_mov_b32_e32 v71, v73
	s_nop 0
	s_nop 0
	v_mul_f32_e64 v10, v10, v78
	v_mul_f32_e64 v11, v11, v79
	v_mul_f32_e64 v20, v20, v80
	v_mul_f32_e64 v21, v21, v81
	v_mul_f32_e64 v18, v18, v78
	v_mul_f32_e64 v19, v19, v79
	v_mul_f32_e64 v16, v16, v70
	v_mul_f32_e64 v17, v17, v71
	v_mul_f32_e64 v28, v28, v70
	v_mul_f32_e64 v29, v29, v71
	s_waitcnt lgkmcnt(0)
	v_mov_b32_e32 v70, v74
	v_mov_b32_e32 v71, v76
	v_mov_b32_e32 v78, v70
	v_mov_b32_e32 v70, v75
	v_mov_b32_e32 v80, v71
	s_nop 0
	v_mov_b32_e32 v81, v77
	v_mov_b32_e32 v79, v70
	ds_read_b128 v[70:73], v0 offset:4352
	ds_read_b128 v[74:77], v0 offset:4416
	s_nop 0
	v_mul_f32_e64 v40, v40, v80
	v_mul_f32_e64 v41, v41, v81
	v_mul_f32_e64 v38, v38, v78
	v_mul_f32_e64 v39, v39, v79
	s_waitcnt lgkmcnt(1)
	s_nop 0
	v_mul_f32_e64 v14, v14, v82
	v_mul_f32_e64 v15, v15, v83
	v_mul_f32_e64 v26, v26, v82
	v_mul_f32_e64 v27, v27, v83
	v_mov_b32_e32 v82, v70
	v_mov_b32_e32 v83, v71
	v_mov_b32_e32 v70, v72
	v_mov_b32_e32 v71, v73
	s_nop 0
	s_nop 0
	v_mul_f32_e64 v52, v52, v80
	v_mul_f32_e64 v53, v53, v81
	v_mul_f32_e64 v50, v50, v78
	v_mul_f32_e64 v51, v51, v79
	v_mfma_f32_16x16x32_bf16 v[46:49], v[88:91], v[92:95], v[46:49]
	v_mul_f32_e64 v24, v24, v70
	v_mul_f32_e64 v25, v25, v71
	v_mul_f32_e64 v36, v36, v70
	v_mul_f32_e64 v37, v37, v71
	s_waitcnt lgkmcnt(0)
	v_mov_b32_e32 v70, v74
	v_mov_b32_e32 v71, v76
	v_mov_b32_e32 v78, v70
	v_mov_b32_e32 v70, v75
	v_mov_b32_e32 v80, v71
	s_nop 0
	v_mov_b32_e32 v81, v77
	v_mov_b32_e32 v79, v70
	ds_read_b128 v[70:73], v0 offset:4480
	ds_read_b128 v[74:77], v0 offset:4544
	v_mfma_f32_16x16x32_bf16 v[62:65], v[88:91], v[96:99], v[62:65]
	s_nop 0
	s_addc_u32 s59, s59, -1
	s_waitcnt lgkmcnt(1)
	s_nop 0
	v_mov_b32_e32 v70, v70
	v_mov_b32_e32 v0, v71
	v_mov_b32_e32 v71, v72
	v_mfma_f32_16x16x32_bf16 v[58:61], v[100:103], v[92:95], v[58:61]
	v_mov_b32_e32 v72, v71
	s_nop 0
	v_mov_b32_e32 v73, v73
	v_mfma_f32_16x16x32_bf16 v[66:69], v[100:103], v[96:99], v[66:69]
	v_mov_b32_e32 v71, v0
	s_waitcnt lgkmcnt(0)
	s_nop 0
	v_mov_b32_e32 v74, v74
	v_mov_b32_e32 v0, v75
	v_mov_b32_e32 v75, v76
	v_mov_b32_e32 v76, v75
	v_mov_b32_e32 v75, v77
	v_mfma_f32_16x16x32_bf16 v[46:49], v[136:139], v[146:149], v[46:49]
	v_mov_b32_e32 v77, v75
	v_mov_b32_e32 v75, v0
	v_mul_f32_e64 v22, v22, v82
	v_mul_f32_e64 v23, v23, v83
	v_mfma_f32_16x16x32_bf16 v[62:65], v[136:139], v[156:159], v[62:65]
	v_mul_f32_e64 v34, v34, v82
	v_mul_f32_e64 v35, v35, v83
	v_mul_f32_e64 v44, v44, v80
	v_mul_f32_e64 v45, v45, v81
	v_mul_f32_e64 v42, v42, v78
	v_mul_f32_e64 v43, v43, v79
	v_mfma_f32_16x16x32_bf16 v[58:61], v[142:145], v[146:149], v[58:61]
	v_mul_f32_e64 v56, v56, v80
	v_mul_f32_e64 v57, v57, v81
	v_mul_f32_e64 v54, v54, v78
	v_mul_f32_e64 v55, v55, v79
	v_mul_f32_e64 v48, v48, v72
	v_mul_f32_e64 v49, v49, v73
	v_mfma_f32_16x16x32_bf16 v[66:69], v[142:145], v[156:159], v[66:69]
	v_mul_f32_e64 v46, v46, v70
	v_mul_f32_e64 v47, v47, v71
	v_mul_f32_e64 v64, v64, v72
	v_mul_f32_e64 v65, v65, v73
	v_mul_f32_e64 v62, v62, v70
	v_mul_f32_e64 v63, v63, v71
	v_mul_f32_e64 v60, v60, v76
	v_mul_f32_e64 v61, v61, v77
	v_mul_f32_e64 v58, v58, v74
	v_mul_f32_e64 v59, v59, v75
	s_nop 1
	v_mul_f32_e64 v68, v68, v76
	v_mul_f32_e64 v69, v69, v77
	s_cmp_lg_u32 s75, 8
	v_mul_f32_e64 v66, v66, v74
	v_mul_f32_e64 v67, v67, v75
	s_cbranch_scc0 .LBB0_654

.LBB0_689:
	ds_read_b128 v[102:105], v201 offset:6144
	ds_read_b128 v[106:109], v201 offset:6160
	s_waitcnt vmcnt(6)
	v_lshlrev_b32_e32 v138, 16, v98
	v_and_b32_e32 v139, 0xffff0000, v98
	s_waitcnt lgkmcnt(1)
	v_mul_f32_e32 v0, 0xbfb8aa3b, v102
	v_exp_f32_e32 v136, v0
	v_mul_f32_e32 v0, 0xbfb8aa3b, v103
	v_exp_f32_e32 v137, v0
	v_mul_f32_e32 v0, 0xbfb8aa3b, v104
	v_mul_f32_e64 v136, v136, v138
	v_mul_f32_e64 v137, v137, v139
	s_nop 0
	v_cvt_pk_bf16_f32 v98, v136, v137
	v_exp_f32_e32 v136, v0
	v_mul_f32_e32 v0, 0xbfb8aa3b, v105
	v_exp_f32_e32 v137, v0
	v_lshlrev_b32_e32 v138, 16, v99
	v_and_b32_e32 v139, 0xffff0000, v99
	s_waitcnt lgkmcnt(0)
	v_mul_f32_e32 v0, 0xbfb8aa3b, v106
	v_mul_f32_e64 v136, v136, v138
	v_mul_f32_e64 v137, v137, v139
	v_lshlrev_b32_e32 v138, 16, v100
	v_cvt_pk_bf16_f32 v99, v136, v137
	v_exp_f32_e32 v136, v0
	v_mul_f32_e32 v0, 0xbfb8aa3b, v107
	v_exp_f32_e32 v137, v0
	v_and_b32_e32 v139, 0xffff0000, v100
	v_mul_f32_e32 v0, 0xbfb8aa3b, v108
	v_mul_f32_e64 v136, v136, v138
	v_mul_f32_e64 v137, v137, v139
	s_nop 0
	v_cvt_pk_bf16_f32 v100, v136, v137
	v_exp_f32_e32 v136, v0
	v_mul_f32_e32 v0, 0xbfb8aa3b, v109
	v_exp_f32_e32 v137, v0
	v_lshlrev_b32_e32 v138, 16, v101
	v_and_b32_e32 v139, 0xffff0000, v101
	v_mul_f32_e32 v0, 0x3fb8aa3b, v102
	v_mul_f32_e64 v136, v136, v138
	v_mul_f32_e64 v137, v137, v139
	s_nop 0
	v_cvt_pk_bf16_f32 v101, v136, v137
	ds_write_b128 v181, v[98:101] offset:56320
	v_exp_f32_e32 v98, v0
	v_mul_f32_e32 v0, 0x3fb8aa3b, v103
	v_exp_f32_e32 v99, v0
	v_lshlrev_b32_e32 v100, 16, v94
	v_and_b32_e32 v101, 0xffff0000, v94
	v_mul_f32_e32 v0, 0x3fb8aa3b, v104
	v_mul_f32_e64 v98, v98, s50
	v_mul_f32_e64 v99, v99, s50
	s_waitcnt vmcnt(4)
	v_lshlrev_b32_e32 v104, 16, v90
	v_mul_f32_e64 v98, v98, v100
	v_mul_f32_e64 v99, v99, v101
	v_lshlrev_b32_e32 v100, 16, v95
	v_cvt_pk_bf16_f32 v94, v98, v99
	v_exp_f32_e32 v98, v0
	v_mul_f32_e32 v0, 0x3fb8aa3b, v105
	v_exp_f32_e32 v99, v0
	v_and_b32_e32 v101, 0xffff0000, v95
	v_mul_f32_e32 v0, 0x3fb8aa3b, v106
	v_and_b32_e32 v105, 0xffff0000, v90
	v_mul_f32_e64 v98, v98, s50
	v_mul_f32_e64 v99, v99, s50
	s_nop 0
	v_mul_f32_e64 v98, v98, v100
	v_mul_f32_e64 v99, v99, v101
	v_lshlrev_b32_e32 v100, 16, v96
	v_cvt_pk_bf16_f32 v95, v98, v99
	v_exp_f32_e32 v98, v0
	v_mul_f32_e32 v0, 0x3fb8aa3b, v107
	v_exp_f32_e32 v99, v0
	v_and_b32_e32 v101, 0xffff0000, v96
	v_mul_f32_e32 v0, 0x3fb8aa3b, v108
	v_mul_f32_e64 v98, v98, s50
	v_mul_f32_e64 v99, v99, s50
	s_nop 0
	v_mul_f32_e64 v98, v98, v100
	v_mul_f32_e64 v99, v99, v101
	v_lshlrev_b32_e32 v100, 16, v97
	v_cvt_pk_bf16_f32 v96, v98, v99
	v_exp_f32_e32 v98, v0
	v_mul_f32_e32 v0, 0x3fb8aa3b, v109
	v_exp_f32_e32 v99, v0
	v_and_b32_e32 v101, 0xffff0000, v97
	v_mul_f32_e64 v98, v98, s50
	v_mul_f32_e64 v99, v99, s50
	s_nop 0
	v_mul_f32_e64 v98, v98, v100
	v_mul_f32_e64 v99, v99, v101
	s_nop 0
	v_cvt_pk_bf16_f32 v97, v98, v99
	ds_write_b128 v181, v[94:97] offset:38912
	ds_read_b128 v[94:97], v202 offset:6144
	ds_read_b128 v[98:101], v202 offset:6160
	s_waitcnt lgkmcnt(1)
	v_mul_f32_e32 v0, 0xbfb8aa3b, v94
	v_exp_f32_e32 v102, v0
	v_mul_f32_e32 v0, 0xbfb8aa3b, v95
	v_exp_f32_e32 v103, v0
	v_mul_f32_e32 v0, 0xbfb8aa3b, v96
	v_mul_f32_e64 v102, v102, v104
	v_mul_f32_e64 v103, v103, v105
	s_nop 0
	v_cvt_pk_bf16_f32 v90, v102, v103
	v_exp_f32_e32 v102, v0
	v_mul_f32_e32 v0, 0xbfb8aa3b, v97
	v_exp_f32_e32 v103, v0
	v_lshlrev_b32_e32 v104, 16, v91
	v_and_b32_e32 v105, 0xffff0000, v91
	s_waitcnt lgkmcnt(0)
	v_mul_f32_e32 v0, 0xbfb8aa3b, v98
	v_mul_f32_e64 v102, v102, v104
	v_mul_f32_e64 v103, v103, v105
	v_lshlrev_b32_e32 v104, 16, v92
	v_cvt_pk_bf16_f32 v91, v102, v103
	v_exp_f32_e32 v102, v0
	v_mul_f32_e32 v0, 0xbfb8aa3b, v99
	v_exp_f32_e32 v103, v0
	v_and_b32_e32 v105, 0xffff0000, v92
	v_mul_f32_e32 v0, 0xbfb8aa3b, v100
	v_mul_f32_e64 v102, v102, v104
	v_mul_f32_e64 v103, v103, v105
	s_nop 0
	v_cvt_pk_bf16_f32 v92, v102, v103
	v_exp_f32_e32 v102, v0
	v_mul_f32_e32 v0, 0xbfb8aa3b, v101
	v_exp_f32_e32 v103, v0
	v_lshlrev_b32_e32 v104, 16, v93
	v_and_b32_e32 v105, 0xffff0000, v93
	v_mul_f32_e32 v0, 0x3fb8aa3b, v94
	v_mul_f32_e64 v102, v102, v104
	v_mul_f32_e64 v103, v103, v105
	s_nop 0
	v_cvt_pk_bf16_f32 v93, v102, v103
	ds_write_b128 v182, v[90:93] offset:56320
	v_exp_f32_e32 v90, v0
	v_mul_f32_e32 v0, 0x3fb8aa3b, v95
	v_exp_f32_e32 v91, v0
	v_lshlrev_b32_e32 v92, 16, v70
	v_and_b32_e32 v93, 0xffff0000, v70
	v_mul_f32_e32 v0, 0x3fb8aa3b, v96
	v_mul_f32_e64 v90, v90, s50
	v_mul_f32_e64 v91, v91, s50
	s_nop 0
	v_mul_f32_e64 v90, v90, v92
	v_mul_f32_e64 v91, v91, v93
	v_lshlrev_b32_e32 v92, 16, v71
	v_cvt_pk_bf16_f32 v70, v90, v91
	v_exp_f32_e32 v90, v0
	v_mul_f32_e32 v0, 0x3fb8aa3b, v97
	v_exp_f32_e32 v91, v0
	v_and_b32_e32 v93, 0xffff0000, v71
	v_mul_f32_e32 v0, 0x3fb8aa3b, v98
	v_mul_f32_e64 v90, v90, s50
	v_mul_f32_e64 v91, v91, s50
	s_nop 0
	v_mul_f32_e64 v90, v90, v92
	v_mul_f32_e64 v91, v91, v93
	v_lshlrev_b32_e32 v92, 16, v72
	v_cvt_pk_bf16_f32 v71, v90, v91
	v_exp_f32_e32 v90, v0
	v_mul_f32_e32 v0, 0x3fb8aa3b, v99
	v_exp_f32_e32 v91, v0
	v_and_b32_e32 v93, 0xffff0000, v72
	v_mul_f32_e32 v0, 0x3fb8aa3b, v100
	v_mul_f32_e64 v90, v90, s50
	v_mul_f32_e64 v91, v91, s50
	s_nop 0
	v_mul_f32_e64 v90, v90, v92
	v_mul_f32_e64 v91, v91, v93
	v_lshlrev_b32_e32 v92, 16, v73
	v_cvt_pk_bf16_f32 v72, v90, v91
	v_exp_f32_e32 v90, v0
	v_mul_f32_e32 v0, 0x3fb8aa3b, v101
	v_exp_f32_e32 v91, v0
	v_and_b32_e32 v93, 0xffff0000, v73
	v_mul_f32_e64 v90, v90, s50
	v_mul_f32_e64 v91, v91, s50
	s_nop 0
	v_mul_f32_e64 v90, v90, v92
	v_mul_f32_e64 v91, v91, v93
	s_nop 0
	v_cvt_pk_bf16_f32 v73, v90, v91
	ds_write_b128 v182, v[70:73] offset:38912
	s_waitcnt vmcnt(3)
	ds_write_b128 v203, v[74:77]
	s_waitcnt vmcnt(2)
	ds_write_b128 v204, v[78:81]
	s_waitcnt vmcnt(1)
	ds_write_b128 v203, v[82:85] offset:16896
	s_waitcnt vmcnt(0)
	ds_write_b128 v205, v[86:89]
	v_lshl_add_u64 v[70:71], s[58:59], 0, v[116:117]
	v_lshl_add_u64 v[72:73], s[58:59], 0, v[120:121]
	v_lshl_add_u64 v[74:75], s[58:59], 0, v[122:123]
	global_load_dwordx2 v[156:157], v[70:71], off
	global_load_dwordx2 v[152:153], v[70:71], off offset:32
	global_load_dwordx2 v[148:149], v[72:73], off
	global_load_dwordx2 v[146:147], v[74:75], off
	v_lshl_add_u64 v[70:71], s[58:59], 0, v[124:125]
	v_lshl_add_u64 v[72:73], s[58:59], 0, v[126:127]
	v_lshl_add_u64 v[74:75], s[58:59], 0, v[128:129]
	v_lshl_add_u64 v[76:77], s[58:59], 0, v[130:131]
	global_load_dwordx2 v[144:145], v[70:71], off
	global_load_dwordx2 v[142:143], v[72:73], off
	global_load_dwordx2 v[138:139], v[74:75], off
	global_load_dwordx2 v[136:137], v[76:77], off
	s_waitcnt lgkmcnt(0)
	s_barrier
	ds_read_b128 v[70:73], v206 offset:56320
	ds_read_b128 v[74:77], v180 offset:38912
	ds_read_b128 v[78:81], v206 offset:56384
	ds_read_b128 v[82:85], v180 offset:38976
	s_waitcnt lgkmcnt(2)
	v_mfma_f32_16x16x32_bf16 v[70:73], v[70:73], v[74:77], 0
	v_mov_b32_e32 v0, s49
	v_cvt_pk_bf16_f32 v166, v62, v63
	v_cvt_pk_bf16_f32 v167, v64, v65
	s_waitcnt lgkmcnt(0)
	v_mfma_f32_16x16x32_bf16 v[70:73], v[78:81], v[82:85], v[70:73]
	ds_read_b128 v[78:81], v206 offset:56448
	ds_read_b128 v[86:89], v180 offset:39040
	v_cvt_pk_bf16_f32 v168, v66, v67
	v_cvt_pk_bf16_f32 v169, v68, v69
	s_waitcnt lgkmcnt(0)
	v_mfma_f32_16x16x32_bf16 v[70:73], v[78:81], v[86:89], v[70:73]
	ds_read_b128 v[78:81], v206 offset:56512
	ds_read_b128 v[90:93], v180 offset:39104
	s_add_u32 s55, s72, s68
	s_addc_u32 s63, s73, 0
	s_waitcnt lgkmcnt(0)
	v_mfma_f32_16x16x32_bf16 v[70:73], v[78:81], v[90:93], v[70:73]
	s_add_u32 s62, s55, 0xafc1000
	s_addc_u32 s63, s63, 0
	s_waitcnt vmcnt(7)
	v_lshlrev_b32_e32 v224, 16, v156
	s_nop 3
	v_cndmask_b32_e64 v0, v70, v0, s[14:15]
	v_cndmask_b32_e64 v70, v71, 0, s[30:31]
	v_cndmask_b32_e64 v71, v72, 0, s[34:35]
	v_cndmask_b32_e64 v72, v73, 0, s[36:37]
	v_cvt_pk_bf16_f32 v70, v0, v70
	v_cvt_pk_bf16_f32 v71, v71, v72
	ds_write_b64 v207, v[70:71]
	ds_read_b128 v[70:73], v208 offset:56320
	s_waitcnt lgkmcnt(0)
	v_mfma_f32_16x16x32_bf16 v[70:73], v[70:73], v[74:77], 0
	ds_read_b128 v[74:77], v208 offset:56384
	v_mov_b32_e32 v0, s49
	v_and_b32_e32 v225, 0xffff0000, v156
	s_waitcnt lgkmcnt(0)
	v_mfma_f32_16x16x32_bf16 v[70:73], v[74:77], v[82:85], v[70:73]
	ds_read_b128 v[74:77], v208 offset:56448
	v_lshlrev_b32_e32 v156, 16, v157
	v_and_b32_e32 v157, 0xffff0000, v157
	s_waitcnt lgkmcnt(0)
	v_mfma_f32_16x16x32_bf16 v[70:73], v[74:77], v[86:89], v[70:73]
	ds_read_b128 v[74:77], v208 offset:56512
	s_waitcnt vmcnt(6)
	v_lshlrev_b32_e32 v226, 16, v152
	v_and_b32_e32 v227, 0xffff0000, v152
	s_waitcnt lgkmcnt(0)
	v_mfma_f32_16x16x32_bf16 v[70:73], v[74:77], v[90:93], v[70:73]
	v_lshlrev_b32_e32 v152, 16, v153
	v_and_b32_e32 v153, 0xffff0000, v153
	s_nop 5
	v_cndmask_b32_e64 v0, v70, v0, s[22:23]
	v_cndmask_b32_e64 v70, v71, 0, s[38:39]
	v_cndmask_b32_e64 v71, v72, 0, s[40:41]
	v_cndmask_b32_e64 v72, v73, 0, s[42:43]
	v_cvt_pk_bf16_f32 v70, v0, v70
	v_cvt_pk_bf16_f32 v71, v71, v72
	ds_write_b64 v209, v[70:71]
	s_waitcnt lgkmcnt(0)
	s_barrier
	ds_read_b64_tr_b16 v[72:73], v210 offset:2112
	ds_read_b64_tr_b16 v[70:71], v210
	ds_read_b64_tr_b16 v[74:75], v210 offset:32
	ds_read_b64_tr_b16 v[78:79], v210 offset:16896
	ds_read_b64_tr_b16 v[80:81], v210 offset:19008
	ds_read_b64_tr_b16 v[76:77], v210 offset:2144
	ds_read_b64_tr_b16 v[82:83], v210 offset:16928
	ds_read_b64_tr_b16 v[84:85], v210 offset:19040
	ds_read_b128 v[86:89], v211
	ds_read_b128 v[94:97], v211 offset:64
	ds_read_b128 v[102:105], v211 offset:2368
	s_waitcnt lgkmcnt(2)
	v_mfma_f32_16x16x32_bf16 v[90:93], v[70:73], v[86:89], 0
	ds_read_b128 v[158:161], v211 offset:4672
	v_mfma_f32_16x16x32_bf16 v[86:89], v[74:77], v[86:89], 0
	s_waitcnt lgkmcnt(2)
	v_mfma_f32_16x16x32_bf16 v[90:93], v[78:81], v[94:97], v[90:93]
	v_mfma_f32_16x16x32_bf16 v[86:89], v[82:85], v[94:97], v[86:89]
	ds_read_b128 v[94:97], v211 offset:2304
	s_waitcnt lgkmcnt(0)
	v_mfma_f32_16x16x32_bf16 v[98:101], v[70:73], v[94:97], 0
	v_mfma_f32_16x16x32_bf16 v[94:97], v[74:77], v[94:97], 0
	v_mfma_f32_16x16x32_bf16 v[98:101], v[78:81], v[102:105], v[98:101]
	v_mfma_f32_16x16x32_bf16 v[94:97], v[82:85], v[102:105], v[94:97]
	ds_read_b128 v[102:105], v211 offset:4608
	s_waitcnt lgkmcnt(0)
	v_mfma_f32_16x16x32_bf16 v[106:109], v[70:73], v[102:105], 0
	v_mfma_f32_16x16x32_bf16 v[102:105], v[74:77], v[102:105], 0
	v_mfma_f32_16x16x32_bf16 v[106:109], v[78:81], v[158:161], v[106:109]
	v_mfma_f32_16x16x32_bf16 v[102:105], v[82:85], v[158:161], v[102:105]
	ds_read_b128 v[158:161], v211 offset:6912
	s_waitcnt lgkmcnt(0)
	v_mfma_f32_16x16x32_bf16 v[70:73], v[70:73], v[158:161], 0
	v_mfma_f32_16x16x32_bf16 v[74:77], v[74:77], v[158:161], 0
	ds_read_b128 v[158:161], v211 offset:6976
	s_waitcnt lgkmcnt(0)
	v_mfma_f32_16x16x32_bf16 v[70:73], v[78:81], v[158:161], v[70:73]
	v_cvt_pk_bf16_f32 v78, v30, v31
	v_cvt_pk_bf16_f32 v79, v32, v33
	v_cvt_pk_bf16_f32 v80, v10, v11
	v_mfma_f32_16x16x32_bf16 v[74:77], v[82:85], v[158:161], v[74:77]
	v_cvt_pk_bf16_f32 v81, v12, v13
	v_cvt_pk_bf16_f32 v82, v6, v7
	v_cvt_pk_bf16_f32 v83, v8, v9
	v_cvt_pk_bf16_f32 v84, v18, v19
	v_cvt_pk_bf16_f32 v85, v20, v21
	ds_read2_b64 v[158:161], v215 offset1:4
	s_waitcnt lgkmcnt(0)
	v_mfma_f32_16x16x32_bf16 v[90:93], v[78:81], v[158:161], v[90:93]
	v_mfma_f32_16x16x32_bf16 v[86:89], v[82:85], v[158:161], v[86:89]
	ds_read2_b64 v[158:161], v216 offset0:32 offset1:36
	s_waitcnt lgkmcnt(0)
	v_mfma_f32_16x16x32_bf16 v[98:101], v[78:81], v[158:161], v[98:101]
	v_mfma_f32_16x16x32_bf16 v[94:97], v[82:85], v[158:161], v[94:97]
	ds_read2_b64 v[158:161], v217 offset0:64 offset1:68
	s_waitcnt lgkmcnt(0)
	v_mfma_f32_16x16x32_bf16 v[106:109], v[78:81], v[158:161], v[106:109]
	v_mfma_f32_16x16x32_bf16 v[102:105], v[82:85], v[158:161], v[102:105]
	ds_read2_b64 v[158:161], v218 offset0:96 offset1:100
	s_waitcnt lgkmcnt(0)
	v_mfma_f32_16x16x32_bf16 v[70:73], v[78:81], v[158:161], v[70:73]
	v_cvt_pk_bf16_f32 v78, v14, v15
	v_cvt_pk_bf16_f32 v79, v16, v17
	v_cvt_pk_bf16_f32 v80, v38, v39
	v_mfma_f32_16x16x32_bf16 v[74:77], v[82:85], v[158:161], v[74:77]
	v_cvt_pk_bf16_f32 v81, v40, v41
	v_cvt_pk_bf16_f32 v82, v26, v27
	v_cvt_pk_bf16_f32 v83, v28, v29
	v_cvt_pk_bf16_f32 v84, v50, v51
	v_cvt_pk_bf16_f32 v85, v52, v53
	ds_read2_b64 v[158:161], v215 offset0:8 offset1:12
	s_waitcnt lgkmcnt(0)
	v_mfma_f32_16x16x32_bf16 v[90:93], v[78:81], v[158:161], v[90:93]
	v_mfma_f32_16x16x32_bf16 v[86:89], v[82:85], v[158:161], v[86:89]
	ds_read2_b64 v[158:161], v216 offset0:40 offset1:44
	s_waitcnt lgkmcnt(0)
	v_mfma_f32_16x16x32_bf16 v[98:101], v[78:81], v[158:161], v[98:101]
	v_mfma_f32_16x16x32_bf16 v[94:97], v[82:85], v[158:161], v[94:97]
	ds_read2_b64 v[158:161], v217 offset0:72 offset1:76
	s_waitcnt lgkmcnt(0)
	v_mfma_f32_16x16x32_bf16 v[106:109], v[78:81], v[158:161], v[106:109]
	v_mfma_f32_16x16x32_bf16 v[102:105], v[82:85], v[158:161], v[102:105]
	ds_read2_b64 v[158:161], v218 offset0:104 offset1:108
	s_waitcnt lgkmcnt(0)
	v_mfma_f32_16x16x32_bf16 v[70:73], v[78:81], v[158:161], v[70:73]
	v_cvt_pk_bf16_f32 v78, v22, v23
	v_cvt_pk_bf16_f32 v79, v24, v25
	v_cvt_pk_bf16_f32 v80, v42, v43
	v_mfma_f32_16x16x32_bf16 v[74:77], v[82:85], v[158:161], v[74:77]
	v_cvt_pk_bf16_f32 v81, v44, v45
	v_cvt_pk_bf16_f32 v82, v34, v35
	v_cvt_pk_bf16_f32 v83, v36, v37
	v_cvt_pk_bf16_f32 v84, v54, v55
	v_cvt_pk_bf16_f32 v85, v56, v57
	ds_read2_b64 v[158:161], v215 offset0:16 offset1:20
	s_waitcnt lgkmcnt(0)
	v_mfma_f32_16x16x32_bf16 v[90:93], v[78:81], v[158:161], v[90:93]
	v_mfma_f32_16x16x32_bf16 v[86:89], v[82:85], v[158:161], v[86:89]
	ds_read2_b64 v[158:161], v216 offset0:48 offset1:52
	s_waitcnt lgkmcnt(0)
	v_mfma_f32_16x16x32_bf16 v[98:101], v[78:81], v[158:161], v[98:101]
	v_mfma_f32_16x16x32_bf16 v[94:97], v[82:85], v[158:161], v[94:97]
	ds_read2_b64 v[158:161], v217 offset0:80 offset1:84
	s_waitcnt lgkmcnt(0)
	v_mfma_f32_16x16x32_bf16 v[162:165], v[78:81], v[158:161], v[106:109]
	v_mfma_f32_16x16x32_bf16 v[158:161], v[82:85], v[158:161], v[102:105]
	s_nop 2
	ds_read2_b64 v[102:105], v218 offset0:112 offset1:116
	s_waitcnt lgkmcnt(0)
	v_mfma_f32_16x16x32_bf16 v[70:73], v[78:81], v[102:105], v[70:73]
	v_cvt_pk_bf16_f32 v78, v46, v47
	v_cvt_pk_bf16_f32 v79, v48, v49
	v_cvt_pk_bf16_f32 v80, v58, v59
	v_mfma_f32_16x16x32_bf16 v[74:77], v[82:85], v[102:105], v[74:77]
	v_cvt_pk_bf16_f32 v81, v60, v61
	ds_read2_b64 v[82:85], v215 offset0:24 offset1:28
	s_waitcnt lgkmcnt(0)
	v_mfma_f32_16x16x32_bf16 v[106:109], v[78:81], v[82:85], v[90:93]
	v_mfma_f32_16x16x32_bf16 v[102:105], v[166:169], v[82:85], v[86:89]
	ds_read2_b64 v[82:85], v216 offset0:56 offset1:60
	s_nop 5
	v_add_f32_e64 v106, v106, v224
	v_add_f32_e64 v107, v107, v225
	v_add_f32_e64 v108, v108, v156
	v_add_f32_e64 v109, v109, v157
	s_waitcnt lgkmcnt(0)
	v_mfma_f32_16x16x32_bf16 v[98:101], v[78:81], v[82:85], v[98:101]
	v_mul_f32_e64 v156, v106, v106
	v_mul_f32_e64 v157, v107, v107
	v_mul_f32_e64 v224, v108, v108
	v_mul_f32_e64 v225, v109, v109
	v_add_f32_e32 v0, v156, v157
	v_mfma_f32_16x16x32_bf16 v[94:97], v[166:169], v[82:85], v[94:97]
	ds_read2_b64 v[82:85], v217 offset0:88 offset1:92
	v_add_f32_e64 v102, v102, v226
	v_add_f32_e64 v103, v103, v227
	v_add_f32_e32 v0, v224, v0
	s_waitcnt lgkmcnt(0)
	v_mfma_f32_16x16x32_bf16 v[86:89], v[166:169], v[82:85], v[158:161]
	v_add_f32_e64 v104, v104, v152
	v_add_f32_e64 v105, v105, v153
	s_nop 0
	ds_read2_b64 v[158:161], v218 offset0:120 offset1:124
	v_mul_f32_e64 v152, v102, v102
	v_mul_f32_e64 v153, v103, v103
	v_mfma_f32_16x16x32_bf16 v[90:93], v[78:81], v[82:85], v[162:165]
	v_add_f32_e32 v0, v225, v0
	v_add_f32_e32 v0, v152, v0
	v_mul_f32_e64 v226, v104, v104
	v_mul_f32_e64 v227, v105, v105
	s_waitcnt lgkmcnt(0)
	v_mfma_f32_16x16x32_bf16 v[82:85], v[78:81], v[158:161], v[70:73]
	v_add_f32_e32 v0, v153, v0
	v_add_f32_e32 v0, v226, v0
	v_add_f32_e32 v0, v227, v0
	v_lshl_add_u64 v[70:71], s[62:63], 0, v[118:119]
	v_add_co_u32_e32 v72, vcc, s81, v70
	v_mfma_f32_16x16x32_bf16 v[78:81], v[166:169], v[158:161], v[74:77]
	s_nop 0
	v_addc_co_u32_e32 v73, vcc, 0, v71, vcc
	global_load_dwordx2 v[168:169], v[70:71], off
	global_load_dwordx2 v[166:167], v[70:71], off offset:32
	global_load_dwordx2 v[164:165], v[72:73], off
	global_load_dwordx2 v[162:163], v[72:73], off offset:32
	v_add_co_u32_e32 v72, vcc, s95, v70
	v_mov_b32_e32 v152, v0
	s_nop 1
	v_permlane16_swap_b32_e32 v152, v0
	s_nop 0
	v_addc_co_u32_e32 v73, vcc, 0, v71, vcc
	v_add_co_u32_e32 v70, vcc, s96, v70
	global_load_dwordx2 v[160:161], v[72:73], off
	global_load_dwordx2 v[158:159], v[72:73], off offset:32
	v_addc_co_u32_e32 v71, vcc, 0, v71, vcc
	global_load_dwordx2 v[150:151], v[70:71], off
	global_load_dwordx2 v[140:141], v[70:71], off offset:32
	global_load_dwordx4 v[74:77], v[134:135], off
	s_nop 0
	global_load_dwordx4 v[70:73], v[134:135], off offset:64
	s_waitcnt lgkmcnt(0)
	v_add_f32_e32 v0, v0, v152
	v_mov_b32_e32 v152, v0
	s_nop 1
	v_permlane32_swap_b32_e32 v152, v0
	s_and_saveexec_b64 s[62:63], s[4:5]
	s_cbranch_execz .LBB0_691
	s_waitcnt lgkmcnt(0)
	v_add_f32_e32 v0, v0, v152
	ds_write_b32 v185, v0
.LBB0_691:
	s_or_b64 exec, exec, s[62:63]
	s_waitcnt vmcnt(15) lgkmcnt(0)
	v_lshlrev_b32_e32 v152, 16, v148
	v_and_b32_e32 v153, 0xffff0000, v148
	v_add_f32_e64 v152, v98, v152
	v_add_f32_e64 v153, v99, v153
	v_lshlrev_b32_e32 v98, 16, v149
	v_and_b32_e32 v99, 0xffff0000, v149
	v_add_f32_e64 v100, v100, v98
	v_add_f32_e64 v101, v101, v99
	v_mul_f32_e64 v148, v152, v152
	v_mul_f32_e64 v149, v153, v153
	v_mul_f32_e64 v156, v100, v100
	v_mul_f32_e64 v157, v101, v101
	s_waitcnt vmcnt(14)
	v_lshlrev_b32_e32 v98, 16, v146
	v_and_b32_e32 v99, 0xffff0000, v146
	v_add_f32_e32 v0, v148, v149
	v_add_f32_e64 v98, v94, v98
	v_add_f32_e64 v99, v95, v99
	v_lshlrev_b32_e32 v94, 16, v147
	v_and_b32_e32 v95, 0xffff0000, v147
	v_add_f32_e32 v0, v156, v0
	v_add_f32_e64 v96, v96, v94
	v_add_f32_e64 v97, v97, v95
	v_mul_f32_e64 v94, v98, v98
	v_mul_f32_e64 v95, v99, v99
	v_add_f32_e32 v0, v157, v0
	v_add_f32_e32 v0, v94, v0
	v_mul_f32_e64 v146, v96, v96
	v_mul_f32_e64 v147, v97, v97
	v_add_f32_e32 v0, v95, v0
	v_add_f32_e32 v0, v146, v0
	v_add_f32_e32 v0, v147, v0
	v_mov_b32_e32 v94, v0
	s_nop 1
	v_permlane16_swap_b32_e32 v94, v0
	s_waitcnt lgkmcnt(0)
	v_add_f32_e32 v0, v0, v94
	v_mov_b32_e32 v94, v0
	s_nop 1
	v_permlane32_swap_b32_e32 v94, v0
	s_and_saveexec_b64 s[62:63], s[4:5]
	s_cbranch_execz .LBB0_693
	s_waitcnt lgkmcnt(0)
	v_add_f32_e32 v0, v0, v94
	ds_write_b32 v185, v0 offset:512
.LBB0_693:
	s_or_b64 exec, exec, s[62:63]
	s_waitcnt vmcnt(13) lgkmcnt(0)
	v_lshlrev_b32_e32 v94, 16, v144
	v_and_b32_e32 v95, 0xffff0000, v144
	v_add_f32_e64 v90, v90, v94
	v_add_f32_e64 v91, v91, v95
	v_lshlrev_b32_e32 v94, 16, v145
	v_and_b32_e32 v95, 0xffff0000, v145
	v_add_f32_e64 v94, v92, v94
	v_add_f32_e64 v95, v93, v95
	v_mul_f32_e64 v144, v90, v90
	v_mul_f32_e64 v145, v91, v91
	v_mul_f32_e64 v146, v94, v94
	v_mul_f32_e64 v147, v95, v95
	s_waitcnt vmcnt(12)
	v_lshlrev_b32_e32 v92, 16, v142
	v_and_b32_e32 v93, 0xffff0000, v142
	v_add_f32_e32 v0, v144, v145
	v_add_f32_e64 v92, v86, v92
	v_add_f32_e64 v93, v87, v93
	v_lshlrev_b32_e32 v86, 16, v143
	v_and_b32_e32 v87, 0xffff0000, v143
	v_add_f32_e32 v0, v146, v0
	v_add_f32_e64 v88, v88, v86
	v_add_f32_e64 v89, v89, v87
	v_mul_f32_e64 v86, v92, v92
	v_mul_f32_e64 v87, v93, v93
	v_add_f32_e32 v0, v147, v0
	v_add_f32_e32 v0, v86, v0
	v_mul_f32_e64 v142, v88, v88
	v_mul_f32_e64 v143, v89, v89
	v_add_f32_e32 v0, v87, v0
	v_add_f32_e32 v0, v142, v0
	v_add_f32_e32 v0, v143, v0
	v_mov_b32_e32 v86, v0
	s_nop 1
	v_permlane16_swap_b32_e32 v86, v0
	s_waitcnt lgkmcnt(0)
	v_add_f32_e32 v0, v0, v86
	v_mov_b32_e32 v86, v0
	s_nop 1
	v_permlane32_swap_b32_e32 v86, v0
	s_and_saveexec_b64 s[62:63], s[4:5]
	s_cbranch_execz .LBB0_695
	s_waitcnt lgkmcnt(0)
	v_add_f32_e32 v0, v0, v86
	ds_write_b32 v185, v0 offset:1024
.LBB0_695:
	s_or_b64 exec, exec, s[62:63]
	s_waitcnt vmcnt(11) lgkmcnt(0)
	v_lshlrev_b32_e32 v86, 16, v138
	v_and_b32_e32 v87, 0xffff0000, v138
	v_add_f32_e64 v86, v82, v86
	v_add_f32_e64 v87, v83, v87
	v_lshlrev_b32_e32 v82, 16, v139
	v_and_b32_e32 v83, 0xffff0000, v139
	v_add_f32_e64 v84, v84, v82
	v_add_f32_e64 v85, v85, v83
	v_mul_f32_e64 v138, v86, v86
	v_mul_f32_e64 v139, v87, v87
	v_mul_f32_e64 v142, v84, v84
	v_mul_f32_e64 v143, v85, v85
	s_waitcnt vmcnt(10)
	v_lshlrev_b32_e32 v82, 16, v136
	v_and_b32_e32 v83, 0xffff0000, v136
	v_add_f32_e32 v0, v138, v139
	v_add_f32_e64 v82, v78, v82
	v_add_f32_e64 v83, v79, v83
	v_lshlrev_b32_e32 v78, 16, v137
	v_and_b32_e32 v79, 0xffff0000, v137
	v_add_f32_e32 v0, v142, v0
	v_add_f32_e64 v78, v80, v78
	v_add_f32_e64 v79, v81, v79
	v_mul_f32_e64 v80, v82, v82
	v_mul_f32_e64 v81, v83, v83
	v_add_f32_e32 v0, v143, v0
	v_add_f32_e32 v0, v80, v0
	v_mul_f32_e64 v136, v78, v78
	v_mul_f32_e64 v137, v79, v79
	v_add_f32_e32 v0, v81, v0
	v_add_f32_e32 v0, v136, v0
	v_add_f32_e32 v0, v137, v0
	v_mov_b32_e32 v80, v0
	s_nop 1
	v_permlane16_swap_b32_e32 v80, v0
	s_waitcnt lgkmcnt(0)
	v_add_f32_e32 v0, v0, v80
	v_mov_b32_e32 v80, v0
	s_nop 1
	v_permlane32_swap_b32_e32 v80, v0
	s_and_saveexec_b64 s[62:63], s[4:5]
	s_cbranch_execz .LBB0_679
	s_waitcnt lgkmcnt(0)
	v_add_f32_e32 v0, v0, v80
	ds_write_b32 v185, v0 offset:1536
	s_branch .LBB0_679

.LBB0_1036:
	s_waitcnt vmcnt(0)
	v_mov_b32_e32 v6, v149
	v_mov_b32_e32 v10, v149
	s_nop 1
	v_permlane16_swap_b32_e32 v6, v10
	v_lshlrev_b64 v[0:1], 11, v[156:157]
	v_lshl_add_u64 v[0:1], s[84:85], 0, v[0:1]
	s_lshl_b32 s80, s89, 7
	v_lshlrev_b32_e32 v72, 1, v78
	s_waitcnt lgkmcnt(0)
	v_add_f32_e32 v10, v10, v6
	v_mov_b32_e32 v11, v10
	s_nop 1
	v_permlane32_swap_b32_e32 v11, v10
	v_lshl_add_u64 v[6:7], v[0:1], 0, s[80:81]
	v_lshl_add_u64 v[8:9], v[6:7], 0, v[72:73]
	s_waitcnt lgkmcnt(0)
	v_add_f32_e32 v0, v10, v11
	v_div_scale_f32 v1, s[0:1], v0, v0, 1.0
	v_div_scale_f32 v13, vcc, 1.0, v0, 1.0
	v_rcp_f32_e32 v12, v1
	s_nop 1
	v_fma_f32 v14, -v1, v12, 1.0
	v_fmac_f32_e32 v12, v14, v12
	v_mul_f32_e32 v14, v13, v12
	v_fma_f32 v15, -v1, v14, v13
	v_fmac_f32_e32 v14, v15, v12
	v_fma_f32 v1, -v1, v14, v13
	v_div_fmas_f32 v1, v1, v12, v14
	v_div_fixup_f32 v0, v1, v0, 1.0
	v_readlane_b32 s0, v240, 11
	s_add_i32 s73, s73, s0
	s_cmpk_lt_i32 s73, 0x1080
	v_readlane_b32 s1, v240, 12
	v_lshlrev_b32_e32 v12, 16, v242
	v_and_b32_e32 v13, 0xffff0000, v242
	v_lshlrev_b32_e32 v4, 16, v243
	v_and_b32_e32 v5, 0xffff0000, v243
	v_mul_f32_e32 v1, 0xbfb8aa3b, v12
	v_mul_f32_e32 v14, 0xbfb8aa3b, v13
	v_mul_f32_e32 v15, 0xbfb8aa3b, v4
	v_mul_f32_e32 v16, 0xbfb8aa3b, v5
	v_exp_f32_e32 v1, v1
	v_exp_f32_e32 v14, v14
	v_exp_f32_e32 v15, v15
	v_exp_f32_e32 v16, v16
	v_add_f32_e32 v1, 1.0, v1
	v_add_f32_e32 v17, 1.0, v14
	v_add_f32_e32 v18, 1.0, v15
	v_add_f32_e32 v19, 1.0, v16
	v_rcp_f32_e32 v14, v1
	v_rcp_f32_e32 v15, v17
	v_rcp_f32_e32 v16, v18
	v_rcp_f32_e32 v17, v19
	v_mul_f32_e64 v18, v36, v0
	v_mul_f32_e64 v19, v37, v0
	v_mul_f32_e64 v20, v38, v0
	v_mul_f32_e64 v21, v39, v0
	v_mul_f32_e64 v12, v14, v12
	v_mul_f32_e64 v13, v15, v13
	v_mul_f32_e64 v4, v16, v4
	v_mul_f32_e64 v5, v17, v5
	v_mul_f32_e64 v12, v18, v12
	v_mul_f32_e64 v13, v19, v13
	v_mul_f32_e64 v4, v20, v4
	v_mul_f32_e64 v5, v21, v5
	v_cvt_pk_bf16_f32 v12, v12, v13
	v_cvt_pk_bf16_f32 v13, v4, v5
	global_store_dwordx2 v[8:9], v[12:13], off
	v_lshlrev_b32_e32 v12, 16, v244
	v_and_b32_e32 v13, 0xffff0000, v244
	v_lshlrev_b32_e32 v4, 16, v245
	v_and_b32_e32 v5, 0xffff0000, v245
	v_mul_f32_e32 v1, 0xbfb8aa3b, v12
	v_mul_f32_e32 v14, 0xbfb8aa3b, v13
	v_mul_f32_e32 v15, 0xbfb8aa3b, v4
	v_mul_f32_e32 v16, 0xbfb8aa3b, v5
	v_exp_f32_e32 v1, v1
	v_exp_f32_e32 v14, v14
	v_exp_f32_e32 v15, v15
	v_exp_f32_e32 v16, v16
	v_add_f32_e32 v1, 1.0, v1
	v_add_f32_e32 v17, 1.0, v14
	v_add_f32_e32 v18, 1.0, v15
	v_add_f32_e32 v19, 1.0, v16
	v_rcp_f32_e32 v14, v1
	v_rcp_f32_e32 v15, v17
	v_rcp_f32_e32 v16, v18
	v_rcp_f32_e32 v17, v19
	v_mul_f32_e64 v18, v32, v0
	v_mul_f32_e64 v19, v33, v0
	v_mul_f32_e64 v20, v34, v0
	v_mul_f32_e64 v21, v35, v0
	v_mul_f32_e64 v12, v14, v12
	v_mul_f32_e64 v13, v15, v13
	v_mul_f32_e64 v4, v16, v4
	v_mul_f32_e64 v5, v17, v5
	v_mul_f32_e64 v12, v18, v12
	v_mul_f32_e64 v13, v19, v13
	v_mul_f32_e64 v4, v20, v4
	v_mul_f32_e64 v5, v21, v5
	v_cvt_pk_bf16_f32 v12, v12, v13
	v_cvt_pk_bf16_f32 v13, v4, v5
	global_store_dwordx2 v[8:9], v[12:13], off offset:32
	v_lshlrev_b32_e32 v12, 16, v246
	v_and_b32_e32 v13, 0xffff0000, v246
	v_lshlrev_b32_e32 v4, 16, v247
	v_and_b32_e32 v5, 0xffff0000, v247
	v_mul_f32_e32 v1, 0xbfb8aa3b, v12
	v_mul_f32_e32 v14, 0xbfb8aa3b, v13
	v_mul_f32_e32 v15, 0xbfb8aa3b, v4
	v_mul_f32_e32 v16, 0xbfb8aa3b, v5
	v_exp_f32_e32 v1, v1
	v_exp_f32_e32 v14, v14
	v_exp_f32_e32 v15, v15
	v_exp_f32_e32 v16, v16
	v_add_f32_e32 v1, 1.0, v1
	v_add_f32_e32 v17, 1.0, v14
	v_add_f32_e32 v18, 1.0, v15
	v_add_f32_e32 v19, 1.0, v16
	v_rcp_f32_e32 v14, v1
	v_rcp_f32_e32 v15, v17
	v_rcp_f32_e32 v16, v18
	v_rcp_f32_e32 v17, v19
	v_mul_f32_e64 v18, v28, v0
	v_mul_f32_e64 v19, v29, v0
	v_mul_f32_e64 v20, v30, v0
	v_mul_f32_e64 v21, v31, v0
	v_mul_f32_e64 v12, v14, v12
	v_mul_f32_e64 v13, v15, v13
	v_mul_f32_e64 v4, v16, v4
	v_mul_f32_e64 v5, v17, v5
	v_mul_f32_e64 v12, v18, v12
	v_mul_f32_e64 v13, v19, v13
	v_mul_f32_e64 v4, v20, v4
	v_mul_f32_e64 v5, v21, v5
	v_cvt_pk_bf16_f32 v12, v12, v13
	v_cvt_pk_bf16_f32 v13, v4, v5
	global_store_dwordx2 v[8:9], v[12:13], off offset:64
	v_lshlrev_b32_e32 v12, 16, v248
	v_and_b32_e32 v13, 0xffff0000, v248
	v_lshlrev_b32_e32 v4, 16, v249
	v_and_b32_e32 v5, 0xffff0000, v249
	v_mul_f32_e32 v1, 0xbfb8aa3b, v12
	v_mul_f32_e32 v14, 0xbfb8aa3b, v13
	v_mul_f32_e32 v15, 0xbfb8aa3b, v4
	v_mul_f32_e32 v16, 0xbfb8aa3b, v5
	v_exp_f32_e32 v1, v1
	v_exp_f32_e32 v14, v14
	v_exp_f32_e32 v15, v15
	v_exp_f32_e32 v16, v16
	v_add_f32_e32 v1, 1.0, v1
	v_add_f32_e32 v17, 1.0, v14
	v_add_f32_e32 v18, 1.0, v15
	v_add_f32_e32 v19, 1.0, v16
	v_rcp_f32_e32 v14, v1
	v_rcp_f32_e32 v15, v17
	v_rcp_f32_e32 v16, v18
	v_rcp_f32_e32 v17, v19
	v_mul_f32_e64 v18, v24, v0
	v_mul_f32_e64 v19, v25, v0
	v_mul_f32_e64 v20, v26, v0
	v_mul_f32_e64 v21, v27, v0
	v_mul_f32_e64 v12, v14, v12
	v_mul_f32_e64 v13, v15, v13
	v_mul_f32_e64 v4, v16, v4
	v_mul_f32_e64 v5, v17, v5
	v_mul_f32_e64 v12, v18, v12
	v_mul_f32_e64 v13, v19, v13
	v_mul_f32_e64 v4, v20, v4
	v_mul_f32_e64 v5, v21, v5
	v_cvt_pk_bf16_f32 v12, v12, v13
	v_cvt_pk_bf16_f32 v13, v4, v5
	global_store_dwordx2 v[8:9], v[12:13], off offset:96
	s_cbranch_scc0 .LBB0_1190

.Lattn_fast:
	v_add_u32_e32 v241, s4, v159
	v_add_u32_e32 v201, v241, v161
	ds_read_b128 v[220:223], v201
	ds_read_b128 v[224:227], v201 offset:64
	ds_read_b128 v[228:231], v201 offset:2304
	ds_read_b128 v[232:235], v201 offset:2368
	ds_read_b128 v[236:239], v201 offset:4608
	ds_read_b128 v[252:255], v201 offset:4672
	s_waitcnt lgkmcnt(4)
	v_mfma_f32_16x16x32_bf16 v[40:43], v[220:223], v[16:19], 0
	v_mfma_f32_16x16x32_bf16 v[40:43], v[224:227], v[20:23], v[40:43]
	ds_read_b128 v[220:223], v201 offset:6912
	ds_read_b128 v[224:227], v201 offset:6976
	s_waitcnt lgkmcnt(4)
	v_mfma_f32_16x16x32_bf16 v[44:47], v[228:231], v[16:19], 0
	v_mfma_f32_16x16x32_bf16 v[44:47], v[232:235], v[20:23], v[44:47]
	ds_read_b128 v[228:231], v201 offset:9216
	ds_read_b128 v[232:235], v201 offset:9280
	s_waitcnt lgkmcnt(4)
	v_mfma_f32_16x16x32_bf16 v[48:51], v[236:239], v[16:19], 0
	v_mfma_f32_16x16x32_bf16 v[48:51], v[252:255], v[20:23], v[48:51]
	ds_read_b128 v[236:239], v201 offset:11520
	ds_read_b128 v[252:255], v201 offset:11584
	s_waitcnt lgkmcnt(4)
	v_mfma_f32_16x16x32_bf16 v[52:55], v[220:223], v[16:19], 0
	v_mfma_f32_16x16x32_bf16 v[52:55], v[224:227], v[20:23], v[52:55]
	ds_read_b128 v[220:223], v201 offset:13824
	ds_read_b128 v[224:227], v201 offset:13888
	s_waitcnt lgkmcnt(4)
	v_mfma_f32_16x16x32_bf16 v[56:59], v[228:231], v[16:19], 0
	v_mfma_f32_16x16x32_bf16 v[56:59], v[232:235], v[20:23], v[56:59]
	ds_read_b128 v[228:231], v201 offset:16128
	ds_read_b128 v[232:235], v201 offset:16192
	s_waitcnt lgkmcnt(4)
	v_mfma_f32_16x16x32_bf16 v[60:63], v[236:239], v[16:19], 0
	v_mfma_f32_16x16x32_bf16 v[60:63], v[252:255], v[20:23], v[60:63]
	s_waitcnt lgkmcnt(2)
	v_mfma_f32_16x16x32_bf16 v[64:67], v[220:223], v[16:19], 0
	v_mfma_f32_16x16x32_bf16 v[64:67], v[224:227], v[20:23], v[64:67]
	s_waitcnt lgkmcnt(0)
	v_mfma_f32_16x16x32_bf16 v[68:71], v[228:231], v[16:19], 0
	v_mfma_f32_16x16x32_bf16 v[68:71], v[232:235], v[20:23], v[68:71]
	s_nop 7
	v_max3_f32 v200, v40, v41, s68
	v_max3_f32 v202, v42, v43, s68
	v_max3_f32 v200, v200, v44, v45
	v_max3_f32 v202, v202, v46, v47
	v_max3_f32 v200, v200, v48, v49
	v_max3_f32 v202, v202, v50, v51
	v_max3_f32 v200, v200, v52, v53
	v_max3_f32 v202, v202, v54, v55
	v_max3_f32 v200, v200, v56, v57
	v_max3_f32 v202, v202, v58, v59
	v_max3_f32 v200, v200, v60, v61
	v_max3_f32 v202, v202, v62, v63
	v_max3_f32 v200, v200, v64, v65
	v_max3_f32 v202, v202, v66, v67
	v_max3_f32 v200, v200, v68, v69
	v_max3_f32 v202, v202, v70, v71
	v_max_f32_e32 v200, v200, v202
	v_max_f32_e32 v151, v200, v200
	v_mov_b32_e32 v72, v151
	s_waitcnt lgkmcnt(0)
	s_nop 1
	v_permlane16_swap_b32_e32 v72, v151
	v_max_f32_e32 v72, v151, v72
	v_mov_b32_e32 v151, v72
	s_nop 1
	v_permlane32_swap_b32_e32 v151, v72
	v_max3_f32 v151, v153, v72, v151
	v_sub_f32_e32 v72, v153, v151
	v_exp_f32_e32 v72, v72
	v_sub_f32_e32 v40, v40, v151
	v_sub_f32_e32 v41, v41, v151
	v_sub_f32_e32 v42, v42, v151
	v_sub_f32_e32 v43, v43, v151
	v_sub_f32_e32 v44, v44, v151
	v_sub_f32_e32 v45, v45, v151
	v_sub_f32_e32 v46, v46, v151
	v_sub_f32_e32 v47, v47, v151
	v_sub_f32_e32 v48, v48, v151
	v_sub_f32_e32 v49, v49, v151
	v_sub_f32_e32 v50, v50, v151
	v_sub_f32_e32 v51, v51, v151
	v_sub_f32_e32 v52, v52, v151
	v_sub_f32_e32 v53, v53, v151
	v_sub_f32_e32 v54, v54, v151
	v_sub_f32_e32 v55, v55, v151
	v_sub_f32_e32 v56, v56, v151
	v_sub_f32_e32 v57, v57, v151
	v_sub_f32_e32 v58, v58, v151
	v_sub_f32_e32 v59, v59, v151
	v_sub_f32_e32 v60, v60, v151
	v_sub_f32_e32 v61, v61, v151
	v_sub_f32_e32 v62, v62, v151
	v_sub_f32_e32 v63, v63, v151
	v_sub_f32_e32 v64, v64, v151
	v_sub_f32_e32 v65, v65, v151
	v_sub_f32_e32 v66, v66, v151
	v_sub_f32_e32 v67, v67, v151
	v_sub_f32_e32 v68, v68, v151
	v_sub_f32_e32 v69, v69, v151
	v_sub_f32_e32 v70, v70, v151
	v_sub_f32_e32 v71, v71, v151
	v_mul_f32_e32 v149, v149, v72
	v_exp_f32_e32 v40, v40
	v_exp_f32_e32 v41, v41
	v_exp_f32_e32 v42, v42
	v_exp_f32_e32 v43, v43
	v_exp_f32_e32 v44, v44
	v_exp_f32_e32 v45, v45
	v_exp_f32_e32 v46, v46
	v_exp_f32_e32 v47, v47
	v_exp_f32_e32 v48, v48
	v_exp_f32_e32 v49, v49
	v_exp_f32_e32 v50, v50
	v_exp_f32_e32 v51, v51
	v_exp_f32_e32 v52, v52
	v_exp_f32_e32 v53, v53
	v_exp_f32_e32 v54, v54
	v_exp_f32_e32 v55, v55
	v_exp_f32_e32 v56, v56
	v_exp_f32_e32 v57, v57
	v_exp_f32_e32 v58, v58
	v_exp_f32_e32 v59, v59
	v_exp_f32_e32 v60, v60
	v_exp_f32_e32 v61, v61
	v_exp_f32_e32 v62, v62
	v_exp_f32_e32 v63, v63
	v_exp_f32_e32 v64, v64
	v_exp_f32_e32 v65, v65
	v_exp_f32_e32 v66, v66
	v_exp_f32_e32 v67, v67
	v_exp_f32_e32 v68, v68
	v_exp_f32_e32 v69, v69
	v_exp_f32_e32 v70, v70
	v_exp_f32_e32 v71, v71
	v_mul_f32_e64 v38, v38, v72
	v_mul_f32_e64 v39, v39, v72
	v_mul_f32_e64 v36, v36, v72
	v_mul_f32_e64 v37, v37, v72
	v_mul_f32_e64 v34, v34, v72
	v_mul_f32_e64 v35, v35, v72
	v_mul_f32_e64 v32, v32, v72
	v_mul_f32_e64 v33, v33, v72
	v_mul_f32_e64 v30, v30, v72
	v_mul_f32_e64 v31, v31, v72
	v_mul_f32_e64 v28, v28, v72
	v_mul_f32_e64 v29, v29, v72
	v_mul_f32_e64 v26, v26, v72
	v_mul_f32_e64 v27, v27, v72
	v_mul_f32_e64 v24, v24, v72
	v_mul_f32_e64 v25, v25, v72
	v_lshl_add_u32 v241, v160, 1, s38
	v_add_u32_e32 v241, v241, v162
	ds_read_b64_tr_b16 v[220:221], v241
	ds_read_b64_tr_b16 v[222:223], v241 offset:2304
	ds_read_b64_tr_b16 v[224:225], v241 offset:32
	ds_read_b64_tr_b16 v[226:227], v241 offset:2336
	ds_read_b64_tr_b16 v[228:229], v241 offset:64
	ds_read_b64_tr_b16 v[230:231], v241 offset:2368
	ds_read_b64_tr_b16 v[232:233], v241 offset:96
	ds_read_b64_tr_b16 v[234:235], v241 offset:2400
	ds_read_b64_tr_b16 v[236:237], v241 offset:4608
	ds_read_b64_tr_b16 v[238:239], v241 offset:6912
	ds_read_b64_tr_b16 v[252:253], v241 offset:4640
	ds_read_b64_tr_b16 v[254:255], v241 offset:6944
	v_add_f32_e32 v149, v40, v149
	v_add_f32_e32 v149, v41, v149
	v_add_f32_e32 v149, v42, v149
	v_add_f32_e32 v149, v43, v149
	v_add_f32_e32 v149, v44, v149
	v_add_f32_e32 v149, v45, v149
	v_add_f32_e32 v149, v46, v149
	v_add_f32_e32 v149, v47, v149
	v_add_f32_e32 v149, v48, v149
	v_add_f32_e32 v149, v49, v149
	v_add_f32_e32 v149, v50, v149
	v_add_f32_e32 v149, v51, v149
	v_add_f32_e32 v149, v52, v149
	v_add_f32_e32 v149, v53, v149
	v_add_f32_e32 v149, v54, v149
	v_add_f32_e32 v149, v55, v149
	v_add_f32_e32 v149, v56, v149
	v_add_f32_e32 v149, v57, v149
	v_add_f32_e32 v149, v58, v149
	v_add_f32_e32 v149, v59, v149
	v_add_f32_e32 v149, v60, v149
	v_add_f32_e32 v149, v61, v149
	v_add_f32_e32 v149, v62, v149
	v_add_f32_e32 v149, v63, v149
	v_add_f32_e32 v149, v64, v149
	v_add_f32_e32 v149, v65, v149
	v_add_f32_e32 v149, v66, v149
	v_add_f32_e32 v149, v67, v149
	v_add_f32_e32 v149, v68, v149
	v_add_f32_e32 v149, v69, v149
	v_add_f32_e32 v149, v70, v149
	v_add_f32_e32 v149, v71, v149
	v_cvt_pk_bf16_f32 v40, v40, v41
	v_cvt_pk_bf16_f32 v41, v42, v43
	v_cvt_pk_bf16_f32 v42, v44, v45
	v_cvt_pk_bf16_f32 v43, v46, v47
	v_cvt_pk_bf16_f32 v48, v48, v49
	v_cvt_pk_bf16_f32 v49, v50, v51
	v_cvt_pk_bf16_f32 v50, v52, v53
	v_cvt_pk_bf16_f32 v51, v54, v55
	v_cvt_pk_bf16_f32 v56, v56, v57
	v_cvt_pk_bf16_f32 v57, v58, v59
	v_cvt_pk_bf16_f32 v58, v60, v61
	v_cvt_pk_bf16_f32 v59, v62, v63
	v_cvt_pk_bf16_f32 v64, v64, v65
	v_cvt_pk_bf16_f32 v65, v66, v67
	v_cvt_pk_bf16_f32 v66, v68, v69
	v_cvt_pk_bf16_f32 v67, v70, v71
	s_nop 1
	s_waitcnt lgkmcnt(10)
	v_mfma_f32_16x16x32_bf16 v[36:39], v[220:223], v[40:43], v[36:39]
	ds_read_b64_tr_b16 v[220:221], v241 offset:4672
	ds_read_b64_tr_b16 v[222:223], v241 offset:6976
	s_waitcnt lgkmcnt(10)
	v_mfma_f32_16x16x32_bf16 v[32:35], v[224:227], v[40:43], v[32:35]
	ds_read_b64_tr_b16 v[224:225], v241 offset:4704
	ds_read_b64_tr_b16 v[226:227], v241 offset:7008
	s_waitcnt lgkmcnt(10)
	v_mfma_f32_16x16x32_bf16 v[28:31], v[228:231], v[40:43], v[28:31]
	ds_read_b64_tr_b16 v[228:229], v241 offset:9216
	ds_read_b64_tr_b16 v[230:231], v241 offset:11520
	s_waitcnt lgkmcnt(10)
	v_mfma_f32_16x16x32_bf16 v[24:27], v[232:235], v[40:43], v[24:27]
	ds_read_b64_tr_b16 v[232:233], v241 offset:9248
	ds_read_b64_tr_b16 v[234:235], v241 offset:11552
	s_waitcnt lgkmcnt(10)
	v_mfma_f32_16x16x32_bf16 v[36:39], v[236:239], v[48:51], v[36:39]
	ds_read_b64_tr_b16 v[236:237], v241 offset:9280
	ds_read_b64_tr_b16 v[238:239], v241 offset:11584
	s_waitcnt lgkmcnt(10)
	v_mfma_f32_16x16x32_bf16 v[32:35], v[252:255], v[48:51], v[32:35]
	ds_read_b64_tr_b16 v[252:253], v241 offset:9312
	ds_read_b64_tr_b16 v[254:255], v241 offset:11616
	s_waitcnt lgkmcnt(10)
	v_mfma_f32_16x16x32_bf16 v[28:31], v[220:223], v[48:51], v[28:31]
	ds_read_b64_tr_b16 v[220:221], v241 offset:13824
	ds_read_b64_tr_b16 v[222:223], v241 offset:16128
	s_waitcnt lgkmcnt(10)
	v_mfma_f32_16x16x32_bf16 v[24:27], v[224:227], v[48:51], v[24:27]
	ds_read_b64_tr_b16 v[224:225], v241 offset:13856
	ds_read_b64_tr_b16 v[226:227], v241 offset:16160
	s_waitcnt lgkmcnt(10)
	v_mfma_f32_16x16x32_bf16 v[36:39], v[228:231], v[56:59], v[36:39]
	ds_read_b64_tr_b16 v[228:229], v241 offset:13888
	ds_read_b64_tr_b16 v[230:231], v241 offset:16192
	s_waitcnt lgkmcnt(10)
	v_mfma_f32_16x16x32_bf16 v[32:35], v[232:235], v[56:59], v[32:35]
	ds_read_b64_tr_b16 v[232:233], v241 offset:13920
	ds_read_b64_tr_b16 v[234:235], v241 offset:16224
	s_waitcnt lgkmcnt(10)
	v_mfma_f32_16x16x32_bf16 v[28:31], v[236:239], v[56:59], v[28:31]
	s_waitcnt lgkmcnt(8)
	v_mfma_f32_16x16x32_bf16 v[24:27], v[252:255], v[56:59], v[24:27]
	s_waitcnt lgkmcnt(6)
	v_mfma_f32_16x16x32_bf16 v[36:39], v[220:223], v[64:67], v[36:39]
	s_waitcnt lgkmcnt(4)
	v_mfma_f32_16x16x32_bf16 v[32:35], v[224:227], v[64:67], v[32:35]
	s_waitcnt lgkmcnt(2)
	v_mfma_f32_16x16x32_bf16 v[28:31], v[228:231], v[64:67], v[28:31]
	s_waitcnt lgkmcnt(0)
	v_mfma_f32_16x16x32_bf16 v[24:27], v[232:235], v[64:67], v[24:27]
	s_nop 7
	s_branch .LBB0_1170

.LBB0_2085:
	ds_read_b128 v[136:139], v119 offset:6144
	ds_read_b128 v[140:143], v119 offset:6160
	s_waitcnt vmcnt(5)
	v_lshlrev_b32_e32 v144, 16, v54
	v_and_b32_e32 v145, 0xffff0000, v54
	s_add_i32 s24, s25, s24
	s_waitcnt lgkmcnt(1)
	v_mul_f32_e32 v136, 0xbfb8aa3b, v136
	v_mul_f32_e32 v137, 0xbfb8aa3b, v137
	v_exp_f32_e32 v136, v136
	v_exp_f32_e32 v137, v137
	v_mul_f32_e32 v54, 0xbfb8aa3b, v138
	v_exp_f32_e32 v138, v54
	v_mul_f32_e32 v54, 0xbfb8aa3b, v139
	v_exp_f32_e32 v139, v54
	v_mul_f32_e64 v136, v136, v144
	v_mul_f32_e64 v137, v137, v145
	s_add_i32 s57, s57, 1
	v_cvt_pk_bf16_f32 v54, v136, v137
	v_lshlrev_b32_e32 v136, 16, v55
	v_and_b32_e32 v137, 0xffff0000, v55
	s_waitcnt lgkmcnt(0)
	v_mul_f32_e32 v55, 0xbfb8aa3b, v140
	v_mul_f32_e64 v136, v138, v136
	v_mul_f32_e64 v137, v139, v137
	v_exp_f32_e32 v138, v55
	v_mul_f32_e32 v55, 0xbfb8aa3b, v141
	v_exp_f32_e32 v139, v55
	v_cvt_pk_bf16_f32 v55, v136, v137
	v_lshlrev_b32_e32 v136, 16, v56
	v_and_b32_e32 v137, 0xffff0000, v56
	v_mul_f32_e32 v56, 0xbfb8aa3b, v142
	v_mul_f32_e64 v136, v138, v136
	v_mul_f32_e64 v137, v139, v137
	v_exp_f32_e32 v138, v56
	v_mul_f32_e32 v56, 0xbfb8aa3b, v143
	v_exp_f32_e32 v139, v56
	v_cvt_pk_bf16_f32 v56, v136, v137
	v_lshlrev_b32_e32 v136, 16, v57
	v_and_b32_e32 v137, 0xffff0000, v57
	v_mul_f32_e64 v136, v138, v136
	v_mul_f32_e64 v137, v139, v137
	s_waitcnt vmcnt(4)
	v_lshlrev_b32_e32 v140, 16, v6
	v_cvt_pk_bf16_f32 v57, v136, v137
	ds_write_b128 v120, v[54:57] offset:56320
	ds_read_b128 v[54:57], v121 offset:6144
	ds_read_b128 v[136:139], v121 offset:6160
	v_and_b32_e32 v141, 0xffff0000, v6
	s_mul_i32 s31, s24, 0x1800
	s_mul_hi_i32 s30, s24, 0x1800
	s_waitcnt lgkmcnt(1)
	v_mul_f32_e32 v54, 0xbfb8aa3b, v54
	v_mul_f32_e32 v55, 0xbfb8aa3b, v55
	v_exp_f32_e32 v54, v54
	v_exp_f32_e32 v55, v55
	v_mul_f32_e32 v6, 0xbfb8aa3b, v56
	v_exp_f32_e32 v56, v6
	v_mul_f32_e32 v6, 0xbfb8aa3b, v57
	v_exp_f32_e32 v57, v6
	v_mul_f32_e64 v54, v54, v140
	v_mul_f32_e64 v55, v55, v141
	s_add_u32 s28, s61, s31
	v_cvt_pk_bf16_f32 v6, v54, v55
	v_lshlrev_b32_e32 v54, 16, v7
	v_and_b32_e32 v55, 0xffff0000, v7
	s_waitcnt lgkmcnt(0)
	v_mul_f32_e32 v7, 0xbfb8aa3b, v136
	v_mul_f32_e64 v54, v56, v54
	v_mul_f32_e64 v55, v57, v55
	v_exp_f32_e32 v56, v7
	v_mul_f32_e32 v7, 0xbfb8aa3b, v137
	v_exp_f32_e32 v57, v7
	v_cvt_pk_bf16_f32 v7, v54, v55
	v_lshlrev_b32_e32 v54, 16, v8
	v_and_b32_e32 v55, 0xffff0000, v8
	v_mul_f32_e32 v8, 0xbfb8aa3b, v138
	v_mul_f32_e64 v54, v56, v54
	v_mul_f32_e64 v55, v57, v55
	v_exp_f32_e32 v56, v8
	v_mul_f32_e32 v8, 0xbfb8aa3b, v139
	v_exp_f32_e32 v57, v8
	v_cvt_pk_bf16_f32 v8, v54, v55
	v_lshlrev_b32_e32 v54, 16, v9
	v_and_b32_e32 v55, 0xffff0000, v9
	v_mul_f32_e64 v54, v56, v54
	v_mul_f32_e64 v55, v57, v55
	s_addc_u32 s29, s62, s30
	v_cvt_pk_bf16_f32 v9, v54, v55
	ds_write_b128 v122, v[6:9] offset:56320
	s_waitcnt vmcnt(3)
	ds_write_b128 v123, v[2:5]
	s_waitcnt vmcnt(2)
	ds_write_b128 v124, v[10:13]
	s_waitcnt vmcnt(1)
	ds_write_b128 v123, v[14:17] offset:16896
	s_waitcnt vmcnt(0)
	ds_write_b128 v125, v[18:21]
	v_lshl_add_u64 v[2:3], s[28:29], 0, v[96:97]
	s_add_u32 s28, s20, s31
	s_addc_u32 s29, s21, s30
	s_add_u32 s28, s28, s56
	s_addc_u32 s29, s29, 0
	s_add_u32 s28, s28, 0xad20800
	v_add_co_u32_e32 v4, vcc, s42, v2
	s_addc_u32 s29, s29, 0
	s_nop 0
	v_addc_co_u32_e32 v5, vcc, 0, v3, vcc
	v_lshl_add_u64 v[14:15], s[28:29], 0, v[98:99]
	v_add_co_u32_e32 v10, vcc, s43, v14
	global_load_dwordx4 v[54:57], v[2:3], off offset:1024
	global_load_dwordx4 v[6:9], v[4:5], off offset:1024
	v_addc_co_u32_e32 v11, vcc, 0, v15, vcc
	v_add_co_u32_e32 v16, vcc, s42, v14
	global_load_dwordx4 v[2:5], v[14:15], off
	s_nop 0
	global_load_dwordx4 v[10:13], v[10:11], off
	v_addc_co_u32_e32 v17, vcc, 0, v15, vcc
	v_add_co_u32_e32 v18, vcc, s44, v14
	s_cmp_eq_u32 s23, s57
	s_nop 0
	v_addc_co_u32_e32 v19, vcc, 0, v15, vcc
	global_load_dwordx4 v[14:17], v[16:17], off
	s_nop 0
	global_load_dwordx4 v[18:21], v[18:19], off
	s_waitcnt lgkmcnt(0)
	s_barrier
	ds_read_b64_tr_b16 v[138:139], v127 offset:57408
	ds_read_b64_tr_b16 v[136:137], v127 offset:56320
	ds_read_b64_tr_b16 v[142:143], v126 offset:2112
	ds_read_b64_tr_b16 v[140:141], v126
	ds_read_b64_tr_b16 v[146:147], v126 offset:2144
	ds_read_b64_tr_b16 v[144:145], v126 offset:32
	ds_read_b64_tr_b16 v[148:149], v127 offset:56352
	ds_read_b64_tr_b16 v[156:157], v127 offset:56384
	ds_read_b64_tr_b16 v[160:161], v127 offset:56416
	ds_read_b64_tr_b16 v[150:151], v127 offset:57440
	ds_read_b64_tr_b16 v[158:159], v127 offset:57472
	ds_read_b64_tr_b16 v[162:163], v127 offset:57504
	ds_read_b64_tr_b16 v[164:165], v127 offset:65024
	ds_read_b64_tr_b16 v[166:167], v128 offset:57408
	ds_read_b64_tr_b16 v[168:169], v126 offset:16896
	ds_read_b64_tr_b16 v[170:171], v126 offset:19008
	ds_read_b64_tr_b16 v[174:175], v126 offset:19040
	ds_read_b64_tr_b16 v[172:173], v126 offset:16928
	s_waitcnt lgkmcnt(8)
	v_mfma_f32_16x16x32_bf16 v[58:61], v[148:151], v[140:143], v[58:61]
	v_mfma_f32_16x16x32_bf16 v[78:81], v[148:151], v[144:147], v[78:81]
	v_mfma_f32_16x16x32_bf16 v[66:69], v[136:139], v[140:143], v[66:69]
	v_mfma_f32_16x16x32_bf16 v[62:65], v[136:139], v[144:147], v[62:65]
	ds_read_b64_tr_b16 v[136:137], v127 offset:65056
	ds_read_b64_tr_b16 v[176:177], v127 offset:65088
	ds_read_b64_tr_b16 v[180:181], v127 offset:65120
	ds_read_b64_tr_b16 v[138:139], v128 offset:57440
	ds_read_b64_tr_b16 v[178:179], v128 offset:57472
	ds_read_b64_tr_b16 v[182:183], v128 offset:57504
	s_waitcnt lgkmcnt(2)
	v_mfma_f32_16x16x32_bf16 v[58:61], v[136:139], v[168:171], v[58:61]
	v_mfma_f32_16x16x32_bf16 v[78:81], v[136:139], v[172:175], v[78:81]
	ds_read_b64_tr_b16 v[136:137], v127 offset:56448
	ds_read_b64_tr_b16 v[138:139], v127 offset:57536
	v_mfma_f32_16x16x32_bf16 v[74:77], v[156:159], v[140:143], v[74:77]
	v_mfma_f32_16x16x32_bf16 v[70:73], v[156:159], v[144:147], v[70:73]
	v_mfma_f32_16x16x32_bf16 v[82:85], v[160:163], v[140:143], v[82:85]
	v_mfma_f32_16x16x32_bf16 v[86:89], v[160:163], v[144:147], v[86:89]
	ds_read_b64_tr_b16 v[148:149], v127 offset:56480
	ds_read_b64_tr_b16 v[156:157], v127 offset:56512
	ds_read_b64_tr_b16 v[160:161], v127 offset:56544
	ds_read_b64_tr_b16 v[150:151], v127 offset:57568
	ds_read_b64_tr_b16 v[158:159], v127 offset:57600
	ds_read_b64_tr_b16 v[162:163], v127 offset:57632
	s_waitcnt lgkmcnt(2)
	v_mfma_f32_16x16x32_bf16 v[22:25], v[148:151], v[140:143], v[22:25]
	v_mfma_f32_16x16x32_bf16 v[50:53], v[148:151], v[144:147], v[50:53]
	v_lshl_add_u32 v150, s63, 9, v111
	v_mfma_f32_16x16x32_bf16 v[66:69], v[164:167], v[168:171], v[66:69]
	v_mfma_f32_16x16x32_bf16 v[62:65], v[164:167], v[172:175], v[62:65]
	ds_read_b64_tr_b16 v[164:165], v127 offset:65152
	ds_read_b64_tr_b16 v[166:167], v128 offset:57536
	v_mfma_f32_16x16x32_bf16 v[74:77], v[176:179], v[168:171], v[74:77]
	v_mfma_f32_16x16x32_bf16 v[70:73], v[176:179], v[172:175], v[70:73]
	v_mfma_f32_16x16x32_bf16 v[82:85], v[180:183], v[168:171], v[82:85]
	v_mfma_f32_16x16x32_bf16 v[86:89], v[180:183], v[172:175], v[86:89]
	v_mfma_f32_16x16x32_bf16 v[30:33], v[136:139], v[140:143], v[30:33]
	v_mfma_f32_16x16x32_bf16 v[26:29], v[136:139], v[144:147], v[26:29]
	ds_read_b64_tr_b16 v[136:137], v127 offset:65184
	ds_read_b64_tr_b16 v[176:177], v127 offset:65216
	ds_read_b64_tr_b16 v[180:181], v127 offset:65248
	ds_read_b64_tr_b16 v[138:139], v128 offset:57568
	ds_read_b64_tr_b16 v[178:179], v128 offset:57600
	ds_read_b64_tr_b16 v[182:183], v128 offset:57632
	s_waitcnt lgkmcnt(2)
	v_mfma_f32_16x16x32_bf16 v[22:25], v[136:139], v[168:171], v[22:25]
	v_mfma_f32_16x16x32_bf16 v[50:53], v[136:139], v[172:175], v[50:53]
	ds_read_b128 v[136:139], v150 offset:4096
	v_mfma_f32_16x16x32_bf16 v[34:37], v[156:159], v[140:143], v[34:37]
	v_mfma_f32_16x16x32_bf16 v[38:41], v[160:163], v[140:143], v[38:41]
	ds_read_b128 v[140:143], v150 offset:4160
	s_waitcnt lgkmcnt(1)
	s_nop 0
	v_mfma_f32_16x16x32_bf16 v[46:49], v[156:159], v[144:147], v[46:49]
	v_mfma_f32_16x16x32_bf16 v[42:45], v[160:163], v[144:147], v[42:45]
	v_mov_b32_e32 v144, v136
	v_mov_b32_e32 v145, v137
	v_mov_b32_e32 v136, v138
	v_mov_b32_e32 v137, v139
	s_nop 0
	s_nop 0
	s_nop 0
	v_mfma_f32_16x16x32_bf16 v[30:33], v[164:167], v[168:171], v[30:33]
	v_mul_f32_e64 v68, v68, v136
	v_mul_f32_e64 v69, v69, v137
	v_mul_f32_e64 v64, v64, v136
	v_mul_f32_e64 v65, v65, v137
	s_waitcnt lgkmcnt(0)
	v_mov_b32_e32 v136, v140
	v_mov_b32_e32 v137, v142
	v_mov_b32_e32 v146, v136
	v_mov_b32_e32 v136, v141
	v_mov_b32_e32 v148, v137
	s_nop 0
	v_mov_b32_e32 v149, v143
	v_mov_b32_e32 v147, v136
	ds_read_b128 v[136:139], v150 offset:4224
	ds_read_b128 v[140:143], v150 offset:4288
	v_mul_f32_e64 v66, v66, v144
	v_mul_f32_e64 v67, v67, v145
	v_mul_f32_e64 v62, v62, v144
	v_mul_f32_e64 v63, v63, v145
	v_mul_f32_e64 v60, v60, v148
	v_mul_f32_e64 v61, v61, v149
	s_waitcnt lgkmcnt(1)
	s_nop 0
	v_mov_b32_e32 v144, v136
	v_mov_b32_e32 v145, v137
	v_mov_b32_e32 v136, v138
	v_mov_b32_e32 v137, v139
	s_nop 0
	s_nop 0
	v_mul_f32_e64 v58, v58, v146
	v_mul_f32_e64 v59, v59, v147
	v_mul_f32_e64 v80, v80, v148
	v_mul_f32_e64 v81, v81, v149
	v_mul_f32_e64 v78, v78, v146
	v_mul_f32_e64 v79, v79, v147
	v_mul_f32_e64 v76, v76, v136
	v_mul_f32_e64 v77, v77, v137
	v_mul_f32_e64 v72, v72, v136
	v_mul_f32_e64 v73, v73, v137
	s_waitcnt lgkmcnt(0)
	v_mov_b32_e32 v136, v140
	v_mov_b32_e32 v137, v142
	v_mov_b32_e32 v146, v136
	v_mov_b32_e32 v136, v141
	v_mov_b32_e32 v148, v137
	s_nop 0
	v_mov_b32_e32 v149, v143
	v_mov_b32_e32 v147, v136
	ds_read_b128 v[136:139], v150 offset:4352
	ds_read_b128 v[140:143], v150 offset:4416
	s_nop 0
	v_mfma_f32_16x16x32_bf16 v[26:29], v[164:167], v[172:175], v[26:29]
	v_mul_f32_e64 v84, v84, v148
	v_mul_f32_e64 v85, v85, v149
	s_waitcnt lgkmcnt(1)
	s_nop 0
	v_mul_f32_e64 v74, v74, v144
	v_mul_f32_e64 v75, v75, v145
	v_mul_f32_e64 v70, v70, v144
	v_mul_f32_e64 v71, v71, v145
	v_mov_b32_e32 v144, v136
	v_mov_b32_e32 v145, v137
	v_mov_b32_e32 v136, v138
	v_mov_b32_e32 v137, v139
	s_nop 0
	s_nop 0
	v_mul_f32_e64 v82, v82, v146
	v_mul_f32_e64 v83, v83, v147
	v_mul_f32_e64 v88, v88, v148
	v_mul_f32_e64 v89, v89, v149
	v_mul_f32_e64 v86, v86, v146
	v_mul_f32_e64 v87, v87, v147
	v_mul_f32_e64 v32, v32, v136
	v_mul_f32_e64 v33, v33, v137
	v_mul_f32_e64 v28, v28, v136
	v_mul_f32_e64 v29, v29, v137
	s_waitcnt lgkmcnt(0)
	v_mov_b32_e32 v136, v140
	v_mov_b32_e32 v137, v142
	v_mov_b32_e32 v146, v136
	v_mov_b32_e32 v136, v141
	v_mov_b32_e32 v148, v137
	s_nop 0
	v_mov_b32_e32 v149, v143
	v_mov_b32_e32 v147, v136
	ds_read_b128 v[136:139], v150 offset:4480
	ds_read_b128 v[140:143], v150 offset:4544
	v_mfma_f32_16x16x32_bf16 v[34:37], v[176:179], v[168:171], v[34:37]
	s_nop 0
	v_mul_f32_e64 v24, v24, v148
	v_mul_f32_e64 v25, v25, v149
	s_waitcnt lgkmcnt(1)
	s_nop 0
	s_nop 0
	s_nop 0
	s_nop 0
	s_waitcnt lgkmcnt(0)
	s_nop 0
	s_nop 0
	s_nop 0
	s_nop 0
	v_mfma_f32_16x16x32_bf16 v[46:49], v[176:179], v[172:175], v[46:49]
	s_nop 0
	s_nop 0
	s_nop 0
	v_mfma_f32_16x16x32_bf16 v[38:41], v[180:183], v[168:171], v[38:41]
	s_nop 0
	s_nop 0
	s_nop 0
	v_mfma_f32_16x16x32_bf16 v[42:45], v[180:183], v[172:175], v[42:45]
	s_nop 0
	s_nop 0
	v_mul_f32_e64 v30, v30, v144
	v_mul_f32_e64 v31, v31, v145
	v_mul_f32_e64 v26, v26, v144
	v_mul_f32_e64 v27, v27, v145
	v_mul_f32_e64 v22, v22, v146
	v_mul_f32_e64 v23, v23, v147
	v_mul_f32_e64 v52, v52, v148
	v_mul_f32_e64 v53, v53, v149
	v_mul_f32_e64 v50, v50, v146
	v_mul_f32_e64 v51, v51, v147
	v_mul_f32_e64 v36, v36, v138
	v_mul_f32_e64 v37, v37, v139
	v_mul_f32_e64 v34, v34, v136
	v_mul_f32_e64 v35, v35, v137
	v_mul_f32_e64 v48, v48, v138
	v_mul_f32_e64 v49, v49, v139
	v_mul_f32_e64 v46, v46, v136
	v_mul_f32_e64 v47, v47, v137
	v_mul_f32_e64 v40, v40, v142
	v_mul_f32_e64 v41, v41, v143
	v_mul_f32_e64 v38, v38, v140
	v_mul_f32_e64 v39, v39, v141
	v_mul_f32_e64 v44, v44, v142
	v_mul_f32_e64 v45, v45, v143
	v_mul_f32_e64 v42, v42, v140
	v_mul_f32_e64 v43, v43, v141
	s_cbranch_scc1 .LBB0_2101

.LBB0_2111:
	s_or_b64 exec, exec, s[14:15]
	ds_read_b128 v[90:93], v119 offset:6144
	ds_read_b128 v[130:133], v119 offset:6160
	s_waitcnt vmcnt(5)
	v_lshlrev_b32_e32 v134, 16, v54
	v_and_b32_e32 v135, 0xffff0000, v54
	s_waitcnt lgkmcnt(1)
	v_mul_f32_e32 v90, 0xbfb8aa3b, v90
	v_mul_f32_e32 v91, 0xbfb8aa3b, v91
	v_exp_f32_e32 v90, v90
	v_exp_f32_e32 v91, v91
	v_mul_f32_e32 v54, 0xbfb8aa3b, v92
	v_exp_f32_e32 v92, v54
	v_mul_f32_e32 v54, 0xbfb8aa3b, v93
	v_exp_f32_e32 v93, v54
	v_mul_f32_e64 v90, v90, v134
	v_mul_f32_e64 v91, v91, v135
	s_nop 0
	v_cvt_pk_bf16_f32 v54, v90, v91
	v_lshlrev_b32_e32 v90, 16, v55
	v_and_b32_e32 v91, 0xffff0000, v55
	s_waitcnt lgkmcnt(0)
	v_mul_f32_e32 v55, 0xbfb8aa3b, v130
	v_mul_f32_e64 v90, v92, v90
	v_mul_f32_e64 v91, v93, v91
	v_exp_f32_e32 v92, v55
	v_mul_f32_e32 v55, 0xbfb8aa3b, v131
	v_exp_f32_e32 v93, v55
	v_cvt_pk_bf16_f32 v55, v90, v91
	v_lshlrev_b32_e32 v90, 16, v56
	v_and_b32_e32 v91, 0xffff0000, v56
	v_mul_f32_e32 v56, 0xbfb8aa3b, v132
	v_mul_f32_e64 v90, v92, v90
	v_mul_f32_e64 v91, v93, v91
	v_exp_f32_e32 v92, v56
	v_mul_f32_e32 v56, 0xbfb8aa3b, v133
	v_exp_f32_e32 v93, v56
	v_cvt_pk_bf16_f32 v56, v90, v91
	v_lshlrev_b32_e32 v90, 16, v57
	v_and_b32_e32 v91, 0xffff0000, v57
	v_mul_f32_e64 v90, v92, v90
	v_mul_f32_e64 v91, v93, v91
	s_waitcnt vmcnt(4)
	v_lshlrev_b32_e32 v130, 16, v6
	v_cvt_pk_bf16_f32 v57, v90, v91
	ds_write_b128 v120, v[54:57] offset:56320
	ds_read_b128 v[54:57], v121 offset:6144
	ds_read_b128 v[90:93], v121 offset:6160
	v_and_b32_e32 v131, 0xffff0000, v6
	s_waitcnt lgkmcnt(1)
	v_mul_f32_e32 v54, 0xbfb8aa3b, v54
	v_mul_f32_e32 v55, 0xbfb8aa3b, v55
	v_exp_f32_e32 v54, v54
	v_exp_f32_e32 v55, v55
	v_mul_f32_e32 v6, 0xbfb8aa3b, v56
	v_exp_f32_e32 v56, v6
	v_mul_f32_e32 v6, 0xbfb8aa3b, v57
	v_exp_f32_e32 v57, v6
	v_mul_f32_e64 v54, v54, v130
	v_mul_f32_e64 v55, v55, v131
	s_nop 0
	v_cvt_pk_bf16_f32 v6, v54, v55
	v_lshlrev_b32_e32 v54, 16, v7
	v_and_b32_e32 v55, 0xffff0000, v7
	s_waitcnt lgkmcnt(0)
	v_mul_f32_e32 v7, 0xbfb8aa3b, v90
	v_mul_f32_e64 v54, v56, v54
	v_mul_f32_e64 v55, v57, v55
	v_exp_f32_e32 v56, v7
	v_mul_f32_e32 v7, 0xbfb8aa3b, v91
	v_exp_f32_e32 v57, v7
	v_cvt_pk_bf16_f32 v7, v54, v55
	v_lshlrev_b32_e32 v54, 16, v8
	v_and_b32_e32 v55, 0xffff0000, v8
	v_mul_f32_e32 v8, 0xbfb8aa3b, v92
	v_mul_f32_e64 v54, v56, v54
	v_mul_f32_e64 v55, v57, v55
	v_exp_f32_e32 v56, v8
	v_mul_f32_e32 v8, 0xbfb8aa3b, v93
	v_exp_f32_e32 v57, v8
	v_cvt_pk_bf16_f32 v8, v54, v55
	v_lshlrev_b32_e32 v54, 16, v9
	v_and_b32_e32 v55, 0xffff0000, v9
	v_mul_f32_e64 v54, v56, v54
	v_mul_f32_e64 v55, v57, v55
	s_nop 0
	v_cvt_pk_bf16_f32 v9, v54, v55
	ds_write_b128 v122, v[6:9] offset:56320
	s_waitcnt vmcnt(3)
	ds_write_b128 v123, v[2:5]
	s_waitcnt vmcnt(2)
	ds_write_b128 v124, v[10:13]
	s_waitcnt vmcnt(1)
	ds_write_b128 v123, v[14:17] offset:16896
	s_waitcnt vmcnt(0)
	ds_write_b128 v125, v[18:21]
	s_waitcnt lgkmcnt(0)
	s_barrier
	ds_read_b64_tr_b16 v[4:5], v127 offset:57408
	ds_read_b64_tr_b16 v[2:3], v127 offset:56320
	ds_read_b64_tr_b16 v[8:9], v126 offset:2112
	ds_read_b64_tr_b16 v[6:7], v126
	ds_read_b64_tr_b16 v[12:13], v126 offset:2144
	ds_read_b64_tr_b16 v[10:11], v126 offset:32
	ds_read_b64_tr_b16 v[14:15], v127 offset:56352
	ds_read_b64_tr_b16 v[18:19], v127 offset:56384
	ds_read_b64_tr_b16 v[54:55], v127 offset:56416
	ds_read_b64_tr_b16 v[16:17], v127 offset:57440
	ds_read_b64_tr_b16 v[20:21], v127 offset:57472
	ds_read_b64_tr_b16 v[56:57], v127 offset:57504
	ds_read_b64_tr_b16 v[90:91], v127 offset:65024
	ds_read_b64_tr_b16 v[92:93], v128 offset:57408
	ds_read_b64_tr_b16 v[130:131], v126 offset:16896
	ds_read_b64_tr_b16 v[132:133], v126 offset:19008
	ds_read_b64_tr_b16 v[136:137], v126 offset:19040
	ds_read_b64_tr_b16 v[134:135], v126 offset:16928
	s_waitcnt lgkmcnt(8)
	v_mfma_f32_16x16x32_bf16 v[58:61], v[14:17], v[6:9], v[58:61]
	v_mfma_f32_16x16x32_bf16 v[14:17], v[14:17], v[10:13], v[78:81]
	v_mfma_f32_16x16x32_bf16 v[66:69], v[2:5], v[6:9], v[66:69]
	v_mfma_f32_16x16x32_bf16 v[2:5], v[2:5], v[10:13], v[62:65]
	s_nop 2
	ds_read_b64_tr_b16 v[62:63], v127 offset:65056
	ds_read_b64_tr_b16 v[138:139], v127 offset:65088
	ds_read_b64_tr_b16 v[142:143], v127 offset:65120
	ds_read_b64_tr_b16 v[64:65], v128 offset:57440
	ds_read_b64_tr_b16 v[140:141], v128 offset:57472
	ds_read_b64_tr_b16 v[144:145], v128 offset:57504
	s_waitcnt lgkmcnt(2)
	v_mfma_f32_16x16x32_bf16 v[58:61], v[62:65], v[130:133], v[58:61]
	v_mfma_f32_16x16x32_bf16 v[14:17], v[62:65], v[134:137], v[14:17]
	v_mfma_f32_16x16x32_bf16 v[62:65], v[18:21], v[6:9], v[74:77]
	s_nop 2
	ds_read_b64_tr_b16 v[74:75], v127 offset:56448
	ds_read_b64_tr_b16 v[76:77], v127 offset:57536
	v_mfma_f32_16x16x32_bf16 v[18:21], v[18:21], v[10:13], v[70:73]
	v_mfma_f32_16x16x32_bf16 v[70:73], v[54:57], v[6:9], v[82:85]
	v_mfma_f32_16x16x32_bf16 v[54:57], v[54:57], v[10:13], v[86:89]
	ds_read_b64_tr_b16 v[78:79], v127 offset:56480
	s_nop 0
	ds_read_b64_tr_b16 v[82:83], v127 offset:56512
	ds_read_b64_tr_b16 v[86:87], v127 offset:56544
	ds_read_b64_tr_b16 v[80:81], v127 offset:57568
	ds_read_b64_tr_b16 v[84:85], v127 offset:57600
	ds_read_b64_tr_b16 v[88:89], v127 offset:57632
	s_waitcnt lgkmcnt(1)
	v_mfma_f32_16x16x32_bf16 v[34:37], v[82:85], v[6:9], v[34:37]
	v_mfma_f32_16x16x32_bf16 v[46:49], v[82:85], v[10:13], v[46:49]
	v_add_u32_e32 v82, s23, v111
	s_ashr_i32 s23, s22, 31
	s_lshl_b64 s[14:15], s[22:23], 17
	v_mfma_f32_16x16x32_bf16 v[66:69], v[90:93], v[130:133], v[66:69]
	v_mfma_f32_16x16x32_bf16 v[2:5], v[90:93], v[134:137], v[2:5]
	ds_read_b64_tr_b16 v[90:91], v127 offset:65152
	ds_read_b64_tr_b16 v[92:93], v128 offset:57536
	v_mfma_f32_16x16x32_bf16 v[62:65], v[138:141], v[130:133], v[62:65]
	v_mfma_f32_16x16x32_bf16 v[18:21], v[138:141], v[134:137], v[18:21]
	v_mfma_f32_16x16x32_bf16 v[70:73], v[142:145], v[130:133], v[70:73]
	v_mfma_f32_16x16x32_bf16 v[54:57], v[142:145], v[134:137], v[54:57]
	v_mfma_f32_16x16x32_bf16 v[30:33], v[74:77], v[6:9], v[30:33]
	v_mfma_f32_16x16x32_bf16 v[26:29], v[74:77], v[10:13], v[26:29]
	ds_read_b64_tr_b16 v[74:75], v127 offset:65184
	ds_read_b64_tr_b16 v[138:139], v127 offset:65216
	ds_read_b64_tr_b16 v[142:143], v127 offset:65248
	ds_read_b64_tr_b16 v[76:77], v128 offset:57568
	ds_read_b64_tr_b16 v[140:141], v128 offset:57600
	ds_read_b64_tr_b16 v[144:145], v128 offset:57632
	v_mfma_f32_16x16x32_bf16 v[22:25], v[78:81], v[6:9], v[22:25]
	s_waitcnt lgkmcnt(8)
	v_mfma_f32_16x16x32_bf16 v[6:9], v[86:89], v[6:9], v[38:41]
	s_nop 2
	ds_read_b128 v[38:41], v82 offset:4096
	v_mfma_f32_16x16x32_bf16 v[50:53], v[78:81], v[10:13], v[50:53]
	v_mfma_f32_16x16x32_bf16 v[10:13], v[86:89], v[10:13], v[42:45]
	s_nop 2
	ds_read_b128 v[42:45], v82 offset:4160
	s_waitcnt lgkmcnt(1)
	s_nop 0
	v_mfma_f32_16x16x32_bf16 v[22:25], v[74:77], v[130:133], v[22:25]
	s_waitcnt lgkmcnt(0)
	s_nop 0
	v_mfma_f32_16x16x32_bf16 v[50:53], v[74:77], v[134:137], v[50:53]
	v_mov_b32_e32 v74, v38
	v_mov_b32_e32 v38, v39
	v_mov_b32_e32 v39, v40
	v_mov_b32_e32 v76, v39
	s_nop 0
	v_mov_b32_e32 v77, v41
	v_mov_b32_e32 v75, v38
	v_mfma_f32_16x16x32_bf16 v[30:33], v[90:93], v[130:133], v[30:33]
	v_mul_f32_e64 v40, v68, v76
	v_mul_f32_e64 v41, v69, v77
	v_mul_f32_e64 v4, v4, v76
	v_mul_f32_e64 v5, v5, v77
	v_mov_b32_e32 v76, v42
	v_mov_b32_e32 v42, v43
	v_mov_b32_e32 v43, v44
	v_mov_b32_e32 v78, v43
	s_nop 0
	v_mov_b32_e32 v79, v45
	v_mov_b32_e32 v77, v42
	ds_read_b128 v[42:45], v82 offset:4224
	v_mul_f32_e64 v38, v66, v74
	v_mul_f32_e64 v39, v67, v75
	ds_read_b128 v[66:69], v82 offset:4288
	v_mul_f32_e64 v2, v2, v74
	v_mul_f32_e64 v3, v3, v75
	v_mul_f32_e64 v60, v60, v78
	v_mul_f32_e64 v61, v61, v79
	s_waitcnt lgkmcnt(1)
	s_nop 0
	v_mov_b32_e32 v74, v42
	v_mov_b32_e32 v42, v43
	v_mov_b32_e32 v43, v44
	v_mov_b32_e32 v75, v42
	v_mov_b32_e32 v80, v43
	s_nop 0
	v_mov_b32_e32 v81, v45
	v_mul_f32_e64 v42, v62, v74
	v_mul_f32_e64 v43, v63, v75
	s_waitcnt lgkmcnt(0)
	v_mov_b32_e32 v62, v66
	v_mov_b32_e32 v63, v68
	v_mul_f32_e64 v58, v58, v76
	v_mul_f32_e64 v59, v59, v77
	v_mul_f32_e64 v16, v16, v78
	v_mul_f32_e64 v17, v17, v79
	v_mul_f32_e64 v14, v14, v76
	v_mul_f32_e64 v15, v15, v77
	v_mov_b32_e32 v76, v62
	v_mov_b32_e32 v62, v67
	v_mov_b32_e32 v78, v63
	v_mov_b32_e32 v63, v69
	v_mul_f32_e64 v44, v64, v80
	v_mul_f32_e64 v45, v65, v81
	v_mov_b32_e32 v79, v63
	v_mov_b32_e32 v77, v62
	ds_read_b128 v[62:65], v82 offset:4352
	v_mul_f32_e64 v18, v18, v74
	v_mul_f32_e64 v19, v19, v75
	v_mul_f32_e64 v68, v72, v78
	v_mul_f32_e64 v69, v73, v79
	v_mul_f32_e64 v66, v70, v76
	v_mul_f32_e64 v67, v71, v77
	ds_read_b128 v[70:73], v82 offset:4416
	s_waitcnt lgkmcnt(1)
	s_nop 0
	v_mov_b32_e32 v74, v62
	v_mov_b32_e32 v75, v63
	v_mov_b32_e32 v62, v64
	v_mov_b32_e32 v63, v65
	v_mfma_f32_16x16x32_bf16 v[26:29], v[90:93], v[134:137], v[26:29]
	s_nop 0
	s_nop 0
	v_mul_f32_e64 v56, v56, v78
	v_mul_f32_e64 v57, v57, v79
	v_mul_f32_e64 v54, v54, v76
	v_mul_f32_e64 v55, v55, v77
	v_mfma_f32_16x16x32_bf16 v[34:37], v[138:141], v[130:133], v[34:37]
	v_mul_f32_e64 v32, v32, v62
	v_mul_f32_e64 v33, v33, v63
	s_nop 0
	v_mul_f32_e64 v28, v28, v62
	v_mul_f32_e64 v29, v29, v63
	s_waitcnt lgkmcnt(0)
	v_mov_b32_e32 v62, v70
	v_mov_b32_e32 v63, v72
	v_mov_b32_e32 v76, v62
	v_mov_b32_e32 v62, v71
	v_mov_b32_e32 v78, v63
	s_nop 0
	v_mov_b32_e32 v79, v73
	v_mov_b32_e32 v77, v62
	ds_read_b128 v[62:65], v82 offset:4480
	ds_read_b128 v[70:73], v82 offset:4544
	v_mfma_f32_16x16x32_bf16 v[46:49], v[138:141], v[134:137], v[46:49]
	v_mul_f32_e64 v20, v20, v80
	v_mul_f32_e64 v21, v21, v81
	s_nop 0
	s_waitcnt lgkmcnt(1)
	s_nop 0
	s_nop 0
	s_nop 0
	s_nop 0
	v_mul_f32_e64 v30, v30, v74
	v_mul_f32_e64 v31, v31, v75
	v_mul_f32_e64 v26, v26, v74
	v_mul_f32_e64 v27, v27, v75
	s_nop 0
	v_mul_f32_e64 v34, v34, v62
	v_mul_f32_e64 v35, v35, v63
	v_mul_f32_e64 v46, v46, v62
	v_mul_f32_e64 v47, v47, v63
	v_lshl_add_u64 v[62:63], v[102:103], 0, s[14:15]
	global_store_dwordx4 v[62:63], v[38:41], off
	s_nop 0
	v_mul_f32_e64 v24, v24, v78
	v_mul_f32_e64 v25, v25, v79
	v_add_co_u32_e32 v38, vcc, s40, v62
	v_mul_f32_e64 v22, v22, v76
	v_mul_f32_e64 v23, v23, v77
	s_nop 0
	v_addc_co_u32_e32 v39, vcc, 0, v63, vcc
	global_store_dwordx4 v[38:39], v[2:5], off
	s_nop 0
	s_nop 0
	v_add_co_u32_e32 v2, vcc, s34, v62
	v_mul_f32_e64 v52, v52, v78
	v_mul_f32_e64 v53, v53, v79
	s_nop 0
	v_addc_co_u32_e32 v3, vcc, 0, v63, vcc
	global_store_dwordx4 v[2:3], v[58:61], off
	v_add_co_u32_e32 v2, vcc, s41, v62
	v_mul_f32_e64 v50, v50, v76
	v_mul_f32_e64 v51, v51, v77
	s_nop 0
	v_addc_co_u32_e32 v3, vcc, 0, v63, vcc
	global_store_dwordx4 v[2:3], v[14:17], off
	v_add_co_u32_e32 v2, vcc, s39, v62
	s_waitcnt lgkmcnt(0)
	s_nop 0
	v_addc_co_u32_e32 v3, vcc, 0, v63, vcc
	global_store_dwordx4 v[2:3], v[42:45], off
	v_add_co_u32_e32 v2, vcc, s48, v62
	s_nop 0
	s_nop 0
	v_addc_co_u32_e32 v3, vcc, 0, v63, vcc
	global_store_dwordx4 v[2:3], v[18:21], off
	v_add_co_u32_e32 v2, vcc, s49, v62
	s_nop 0
	s_nop 0
	v_addc_co_u32_e32 v3, vcc, 0, v63, vcc
	global_store_dwordx4 v[2:3], v[66:69], off
	v_add_co_u32_e32 v2, vcc, s50, v62
	s_nop 0
	s_nop 0
	v_addc_co_u32_e32 v3, vcc, 0, v63, vcc
	global_store_dwordx4 v[2:3], v[54:57], off
	v_add_co_u32_e32 v2, vcc, s51, v62
	v_mfma_f32_16x16x32_bf16 v[6:9], v[142:145], v[130:133], v[6:9]
	s_nop 0
	v_addc_co_u32_e32 v3, vcc, 0, v63, vcc
	global_store_dwordx4 v[2:3], v[30:33], off
	v_add_co_u32_e32 v2, vcc, s45, v62
	v_mul_f32_e64 v36, v36, v64
	v_mul_f32_e64 v37, v37, v65
	s_nop 0
	v_addc_co_u32_e32 v3, vcc, 0, v63, vcc
	global_store_dwordx4 v[2:3], v[26:29], off
	v_add_co_u32_e32 v2, vcc, s52, v62
	s_nop 0
	s_nop 0
	v_addc_co_u32_e32 v3, vcc, 0, v63, vcc
	global_store_dwordx4 v[2:3], v[22:25], off
	v_add_co_u32_e32 v2, vcc, s53, v62
	s_nop 0
	s_nop 0
	v_addc_co_u32_e32 v3, vcc, 0, v63, vcc
	global_store_dwordx4 v[2:3], v[50:53], off
	v_add_co_u32_e32 v2, vcc, s43, v62
	s_nop 0
	s_nop 0
	v_addc_co_u32_e32 v3, vcc, 0, v63, vcc
	global_store_dwordx4 v[2:3], v[34:37], off
	v_add_co_u32_e32 v2, vcc, s54, v62
	v_mfma_f32_16x16x32_bf16 v[10:13], v[142:145], v[134:137], v[10:13]
	v_mul_f32_e64 v48, v48, v64
	v_mul_f32_e64 v49, v49, v65
	v_addc_co_u32_e32 v3, vcc, 0, v63, vcc
	global_store_dwordx4 v[2:3], v[46:49], off
	v_add_co_u32_e32 v2, vcc, 0x1c000, v62
	v_mul_f32_e64 v8, v8, v72
	v_mul_f32_e64 v9, v9, v73
	v_mul_f32_e64 v6, v6, v70
	v_mul_f32_e64 v7, v7, v71
	v_addc_co_u32_e32 v3, vcc, 0, v63, vcc
	global_store_dwordx4 v[2:3], v[6:9], off
	v_add_co_u32_e32 v2, vcc, 0x1e000, v62
	v_mul_f32_e64 v12, v12, v72
	v_mul_f32_e64 v13, v13, v73
	v_mul_f32_e64 v10, v10, v70
	v_mul_f32_e64 v11, v11, v71
	v_addc_co_u32_e32 v3, vcc, 0, v63, vcc
	global_store_dwordx4 v[2:3], v[10:13], off
	s_and_saveexec_b64 s[14:15], s[4:5]
	s_cbranch_execz .LBB0_2073
	v_mul_f32_e32 v1, 0x3fb8aa3b, v1
	v_exp_f32_e32 v1, v1
	s_lshl_b64 s[24:25], s[22:23], 9
	v_lshl_add_u64 v[2:3], v[100:101], 0, s[24:25]
	global_store_dword v[2:3], v1, off
	s_branch .LBB0_2073

.LBB0_2182:
	s_or_b64 exec, exec, s[0:1]
	s_waitcnt lgkmcnt(0)
	s_barrier
	ds_read_b128 v[132:135], v180
	ds_read_b128 v[138:141], v180 offset:16
	s_add_i32 s56, s56, 1
	s_add_u32 s46, s46, 0xffffe000
	s_addc_u32 s47, s47, -1
	s_waitcnt lgkmcnt(1)
	v_mov_b32_e32 v78, v133
	v_mov_b32_e32 v79, v134
	v_mov_b32_e32 v133, v135
	s_waitcnt vmcnt(9)
	v_lshlrev_b32_e32 v134, 16, v162
	v_and_b32_e32 v135, 0xffff0000, v162
	v_add_f32_e64 v78, v78, v132
	v_add_f32_e64 v79, v79, v133
	s_waitcnt lgkmcnt(0)
	v_mov_b32_e32 v132, v140
	v_mov_b32_e32 v133, v138
	v_mov_b32_e32 v138, v141
	v_mul_f32_e32 v140, 0xbfb8aa3b, v134
	v_mul_f32_e32 v141, 0xbfb8aa3b, v135
	v_exp_f32_e32 v140, v140
	v_exp_f32_e32 v141, v141
	v_add_f32_e64 v144, v132, v138
	v_add_f32_e64 v145, v133, v139
	v_lshlrev_b32_e32 v138, 16, v163
	v_and_b32_e32 v139, 0xffff0000, v163
	v_add_f32_e32 v132, 1.0, v140
	v_add_f32_e32 v133, 1.0, v141
	v_mul_f32_e32 v140, 0xbfb8aa3b, v138
	v_mul_f32_e32 v141, 0xbfb8aa3b, v139
	v_rcp_f32_e32 v132, v132
	v_rcp_f32_e32 v133, v133
	v_exp_f32_e32 v140, v140
	v_exp_f32_e32 v141, v141
	s_waitcnt vmcnt(8)
	v_lshlrev_b32_e32 v162, 16, v152
	v_mul_f32_e64 v146, v132, v134
	v_mul_f32_e64 v147, v133, v135
	v_add_f32_e32 v132, 1.0, v140
	v_add_f32_e32 v133, 1.0, v141
	v_and_b32_e32 v163, 0xffff0000, v152
	v_mul_f32_e32 v134, 0xbfb8aa3b, v162
	v_rcp_f32_e32 v132, v132
	v_rcp_f32_e32 v133, v133
	v_exp_f32_e32 v134, v134
	v_mul_f32_e32 v135, 0xbfb8aa3b, v163
	v_exp_f32_e32 v135, v135
	v_mul_f32_e64 v200, v132, v138
	v_mul_f32_e64 v201, v133, v139
	v_add_f32_e32 v132, 1.0, v134
	v_rcp_f32_e32 v202, v132
	v_add_f32_e32 v132, 1.0, v135
	v_lshlrev_b32_e32 v152, 16, v153
	v_and_b32_e32 v153, 0xffff0000, v153
	v_rcp_f32_e32 v203, v132
	v_mul_f32_e32 v132, 0xbfb8aa3b, v152
	v_mul_f32_e32 v133, 0xbfb8aa3b, v153
	v_exp_f32_e32 v132, v132
	v_exp_f32_e32 v138, v133
	s_add_u32 s34, s34, 0xfffa0000
	s_addc_u32 s35, s35, -1
	v_add_f32_e32 v139, 1.0, v132
	ds_read_b128 v[132:135], v180 offset:512
	v_add_f32_e32 v138, 1.0, v138
	v_rcp_f32_e32 v204, v139
	v_rcp_f32_e32 v205, v138
	ds_read_b128 v[138:141], v180 offset:528
	s_waitcnt lgkmcnt(1)
	v_mov_b32_e32 v206, v133
	v_mov_b32_e32 v207, v134
	v_mov_b32_e32 v133, v135
	v_add_f32_e64 v132, v206, v132
	v_add_f32_e64 v133, v207, v133
	s_waitcnt lgkmcnt(0)
	v_mov_b32_e32 v134, v140
	v_mov_b32_e32 v135, v138
	v_mov_b32_e32 v138, v141
	v_add_f32_e64 v134, v134, v138
	v_add_f32_e64 v135, v135, v139
	v_mov_b32_e32 v138, v132
	v_mov_b32_e32 v139, v78
	v_mov_b32_e32 v78, v133
	v_add_f32_e64 v78, v138, v78
	v_add_f32_e64 v79, v139, v79
	v_mov_b32_e32 v132, v135
	v_mov_b32_e32 v133, v145
	v_add_f32_e64 v78, v78, v132
	v_add_f32_e64 v79, v79, v133
	v_mov_b32_e32 v135, v144
	v_add_f32_e64 v132, v134, v78
	v_add_f32_e64 v133, v135, v79
	v_mov_b64_e32 v[78:79], s[40:41]
	v_fma_f32 v132, v132, s38, v78
	v_fma_f32 v133, v133, s38, v78
	v_mul_f32_e64 v138, v202, v162
	v_mul_f32_e64 v139, v203, v163
	v_mul_f32_e32 v134, 0x4b800000, v133
	v_cmp_gt_f32_e64 s[0:1], s55, v133
	v_mul_f32_e64 v140, v204, v152
	v_mul_f32_e64 v141, v205, v153
	v_lshl_add_u64 v[152:153], s[28:29], 0, v[116:117]
	v_cndmask_b32_e64 v133, v133, v134, s[0:1]
	v_rsq_f32_e32 v133, v133
	v_lshl_add_u64 v[134:135], s[28:29], 0, v[106:107]
	v_mul_f32_e32 v144, 0x45800000, v133
	v_cndmask_b32_e64 v144, v133, v144, s[0:1]
	v_mul_f32_e64 v148, v148, v144
	v_mul_f32_e64 v149, v149, v144
	v_mul_f32_e32 v133, 0x4b800000, v132
	s_waitcnt vmcnt(1)
	v_mul_f32_e64 v148, v72, v148
	v_mul_f32_e64 v149, v73, v149
	v_cmp_gt_f32_e64 s[0:1], s55, v132
	v_mul_f32_e64 v146, v146, v148
	v_mul_f32_e64 v147, v147, v149
	v_mul_f32_e64 v148, v150, v144
	v_mul_f32_e64 v149, v151, v144
	v_cvt_pk_bf16_f32 v146, v146, v147
	v_mul_f32_e64 v148, v74, v148
	v_mul_f32_e64 v149, v75, v149
	v_cndmask_b32_e64 v132, v132, v133, s[0:1]
	v_mul_f32_e64 v148, v200, v148
	v_mul_f32_e64 v149, v201, v149
	v_rsq_f32_e32 v133, v132
	v_cvt_pk_bf16_f32 v147, v148, v149
	global_store_dwordx2 v[134:135], v[146:147], off
	v_mul_f32_e64 v146, v156, v144
	v_mul_f32_e64 v147, v157, v144
	v_mul_f32_e64 v145, v159, v144
	v_mul_f32_e64 v144, v158, v144
	s_waitcnt vmcnt(1)
	v_mul_f32_e64 v146, v68, v146
	v_mul_f32_e64 v147, v69, v147
	v_mul_f32_e64 v144, v70, v144
	v_mul_f32_e64 v145, v71, v145
	v_mul_f32_e64 v138, v138, v146
	v_mul_f32_e64 v139, v139, v147
	v_mul_f32_e64 v140, v140, v144
	v_mul_f32_e64 v141, v141, v145
	v_cvt_pk_bf16_f32 v138, v138, v139
	v_cvt_pk_bf16_f32 v139, v140, v141
	v_lshlrev_b32_e32 v132, 16, v142
	global_store_dwordx2 v[134:135], v[138:139], off offset:32
	v_mul_f32_e32 v134, 0xbfb8aa3b, v132
	v_exp_f32_e32 v135, v134
	v_mul_f32_e32 v134, 0x45800000, v133
	v_cndmask_b32_e64 v134, v133, v134, s[0:1]
	v_and_b32_e32 v133, 0xffff0000, v142
	v_mul_f32_e32 v138, 0xbfb8aa3b, v133
	v_exp_f32_e32 v139, v138
	v_add_f32_e32 v135, 1.0, v135
	v_rcp_f32_e32 v138, v135
	v_mul_f32_e64 v140, v160, v134
	v_mul_f32_e64 v141, v161, v134
	v_add_f32_e32 v135, 1.0, v139
	v_lshlrev_b32_e32 v142, 16, v143
	v_rcp_f32_e32 v139, v135
	v_and_b32_e32 v143, 0xffff0000, v143
	v_mul_f32_e32 v135, 0xbfb8aa3b, v142
	v_exp_f32_e32 v135, v135
	v_mul_f32_e32 v144, 0xbfb8aa3b, v143
	v_exp_f32_e32 v144, v144
	v_mul_f32_e64 v132, v138, v132
	v_mul_f32_e64 v133, v139, v133
	v_add_f32_e32 v135, 1.0, v135
	v_rcp_f32_e32 v138, v135
	v_add_f32_e32 v135, 1.0, v144
	v_rcp_f32_e32 v139, v135
	v_mul_f32_e64 v98, v98, v134
	v_mul_f32_e64 v99, v99, v134
	v_mul_f32_e64 v140, v72, v140
	v_mul_f32_e64 v141, v73, v141
	v_mul_f32_e64 v98, v74, v98
	v_mul_f32_e64 v99, v75, v99
	v_mul_f32_e64 v138, v138, v142
	v_mul_f32_e64 v139, v139, v143
	v_mul_f32_e64 v132, v132, v140
	v_mul_f32_e64 v133, v133, v141
	v_mul_f32_e64 v98, v138, v98
	v_mul_f32_e64 v99, v139, v99
	v_cvt_pk_bf16_f32 v132, v132, v133
	v_cvt_pk_bf16_f32 v133, v98, v99
	v_lshlrev_b32_e32 v98, 16, v136
	v_mul_f32_e32 v99, 0xbfb8aa3b, v98
	v_exp_f32_e32 v135, v99
	v_lshl_add_u64 v[138:139], s[28:29], 0, v[110:111]
	v_and_b32_e32 v99, 0xffff0000, v136
	global_store_dwordx2 v[138:139], v[132:133], off
	v_mul_f32_e32 v133, 0xbfb8aa3b, v99
	v_exp_f32_e32 v133, v133
	v_lshlrev_b32_e32 v136, 16, v137
	v_and_b32_e32 v137, 0xffff0000, v137
	v_add_f32_e32 v132, 1.0, v135
	v_mul_f32_e64 v96, v96, v134
	v_mul_f32_e64 v97, v97, v134
	v_add_f32_e32 v133, 1.0, v133
	v_mul_f32_e32 v135, 0xbfb8aa3b, v136
	v_mul_f32_e32 v138, 0xbfb8aa3b, v137
	v_rcp_f32_e32 v132, v132
	v_rcp_f32_e32 v133, v133
	v_exp_f32_e32 v135, v135
	v_exp_f32_e32 v138, v138
	v_mul_f32_e64 v96, v68, v96
	v_mul_f32_e64 v97, v69, v97
	v_mul_f32_e64 v98, v132, v98
	v_mul_f32_e64 v99, v133, v99
	v_add_f32_e32 v132, 1.0, v135
	v_add_f32_e32 v133, 1.0, v138
	v_rcp_f32_e32 v132, v132
	v_rcp_f32_e32 v133, v133
	v_mul_f32_e64 v94, v94, v134
	v_mul_f32_e64 v95, v95, v134
	v_mul_f32_e64 v96, v98, v96
	v_mul_f32_e64 v97, v99, v97
	v_mul_f32_e64 v94, v70, v94
	v_mul_f32_e64 v95, v71, v95
	v_mul_f32_e64 v98, v132, v136
	v_mul_f32_e64 v99, v133, v137
	v_cvt_pk_bf16_f32 v132, v96, v97
	v_mul_f32_e64 v98, v98, v94
	v_mul_f32_e64 v99, v99, v95
	ds_read_b128 v[94:97], v180 offset:1024
	v_cvt_pk_bf16_f32 v133, v98, v99
	v_lshl_add_u64 v[98:99], s[28:29], 0, v[112:113]
	global_store_dwordx2 v[98:99], v[132:133], off
	ds_read_b128 v[132:135], v180 offset:1040
	s_waitcnt lgkmcnt(1)
	v_mov_b32_e32 v98, v95
	v_mov_b32_e32 v99, v96
	v_mov_b32_e32 v95, v97
	v_lshlrev_b32_e32 v96, 16, v130
	v_add_f32_e64 v98, v98, v94
	v_add_f32_e64 v99, v99, v95
	v_and_b32_e32 v97, 0xffff0000, v130
	v_mul_f32_e32 v95, 0xbfb8aa3b, v96
	v_exp_f32_e32 v130, v95
	v_mul_f32_e32 v95, 0xbfb8aa3b, v97
	s_waitcnt lgkmcnt(0)
	v_mov_b32_e32 v94, v134
	v_exp_f32_e32 v134, v95
	v_lshlrev_b32_e32 v136, 16, v131
	v_and_b32_e32 v137, 0xffff0000, v131
	v_mul_f32_e32 v131, 0xbfb8aa3b, v136
	v_mov_b32_e32 v95, v132
	v_add_f32_e32 v132, 1.0, v134
	v_exp_f32_e32 v134, v131
	v_mul_f32_e32 v131, 0xbfb8aa3b, v137
	v_exp_f32_e32 v139, v131
	v_rcp_f32_e32 v131, v132
	v_add_f32_e32 v132, 1.0, v134
	v_rcp_f32_e32 v138, v132
	v_add_f32_e32 v132, 1.0, v139
	v_rcp_f32_e32 v139, v132
	v_mov_b32_e32 v132, v135
	v_add_f32_e64 v132, v94, v132
	v_add_f32_e64 v133, v95, v133
	v_lshlrev_b32_e32 v144, 16, v129
	v_mul_f32_e64 v136, v138, v136
	v_mul_f32_e64 v137, v139, v137
	v_lshlrev_b32_e32 v138, 16, v128
	v_and_b32_e32 v139, 0xffff0000, v128
	v_mul_f32_e32 v94, 0xbfb8aa3b, v138
	v_exp_f32_e32 v94, v94
	v_mul_f32_e32 v95, 0xbfb8aa3b, v139
	v_exp_f32_e32 v95, v95
	v_and_b32_e32 v145, 0xffff0000, v129
	v_add_f32_e32 v94, 1.0, v94
	v_rcp_f32_e32 v142, v94
	v_add_f32_e32 v94, 1.0, v95
	v_add_f32_e32 v130, 1.0, v130
	v_rcp_f32_e32 v143, v94
	v_mul_f32_e32 v94, 0xbfb8aa3b, v144
	v_mul_f32_e32 v95, 0xbfb8aa3b, v145
	v_rcp_f32_e32 v130, v130
	v_exp_f32_e32 v94, v94
	v_exp_f32_e32 v128, v95
	v_lshl_add_u64 v[140:141], s[28:29], 0, v[114:115]
	v_mul_f32_e64 v134, v130, v96
	v_mul_f32_e64 v135, v131, v97
	v_add_f32_e32 v129, 1.0, v94
	ds_read_b128 v[94:97], v180 offset:1536
	v_add_f32_e32 v128, 1.0, v128
	v_rcp_f32_e32 v146, v129
	v_rcp_f32_e32 v147, v128
	ds_read_b128 v[128:131], v180 offset:1552
	s_waitcnt lgkmcnt(1)
	v_mov_b32_e32 v148, v95
	v_mov_b32_e32 v149, v96
	v_mov_b32_e32 v95, v97
	v_add_f32_e64 v94, v148, v94
	v_add_f32_e64 v95, v149, v95
	s_waitcnt lgkmcnt(0)
	v_mov_b32_e32 v96, v130
	v_mov_b32_e32 v97, v128
	v_mov_b32_e32 v128, v131
	v_add_f32_e64 v96, v96, v128
	v_add_f32_e64 v97, v97, v129
	v_mov_b32_e32 v128, v94
	v_mov_b32_e32 v129, v98
	v_mov_b32_e32 v98, v95
	v_add_f32_e64 v94, v128, v98
	v_add_f32_e64 v95, v129, v99
	v_mov_b32_e32 v98, v97
	v_mov_b32_e32 v99, v133
	v_add_f32_e64 v94, v94, v98
	v_add_f32_e64 v95, v95, v99
	v_mov_b32_e32 v97, v132
	v_add_f32_e64 v94, v96, v94
	v_add_f32_e64 v95, v97, v95
	v_mul_f32_e64 v98, v146, v144
	v_mul_f32_e64 v99, v147, v145
	v_fma_f32 v79, v95, s38, v78
	v_fma_f32 v78, v94, s38, v78
	s_nop 0
	v_mul_f32_e32 v94, 0x4b800000, v79
	v_cmp_gt_f32_e64 s[0:1], s55, v79
	s_nop 1
	v_cndmask_b32_e64 v79, v79, v94, s[0:1]
	v_rsq_f32_e32 v79, v79
	v_mul_f32_e64 v94, v142, v138
	v_mul_f32_e64 v95, v143, v139
	v_mul_f32_e32 v96, 0x45800000, v79
	v_cndmask_b32_e64 v96, v79, v96, s[0:1]
	v_mul_f32_e64 v88, v88, v96
	v_mul_f32_e64 v89, v89, v96
	v_mul_f32_e64 v92, v92, v96
	v_mul_f32_e64 v93, v93, v96
	v_mul_f32_e64 v88, v72, v88
	v_mul_f32_e64 v89, v73, v89
	v_mul_f32_e64 v92, v74, v92
	v_mul_f32_e64 v93, v75, v93
	v_mul_f32_e64 v88, v134, v88
	v_mul_f32_e64 v89, v135, v89
	v_mul_f32_e64 v92, v136, v92
	v_mul_f32_e64 v93, v137, v93
	v_cvt_pk_bf16_f32 v88, v88, v89
	v_cvt_pk_bf16_f32 v89, v92, v93
	global_store_dwordx2 v[140:141], v[88:89], off
	v_mul_f32_e64 v88, v90, v96
	v_mul_f32_e64 v89, v91, v96
	v_mul_f32_e32 v79, 0x4b800000, v78
	v_cmp_gt_f32_e64 s[0:1], s55, v78
	v_mul_f32_e64 v88, v68, v88
	v_mul_f32_e64 v89, v69, v89
	v_mul_f32_e64 v86, v86, v96
	v_mul_f32_e64 v87, v87, v96
	v_cndmask_b32_e64 v78, v78, v79, s[0:1]
	v_mul_f32_e64 v200, v94, v88
	v_mul_f32_e64 v201, v95, v89
	v_mul_f32_e64 v202, v70, v86
	v_mul_f32_e64 v203, v71, v87
	ds_read_b64_tr_b16 v[88:89], v196 offset:57408
	ds_read_b64_tr_b16 v[86:87], v196 offset:56320
	ds_read_b64_tr_b16 v[92:93], v198 offset:2112
	ds_read_b64_tr_b16 v[90:91], v198
	ds_read_b64_tr_b16 v[96:97], v198 offset:2144
	ds_read_b64_tr_b16 v[94:95], v198 offset:32
	ds_read_b64_tr_b16 v[128:129], v196 offset:56352
	ds_read_b64_tr_b16 v[132:133], v196 offset:56384
	ds_read_b64_tr_b16 v[136:137], v196 offset:56416
	ds_read_b64_tr_b16 v[130:131], v196 offset:57440
	ds_read_b64_tr_b16 v[134:135], v196 offset:57472
	ds_read_b64_tr_b16 v[138:139], v196 offset:57504
	v_rsq_f32_e32 v78, v78
	ds_read_b64_tr_b16 v[140:141], v196 offset:65024
	ds_read_b64_tr_b16 v[142:143], v197 offset:57408
	ds_read_b64_tr_b16 v[144:145], v198 offset:16896
	ds_read_b64_tr_b16 v[146:147], v198 offset:19008
	ds_read_b64_tr_b16 v[150:151], v198 offset:19040
	ds_read_b64_tr_b16 v[148:149], v198 offset:16928
	v_mul_f32_e64 v98, v98, v202
	v_mul_f32_e64 v99, v99, v203
	s_waitcnt lgkmcnt(8)
	v_mfma_f32_16x16x32_bf16 v[12:15], v[128:131], v[90:93], v[12:15]
	v_cvt_pk_bf16_f32 v200, v200, v201
	v_cvt_pk_bf16_f32 v201, v98, v99
	v_mul_f32_e32 v79, 0x45800000, v78
	v_mfma_f32_16x16x32_bf16 v[36:39], v[128:131], v[94:97], v[36:39]
	v_lshlrev_b32_e32 v98, 16, v126
	v_cndmask_b32_e64 v78, v78, v79, s[0:1]
	v_and_b32_e32 v99, 0xffff0000, v126
	v_mfma_f32_16x16x32_bf16 v[8:11], v[86:89], v[90:93], v[8:11]
	v_mul_f32_e32 v79, 0xbfb8aa3b, v98
	v_exp_f32_e32 v79, v79
	v_mul_f32_e32 v126, 0xbfb8aa3b, v99
	v_mfma_f32_16x16x32_bf16 v[4:7], v[86:89], v[94:97], v[4:7]
	ds_read_b64_tr_b16 v[86:87], v196 offset:65056
	ds_read_b64_tr_b16 v[156:157], v196 offset:65088
	ds_read_b64_tr_b16 v[160:161], v196 offset:65120
	ds_read_b64_tr_b16 v[88:89], v197 offset:57440
	ds_read_b64_tr_b16 v[158:159], v197 offset:57472
	ds_read_b64_tr_b16 v[162:163], v197 offset:57504
	v_add_f32_e32 v79, 1.0, v79
	global_store_dwordx2 v[152:153], v[200:201], off
	s_waitcnt lgkmcnt(2)
	v_mfma_f32_16x16x32_bf16 v[12:15], v[86:89], v[144:147], v[12:15]
	v_mfma_f32_16x16x32_bf16 v[36:39], v[86:89], v[148:151], v[36:39]
	v_exp_f32_e32 v87, v126
	v_rcp_f32_e32 v86, v79
	v_add_f32_e32 v79, 1.0, v87
	v_rcp_f32_e32 v87, v79
	v_mul_f32_e64 v84, v84, v78
	v_mul_f32_e64 v85, v85, v78
	v_mfma_f32_16x16x32_bf16 v[24:27], v[132:135], v[90:93], v[24:27]
	v_mul_f32_e64 v72, v72, v84
	v_mul_f32_e64 v73, v73, v85
	v_mul_f32_e64 v84, v86, v98
	v_mul_f32_e64 v85, v87, v99
	v_lshlrev_b32_e32 v86, 16, v127
	v_mul_f32_e32 v79, 0xbfb8aa3b, v86
	v_exp_f32_e32 v79, v79
	v_mul_f32_e64 v98, v84, v72
	v_mul_f32_e64 v99, v85, v73
	v_and_b32_e32 v87, 0xffff0000, v127
	v_mfma_f32_16x16x32_bf16 v[32:35], v[132:135], v[94:97], v[32:35]
	v_add_f32_e32 v72, 1.0, v79
	v_rcp_f32_e32 v84, v72
	v_mul_f32_e32 v72, 0xbfb8aa3b, v87
	v_exp_f32_e32 v79, v72
	v_mfma_f32_16x16x32_bf16 v[40:43], v[136:139], v[90:93], v[40:43]
	v_cvt_pk_bf16_f32 v98, v98, v99
	v_mul_f32_e64 v72, v82, v78
	v_mul_f32_e64 v73, v83, v78
	s_nop 0
	v_mul_f32_e64 v134, v74, v72
	v_mul_f32_e64 v135, v75, v73
	v_add_f32_e32 v72, 1.0, v79
	v_rcp_f32_e32 v85, v72
	ds_read_b64_tr_b16 v[72:73], v196 offset:56448
	ds_read_b64_tr_b16 v[74:75], v196 offset:57536
	v_mfma_f32_16x16x32_bf16 v[64:67], v[136:139], v[94:97], v[64:67]
	v_mul_f32_e64 v136, v84, v86
	v_mul_f32_e64 v137, v85, v87
	ds_read_b64_tr_b16 v[82:83], v196 offset:56480
	ds_read_b64_tr_b16 v[86:87], v196 offset:56512
	ds_read_b64_tr_b16 v[126:127], v196 offset:56544
	ds_read_b64_tr_b16 v[84:85], v196 offset:57568
	ds_read_b64_tr_b16 v[88:89], v196 offset:57600
	ds_read_b64_tr_b16 v[128:129], v196 offset:57632
	v_mfma_f32_16x16x32_bf16 v[8:11], v[140:143], v[144:147], v[8:11]
	ds_read_b64_tr_b16 v[130:131], v196 offset:65152
	ds_read_b64_tr_b16 v[132:133], v197 offset:57536
	v_mfma_f32_16x16x32_bf16 v[4:7], v[140:143], v[148:151], v[4:7]
	v_mul_f32_e64 v142, v136, v134
	v_mul_f32_e64 v143, v137, v135
	v_cvt_pk_bf16_f32 v99, v142, v143
	v_lshl_add_u64 v[142:143], s[28:29], 0, v[118:119]
	s_waitcnt lgkmcnt(8)
	v_mfma_f32_16x16x32_bf16 v[16:19], v[72:75], v[90:93], v[16:19]
	v_mfma_f32_16x16x32_bf16 v[20:23], v[72:75], v[94:97], v[20:23]
	ds_read_b64_tr_b16 v[72:73], v196 offset:65184
	ds_read_b64_tr_b16 v[134:135], v196 offset:65216
	ds_read_b64_tr_b16 v[138:139], v196 offset:65248
	ds_read_b64_tr_b16 v[74:75], v197 offset:57568
	ds_read_b64_tr_b16 v[136:137], v197 offset:57600
	ds_read_b64_tr_b16 v[140:141], v197 offset:57632
	global_store_dwordx2 v[142:143], v[98:99], off
	v_lshlrev_b32_e32 v98, 16, v124
	v_and_b32_e32 v99, 0xffff0000, v124
	v_mul_f32_e32 v79, 0xbfb8aa3b, v98
	v_exp_f32_e32 v79, v79
	v_mul_f32_e32 v124, 0xbfb8aa3b, v99
	s_waitcnt lgkmcnt(10)
	v_mfma_f32_16x16x32_bf16 v[28:31], v[82:85], v[90:93], v[28:31]
	v_add_f32_e32 v79, 1.0, v79
	v_mfma_f32_16x16x32_bf16 v[48:51], v[82:85], v[94:97], v[48:51]
	v_exp_f32_e32 v83, v124
	v_rcp_f32_e32 v82, v79
	v_add_f32_e32 v79, 1.0, v83
	v_rcp_f32_e32 v83, v79
	v_mul_f32_e64 v80, v80, v78
	v_mul_f32_e64 v81, v81, v78
	s_waitcnt lgkmcnt(2)
	v_mfma_f32_16x16x32_bf16 v[28:31], v[72:75], v[144:147], v[28:31]
	v_mul_f32_e64 v68, v68, v80
	v_mul_f32_e64 v69, v69, v81
	v_mul_f32_e64 v76, v76, v78
	v_mul_f32_e64 v77, v77, v78
	v_lshl_add_u64 v[78:79], s[28:29], 0, v[120:121]
	v_mfma_f32_16x16x32_bf16 v[48:51], v[72:75], v[148:151], v[48:51]
	v_mul_f32_e64 v72, v82, v98
	v_mul_f32_e64 v73, v83, v99
	v_mul_f32_e64 v70, v70, v76
	v_mul_f32_e64 v71, v71, v77
	v_mul_f32_e64 v68, v72, v68
	v_mul_f32_e64 v69, v73, v69
	v_lshlrev_b32_e32 v72, 16, v125
	v_and_b32_e32 v73, 0xffff0000, v125
	v_mul_f32_e32 v74, 0xbfb8aa3b, v72
	v_mul_f32_e32 v75, 0xbfb8aa3b, v73
	v_exp_f32_e32 v74, v74
	v_exp_f32_e32 v75, v75
	v_lshl_add_u32 v82, s57, 9, v176
	v_cvt_pk_bf16_f32 v76, v68, v69
	v_add_f32_e32 v74, 1.0, v74
	v_add_f32_e32 v75, 1.0, v75
	v_rcp_f32_e32 v74, v74
	v_rcp_f32_e32 v75, v75
	v_mfma_f32_16x16x32_bf16 v[24:27], v[156:159], v[144:147], v[24:27]
	s_add_u32 s28, s28, 0xfffe0000
	s_addc_u32 s29, s29, -1
	v_mul_f32_e64 v72, v74, v72
	v_mul_f32_e64 v73, v75, v73
	v_mfma_f32_16x16x32_bf16 v[32:35], v[156:159], v[148:151], v[32:35]
	v_mul_f32_e64 v72, v72, v70
	v_mul_f32_e64 v73, v73, v71
	ds_read_b128 v[68:71], v82 offset:4096
	v_cvt_pk_bf16_f32 v77, v72, v73
	ds_read_b128 v[72:75], v82 offset:4160
	global_store_dwordx2 v[78:79], v[76:77], off
	v_mfma_f32_16x16x32_bf16 v[16:19], v[130:133], v[144:147], v[16:19]
	s_waitcnt lgkmcnt(1)
	s_nop 0
	v_mov_b32_e32 v80, v68
	v_mov_b32_e32 v81, v69
	v_mov_b32_e32 v68, v70
	v_mov_b32_e32 v69, v71
	s_nop 0
	s_nop 0
	s_nop 0
	v_mfma_f32_16x16x32_bf16 v[20:23], v[130:133], v[148:151], v[20:23]
	s_add_u32 s30, s30, 0xfffe0000
	v_mul_f32_e64 v10, v10, v68
	v_mul_f32_e64 v11, v11, v69
	v_mul_f32_e64 v6, v6, v68
	v_mul_f32_e64 v7, v7, v69
	s_waitcnt lgkmcnt(0)
	v_mov_b32_e32 v68, v72
	v_mov_b32_e32 v69, v74
	v_mov_b32_e32 v76, v68
	v_mov_b32_e32 v68, v73
	v_mov_b32_e32 v78, v69
	s_nop 0
	v_mov_b32_e32 v79, v75
	v_mov_b32_e32 v77, v68
	ds_read_b128 v[68:71], v82 offset:4224
	ds_read_b128 v[72:75], v82 offset:4288
	v_mul_f32_e64 v8, v8, v80
	v_mul_f32_e64 v9, v9, v81
	v_mul_f32_e64 v4, v4, v80
	v_mul_f32_e64 v5, v5, v81
	v_mul_f32_e64 v14, v14, v78
	v_mul_f32_e64 v15, v15, v79
	s_waitcnt lgkmcnt(1)
	s_nop 0
	v_mov_b32_e32 v80, v68
	v_mov_b32_e32 v81, v69
	v_mov_b32_e32 v68, v70
	v_mov_b32_e32 v69, v71
	s_nop 0
	s_nop 0
	v_mul_f32_e64 v12, v12, v76
	v_mul_f32_e64 v13, v13, v77
	v_mul_f32_e64 v38, v38, v78
	v_mul_f32_e64 v39, v39, v79
	v_mul_f32_e64 v36, v36, v76
	v_mul_f32_e64 v37, v37, v77
	v_mul_f32_e64 v26, v26, v68
	v_mul_f32_e64 v27, v27, v69
	v_mul_f32_e64 v34, v34, v68
	v_mul_f32_e64 v35, v35, v69
	s_waitcnt lgkmcnt(0)
	v_mov_b32_e32 v68, v72
	v_mov_b32_e32 v69, v74
	v_mov_b32_e32 v76, v68
	v_mov_b32_e32 v68, v73
	v_mov_b32_e32 v78, v69
	s_nop 0
	v_mov_b32_e32 v79, v75
	v_mov_b32_e32 v77, v68
	ds_read_b128 v[68:71], v82 offset:4352
	ds_read_b128 v[72:75], v82 offset:4416
	s_nop 0
	v_mfma_f32_16x16x32_bf16 v[40:43], v[160:163], v[144:147], v[40:43]
	s_addc_u32 s31, s31, -1
	s_waitcnt lgkmcnt(1)
	s_nop 0
	v_mul_f32_e64 v24, v24, v80
	v_mul_f32_e64 v25, v25, v81
	v_mul_f32_e64 v32, v32, v80
	v_mul_f32_e64 v33, v33, v81
	v_mov_b32_e32 v80, v68
	v_mov_b32_e32 v81, v69
	v_mov_b32_e32 v68, v70
	v_mov_b32_e32 v69, v71
	s_nop 0
	s_nop 0
	v_mfma_f32_16x16x32_bf16 v[64:67], v[160:163], v[148:151], v[64:67]
	v_mul_f32_e64 v42, v42, v78
	v_mul_f32_e64 v43, v43, v79
	v_mul_f32_e64 v40, v40, v76
	v_mul_f32_e64 v41, v41, v77
	v_mul_f32_e64 v18, v18, v68
	v_mul_f32_e64 v19, v19, v69
	v_mul_f32_e64 v22, v22, v68
	v_mul_f32_e64 v23, v23, v69
	s_waitcnt lgkmcnt(0)
	v_mov_b32_e32 v68, v72
	v_mov_b32_e32 v69, v74
	v_mul_f32_e64 v66, v66, v78
	v_mul_f32_e64 v67, v67, v79
	v_mul_f32_e64 v64, v64, v76
	v_mul_f32_e64 v65, v65, v77
	v_mov_b32_e32 v76, v68
	v_mov_b32_e32 v68, v73
	v_mov_b32_e32 v78, v69
	s_nop 0
	v_mov_b32_e32 v79, v75
	v_mov_b32_e32 v77, v68
	ds_read_b128 v[68:71], v82 offset:4480
	ds_read_b128 v[72:75], v82 offset:4544
	v_mfma_f32_16x16x32_bf16 v[44:47], v[86:89], v[90:93], v[44:47]
	s_nop 0
	v_mul_f32_e64 v30, v30, v78
	v_mul_f32_e64 v31, v31, v79
	s_waitcnt lgkmcnt(1)
	s_nop 0
	v_mfma_f32_16x16x32_bf16 v[56:59], v[86:89], v[94:97], v[56:59]
	s_nop 0
	s_nop 0
	s_nop 0
	v_mfma_f32_16x16x32_bf16 v[52:55], v[126:129], v[90:93], v[52:55]
	s_waitcnt lgkmcnt(0)
	s_nop 0
	s_nop 0
	s_nop 0
	v_mfma_f32_16x16x32_bf16 v[60:63], v[126:129], v[94:97], v[60:63]
	s_nop 0
	s_nop 0
	s_nop 0
	v_mfma_f32_16x16x32_bf16 v[44:47], v[134:137], v[144:147], v[44:47]
	s_nop 0
	s_nop 0
	s_nop 0
	v_mfma_f32_16x16x32_bf16 v[56:59], v[134:137], v[148:151], v[56:59]
	s_nop 0
	s_nop 0
	s_nop 0
	v_mfma_f32_16x16x32_bf16 v[52:55], v[138:141], v[144:147], v[52:55]
	v_mul_f32_e64 v16, v16, v80
	v_mul_f32_e64 v17, v17, v81
	v_mul_f32_e64 v20, v20, v80
	v_mul_f32_e64 v21, v21, v81
	v_mul_f32_e64 v28, v28, v76
	v_mul_f32_e64 v29, v29, v77
	v_mfma_f32_16x16x32_bf16 v[60:63], v[138:141], v[148:151], v[60:63]
	v_mul_f32_e64 v50, v50, v78
	v_mul_f32_e64 v51, v51, v79
	v_mul_f32_e64 v48, v48, v76
	v_mul_f32_e64 v49, v49, v77
	v_mul_f32_e64 v46, v46, v70
	v_mul_f32_e64 v47, v47, v71
	v_mul_f32_e64 v44, v44, v68
	v_mul_f32_e64 v45, v45, v69
	v_mul_f32_e64 v58, v58, v70
	v_mul_f32_e64 v59, v59, v71
	v_mul_f32_e64 v56, v56, v68
	v_mul_f32_e64 v57, v57, v69
	v_mul_f32_e64 v54, v54, v74
	v_mul_f32_e64 v55, v55, v75
	v_mul_f32_e64 v52, v52, v72
	v_mul_f32_e64 v53, v53, v73
	v_mul_f32_e64 v62, v62, v74
	v_mul_f32_e64 v63, v63, v75
	s_cmp_eq_u32 s56, 4
	v_mul_f32_e64 v60, v60, v72
	v_mul_f32_e64 v61, v61, v73
	s_cbranch_scc1 .LBB0_2200

.LBB0_2266:
	ds_read_b128 v[138:141], v205 offset:6144
	ds_read_b128 v[142:145], v205 offset:6160
	s_waitcnt vmcnt(6)
	v_lshlrev_b32_e32 v146, 16, v98
	v_and_b32_e32 v147, 0xffff0000, v98
	v_add_u32_e32 v219, 0x9800, v216
	s_waitcnt lgkmcnt(1)
	v_mul_f32_e32 v107, 0xbfb8aa3b, v138
	v_exp_f32_e32 v108, v107
	v_mul_f32_e32 v107, 0xbfb8aa3b, v139
	v_exp_f32_e32 v109, v107
	v_mul_f32_e32 v107, 0xbfb8aa3b, v140
	v_cvt_pk_bf16_f32 v160, v10, v11
	v_cvt_pk_bf16_f32 v161, v12, v13
	v_mul_f32_e64 v108, v108, v146
	v_mul_f32_e64 v109, v109, v147
	v_lshlrev_b32_e32 v146, 16, v99
	v_cvt_pk_bf16_f32 v98, v108, v109
	v_exp_f32_e32 v108, v107
	v_mul_f32_e32 v107, 0xbfb8aa3b, v141
	v_exp_f32_e32 v109, v107
	v_and_b32_e32 v147, 0xffff0000, v99
	s_waitcnt lgkmcnt(0)
	v_mul_f32_e32 v107, 0xbfb8aa3b, v142
	v_cvt_pk_bf16_f32 v162, v26, v27
	v_mul_f32_e64 v108, v108, v146
	v_mul_f32_e64 v109, v109, v147
	v_lshlrev_b32_e32 v146, 16, v100
	v_cvt_pk_bf16_f32 v99, v108, v109
	v_exp_f32_e32 v108, v107
	v_mul_f32_e32 v107, 0xbfb8aa3b, v143
	v_exp_f32_e32 v109, v107
	v_and_b32_e32 v147, 0xffff0000, v100
	v_mul_f32_e32 v107, 0xbfb8aa3b, v144
	v_cvt_pk_bf16_f32 v163, v28, v29
	v_mul_f32_e64 v108, v108, v146
	v_mul_f32_e64 v109, v109, v147
	v_lshlrev_b32_e32 v146, 16, v101
	v_cvt_pk_bf16_f32 v100, v108, v109
	v_exp_f32_e32 v108, v107
	v_mul_f32_e32 v107, 0xbfb8aa3b, v145
	v_exp_f32_e32 v109, v107
	v_and_b32_e32 v147, 0xffff0000, v101
	v_add_u32_e32 v220, 0xa800, v216
	v_add_u32_e32 v221, 0xb800, v216
	v_mul_f32_e64 v108, v108, v146
	v_mul_f32_e64 v109, v109, v147
	v_add_u32_e32 v222, 0xc800, v216
	v_cvt_pk_bf16_f32 v101, v108, v109
	ds_write_b128 v184, v[98:101] offset:56320
	v_mul_f32_e32 v98, 0x3fb8aa3b, v138
	v_mul_f32_e32 v99, 0x3fb8aa3b, v139
	v_exp_f32_e32 v98, v98
	v_exp_f32_e32 v99, v99
	v_lshlrev_b32_e32 v100, 16, v94
	v_and_b32_e32 v101, 0xffff0000, v94
	s_waitcnt vmcnt(4)
	v_lshlrev_b32_e32 v138, 16, v90
	v_mul_f32_e64 v98, v98, s48
	v_mul_f32_e64 v99, v99, s48
	v_and_b32_e32 v139, 0xffff0000, v90
	v_mul_f32_e64 v98, v98, v100
	v_mul_f32_e64 v99, v99, v101
	v_lshlrev_b32_e32 v100, 16, v95
	v_cvt_pk_bf16_f32 v94, v98, v99
	v_mul_f32_e32 v98, 0x3fb8aa3b, v140
	v_mul_f32_e32 v99, 0x3fb8aa3b, v141
	v_exp_f32_e32 v98, v98
	v_exp_f32_e32 v99, v99
	v_and_b32_e32 v101, 0xffff0000, v95
	s_mov_b32 s61, 0x8000
	s_add_u32 s74, s74, 0x60000
	v_mul_f32_e64 v98, v98, s48
	v_mul_f32_e64 v99, v99, s48
	s_addc_u32 s75, s75, 0
	v_mul_f32_e64 v98, v98, v100
	v_mul_f32_e64 v99, v99, v101
	v_lshlrev_b32_e32 v100, 16, v96
	v_cvt_pk_bf16_f32 v95, v98, v99
	v_mul_f32_e32 v98, 0x3fb8aa3b, v142
	v_mul_f32_e32 v99, 0x3fb8aa3b, v143
	v_exp_f32_e32 v98, v98
	v_exp_f32_e32 v99, v99
	v_and_b32_e32 v101, 0xffff0000, v96
	s_add_i32 s60, s60, 64
	v_mul_f32_e64 v98, v98, s48
	v_mul_f32_e64 v99, v99, s48
	s_nop 0
	v_mul_f32_e64 v98, v98, v100
	v_mul_f32_e64 v99, v99, v101
	v_lshlrev_b32_e32 v100, 16, v97
	v_cvt_pk_bf16_f32 v96, v98, v99
	v_mul_f32_e32 v98, 0x3fb8aa3b, v144
	v_mul_f32_e32 v99, 0x3fb8aa3b, v145
	v_exp_f32_e32 v98, v98
	v_exp_f32_e32 v99, v99
	v_and_b32_e32 v101, 0xffff0000, v97
	v_mul_f32_e64 v98, v98, s48
	v_mul_f32_e64 v99, v99, s48
	s_nop 0
	v_mul_f32_e64 v98, v98, v100
	v_mul_f32_e64 v99, v99, v101
	s_nop 0
	v_cvt_pk_bf16_f32 v97, v98, v99
	ds_write_b128 v184, v[94:97] offset:38912
	ds_read_b128 v[94:97], v206 offset:6144
	ds_read_b128 v[98:101], v206 offset:6160
	s_waitcnt lgkmcnt(1)
	v_mul_f32_e32 v107, 0xbfb8aa3b, v94
	v_exp_f32_e32 v108, v107
	v_mul_f32_e32 v107, 0xbfb8aa3b, v95
	v_exp_f32_e32 v109, v107
	v_mul_f32_e32 v107, 0xbfb8aa3b, v96
	v_mul_f32_e64 v108, v108, v138
	v_mul_f32_e64 v109, v109, v139
	s_nop 0
	v_cvt_pk_bf16_f32 v90, v108, v109
	v_exp_f32_e32 v108, v107
	v_mul_f32_e32 v107, 0xbfb8aa3b, v97
	v_exp_f32_e32 v109, v107
	v_lshlrev_b32_e32 v138, 16, v91
	v_and_b32_e32 v139, 0xffff0000, v91
	s_waitcnt lgkmcnt(0)
	v_mul_f32_e32 v107, 0xbfb8aa3b, v98
	v_mul_f32_e64 v108, v108, v138
	v_mul_f32_e64 v109, v109, v139
	v_lshlrev_b32_e32 v138, 16, v92
	v_cvt_pk_bf16_f32 v91, v108, v109
	v_exp_f32_e32 v108, v107
	v_mul_f32_e32 v107, 0xbfb8aa3b, v99
	v_exp_f32_e32 v109, v107
	v_and_b32_e32 v139, 0xffff0000, v92
	v_mul_f32_e32 v107, 0xbfb8aa3b, v100
	v_mul_f32_e64 v108, v108, v138
	v_mul_f32_e64 v109, v109, v139
	s_nop 0
	v_cvt_pk_bf16_f32 v92, v108, v109
	v_exp_f32_e32 v108, v107
	v_mul_f32_e32 v107, 0xbfb8aa3b, v101
	v_exp_f32_e32 v109, v107
	v_lshlrev_b32_e32 v138, 16, v93
	v_and_b32_e32 v139, 0xffff0000, v93
	v_mul_f32_e64 v108, v108, v138
	v_mul_f32_e64 v109, v109, v139
	s_nop 0
	v_cvt_pk_bf16_f32 v93, v108, v109
	ds_write_b128 v185, v[90:93] offset:56320
	v_mul_f32_e32 v90, 0x3fb8aa3b, v94
	v_mul_f32_e32 v91, 0x3fb8aa3b, v95
	v_exp_f32_e32 v90, v90
	v_exp_f32_e32 v91, v91
	v_lshlrev_b32_e32 v92, 16, v70
	v_and_b32_e32 v93, 0xffff0000, v70
	v_mul_f32_e64 v90, v90, s48
	v_mul_f32_e64 v91, v91, s48
	s_nop 0
	v_mul_f32_e64 v90, v90, v92
	v_mul_f32_e64 v91, v91, v93
	v_lshlrev_b32_e32 v92, 16, v71
	v_cvt_pk_bf16_f32 v70, v90, v91
	v_mul_f32_e32 v90, 0x3fb8aa3b, v96
	v_mul_f32_e32 v91, 0x3fb8aa3b, v97
	v_exp_f32_e32 v90, v90
	v_exp_f32_e32 v91, v91
	v_and_b32_e32 v93, 0xffff0000, v71
	v_mul_f32_e64 v90, v90, s48
	v_mul_f32_e64 v91, v91, s48
	s_nop 0
	v_mul_f32_e64 v90, v90, v92
	v_mul_f32_e64 v91, v91, v93
	v_lshlrev_b32_e32 v92, 16, v72
	v_cvt_pk_bf16_f32 v71, v90, v91
	v_mul_f32_e32 v90, 0x3fb8aa3b, v98
	v_mul_f32_e32 v91, 0x3fb8aa3b, v99
	v_exp_f32_e32 v90, v90
	v_exp_f32_e32 v91, v91
	v_and_b32_e32 v93, 0xffff0000, v72
	v_mul_f32_e64 v90, v90, s48
	v_mul_f32_e64 v91, v91, s48
	s_nop 0
	v_mul_f32_e64 v90, v90, v92
	v_mul_f32_e64 v91, v91, v93
	v_lshlrev_b32_e32 v92, 16, v73
	v_cvt_pk_bf16_f32 v72, v90, v91
	v_mul_f32_e32 v90, 0x3fb8aa3b, v100
	v_mul_f32_e32 v91, 0x3fb8aa3b, v101
	v_exp_f32_e32 v90, v90
	v_exp_f32_e32 v91, v91
	v_and_b32_e32 v93, 0xffff0000, v73
	v_mul_f32_e64 v90, v90, s48
	v_mul_f32_e64 v91, v91, s48
	s_nop 0
	v_mul_f32_e64 v90, v90, v92
	v_mul_f32_e64 v91, v91, v93
	s_nop 0
	v_cvt_pk_bf16_f32 v73, v90, v91
	ds_write_b128 v185, v[70:73] offset:38912
	s_waitcnt vmcnt(3)
	ds_write_b128 v207, v[74:77]
	s_waitcnt vmcnt(2)
	ds_write_b128 v208, v[78:81]
	s_waitcnt vmcnt(1)
	ds_write_b128 v207, v[82:85] offset:16896
	s_waitcnt vmcnt(0)
	ds_write_b128 v209, v[86:89]
	s_waitcnt lgkmcnt(0)
	s_barrier
	ds_read_b128 v[70:73], v210 offset:56320
	ds_read_b128 v[74:77], v183 offset:38912
	ds_read_b128 v[78:81], v210 offset:56384
	ds_read_b128 v[82:85], v183 offset:38976
	s_waitcnt lgkmcnt(2)
	v_mfma_f32_16x16x32_bf16 v[70:73], v[70:73], v[74:77], 0
	s_waitcnt lgkmcnt(0)
	v_mfma_f32_16x16x32_bf16 v[70:73], v[78:81], v[82:85], v[70:73]
	ds_read_b128 v[78:81], v210 offset:56448
	ds_read_b128 v[86:89], v183 offset:39040
	s_waitcnt lgkmcnt(0)
	v_mfma_f32_16x16x32_bf16 v[70:73], v[78:81], v[86:89], v[70:73]
	ds_read_b128 v[78:81], v210 offset:56512
	ds_read_b128 v[90:93], v183 offset:39104
	s_waitcnt lgkmcnt(0)
	v_mfma_f32_16x16x32_bf16 v[70:73], v[78:81], v[90:93], v[70:73]
	v_mov_b32_e32 v78, s93
	s_nop 6
	v_cndmask_b32_e64 v78, v70, v78, s[12:13]
	v_cndmask_b32_e64 v70, v78, v70, s[14:15]
	v_cndmask_b32_e64 v71, 0, v71, s[14:15]
	v_cndmask_b32_e64 v72, v72, 0, s[16:17]
	v_cndmask_b32_e64 v73, v73, 0, s[18:19]
	v_cvt_pk_bf16_f32 v70, v70, v71
	v_cvt_pk_bf16_f32 v71, v72, v73
	ds_write_b64 v211, v[70:71]
	ds_read_b128 v[70:73], v212 offset:56320
	s_waitcnt lgkmcnt(0)
	v_mfma_f32_16x16x32_bf16 v[70:73], v[70:73], v[74:77], 0
	ds_read_b128 v[74:77], v212 offset:56384
	s_waitcnt lgkmcnt(0)
	v_mfma_f32_16x16x32_bf16 v[70:73], v[74:77], v[82:85], v[70:73]
	ds_read_b128 v[74:77], v212 offset:56448
	s_waitcnt lgkmcnt(0)
	v_mfma_f32_16x16x32_bf16 v[70:73], v[74:77], v[86:89], v[70:73]
	ds_read_b128 v[74:77], v212 offset:56512
	s_waitcnt lgkmcnt(0)
	v_mfma_f32_16x16x32_bf16 v[70:73], v[74:77], v[90:93], v[70:73]
	v_mov_b32_e32 v74, s93
	s_nop 6
	v_cndmask_b32_e64 v74, v70, v74, s[20:21]
	v_cndmask_b32_e64 v70, v74, v70, s[22:23]
	v_cndmask_b32_e64 v71, 0, v71, s[22:23]
	v_cndmask_b32_e64 v72, v72, 0, s[24:25]
	v_cndmask_b32_e64 v73, v73, 0, s[26:27]
	v_cvt_pk_bf16_f32 v70, v70, v71
	v_cvt_pk_bf16_f32 v71, v72, v73
	ds_write_b64 v213, v[70:71]
	s_waitcnt lgkmcnt(0)
	s_barrier
	ds_read_b64_tr_b16 v[80:81], v214 offset:2112
	ds_read_b64_tr_b16 v[78:79], v214
	ds_read_b64_tr_b16 v[82:83], v214 offset:32
	ds_read_b64_tr_b16 v[70:71], v214 offset:16896
	ds_read_b64_tr_b16 v[72:73], v214 offset:19008
	ds_read_b64_tr_b16 v[84:85], v214 offset:2144
	ds_read_b64_tr_b16 v[74:75], v214 offset:16928
	ds_read_b64_tr_b16 v[76:77], v214 offset:19040
	ds_read_b128 v[86:89], v215
	ds_read_b128 v[94:97], v215 offset:64
	ds_read_b128 v[138:141], v215 offset:2368
	s_waitcnt lgkmcnt(2)
	v_mfma_f32_16x16x32_bf16 v[90:93], v[78:81], v[86:89], 0
	ds_read_b128 v[146:149], v215 offset:4672
	ds_read_b128 v[156:159], v215 offset:6976
	ds_read2_b64 v[164:167], v219 offset1:4
	v_mfma_f32_16x16x32_bf16 v[86:89], v[82:85], v[86:89], 0
	s_waitcnt lgkmcnt(4)
	v_mfma_f32_16x16x32_bf16 v[90:93], v[70:73], v[94:97], v[90:93]
	v_mfma_f32_16x16x32_bf16 v[86:89], v[74:77], v[94:97], v[86:89]
	ds_read_b128 v[94:97], v215 offset:2304
	s_waitcnt lgkmcnt(0)
	v_mfma_f32_16x16x32_bf16 v[98:101], v[78:81], v[94:97], 0
	v_mfma_f32_16x16x32_bf16 v[94:97], v[82:85], v[94:97], 0
	v_mfma_f32_16x16x32_bf16 v[98:101], v[70:73], v[138:141], v[98:101]
	v_mfma_f32_16x16x32_bf16 v[94:97], v[74:77], v[138:141], v[94:97]
	ds_read_b128 v[138:141], v215 offset:4608
	s_waitcnt lgkmcnt(0)
	v_mfma_f32_16x16x32_bf16 v[142:145], v[78:81], v[138:141], 0
	v_mfma_f32_16x16x32_bf16 v[138:141], v[82:85], v[138:141], 0
	v_mfma_f32_16x16x32_bf16 v[142:145], v[70:73], v[146:149], v[142:145]
	v_mfma_f32_16x16x32_bf16 v[138:141], v[74:77], v[146:149], v[138:141]
	ds_read_b128 v[146:149], v215 offset:6912
	s_waitcnt lgkmcnt(0)
	v_mfma_f32_16x16x32_bf16 v[150:153], v[78:81], v[146:149], 0
	v_mfma_f32_16x16x32_bf16 v[146:149], v[82:85], v[146:149], 0
	v_mfma_f32_16x16x32_bf16 v[150:153], v[70:73], v[156:159], v[150:153]
	v_mfma_f32_16x16x32_bf16 v[146:149], v[74:77], v[156:159], v[146:149]
	v_cvt_pk_bf16_f32 v156, v6, v7
	v_cvt_pk_bf16_f32 v157, v8, v9
	v_cvt_pk_bf16_f32 v158, v22, v23
	v_cvt_pk_bf16_f32 v159, v24, v25
	v_mfma_f32_16x16x32_bf16 v[86:89], v[160:163], v[164:167], v[86:89]
	s_nop 0
	v_mfma_f32_16x16x32_bf16 v[90:93], v[156:159], v[164:167], v[90:93]
	ds_read2_b64 v[164:167], v220 offset0:32 offset1:36
	s_waitcnt lgkmcnt(0)
	v_mfma_f32_16x16x32_bf16 v[98:101], v[156:159], v[164:167], v[98:101]
	v_mfma_f32_16x16x32_bf16 v[94:97], v[160:163], v[164:167], v[94:97]
	ds_read2_b64 v[164:167], v221 offset0:64 offset1:68
	s_waitcnt lgkmcnt(0)
	v_mfma_f32_16x16x32_bf16 v[142:145], v[156:159], v[164:167], v[142:145]
	v_mfma_f32_16x16x32_bf16 v[138:141], v[160:163], v[164:167], v[138:141]
	ds_read2_b64 v[164:167], v222 offset0:96 offset1:100
	s_waitcnt lgkmcnt(0)
	v_mfma_f32_16x16x32_bf16 v[150:153], v[156:159], v[164:167], v[150:153]
	v_cvt_pk_bf16_f32 v156, v14, v15
	v_cvt_pk_bf16_f32 v157, v16, v17
	v_cvt_pk_bf16_f32 v158, v38, v39
	v_mfma_f32_16x16x32_bf16 v[146:149], v[160:163], v[164:167], v[146:149]
	v_cvt_pk_bf16_f32 v159, v40, v41
	v_cvt_pk_bf16_f32 v160, v18, v19
	v_cvt_pk_bf16_f32 v161, v20, v21
	v_cvt_pk_bf16_f32 v162, v42, v43
	v_cvt_pk_bf16_f32 v163, v44, v45
	ds_read2_b64 v[164:167], v219 offset0:8 offset1:12
	s_waitcnt lgkmcnt(0)
	v_mfma_f32_16x16x32_bf16 v[90:93], v[156:159], v[164:167], v[90:93]
	v_mfma_f32_16x16x32_bf16 v[86:89], v[160:163], v[164:167], v[86:89]
	ds_read2_b64 v[164:167], v220 offset0:40 offset1:44
	s_waitcnt lgkmcnt(0)
	v_mfma_f32_16x16x32_bf16 v[98:101], v[156:159], v[164:167], v[98:101]
	v_mfma_f32_16x16x32_bf16 v[94:97], v[160:163], v[164:167], v[94:97]
	ds_read2_b64 v[164:167], v221 offset0:72 offset1:76
	s_waitcnt lgkmcnt(0)
	v_mfma_f32_16x16x32_bf16 v[142:145], v[156:159], v[164:167], v[142:145]
	v_mfma_f32_16x16x32_bf16 v[138:141], v[160:163], v[164:167], v[138:141]
	ds_read2_b64 v[164:167], v222 offset0:104 offset1:108
	s_waitcnt lgkmcnt(0)
	v_mfma_f32_16x16x32_bf16 v[150:153], v[156:159], v[164:167], v[150:153]
	v_cvt_pk_bf16_f32 v156, v30, v31
	v_cvt_pk_bf16_f32 v157, v32, v33
	v_cvt_pk_bf16_f32 v158, v46, v47
	v_mfma_f32_16x16x32_bf16 v[146:149], v[160:163], v[164:167], v[146:149]
	v_cvt_pk_bf16_f32 v159, v48, v49
	v_cvt_pk_bf16_f32 v160, v34, v35
	v_cvt_pk_bf16_f32 v161, v36, v37
	v_cvt_pk_bf16_f32 v162, v54, v55
	v_cvt_pk_bf16_f32 v163, v56, v57
	ds_read2_b64 v[164:167], v219 offset0:16 offset1:20
	s_waitcnt lgkmcnt(0)
	v_mfma_f32_16x16x32_bf16 v[90:93], v[156:159], v[164:167], v[90:93]
	v_mfma_f32_16x16x32_bf16 v[86:89], v[160:163], v[164:167], v[86:89]
	ds_read2_b64 v[164:167], v220 offset0:48 offset1:52
	s_waitcnt lgkmcnt(0)
	v_mfma_f32_16x16x32_bf16 v[98:101], v[156:159], v[164:167], v[98:101]
	v_mfma_f32_16x16x32_bf16 v[94:97], v[160:163], v[164:167], v[94:97]
	ds_read2_b64 v[164:167], v221 offset0:80 offset1:84
	s_waitcnt lgkmcnt(0)
	v_mfma_f32_16x16x32_bf16 v[142:145], v[156:159], v[164:167], v[142:145]
	v_mfma_f32_16x16x32_bf16 v[138:141], v[160:163], v[164:167], v[138:141]
	ds_read2_b64 v[164:167], v222 offset0:112 offset1:116
	s_waitcnt lgkmcnt(0)
	v_mfma_f32_16x16x32_bf16 v[150:153], v[156:159], v[164:167], v[150:153]
	v_cvt_pk_bf16_f32 v156, v50, v51
	v_cvt_pk_bf16_f32 v157, v52, v53
	v_cvt_pk_bf16_f32 v158, v62, v63
	v_mfma_f32_16x16x32_bf16 v[146:149], v[160:163], v[164:167], v[146:149]
	v_cvt_pk_bf16_f32 v159, v64, v65
	v_cvt_pk_bf16_f32 v160, v58, v59
	v_cvt_pk_bf16_f32 v161, v60, v61
	v_cvt_pk_bf16_f32 v162, v66, v67
	v_cvt_pk_bf16_f32 v163, v68, v69
	ds_read2_b64 v[164:167], v219 offset0:24 offset1:28
	s_waitcnt lgkmcnt(0)
	v_mfma_f32_16x16x32_bf16 v[90:93], v[156:159], v[164:167], v[90:93]
	v_mfma_f32_16x16x32_bf16 v[86:89], v[160:163], v[164:167], v[86:89]
	ds_read2_b64 v[164:167], v220 offset0:56 offset1:60
	s_nop 5
	v_cvt_pk_bf16_f32 v90, v90, v91
	v_cvt_pk_bf16_f32 v91, v92, v93
	s_waitcnt lgkmcnt(0)
	v_mfma_f32_16x16x32_bf16 v[98:101], v[156:159], v[164:167], v[98:101]
	v_lshl_add_u64 v[92:93], s[64:65], 0, v[118:119]
	v_cvt_pk_bf16_f32 v86, v86, v87
	v_cvt_pk_bf16_f32 v87, v88, v89
	v_mfma_f32_16x16x32_bf16 v[94:97], v[160:163], v[164:167], v[94:97]
	ds_read2_b64 v[164:167], v221 offset0:88 offset1:92
	v_add_co_u32_e32 v88, vcc, s61, v92
	s_waitcnt lgkmcnt(0)
	v_mfma_f32_16x16x32_bf16 v[142:145], v[156:159], v[164:167], v[142:145]
	global_store_dwordx2 v[92:93], v[86:87], off offset:32
	v_cvt_pk_bf16_f32 v86, v98, v99
	v_cvt_pk_bf16_f32 v87, v100, v101
	v_mfma_f32_16x16x32_bf16 v[138:141], v[160:163], v[164:167], v[138:141]
	ds_read2_b64 v[164:167], v222 offset0:120 offset1:124
	v_addc_co_u32_e32 v89, vcc, 0, v93, vcc
	global_store_dwordx2 v[88:89], v[86:87], off
	v_cvt_pk_bf16_f32 v86, v94, v95
	v_cvt_pk_bf16_f32 v87, v96, v97
	s_mov_b32 s61, 0x10000
	s_waitcnt lgkmcnt(0)
	v_mfma_f32_16x16x32_bf16 v[150:153], v[156:159], v[164:167], v[150:153]
	global_store_dwordx2 v[88:89], v[86:87], off offset:32
	v_add_co_u32_e32 v88, vcc, s61, v92
	v_mfma_f32_16x16x32_bf16 v[146:149], v[160:163], v[164:167], v[146:149]
	v_cvt_pk_bf16_f32 v86, v142, v143
	v_cvt_pk_bf16_f32 v87, v144, v145
	v_addc_co_u32_e32 v89, vcc, 0, v93, vcc
	global_store_dwordx2 v[88:89], v[86:87], off
	v_cvt_pk_bf16_f32 v86, v138, v139
	v_cvt_pk_bf16_f32 v87, v140, v141
	global_store_dwordx2 v[88:89], v[86:87], off offset:32
	v_add_co_u32_e32 v88, vcc, s81, v92
	v_cvt_pk_bf16_f32 v86, v150, v151
	v_cvt_pk_bf16_f32 v87, v152, v153
	v_addc_co_u32_e32 v89, vcc, 0, v93, vcc
	global_store_dwordx2 v[88:89], v[86:87], off
	v_cvt_pk_bf16_f32 v86, v146, v147
	v_cvt_pk_bf16_f32 v87, v148, v149
	global_store_dwordx2 v[92:93], v[90:91], off
	global_store_dwordx2 v[88:89], v[86:87], off offset:32
	ds_read_b64_tr_b16 v[88:89], v217 offset:57408
	ds_read_b64_tr_b16 v[86:87], v217 offset:56320
	ds_read_b64_tr_b16 v[90:91], v217 offset:56352
	s_waitcnt lgkmcnt(1)
	v_mfma_f32_16x16x32_bf16 v[6:9], v[86:89], v[78:81], v[6:9]
	s_add_u32 s64, s64, 0x20000
	s_addc_u32 s65, s65, 0
	s_add_i32 s95, s95, 1
	v_mfma_f32_16x16x32_bf16 v[10:13], v[86:89], v[82:85], v[10:13]
	ds_read_b64_tr_b16 v[86:87], v217 offset:65024
	ds_read_b64_tr_b16 v[88:89], v218 offset:57408
	ds_read_b64_tr_b16 v[94:95], v218 offset:57440
	ds_read_b64_tr_b16 v[92:93], v217 offset:57440
	s_cmp_lg_u32 s74, 0x300000
	s_waitcnt lgkmcnt(2)
	v_mfma_f32_16x16x32_bf16 v[6:9], v[86:89], v[70:73], v[6:9]
	v_mfma_f32_16x16x32_bf16 v[10:13], v[86:89], v[74:77], v[10:13]
	s_waitcnt lgkmcnt(0)
	v_mfma_f32_16x16x32_bf16 v[22:25], v[90:93], v[78:81], v[22:25]
	v_mfma_f32_16x16x32_bf16 v[26:29], v[90:93], v[82:85], v[26:29]
	ds_read_b64_tr_b16 v[92:93], v217 offset:65056
	ds_read_b64_tr_b16 v[86:87], v217 offset:56384
	ds_read_b64_tr_b16 v[88:89], v217 offset:57472
	s_waitcnt lgkmcnt(0)
	v_mfma_f32_16x16x32_bf16 v[14:17], v[86:89], v[78:81], v[14:17]
	v_mfma_f32_16x16x32_bf16 v[18:21], v[86:89], v[82:85], v[18:21]
	ds_read_b64_tr_b16 v[86:87], v217 offset:65088
	ds_read_b64_tr_b16 v[88:89], v218 offset:57472
	s_waitcnt lgkmcnt(0)
	v_mfma_f32_16x16x32_bf16 v[14:17], v[86:89], v[70:73], v[14:17]
	v_mfma_f32_16x16x32_bf16 v[18:21], v[86:89], v[74:77], v[18:21]
	ds_read_b64_tr_b16 v[86:87], v217 offset:56416
	ds_read_b64_tr_b16 v[88:89], v217 offset:57504
	s_waitcnt lgkmcnt(0)
	v_mfma_f32_16x16x32_bf16 v[38:41], v[86:89], v[78:81], v[38:41]
	v_mfma_f32_16x16x32_bf16 v[42:45], v[86:89], v[82:85], v[42:45]
	ds_read_b64_tr_b16 v[86:87], v217 offset:65120
	ds_read_b64_tr_b16 v[88:89], v218 offset:57504
	s_waitcnt lgkmcnt(0)
	v_mfma_f32_16x16x32_bf16 v[38:41], v[86:89], v[70:73], v[38:41]
	v_mfma_f32_16x16x32_bf16 v[42:45], v[86:89], v[74:77], v[42:45]
	ds_read_b64_tr_b16 v[86:87], v217 offset:56448
	ds_read_b64_tr_b16 v[88:89], v217 offset:57536
	s_waitcnt lgkmcnt(0)
	v_mfma_f32_16x16x32_bf16 v[30:33], v[86:89], v[78:81], v[30:33]
	v_mfma_f32_16x16x32_bf16 v[34:37], v[86:89], v[82:85], v[34:37]
	ds_read_b64_tr_b16 v[86:87], v217 offset:65152
	ds_read_b64_tr_b16 v[88:89], v218 offset:57536
	s_waitcnt lgkmcnt(0)
	v_mfma_f32_16x16x32_bf16 v[30:33], v[86:89], v[70:73], v[30:33]
	v_mfma_f32_16x16x32_bf16 v[34:37], v[86:89], v[74:77], v[34:37]
	ds_read_b64_tr_b16 v[86:87], v217 offset:56480
	ds_read_b64_tr_b16 v[88:89], v217 offset:57568
	s_waitcnt lgkmcnt(0)
	v_mfma_f32_16x16x32_bf16 v[46:49], v[86:89], v[78:81], v[46:49]
	v_mfma_f32_16x16x32_bf16 v[54:57], v[86:89], v[82:85], v[54:57]
	ds_read_b64_tr_b16 v[86:87], v217 offset:65184
	ds_read_b64_tr_b16 v[88:89], v218 offset:57568
	s_waitcnt lgkmcnt(0)
	v_mfma_f32_16x16x32_bf16 v[46:49], v[86:89], v[70:73], v[46:49]
	v_mfma_f32_16x16x32_bf16 v[54:57], v[86:89], v[74:77], v[54:57]
	ds_read_b64_tr_b16 v[86:87], v217 offset:56512
	ds_read_b64_tr_b16 v[88:89], v217 offset:57600
	s_waitcnt lgkmcnt(0)
	v_mfma_f32_16x16x32_bf16 v[50:53], v[86:89], v[78:81], v[50:53]
	v_mfma_f32_16x16x32_bf16 v[58:61], v[86:89], v[82:85], v[58:61]
	ds_read_b64_tr_b16 v[86:87], v217 offset:65216
	ds_read_b64_tr_b16 v[88:89], v218 offset:57600
	s_waitcnt lgkmcnt(0)
	v_mfma_f32_16x16x32_bf16 v[50:53], v[86:89], v[70:73], v[50:53]
	v_mfma_f32_16x16x32_bf16 v[58:61], v[86:89], v[74:77], v[58:61]
	ds_read_b64_tr_b16 v[86:87], v217 offset:56544
	ds_read_b64_tr_b16 v[88:89], v217 offset:57632
	s_waitcnt lgkmcnt(0)
	v_mfma_f32_16x16x32_bf16 v[62:65], v[86:89], v[78:81], v[62:65]
	ds_read_b64_tr_b16 v[78:79], v217 offset:65248
	ds_read_b64_tr_b16 v[80:81], v218 offset:57632
	v_mfma_f32_16x16x32_bf16 v[66:69], v[86:89], v[82:85], v[66:69]
	v_mfma_f32_16x16x32_bf16 v[22:25], v[92:95], v[70:73], v[22:25]
	s_waitcnt lgkmcnt(0)
	v_mfma_f32_16x16x32_bf16 v[62:65], v[78:81], v[70:73], v[62:65]
	v_lshl_add_u32 v70, s49, 9, v182
	v_mfma_f32_16x16x32_bf16 v[26:29], v[92:95], v[74:77], v[26:29]
	v_mfma_f32_16x16x32_bf16 v[66:69], v[78:81], v[74:77], v[66:69]
	ds_read_b128 v[72:75], v70 offset:4096
	s_waitcnt lgkmcnt(0)
	s_nop 0
	v_mov_b32_e32 v72, v72
	s_nop 0
	v_mov_b32_e32 v73, v73
	s_nop 0
	v_mov_b32_e32 v74, v74
	s_nop 0
	v_mov_b32_e32 v75, v75
	v_mul_f32_e64 v6, v6, v72
	v_mul_f32_e64 v7, v7, v73
	v_mul_f32_e64 v10, v10, v72
	v_mul_f32_e64 v11, v11, v73
	v_mul_f32_e64 v8, v8, v74
	v_mul_f32_e64 v9, v9, v75
	v_mul_f32_e64 v12, v12, v74
	v_mul_f32_e64 v13, v13, v75
	ds_read_b128 v[72:75], v70 offset:4160
	s_waitcnt lgkmcnt(0)
	s_nop 0
	v_mov_b32_e32 v72, v72
	s_nop 0
	v_mov_b32_e32 v73, v73
	s_nop 0
	v_mov_b32_e32 v74, v74
	s_nop 0
	v_mov_b32_e32 v75, v75
	v_mul_f32_e64 v22, v22, v72
	v_mul_f32_e64 v23, v23, v73
	v_mul_f32_e64 v26, v26, v72
	v_mul_f32_e64 v27, v27, v73
	v_mul_f32_e64 v24, v24, v74
	v_mul_f32_e64 v25, v25, v75
	v_mul_f32_e64 v28, v28, v74
	v_mul_f32_e64 v29, v29, v75
	ds_read_b128 v[72:75], v70 offset:4224
	s_waitcnt lgkmcnt(0)
	s_nop 0
	v_mov_b32_e32 v72, v72
	s_nop 0
	v_mov_b32_e32 v73, v73
	s_nop 0
	v_mov_b32_e32 v74, v74
	s_nop 0
	v_mov_b32_e32 v75, v75
	v_mul_f32_e64 v14, v14, v72
	v_mul_f32_e64 v15, v15, v73
	v_mul_f32_e64 v18, v18, v72
	v_mul_f32_e64 v19, v19, v73
	v_mul_f32_e64 v16, v16, v74
	v_mul_f32_e64 v17, v17, v75
	v_mul_f32_e64 v20, v20, v74
	v_mul_f32_e64 v21, v21, v75
	ds_read_b128 v[72:75], v70 offset:4288
	s_waitcnt lgkmcnt(0)
	s_nop 0
	v_mov_b32_e32 v72, v72
	s_nop 0
	v_mov_b32_e32 v73, v73
	s_nop 0
	v_mov_b32_e32 v74, v74
	s_nop 0
	v_mov_b32_e32 v75, v75
	v_mul_f32_e64 v38, v38, v72
	v_mul_f32_e64 v39, v39, v73
	v_mul_f32_e64 v42, v42, v72
	v_mul_f32_e64 v43, v43, v73
	v_mul_f32_e64 v40, v40, v74
	v_mul_f32_e64 v41, v41, v75
	v_mul_f32_e64 v44, v44, v74
	v_mul_f32_e64 v45, v45, v75
	ds_read_b128 v[72:75], v70 offset:4352
	s_waitcnt lgkmcnt(0)
	s_nop 0
	v_mov_b32_e32 v72, v72
	s_nop 0
	v_mov_b32_e32 v73, v73
	s_nop 0
	v_mov_b32_e32 v74, v74
	s_nop 0
	v_mov_b32_e32 v75, v75
	v_mul_f32_e64 v30, v30, v72
	v_mul_f32_e64 v31, v31, v73
	v_mul_f32_e64 v34, v34, v72
	v_mul_f32_e64 v35, v35, v73
	v_mul_f32_e64 v32, v32, v74
	v_mul_f32_e64 v33, v33, v75
	v_mul_f32_e64 v36, v36, v74
	v_mul_f32_e64 v37, v37, v75
	ds_read_b128 v[72:75], v70 offset:4416
	s_waitcnt lgkmcnt(0)
	s_nop 0
	v_mov_b32_e32 v72, v72
	s_nop 0
	v_mov_b32_e32 v73, v73
	s_nop 0
	v_mov_b32_e32 v74, v74
	s_nop 0
	v_mov_b32_e32 v75, v75
	v_mul_f32_e64 v46, v46, v72
	v_mul_f32_e64 v47, v47, v73
	v_mul_f32_e64 v54, v54, v72
	v_mul_f32_e64 v55, v55, v73
	v_mul_f32_e64 v48, v48, v74
	v_mul_f32_e64 v49, v49, v75
	v_mul_f32_e64 v56, v56, v74
	v_mul_f32_e64 v57, v57, v75
	ds_read_b128 v[72:75], v70 offset:4480
	s_waitcnt lgkmcnt(0)
	s_nop 0
	v_mov_b32_e32 v72, v72
	s_nop 0
	v_mov_b32_e32 v73, v73
	s_nop 0
	v_mov_b32_e32 v74, v74
	s_nop 0
	v_mov_b32_e32 v75, v75
	v_mul_f32_e64 v50, v50, v72
	v_mul_f32_e64 v51, v51, v73
	v_mul_f32_e64 v58, v58, v72
	v_mul_f32_e64 v59, v59, v73
	ds_read_b128 v[70:73], v70 offset:4544
	v_mul_f32_e64 v52, v52, v74
	v_mul_f32_e64 v53, v53, v75
	v_mul_f32_e64 v60, v60, v74
	v_mul_f32_e64 v61, v61, v75
	s_waitcnt lgkmcnt(0)
	s_nop 0
	s_nop 0
	s_nop 0
	s_nop 0
	s_nop 0
	s_nop 0
	s_nop 0
	s_nop 0
	v_mul_f32_e64 v62, v62, v70
	v_mul_f32_e64 v63, v63, v71
	v_mul_f32_e64 v66, v66, v70
	v_mul_f32_e64 v67, v67, v71
	v_mul_f32_e64 v64, v64, v72
	v_mul_f32_e64 v65, v65, v73
	v_mul_f32_e64 v68, v68, v72
	v_mul_f32_e64 v69, v69, v73
	s_cbranch_scc0 .LBB0_2275

.LBB0_2282:
	s_or_b64 exec, exec, s[60:61]
	s_waitcnt lgkmcnt(0)
	s_barrier
	ds_read_b128 v[140:143], v188
	ds_read_b128 v[146:149], v188 offset:16
	s_waitcnt vmcnt(8)
	v_lshlrev_b32_e32 v160, 16, v170
	v_and_b32_e32 v161, 0xffff0000, v170
	v_lshlrev_b32_e32 v170, 16, v171
	s_waitcnt lgkmcnt(1)
	v_mov_b32_e32 v81, v142
	v_lshlrev_b32_e32 v142, 16, v172
	v_mov_b32_e32 v80, v141
	v_mov_b32_e32 v141, v143
	v_and_b32_e32 v143, 0xffff0000, v172
	v_mul_f32_e32 v0, 0xbfb8aa3b, v142
	v_exp_f32_e32 v0, v0
	v_mul_f32_e32 v135, 0xbfb8aa3b, v143
	v_exp_f32_e32 v135, v135
	v_add_f32_e64 v80, v80, v140
	v_add_f32_e64 v81, v81, v141
	s_waitcnt lgkmcnt(0)
	v_mov_b32_e32 v140, v148
	v_mov_b32_e32 v141, v146
	v_mov_b32_e32 v146, v149
	v_add_f32_e32 v0, 1.0, v0
	v_add_f32_e64 v150, v140, v146
	v_add_f32_e64 v151, v141, v147
	v_rcp_f32_e32 v140, v0
	v_add_f32_e32 v0, 1.0, v135
	v_lshlrev_b32_e32 v146, 16, v173
	v_rcp_f32_e32 v141, v0
	v_and_b32_e32 v147, 0xffff0000, v173
	v_mul_f32_e32 v0, 0xbfb8aa3b, v146
	v_exp_f32_e32 v0, v0
	v_mul_f32_e32 v135, 0xbfb8aa3b, v147
	v_exp_f32_e32 v135, v135
	v_mul_f32_e64 v152, v140, v142
	v_mul_f32_e64 v153, v141, v143
	v_add_f32_e32 v0, 1.0, v0
	v_rcp_f32_e32 v140, v0
	v_add_f32_e32 v0, 1.0, v135
	v_rcp_f32_e32 v141, v0
	v_mul_f32_e32 v0, 0xbfb8aa3b, v160
	v_exp_f32_e32 v0, v0
	v_mul_f32_e32 v135, 0xbfb8aa3b, v161
	v_exp_f32_e32 v135, v135
	v_mul_f32_e64 v172, v140, v146
	v_mul_f32_e64 v173, v141, v147
	ds_read_b128 v[140:143], v188 offset:512
	ds_read_b128 v[146:149], v188 offset:528
	v_add_f32_e32 v0, 1.0, v0
	v_rcp_f32_e32 v228, v0
	v_add_f32_e32 v0, 1.0, v135
	v_rcp_f32_e32 v229, v0
	v_mul_f32_e32 v0, 0xbfb8aa3b, v170
	v_and_b32_e32 v171, 0xffff0000, v171
	s_waitcnt lgkmcnt(1)
	v_mov_b32_e32 v232, v141
	v_mov_b32_e32 v233, v142
	v_mov_b32_e32 v141, v143
	v_exp_f32_e32 v0, v0
	v_mul_f32_e32 v135, 0xbfb8aa3b, v171
	v_add_f32_e64 v140, v232, v140
	v_add_f32_e64 v141, v233, v141
	s_waitcnt lgkmcnt(0)
	v_mov_b32_e32 v142, v148
	v_mov_b32_e32 v143, v146
	v_mov_b32_e32 v146, v149
	v_exp_f32_e32 v135, v135
	v_add_f32_e64 v142, v142, v146
	v_add_f32_e64 v143, v143, v147
	v_mov_b32_e32 v146, v140
	v_mov_b32_e32 v147, v80
	v_mov_b32_e32 v80, v141
	v_add_f32_e64 v80, v146, v80
	v_add_f32_e64 v81, v147, v81
	v_mov_b32_e32 v140, v143
	v_mov_b32_e32 v141, v151
	v_add_f32_e64 v80, v80, v140
	v_add_f32_e64 v81, v81, v141
	v_mov_b32_e32 v143, v150
	s_mov_b32 s60, 0x358637bd
	v_add_f32_e32 v0, 1.0, v0
	v_add_f32_e64 v140, v142, v80
	v_add_f32_e64 v141, v143, v81
	v_mov_b64_e32 v[80:81], s[60:61]
	v_rcp_f32_e32 v230, v0
	v_add_f32_e32 v0, 1.0, v135
	v_fma_f32 v140, v140, s50, v80
	v_fma_f32 v141, v141, s50, v80
	v_rcp_f32_e32 v231, v0
	v_mul_f32_e32 v0, 0x4b800000, v141
	v_cmp_gt_f32_e32 vcc, s80, v141
	v_mul_f32_e64 v146, v228, v160
	v_mul_f32_e64 v147, v229, v161
	v_mul_f32_e64 v148, v230, v170
	v_mul_f32_e64 v149, v231, v171
	v_cndmask_b32_e32 v0, v141, v0, vcc
	v_rsq_f32_e32 v0, v0
	v_lshl_add_u64 v[142:143], s[54:55], 0, v[118:119]
	s_waitcnt vmcnt(4)
	v_lshlrev_b32_e32 v150, 16, v163
	v_and_b32_e32 v151, 0xffff0000, v163
	v_mul_f32_e32 v135, 0x45800000, v0
	v_cndmask_b32_e32 v0, v0, v135, vcc
	v_mul_f32_e64 v106, v106, v0
	v_mul_f32_e64 v107, v107, v0
	v_mul_f32_e64 v108, v108, v0
	v_mul_f32_e64 v109, v109, v0
	v_mul_f32_e64 v102, v102, v0
	v_mul_f32_e64 v103, v103, v0
	v_mul_f32_e64 v104, v104, v0
	v_mul_f32_e64 v105, v105, v0
	v_mul_f32_e32 v0, 0x4b800000, v140
	v_cmp_gt_f32_e32 vcc, s80, v140
	s_waitcnt vmcnt(0)
	v_mul_f32_e64 v102, v70, v102
	v_mul_f32_e64 v103, v71, v103
	v_mul_f32_e64 v104, v72, v104
	v_mul_f32_e64 v105, v73, v105
	v_cndmask_b32_e32 v0, v140, v0, vcc
	v_mul_f32_e64 v102, v146, v102
	v_mul_f32_e64 v103, v147, v103
	v_mul_f32_e64 v104, v148, v104
	v_mul_f32_e64 v105, v149, v105
	v_rsq_f32_e32 v0, v0
	v_cvt_pk_bf16_f32 v102, v102, v103
	v_cvt_pk_bf16_f32 v103, v104, v105
	global_store_dwordx2 v[142:143], v[102:103], off offset:32
	v_lshlrev_b32_e32 v102, 16, v168
	v_mul_f32_e32 v103, 0xbfb8aa3b, v102
	v_exp_f32_e32 v104, v103
	v_mul_f32_e32 v103, 0x45800000, v0
	v_cndmask_b32_e32 v0, v0, v103, vcc
	v_and_b32_e32 v103, 0xffff0000, v168
	v_mul_f32_e32 v105, 0xbfb8aa3b, v103
	v_exp_f32_e32 v105, v105
	v_mul_f32_e64 v106, v74, v106
	v_mul_f32_e64 v107, v75, v107
	v_mul_f32_e64 v108, v76, v108
	v_mul_f32_e64 v109, v77, v109
	v_mul_f32_e64 v106, v152, v106
	v_mul_f32_e64 v107, v153, v107
	v_mul_f32_e64 v108, v172, v108
	v_mul_f32_e64 v109, v173, v109
	v_cvt_pk_bf16_f32 v106, v106, v107
	v_cvt_pk_bf16_f32 v107, v108, v109
	v_lshlrev_b32_e32 v108, 16, v169
	v_and_b32_e32 v109, 0xffff0000, v169
	v_add_f32_e32 v104, 1.0, v104
	v_add_f32_e32 v105, 1.0, v105
	v_mul_f32_e32 v135, 0xbfb8aa3b, v108
	v_mul_f32_e32 v137, 0xbfb8aa3b, v109
	v_rcp_f32_e32 v104, v104
	v_rcp_f32_e32 v105, v105
	v_exp_f32_e32 v135, v135
	v_exp_f32_e32 v137, v137
	global_store_dwordx2 v[142:143], v[106:107], off
	v_mul_f32_e64 v102, v104, v102
	v_mul_f32_e64 v103, v105, v103
	v_add_f32_e32 v104, 1.0, v135
	v_add_f32_e32 v105, 1.0, v137
	v_rcp_f32_e32 v104, v104
	v_rcp_f32_e32 v105, v105
	v_mul_f32_e64 v106, v158, v0
	v_mul_f32_e64 v107, v159, v0
	v_mul_f32_e64 v100, v100, v0
	v_mul_f32_e64 v101, v101, v0
	v_mul_f32_e64 v106, v74, v106
	v_mul_f32_e64 v107, v75, v107
	v_mul_f32_e64 v100, v76, v100
	v_mul_f32_e64 v101, v77, v101
	v_mul_f32_e64 v104, v104, v108
	v_mul_f32_e64 v105, v105, v109
	v_mul_f32_e64 v102, v102, v106
	v_mul_f32_e64 v103, v103, v107
	v_mul_f32_e64 v100, v104, v100
	v_mul_f32_e64 v101, v105, v101
	v_cvt_pk_bf16_f32 v102, v102, v103
	v_cvt_pk_bf16_f32 v103, v100, v101
	v_lshlrev_b32_e32 v100, 16, v166
	v_mul_f32_e32 v101, 0xbfb8aa3b, v100
	v_exp_f32_e32 v106, v101
	v_lshl_add_u64 v[104:105], s[54:55], 0, v[122:123]
	v_and_b32_e32 v101, 0xffff0000, v166
	global_store_dwordx2 v[104:105], v[102:103], off
	v_mul_f32_e32 v103, 0xbfb8aa3b, v101
	v_exp_f32_e32 v103, v103
	v_lshlrev_b32_e32 v104, 16, v167
	v_and_b32_e32 v105, 0xffff0000, v167
	v_add_f32_e32 v102, 1.0, v106
	v_add_f32_e32 v103, 1.0, v103
	v_mul_f32_e32 v106, 0xbfb8aa3b, v104
	v_mul_f32_e32 v107, 0xbfb8aa3b, v105
	v_rcp_f32_e32 v102, v102
	v_rcp_f32_e32 v103, v103
	v_exp_f32_e32 v106, v106
	v_exp_f32_e32 v107, v107
	v_mul_f32_e64 v98, v98, v0
	v_mul_f32_e64 v99, v99, v0
	v_mul_f32_e64 v100, v102, v100
	v_mul_f32_e64 v101, v103, v101
	v_add_f32_e32 v102, 1.0, v106
	v_add_f32_e32 v103, 1.0, v107
	v_rcp_f32_e32 v102, v102
	v_rcp_f32_e32 v103, v103
	v_mul_f32_e64 v98, v70, v98
	v_mul_f32_e64 v99, v71, v99
	v_mul_f32_e64 v96, v96, v0
	v_mul_f32_e64 v97, v97, v0
	v_mul_f32_e64 v98, v100, v98
	v_mul_f32_e64 v99, v101, v99
	v_mul_f32_e64 v96, v72, v96
	v_mul_f32_e64 v97, v73, v97
	v_mul_f32_e64 v100, v102, v104
	v_mul_f32_e64 v101, v103, v105
	v_cvt_pk_bf16_f32 v102, v98, v99
	v_mul_f32_e64 v100, v100, v96
	v_mul_f32_e64 v101, v101, v97
	ds_read_b128 v[96:99], v188 offset:1024
	v_cvt_pk_bf16_f32 v103, v100, v101
	v_lshl_add_u64 v[100:101], s[54:55], 0, v[124:125]
	global_store_dwordx2 v[100:101], v[102:103], off
	ds_read_b128 v[100:103], v188 offset:1040
	s_waitcnt lgkmcnt(1)
	v_mov_b32_e32 v105, v98
	v_lshlrev_b32_e32 v98, 16, v164
	v_mov_b32_e32 v104, v97
	v_mov_b32_e32 v97, v99
	v_and_b32_e32 v99, 0xffff0000, v164
	v_mul_f32_e32 v0, 0xbfb8aa3b, v98
	v_add_f32_e64 v104, v104, v96
	v_add_f32_e64 v105, v105, v97
	v_exp_f32_e32 v0, v0
	v_mul_f32_e32 v97, 0xbfb8aa3b, v99
	s_waitcnt lgkmcnt(0)
	v_mov_b32_e32 v96, v102
	v_exp_f32_e32 v102, v97
	v_lshlrev_b32_e32 v108, 16, v165
	v_mov_b32_e32 v97, v100
	v_add_f32_e32 v0, 1.0, v0
	v_and_b32_e32 v109, 0xffff0000, v165
	v_mul_f32_e32 v100, 0xbfb8aa3b, v108
	v_rcp_f32_e32 v106, v0
	v_add_f32_e32 v0, 1.0, v102
	v_exp_f32_e32 v100, v100
	v_mul_f32_e32 v102, 0xbfb8aa3b, v109
	v_exp_f32_e32 v102, v102
	v_rcp_f32_e32 v107, v0
	v_add_f32_e32 v0, 1.0, v100
	v_rcp_f32_e32 v140, v0
	v_add_f32_e32 v0, 1.0, v102
	v_rcp_f32_e32 v141, v0
	v_mov_b32_e32 v100, v103
	v_add_f32_e64 v142, v96, v100
	v_add_f32_e64 v143, v97, v101
	v_mul_f32_e64 v106, v106, v98
	v_mul_f32_e64 v107, v107, v99
	v_mul_f32_e64 v108, v140, v108
	v_mul_f32_e64 v109, v141, v109
	v_lshlrev_b32_e32 v140, 16, v162
	v_and_b32_e32 v141, 0xffff0000, v162
	v_mul_f32_e32 v0, 0xbfb8aa3b, v140
	v_exp_f32_e32 v0, v0
	v_mul_f32_e32 v96, 0xbfb8aa3b, v141
	v_exp_f32_e32 v96, v96
	v_lshl_add_u64 v[146:147], s[54:55], 0, v[126:127]
	v_add_f32_e32 v0, 1.0, v0
	v_rcp_f32_e32 v148, v0
	v_add_f32_e32 v0, 1.0, v96
	v_rcp_f32_e32 v149, v0
	v_mul_f32_e32 v0, 0xbfb8aa3b, v150
	v_exp_f32_e32 v0, v0
	v_mul_f32_e32 v96, 0xbfb8aa3b, v151
	v_exp_f32_e32 v100, v96
	ds_read_b128 v[96:99], v188 offset:1536
	v_add_f32_e32 v0, 1.0, v0
	v_rcp_f32_e32 v152, v0
	v_add_f32_e32 v0, 1.0, v100
	ds_read_b128 v[100:103], v188 offset:1552
	s_waitcnt lgkmcnt(1)
	v_mov_b32_e32 v158, v97
	v_mov_b32_e32 v159, v98
	v_mov_b32_e32 v97, v99
	v_add_f32_e64 v96, v158, v96
	v_add_f32_e64 v97, v159, v97
	s_waitcnt lgkmcnt(0)
	v_mov_b32_e32 v98, v102
	v_mov_b32_e32 v99, v100
	v_mov_b32_e32 v100, v103
	v_add_f32_e64 v98, v98, v100
	v_add_f32_e64 v99, v99, v101
	v_mov_b32_e32 v100, v96
	v_mov_b32_e32 v101, v104
	v_mov_b32_e32 v104, v97
	v_add_f32_e64 v96, v100, v104
	v_add_f32_e64 v97, v101, v105
	v_mov_b32_e32 v100, v99
	v_mov_b32_e32 v101, v143
	v_add_f32_e64 v96, v96, v100
	v_add_f32_e64 v97, v97, v101
	v_mov_b32_e32 v99, v142
	v_add_f32_e64 v96, v98, v96
	v_add_f32_e64 v97, v99, v97
	v_rcp_f32_e32 v153, v0
	v_fma_f32 v81, v97, s50, v80
	v_fma_f32 v80, v96, s50, v80
	v_mul_f32_e64 v96, v148, v140
	v_mul_f32_e64 v97, v149, v141
	v_mul_f32_e32 v0, 0x4b800000, v81
	v_cmp_gt_f32_e32 vcc, s80, v81
	v_mul_f32_e64 v170, v152, v150
	v_mul_f32_e64 v171, v153, v151
	v_lshl_add_u64 v[172:173], s[54:55], 0, v[128:129]
	v_cndmask_b32_e32 v0, v81, v0, vcc
	v_rsq_f32_e32 v0, v0
	s_add_i32 s74, s74, 1
	s_add_u32 s58, s58, 0xfffa0000
	s_addc_u32 s59, s59, -1
	v_mul_f32_e32 v81, 0x45800000, v0
	v_cndmask_b32_e32 v0, v0, v81, vcc
	v_mul_f32_e64 v90, v90, v0
	v_mul_f32_e64 v91, v91, v0
	v_mul_f32_e64 v94, v94, v0
	v_mul_f32_e64 v95, v95, v0
	v_mul_f32_e64 v90, v74, v90
	v_mul_f32_e64 v91, v75, v91
	v_mul_f32_e64 v94, v76, v94
	v_mul_f32_e64 v95, v77, v95
	v_mul_f32_e64 v90, v106, v90
	v_mul_f32_e64 v91, v107, v91
	v_mul_f32_e64 v94, v108, v94
	v_mul_f32_e64 v95, v109, v95
	v_cvt_pk_bf16_f32 v90, v90, v91
	v_cvt_pk_bf16_f32 v91, v94, v95
	global_store_dwordx2 v[146:147], v[90:91], off
	v_mul_f32_e64 v90, v92, v0
	v_mul_f32_e64 v91, v93, v0
	v_mul_f32_e64 v88, v88, v0
	v_mul_f32_e64 v89, v89, v0
	v_mul_f32_e32 v0, 0x4b800000, v80
	v_cmp_gt_f32_e32 vcc, s80, v80
	v_mul_f32_e64 v90, v70, v90
	v_mul_f32_e64 v91, v71, v91
	v_mul_f32_e64 v228, v72, v88
	v_mul_f32_e64 v229, v73, v89
	v_cndmask_b32_e32 v0, v80, v0, vcc
	v_mul_f32_e64 v108, v96, v90
	v_mul_f32_e64 v109, v97, v91
	ds_read_b64_tr_b16 v[90:91], v217 offset:57408
	ds_read_b64_tr_b16 v[88:89], v217 offset:56320
	ds_read_b64_tr_b16 v[94:95], v214 offset:2112
	ds_read_b64_tr_b16 v[92:93], v214
	ds_read_b64_tr_b16 v[98:99], v214 offset:2144
	ds_read_b64_tr_b16 v[96:97], v214 offset:32
	ds_read_b64_tr_b16 v[100:101], v217 offset:56352
	ds_read_b64_tr_b16 v[104:105], v217 offset:56384
	ds_read_b64_tr_b16 v[140:141], v217 offset:56416
	ds_read_b64_tr_b16 v[102:103], v217 offset:57440
	ds_read_b64_tr_b16 v[106:107], v217 offset:57472
	ds_read_b64_tr_b16 v[142:143], v217 offset:57504
	v_rsq_f32_e32 v0, v0
	ds_read_b64_tr_b16 v[146:147], v217 offset:65024
	ds_read_b64_tr_b16 v[148:149], v218 offset:57408
	ds_read_b64_tr_b16 v[150:151], v214 offset:16896
	ds_read_b64_tr_b16 v[152:153], v214 offset:19008
	ds_read_b64_tr_b16 v[160:161], v214 offset:19040
	ds_read_b64_tr_b16 v[158:159], v214 offset:16928
	s_waitcnt lgkmcnt(8)
	v_mfma_f32_16x16x32_bf16 v[10:13], v[100:103], v[92:95], v[10:13]
	v_and_b32_e32 v81, 0xffff0000, v156
	v_mul_f32_e32 v80, 0x45800000, v0
	v_cndmask_b32_e32 v0, v0, v80, vcc
	v_mfma_f32_16x16x32_bf16 v[18:21], v[100:103], v[96:99], v[18:21]
	v_lshlrev_b32_e32 v80, 16, v156
	v_mul_f32_e32 v100, 0xbfb8aa3b, v80
	v_mul_f32_e32 v101, 0xbfb8aa3b, v81
	v_mfma_f32_16x16x32_bf16 v[30:33], v[88:91], v[92:95], v[30:33]
	v_exp_f32_e32 v100, v100
	v_mul_f32_e64 v86, v86, v0
	v_mul_f32_e64 v87, v87, v0
	v_mul_f32_e64 v170, v170, v228
	v_mul_f32_e64 v171, v171, v229
	v_mfma_f32_16x16x32_bf16 v[6:9], v[88:91], v[96:99], v[6:9]
	ds_read_b64_tr_b16 v[88:89], v217 offset:65056
	ds_read_b64_tr_b16 v[162:163], v217 offset:65088
	ds_read_b64_tr_b16 v[166:167], v217 offset:65120
	ds_read_b64_tr_b16 v[90:91], v218 offset:57440
	ds_read_b64_tr_b16 v[164:165], v218 offset:57472
	ds_read_b64_tr_b16 v[168:169], v218 offset:57504
	v_mul_f32_e64 v74, v74, v86
	v_mul_f32_e64 v75, v75, v87
	v_lshlrev_b32_e32 v86, 16, v157
	s_waitcnt lgkmcnt(2)
	v_mfma_f32_16x16x32_bf16 v[10:13], v[88:91], v[150:153], v[10:13]
	v_mul_f32_e32 v87, 0xbfb8aa3b, v86
	v_cvt_pk_bf16_f32 v108, v108, v109
	v_cvt_pk_bf16_f32 v109, v170, v171
	v_mfma_f32_16x16x32_bf16 v[18:21], v[88:91], v[158:161], v[18:21]
	v_exp_f32_e32 v89, v101
	v_add_f32_e32 v88, 1.0, v100
	v_rcp_f32_e32 v88, v88
	global_store_dwordx2 v[172:173], v[108:109], off
	v_add_f32_e32 v89, 1.0, v89
	v_rcp_f32_e32 v89, v89
	v_mfma_f32_16x16x32_bf16 v[14:17], v[104:107], v[92:95], v[14:17]
	v_mul_f32_e64 v82, v82, v0
	v_mul_f32_e64 v83, v83, v0
	v_mul_f32_e64 v78, v78, v0
	v_mul_f32_e64 v79, v79, v0
	v_mul_f32_e64 v80, v88, v80
	v_mul_f32_e64 v81, v89, v81
	v_exp_f32_e32 v88, v87
	v_mul_f32_e64 v80, v80, v74
	v_mul_f32_e64 v81, v81, v75
	v_and_b32_e32 v87, 0xffff0000, v157
	v_mfma_f32_16x16x32_bf16 v[26:29], v[104:107], v[96:99], v[26:29]
	v_add_f32_e32 v74, 1.0, v88
	v_rcp_f32_e32 v88, v74
	v_mul_f32_e32 v74, 0xbfb8aa3b, v87
	v_exp_f32_e32 v89, v74
	v_mul_f32_e64 v74, v84, v0
	v_mul_f32_e64 v75, v85, v0
	v_mfma_f32_16x16x32_bf16 v[38:41], v[140:143], v[92:95], v[38:41]
	v_mul_f32_e64 v108, v76, v74
	v_mul_f32_e64 v109, v77, v75
	v_add_f32_e32 v74, 1.0, v89
	v_rcp_f32_e32 v89, v74
	ds_read_b64_tr_b16 v[74:75], v217 offset:56448
	ds_read_b64_tr_b16 v[76:77], v217 offset:57536
	v_mfma_f32_16x16x32_bf16 v[50:53], v[140:143], v[96:99], v[50:53]
	v_cvt_pk_bf16_f32 v80, v80, v81
	v_mul_f32_e64 v140, v88, v86
	v_mul_f32_e64 v141, v89, v87
	ds_read_b64_tr_b16 v[84:85], v217 offset:56480
	ds_read_b64_tr_b16 v[88:89], v217 offset:56512
	ds_read_b64_tr_b16 v[100:101], v217 offset:56544
	ds_read_b64_tr_b16 v[86:87], v217 offset:57568
	ds_read_b64_tr_b16 v[90:91], v217 offset:57600
	ds_read_b64_tr_b16 v[102:103], v217 offset:57632
	ds_read_b64_tr_b16 v[104:105], v217 offset:65152
	ds_read_b64_tr_b16 v[106:107], v218 offset:57536
	s_waitcnt lgkmcnt(8)
	v_mfma_f32_16x16x32_bf16 v[22:25], v[74:77], v[92:95], v[22:25]
	v_mul_f32_e64 v108, v140, v108
	v_mul_f32_e64 v109, v141, v109
	v_mul_f32_e64 v70, v70, v82
	v_mul_f32_e64 v71, v71, v83
	v_cvt_pk_bf16_f32 v81, v108, v109
	v_mfma_f32_16x16x32_bf16 v[34:37], v[74:77], v[96:99], v[34:37]
	v_lshl_add_u64 v[108:109], s[54:55], 0, v[130:131]
	v_mul_f32_e64 v72, v72, v78
	v_mul_f32_e64 v73, v73, v79
	v_lshl_add_u32 v0, s68, 9, v182
	v_mfma_f32_16x16x32_bf16 v[30:33], v[146:149], v[150:153], v[30:33]
	s_sub_i32 s52, s52, 64
	v_mfma_f32_16x16x32_bf16 v[6:9], v[146:149], v[158:161], v[6:9]
	ds_read_b64_tr_b16 v[74:75], v217 offset:65184
	ds_read_b64_tr_b16 v[140:141], v217 offset:65216
	ds_read_b64_tr_b16 v[146:147], v217 offset:65248
	ds_read_b64_tr_b16 v[76:77], v218 offset:57568
	ds_read_b64_tr_b16 v[142:143], v218 offset:57600
	ds_read_b64_tr_b16 v[148:149], v218 offset:57632
	global_store_dwordx2 v[108:109], v[80:81], off
	v_lshlrev_b32_e32 v80, 16, v144
	v_and_b32_e32 v81, 0xffff0000, v144
	s_waitcnt lgkmcnt(6)
	v_mfma_f32_16x16x32_bf16 v[22:25], v[104:107], v[150:153], v[22:25]
	v_mfma_f32_16x16x32_bf16 v[34:37], v[104:107], v[158:161], v[34:37]
	v_mul_f32_e32 v104, 0xbfb8aa3b, v80
	v_mul_f32_e32 v105, 0xbfb8aa3b, v81
	v_exp_f32_e32 v104, v104
	v_mfma_f32_16x16x32_bf16 v[42:45], v[84:87], v[92:95], v[42:45]
	v_mfma_f32_16x16x32_bf16 v[54:57], v[84:87], v[96:99], v[54:57]
	v_exp_f32_e32 v85, v105
	v_add_f32_e32 v84, 1.0, v104
	v_rcp_f32_e32 v84, v84
	s_waitcnt lgkmcnt(2)
	v_mfma_f32_16x16x32_bf16 v[42:45], v[74:77], v[150:153], v[42:45]
	v_add_f32_e32 v85, 1.0, v85
	v_rcp_f32_e32 v85, v85
	v_mfma_f32_16x16x32_bf16 v[54:57], v[74:77], v[158:161], v[54:57]
	v_mul_f32_e64 v74, v84, v80
	v_mul_f32_e64 v75, v85, v81
	v_mul_f32_e64 v70, v74, v70
	v_mul_f32_e64 v71, v75, v71
	v_lshlrev_b32_e32 v74, 16, v145
	v_and_b32_e32 v75, 0xffff0000, v145
	v_mul_f32_e32 v76, 0xbfb8aa3b, v74
	v_mul_f32_e32 v77, 0xbfb8aa3b, v75
	v_exp_f32_e32 v76, v76
	v_exp_f32_e32 v77, v77
	v_cvt_pk_bf16_f32 v78, v70, v71
	v_lshl_add_u64 v[80:81], s[54:55], 0, v[132:133]
	v_add_f32_e32 v76, 1.0, v76
	v_add_f32_e32 v77, 1.0, v77
	v_rcp_f32_e32 v76, v76
	v_rcp_f32_e32 v77, v77
	v_mfma_f32_16x16x32_bf16 v[14:17], v[162:165], v[150:153], v[14:17]
	s_add_u32 s54, s54, 0xfffe0000
	s_addc_u32 s55, s55, -1
	v_mul_f32_e64 v74, v76, v74
	v_mul_f32_e64 v75, v77, v75
	v_mfma_f32_16x16x32_bf16 v[26:29], v[162:165], v[158:161], v[26:29]
	v_mul_f32_e64 v74, v74, v72
	v_mul_f32_e64 v75, v75, v73
	ds_read_b128 v[70:73], v0 offset:4096
	v_cvt_pk_bf16_f32 v79, v74, v75
	ds_read_b128 v[74:77], v0 offset:4160
	global_store_dwordx2 v[80:81], v[78:79], off
	v_mfma_f32_16x16x32_bf16 v[38:41], v[166:169], v[150:153], v[38:41]
	s_waitcnt lgkmcnt(1)
	s_nop 0
	v_mov_b32_e32 v82, v70
	v_mov_b32_e32 v83, v71
	v_mov_b32_e32 v70, v72
	v_mov_b32_e32 v71, v73
	s_nop 0
	s_nop 0
	s_nop 0
	v_mfma_f32_16x16x32_bf16 v[50:53], v[166:169], v[158:161], v[50:53]
	s_add_u32 s56, s56, 0xfffe0000
	v_mul_f32_e64 v32, v32, v70
	v_mul_f32_e64 v33, v33, v71
	v_mul_f32_e64 v8, v8, v70
	v_mul_f32_e64 v9, v9, v71
	s_waitcnt lgkmcnt(0)
	v_mov_b32_e32 v70, v74
	v_mov_b32_e32 v71, v76
	v_mov_b32_e32 v78, v70
	v_mov_b32_e32 v70, v75
	v_mov_b32_e32 v80, v71
	s_nop 0
	v_mov_b32_e32 v81, v77
	v_mov_b32_e32 v79, v70
	ds_read_b128 v[70:73], v0 offset:4224
	ds_read_b128 v[74:77], v0 offset:4288
	v_mul_f32_e64 v30, v30, v82
	v_mul_f32_e64 v31, v31, v83
	v_mul_f32_e64 v6, v6, v82
	v_mul_f32_e64 v7, v7, v83
	v_mul_f32_e64 v12, v12, v80
	v_mul_f32_e64 v13, v13, v81
	s_waitcnt lgkmcnt(1)
	s_nop 0
	v_mov_b32_e32 v82, v70
	v_mov_b32_e32 v83, v71
	v_mov_b32_e32 v70, v72
	v_mov_b32_e32 v71, v73
	s_nop 0
	s_nop 0
	v_mul_f32_e64 v10, v10, v78
	v_mul_f32_e64 v11, v11, v79
	v_mul_f32_e64 v20, v20, v80
	v_mul_f32_e64 v21, v21, v81
	v_mul_f32_e64 v18, v18, v78
	v_mul_f32_e64 v19, v19, v79
	v_mul_f32_e64 v16, v16, v70
	v_mul_f32_e64 v17, v17, v71
	v_mul_f32_e64 v28, v28, v70
	v_mul_f32_e64 v29, v29, v71
	s_waitcnt lgkmcnt(0)
	v_mov_b32_e32 v70, v74
	v_mov_b32_e32 v71, v76
	v_mov_b32_e32 v78, v70
	v_mov_b32_e32 v70, v75
	v_mov_b32_e32 v80, v71
	s_nop 0
	v_mov_b32_e32 v81, v77
	v_mov_b32_e32 v79, v70
	ds_read_b128 v[70:73], v0 offset:4352
	ds_read_b128 v[74:77], v0 offset:4416
	s_nop 0
	v_mul_f32_e64 v40, v40, v80
	v_mul_f32_e64 v41, v41, v81
	v_mul_f32_e64 v38, v38, v78
	v_mul_f32_e64 v39, v39, v79
	s_waitcnt lgkmcnt(1)
	s_nop 0
	v_mul_f32_e64 v14, v14, v82
	v_mul_f32_e64 v15, v15, v83
	v_mul_f32_e64 v26, v26, v82
	v_mul_f32_e64 v27, v27, v83
	v_mov_b32_e32 v82, v70
	v_mov_b32_e32 v83, v71
	v_mov_b32_e32 v70, v72
	v_mov_b32_e32 v71, v73
	s_nop 0
	s_nop 0
	v_mul_f32_e64 v52, v52, v80
	v_mul_f32_e64 v53, v53, v81
	v_mul_f32_e64 v50, v50, v78
	v_mul_f32_e64 v51, v51, v79
	v_mfma_f32_16x16x32_bf16 v[46:49], v[88:91], v[92:95], v[46:49]
	v_mul_f32_e64 v24, v24, v70
	v_mul_f32_e64 v25, v25, v71
	v_mul_f32_e64 v36, v36, v70
	v_mul_f32_e64 v37, v37, v71
	s_waitcnt lgkmcnt(0)
	v_mov_b32_e32 v70, v74
	v_mov_b32_e32 v71, v76
	v_mov_b32_e32 v78, v70
	v_mov_b32_e32 v70, v75
	v_mov_b32_e32 v80, v71
	s_nop 0
	v_mov_b32_e32 v81, v77
	v_mov_b32_e32 v79, v70
	ds_read_b128 v[70:73], v0 offset:4480
	ds_read_b128 v[74:77], v0 offset:4544
	v_mfma_f32_16x16x32_bf16 v[62:65], v[88:91], v[96:99], v[62:65]
	s_nop 0
	s_addc_u32 s57, s57, -1
	s_waitcnt lgkmcnt(1)
	s_nop 0
	v_mov_b32_e32 v70, v70
	v_mov_b32_e32 v0, v71
	v_mov_b32_e32 v71, v72
	v_mfma_f32_16x16x32_bf16 v[58:61], v[100:103], v[92:95], v[58:61]
	v_mov_b32_e32 v72, v71
	s_nop 0
	v_mov_b32_e32 v73, v73
	v_mfma_f32_16x16x32_bf16 v[66:69], v[100:103], v[96:99], v[66:69]
	v_mov_b32_e32 v71, v0
	s_waitcnt lgkmcnt(0)
	s_nop 0
	v_mov_b32_e32 v74, v74
	v_mov_b32_e32 v0, v75
	v_mov_b32_e32 v75, v76
	v_mov_b32_e32 v76, v75
	v_mov_b32_e32 v75, v77
	v_mfma_f32_16x16x32_bf16 v[46:49], v[140:143], v[150:153], v[46:49]
	v_mov_b32_e32 v77, v75
	v_mov_b32_e32 v75, v0
	v_mul_f32_e64 v22, v22, v82
	v_mul_f32_e64 v23, v23, v83
	v_mfma_f32_16x16x32_bf16 v[62:65], v[140:143], v[158:161], v[62:65]
	v_mul_f32_e64 v34, v34, v82
	v_mul_f32_e64 v35, v35, v83
	v_mul_f32_e64 v44, v44, v80
	v_mul_f32_e64 v45, v45, v81
	v_mul_f32_e64 v42, v42, v78
	v_mul_f32_e64 v43, v43, v79
	v_mfma_f32_16x16x32_bf16 v[58:61], v[146:149], v[150:153], v[58:61]
	v_mul_f32_e64 v56, v56, v80
	v_mul_f32_e64 v57, v57, v81
	v_mul_f32_e64 v54, v54, v78
	v_mul_f32_e64 v55, v55, v79
	v_mul_f32_e64 v48, v48, v72
	v_mul_f32_e64 v49, v49, v73
	v_mfma_f32_16x16x32_bf16 v[66:69], v[146:149], v[158:161], v[66:69]
	v_mul_f32_e64 v46, v46, v70
	v_mul_f32_e64 v47, v47, v71
	v_mul_f32_e64 v64, v64, v72
	v_mul_f32_e64 v65, v65, v73
	v_mul_f32_e64 v62, v62, v70
	v_mul_f32_e64 v63, v63, v71
	v_mul_f32_e64 v60, v60, v76
	v_mul_f32_e64 v61, v61, v77
	v_mul_f32_e64 v58, v58, v74
	v_mul_f32_e64 v59, v59, v75
	s_nop 1
	v_mul_f32_e64 v68, v68, v76
	v_mul_f32_e64 v69, v69, v77
	s_cmp_lg_u32 s74, 8
	v_mul_f32_e64 v66, v66, v74
	v_mul_f32_e64 v67, v67, v75
	s_cbranch_scc0 .LBB0_2257

.LBB0_2292:
	ds_read_b128 v[102:105], v205 offset:6144
	ds_read_b128 v[106:109], v205 offset:6160
	s_waitcnt vmcnt(6)
	v_lshlrev_b32_e32 v142, 16, v98
	v_and_b32_e32 v143, 0xffff0000, v98
	s_waitcnt lgkmcnt(1)
	v_mul_f32_e32 v0, 0xbfb8aa3b, v102
	v_exp_f32_e32 v140, v0
	v_mul_f32_e32 v0, 0xbfb8aa3b, v103
	v_exp_f32_e32 v141, v0
	v_mul_f32_e32 v0, 0xbfb8aa3b, v104
	v_mul_f32_e64 v140, v140, v142
	v_mul_f32_e64 v141, v141, v143
	s_nop 0
	v_cvt_pk_bf16_f32 v98, v140, v141
	v_exp_f32_e32 v140, v0
	v_mul_f32_e32 v0, 0xbfb8aa3b, v105
	v_exp_f32_e32 v141, v0
	v_lshlrev_b32_e32 v142, 16, v99
	v_and_b32_e32 v143, 0xffff0000, v99
	s_waitcnt lgkmcnt(0)
	v_mul_f32_e32 v0, 0xbfb8aa3b, v106
	v_mul_f32_e64 v140, v140, v142
	v_mul_f32_e64 v141, v141, v143
	v_lshlrev_b32_e32 v142, 16, v100
	v_cvt_pk_bf16_f32 v99, v140, v141
	v_exp_f32_e32 v140, v0
	v_mul_f32_e32 v0, 0xbfb8aa3b, v107
	v_exp_f32_e32 v141, v0
	v_and_b32_e32 v143, 0xffff0000, v100
	v_mul_f32_e32 v0, 0xbfb8aa3b, v108
	v_mul_f32_e64 v140, v140, v142
	v_mul_f32_e64 v141, v141, v143
	s_nop 0
	v_cvt_pk_bf16_f32 v100, v140, v141
	v_exp_f32_e32 v140, v0
	v_mul_f32_e32 v0, 0xbfb8aa3b, v109
	v_exp_f32_e32 v141, v0
	v_lshlrev_b32_e32 v142, 16, v101
	v_and_b32_e32 v143, 0xffff0000, v101
	v_mul_f32_e32 v0, 0x3fb8aa3b, v102
	v_mul_f32_e64 v140, v140, v142
	v_mul_f32_e64 v141, v141, v143
	s_nop 0
	v_cvt_pk_bf16_f32 v101, v140, v141
	ds_write_b128 v184, v[98:101] offset:56320
	v_exp_f32_e32 v98, v0
	v_mul_f32_e32 v0, 0x3fb8aa3b, v103
	v_exp_f32_e32 v99, v0
	v_lshlrev_b32_e32 v100, 16, v94
	v_and_b32_e32 v101, 0xffff0000, v94
	v_mul_f32_e32 v0, 0x3fb8aa3b, v104
	v_mul_f32_e64 v98, v98, s48
	v_mul_f32_e64 v99, v99, s48
	s_waitcnt vmcnt(4)
	v_lshlrev_b32_e32 v104, 16, v90
	v_mul_f32_e64 v98, v98, v100
	v_mul_f32_e64 v99, v99, v101
	v_lshlrev_b32_e32 v100, 16, v95
	v_cvt_pk_bf16_f32 v94, v98, v99
	v_exp_f32_e32 v98, v0
	v_mul_f32_e32 v0, 0x3fb8aa3b, v105
	v_exp_f32_e32 v99, v0
	v_and_b32_e32 v101, 0xffff0000, v95
	v_mul_f32_e32 v0, 0x3fb8aa3b, v106
	v_and_b32_e32 v105, 0xffff0000, v90
	v_mul_f32_e64 v98, v98, s48
	v_mul_f32_e64 v99, v99, s48
	s_nop 0
	v_mul_f32_e64 v98, v98, v100
	v_mul_f32_e64 v99, v99, v101
	v_lshlrev_b32_e32 v100, 16, v96
	v_cvt_pk_bf16_f32 v95, v98, v99
	v_exp_f32_e32 v98, v0
	v_mul_f32_e32 v0, 0x3fb8aa3b, v107
	v_exp_f32_e32 v99, v0
	v_and_b32_e32 v101, 0xffff0000, v96
	v_mul_f32_e32 v0, 0x3fb8aa3b, v108
	v_mul_f32_e64 v98, v98, s48
	v_mul_f32_e64 v99, v99, s48
	s_nop 0
	v_mul_f32_e64 v98, v98, v100
	v_mul_f32_e64 v99, v99, v101
	v_lshlrev_b32_e32 v100, 16, v97
	v_cvt_pk_bf16_f32 v96, v98, v99
	v_exp_f32_e32 v98, v0
	v_mul_f32_e32 v0, 0x3fb8aa3b, v109
	v_exp_f32_e32 v99, v0
	v_and_b32_e32 v101, 0xffff0000, v97
	v_mul_f32_e64 v98, v98, s48
	v_mul_f32_e64 v99, v99, s48
	s_nop 0
	v_mul_f32_e64 v98, v98, v100
	v_mul_f32_e64 v99, v99, v101
	s_nop 0
	v_cvt_pk_bf16_f32 v97, v98, v99
	ds_write_b128 v184, v[94:97] offset:38912
	ds_read_b128 v[94:97], v206 offset:6144
	ds_read_b128 v[98:101], v206 offset:6160
	s_waitcnt lgkmcnt(1)
	v_mul_f32_e32 v0, 0xbfb8aa3b, v94
	v_exp_f32_e32 v102, v0
	v_mul_f32_e32 v0, 0xbfb8aa3b, v95
	v_exp_f32_e32 v103, v0
	v_mul_f32_e32 v0, 0xbfb8aa3b, v96
	v_mul_f32_e64 v102, v102, v104
	v_mul_f32_e64 v103, v103, v105
	s_nop 0
	v_cvt_pk_bf16_f32 v90, v102, v103
	v_exp_f32_e32 v102, v0
	v_mul_f32_e32 v0, 0xbfb8aa3b, v97
	v_exp_f32_e32 v103, v0
	v_lshlrev_b32_e32 v104, 16, v91
	v_and_b32_e32 v105, 0xffff0000, v91
	s_waitcnt lgkmcnt(0)
	v_mul_f32_e32 v0, 0xbfb8aa3b, v98
	v_mul_f32_e64 v102, v102, v104
	v_mul_f32_e64 v103, v103, v105
	v_lshlrev_b32_e32 v104, 16, v92
	v_cvt_pk_bf16_f32 v91, v102, v103
	v_exp_f32_e32 v102, v0
	v_mul_f32_e32 v0, 0xbfb8aa3b, v99
	v_exp_f32_e32 v103, v0
	v_and_b32_e32 v105, 0xffff0000, v92
	v_mul_f32_e32 v0, 0xbfb8aa3b, v100
	v_mul_f32_e64 v102, v102, v104
	v_mul_f32_e64 v103, v103, v105
	s_nop 0
	v_cvt_pk_bf16_f32 v92, v102, v103
	v_exp_f32_e32 v102, v0
	v_mul_f32_e32 v0, 0xbfb8aa3b, v101
	v_exp_f32_e32 v103, v0
	v_lshlrev_b32_e32 v104, 16, v93
	v_and_b32_e32 v105, 0xffff0000, v93
	v_mul_f32_e32 v0, 0x3fb8aa3b, v94
	v_mul_f32_e64 v102, v102, v104
	v_mul_f32_e64 v103, v103, v105
	s_nop 0
	v_cvt_pk_bf16_f32 v93, v102, v103
	ds_write_b128 v185, v[90:93] offset:56320
	v_exp_f32_e32 v90, v0
	v_mul_f32_e32 v0, 0x3fb8aa3b, v95
	v_exp_f32_e32 v91, v0
	v_lshlrev_b32_e32 v92, 16, v70
	v_and_b32_e32 v93, 0xffff0000, v70
	v_mul_f32_e32 v0, 0x3fb8aa3b, v96
	v_mul_f32_e64 v90, v90, s48
	v_mul_f32_e64 v91, v91, s48
	s_nop 0
	v_mul_f32_e64 v90, v90, v92
	v_mul_f32_e64 v91, v91, v93
	v_lshlrev_b32_e32 v92, 16, v71
	v_cvt_pk_bf16_f32 v70, v90, v91
	v_exp_f32_e32 v90, v0
	v_mul_f32_e32 v0, 0x3fb8aa3b, v97
	v_exp_f32_e32 v91, v0
	v_and_b32_e32 v93, 0xffff0000, v71
	v_mul_f32_e32 v0, 0x3fb8aa3b, v98
	v_mul_f32_e64 v90, v90, s48
	v_mul_f32_e64 v91, v91, s48
	s_nop 0
	v_mul_f32_e64 v90, v90, v92
	v_mul_f32_e64 v91, v91, v93
	v_lshlrev_b32_e32 v92, 16, v72
	v_cvt_pk_bf16_f32 v71, v90, v91
	v_exp_f32_e32 v90, v0
	v_mul_f32_e32 v0, 0x3fb8aa3b, v99
	v_exp_f32_e32 v91, v0
	v_and_b32_e32 v93, 0xffff0000, v72
	v_mul_f32_e32 v0, 0x3fb8aa3b, v100
	v_mul_f32_e64 v90, v90, s48
	v_mul_f32_e64 v91, v91, s48
	s_nop 0
	v_mul_f32_e64 v90, v90, v92
	v_mul_f32_e64 v91, v91, v93
	v_lshlrev_b32_e32 v92, 16, v73
	v_cvt_pk_bf16_f32 v72, v90, v91
	v_exp_f32_e32 v90, v0
	v_mul_f32_e32 v0, 0x3fb8aa3b, v101
	v_exp_f32_e32 v91, v0
	v_and_b32_e32 v93, 0xffff0000, v73
	v_mul_f32_e64 v90, v90, s48
	v_mul_f32_e64 v91, v91, s48
	s_nop 0
	v_mul_f32_e64 v90, v90, v92
	v_mul_f32_e64 v91, v91, v93
	s_nop 0
	v_cvt_pk_bf16_f32 v73, v90, v91
	ds_write_b128 v185, v[70:73] offset:38912
	s_waitcnt vmcnt(3)
	ds_write_b128 v207, v[74:77]
	s_waitcnt vmcnt(2)
	ds_write_b128 v208, v[78:81]
	s_waitcnt vmcnt(1)
	ds_write_b128 v207, v[82:85] offset:16896
	s_waitcnt vmcnt(0)
	ds_write_b128 v209, v[86:89]
	v_lshl_add_u64 v[70:71], s[56:57], 0, v[118:119]
	v_lshl_add_u64 v[72:73], s[56:57], 0, v[122:123]
	v_lshl_add_u64 v[74:75], s[56:57], 0, v[124:125]
	global_load_dwordx2 v[160:161], v[70:71], off
	global_load_dwordx2 v[158:159], v[70:71], off offset:32
	global_load_dwordx2 v[152:153], v[72:73], off
	global_load_dwordx2 v[150:151], v[74:75], off
	v_lshl_add_u64 v[70:71], s[56:57], 0, v[126:127]
	v_lshl_add_u64 v[72:73], s[56:57], 0, v[128:129]
	v_lshl_add_u64 v[74:75], s[56:57], 0, v[130:131]
	v_lshl_add_u64 v[76:77], s[56:57], 0, v[132:133]
	global_load_dwordx2 v[148:149], v[70:71], off
	global_load_dwordx2 v[146:147], v[72:73], off
	global_load_dwordx2 v[142:143], v[74:75], off
	global_load_dwordx2 v[140:141], v[76:77], off
	s_waitcnt lgkmcnt(0)
	s_barrier
	ds_read_b128 v[70:73], v210 offset:56320
	ds_read_b128 v[74:77], v183 offset:38912
	ds_read_b128 v[78:81], v210 offset:56384
	ds_read_b128 v[82:85], v183 offset:38976
	s_waitcnt lgkmcnt(2)
	v_mfma_f32_16x16x32_bf16 v[70:73], v[70:73], v[74:77], 0
	v_mov_b32_e32 v0, s93
	v_cvt_pk_bf16_f32 v170, v62, v63
	v_cvt_pk_bf16_f32 v171, v64, v65
	s_waitcnt lgkmcnt(0)
	v_mfma_f32_16x16x32_bf16 v[70:73], v[78:81], v[82:85], v[70:73]
	ds_read_b128 v[78:81], v210 offset:56448
	ds_read_b128 v[86:89], v183 offset:39040
	v_cvt_pk_bf16_f32 v172, v66, v67
	v_cvt_pk_bf16_f32 v173, v68, v69
	s_waitcnt lgkmcnt(0)
	v_mfma_f32_16x16x32_bf16 v[70:73], v[78:81], v[86:89], v[70:73]
	ds_read_b128 v[78:81], v210 offset:56512
	ds_read_b128 v[90:93], v183 offset:39104
	s_add_u32 s49, s49, s0
	s_addc_u32 s53, s69, 0
	s_waitcnt lgkmcnt(0)
	v_mfma_f32_16x16x32_bf16 v[70:73], v[78:81], v[90:93], v[70:73]
	s_add_u32 s60, s49, 0xafc1000
	s_addc_u32 s61, s53, 0
	s_waitcnt vmcnt(7)
	v_lshlrev_b32_e32 v228, 16, v160
	s_nop 3
	v_cndmask_b32_e64 v0, v70, v0, s[14:15]
	v_cndmask_b32_e64 v70, v71, 0, s[30:31]
	v_cndmask_b32_e64 v71, v72, 0, s[34:35]
	v_cndmask_b32_e64 v72, v73, 0, s[36:37]
	v_cvt_pk_bf16_f32 v70, v0, v70
	v_cvt_pk_bf16_f32 v71, v71, v72
	ds_write_b64 v211, v[70:71]
	ds_read_b128 v[70:73], v212 offset:56320
	s_waitcnt lgkmcnt(0)
	v_mfma_f32_16x16x32_bf16 v[70:73], v[70:73], v[74:77], 0
	ds_read_b128 v[74:77], v212 offset:56384
	v_mov_b32_e32 v0, s93
	v_and_b32_e32 v229, 0xffff0000, v160
	s_waitcnt lgkmcnt(0)
	v_mfma_f32_16x16x32_bf16 v[70:73], v[74:77], v[82:85], v[70:73]
	ds_read_b128 v[74:77], v212 offset:56448
	v_lshlrev_b32_e32 v160, 16, v161
	v_and_b32_e32 v161, 0xffff0000, v161
	s_waitcnt lgkmcnt(0)
	v_mfma_f32_16x16x32_bf16 v[70:73], v[74:77], v[86:89], v[70:73]
	ds_read_b128 v[74:77], v212 offset:56512
	s_waitcnt vmcnt(6)
	v_lshlrev_b32_e32 v230, 16, v158
	v_and_b32_e32 v231, 0xffff0000, v158
	s_waitcnt lgkmcnt(0)
	v_mfma_f32_16x16x32_bf16 v[70:73], v[74:77], v[90:93], v[70:73]
	v_lshlrev_b32_e32 v158, 16, v159
	v_and_b32_e32 v159, 0xffff0000, v159
	s_nop 5
	v_cndmask_b32_e64 v0, v70, v0, s[22:23]
	v_cndmask_b32_e64 v70, v71, 0, s[38:39]
	v_cndmask_b32_e64 v71, v72, 0, s[40:41]
	v_cndmask_b32_e64 v72, v73, 0, s[42:43]
	v_cvt_pk_bf16_f32 v70, v0, v70
	v_cvt_pk_bf16_f32 v71, v71, v72
	ds_write_b64 v213, v[70:71]
	s_waitcnt lgkmcnt(0)
	s_barrier
	ds_read_b64_tr_b16 v[72:73], v214 offset:2112
	ds_read_b64_tr_b16 v[70:71], v214
	ds_read_b64_tr_b16 v[74:75], v214 offset:32
	ds_read_b64_tr_b16 v[78:79], v214 offset:16896
	ds_read_b64_tr_b16 v[80:81], v214 offset:19008
	ds_read_b64_tr_b16 v[76:77], v214 offset:2144
	ds_read_b64_tr_b16 v[82:83], v214 offset:16928
	ds_read_b64_tr_b16 v[84:85], v214 offset:19040
	ds_read_b128 v[86:89], v215
	ds_read_b128 v[94:97], v215 offset:64
	ds_read_b128 v[102:105], v215 offset:2368
	s_waitcnt lgkmcnt(2)
	v_mfma_f32_16x16x32_bf16 v[90:93], v[70:73], v[86:89], 0
	ds_read_b128 v[162:165], v215 offset:4672
	v_mfma_f32_16x16x32_bf16 v[86:89], v[74:77], v[86:89], 0
	s_waitcnt lgkmcnt(2)
	v_mfma_f32_16x16x32_bf16 v[90:93], v[78:81], v[94:97], v[90:93]
	v_mfma_f32_16x16x32_bf16 v[86:89], v[82:85], v[94:97], v[86:89]
	ds_read_b128 v[94:97], v215 offset:2304
	s_waitcnt lgkmcnt(0)
	v_mfma_f32_16x16x32_bf16 v[98:101], v[70:73], v[94:97], 0
	v_mfma_f32_16x16x32_bf16 v[94:97], v[74:77], v[94:97], 0
	v_mfma_f32_16x16x32_bf16 v[98:101], v[78:81], v[102:105], v[98:101]
	v_mfma_f32_16x16x32_bf16 v[94:97], v[82:85], v[102:105], v[94:97]
	ds_read_b128 v[102:105], v215 offset:4608
	s_waitcnt lgkmcnt(0)
	v_mfma_f32_16x16x32_bf16 v[106:109], v[70:73], v[102:105], 0
	v_mfma_f32_16x16x32_bf16 v[102:105], v[74:77], v[102:105], 0
	v_mfma_f32_16x16x32_bf16 v[106:109], v[78:81], v[162:165], v[106:109]
	v_mfma_f32_16x16x32_bf16 v[102:105], v[82:85], v[162:165], v[102:105]
	ds_read_b128 v[162:165], v215 offset:6912
	s_waitcnt lgkmcnt(0)
	v_mfma_f32_16x16x32_bf16 v[70:73], v[70:73], v[162:165], 0
	v_mfma_f32_16x16x32_bf16 v[74:77], v[74:77], v[162:165], 0
	ds_read_b128 v[162:165], v215 offset:6976
	s_waitcnt lgkmcnt(0)
	v_mfma_f32_16x16x32_bf16 v[70:73], v[78:81], v[162:165], v[70:73]
	v_cvt_pk_bf16_f32 v78, v30, v31
	v_cvt_pk_bf16_f32 v79, v32, v33
	v_cvt_pk_bf16_f32 v80, v10, v11
	v_mfma_f32_16x16x32_bf16 v[74:77], v[82:85], v[162:165], v[74:77]
	v_cvt_pk_bf16_f32 v81, v12, v13
	v_cvt_pk_bf16_f32 v82, v6, v7
	v_cvt_pk_bf16_f32 v83, v8, v9
	v_cvt_pk_bf16_f32 v84, v18, v19
	v_cvt_pk_bf16_f32 v85, v20, v21
	ds_read2_b64 v[162:165], v219 offset1:4
	s_waitcnt lgkmcnt(0)
	v_mfma_f32_16x16x32_bf16 v[90:93], v[78:81], v[162:165], v[90:93]
	v_mfma_f32_16x16x32_bf16 v[86:89], v[82:85], v[162:165], v[86:89]
	ds_read2_b64 v[162:165], v220 offset0:32 offset1:36
	s_waitcnt lgkmcnt(0)
	v_mfma_f32_16x16x32_bf16 v[98:101], v[78:81], v[162:165], v[98:101]
	v_mfma_f32_16x16x32_bf16 v[94:97], v[82:85], v[162:165], v[94:97]
	ds_read2_b64 v[162:165], v221 offset0:64 offset1:68
	s_waitcnt lgkmcnt(0)
	v_mfma_f32_16x16x32_bf16 v[106:109], v[78:81], v[162:165], v[106:109]
	v_mfma_f32_16x16x32_bf16 v[102:105], v[82:85], v[162:165], v[102:105]
	ds_read2_b64 v[162:165], v222 offset0:96 offset1:100
	s_waitcnt lgkmcnt(0)
	v_mfma_f32_16x16x32_bf16 v[70:73], v[78:81], v[162:165], v[70:73]
	v_cvt_pk_bf16_f32 v78, v14, v15
	v_cvt_pk_bf16_f32 v79, v16, v17
	v_cvt_pk_bf16_f32 v80, v38, v39
	v_mfma_f32_16x16x32_bf16 v[74:77], v[82:85], v[162:165], v[74:77]
	v_cvt_pk_bf16_f32 v81, v40, v41
	v_cvt_pk_bf16_f32 v82, v26, v27
	v_cvt_pk_bf16_f32 v83, v28, v29
	v_cvt_pk_bf16_f32 v84, v50, v51
	v_cvt_pk_bf16_f32 v85, v52, v53
	ds_read2_b64 v[162:165], v219 offset0:8 offset1:12
	s_waitcnt lgkmcnt(0)
	v_mfma_f32_16x16x32_bf16 v[90:93], v[78:81], v[162:165], v[90:93]
	v_mfma_f32_16x16x32_bf16 v[86:89], v[82:85], v[162:165], v[86:89]
	ds_read2_b64 v[162:165], v220 offset0:40 offset1:44
	s_waitcnt lgkmcnt(0)
	v_mfma_f32_16x16x32_bf16 v[98:101], v[78:81], v[162:165], v[98:101]
	v_mfma_f32_16x16x32_bf16 v[94:97], v[82:85], v[162:165], v[94:97]
	ds_read2_b64 v[162:165], v221 offset0:72 offset1:76
	s_waitcnt lgkmcnt(0)
	v_mfma_f32_16x16x32_bf16 v[106:109], v[78:81], v[162:165], v[106:109]
	v_mfma_f32_16x16x32_bf16 v[102:105], v[82:85], v[162:165], v[102:105]
	ds_read2_b64 v[162:165], v222 offset0:104 offset1:108
	s_waitcnt lgkmcnt(0)
	v_mfma_f32_16x16x32_bf16 v[70:73], v[78:81], v[162:165], v[70:73]
	v_cvt_pk_bf16_f32 v78, v22, v23
	v_cvt_pk_bf16_f32 v79, v24, v25
	v_cvt_pk_bf16_f32 v80, v42, v43
	v_mfma_f32_16x16x32_bf16 v[74:77], v[82:85], v[162:165], v[74:77]
	v_cvt_pk_bf16_f32 v81, v44, v45
	v_cvt_pk_bf16_f32 v82, v34, v35
	v_cvt_pk_bf16_f32 v83, v36, v37
	v_cvt_pk_bf16_f32 v84, v54, v55
	v_cvt_pk_bf16_f32 v85, v56, v57
	ds_read2_b64 v[162:165], v219 offset0:16 offset1:20
	s_waitcnt lgkmcnt(0)
	v_mfma_f32_16x16x32_bf16 v[90:93], v[78:81], v[162:165], v[90:93]
	v_mfma_f32_16x16x32_bf16 v[86:89], v[82:85], v[162:165], v[86:89]
	ds_read2_b64 v[162:165], v220 offset0:48 offset1:52
	s_waitcnt lgkmcnt(0)
	v_mfma_f32_16x16x32_bf16 v[98:101], v[78:81], v[162:165], v[98:101]
	v_mfma_f32_16x16x32_bf16 v[94:97], v[82:85], v[162:165], v[94:97]
	ds_read2_b64 v[162:165], v221 offset0:80 offset1:84
	s_waitcnt lgkmcnt(0)
	v_mfma_f32_16x16x32_bf16 v[166:169], v[78:81], v[162:165], v[106:109]
	v_mfma_f32_16x16x32_bf16 v[162:165], v[82:85], v[162:165], v[102:105]
	s_nop 2
	ds_read2_b64 v[102:105], v222 offset0:112 offset1:116
	s_waitcnt lgkmcnt(0)
	v_mfma_f32_16x16x32_bf16 v[70:73], v[78:81], v[102:105], v[70:73]
	v_cvt_pk_bf16_f32 v78, v46, v47
	v_cvt_pk_bf16_f32 v79, v48, v49
	v_cvt_pk_bf16_f32 v80, v58, v59
	v_mfma_f32_16x16x32_bf16 v[74:77], v[82:85], v[102:105], v[74:77]
	v_cvt_pk_bf16_f32 v81, v60, v61
	ds_read2_b64 v[82:85], v219 offset0:24 offset1:28
	s_waitcnt lgkmcnt(0)
	v_mfma_f32_16x16x32_bf16 v[106:109], v[78:81], v[82:85], v[90:93]
	v_mfma_f32_16x16x32_bf16 v[102:105], v[170:173], v[82:85], v[86:89]
	ds_read2_b64 v[82:85], v220 offset0:56 offset1:60
	s_nop 5
	v_add_f32_e64 v106, v106, v228
	v_add_f32_e64 v107, v107, v229
	v_add_f32_e64 v108, v108, v160
	v_add_f32_e64 v109, v109, v161
	s_waitcnt lgkmcnt(0)
	v_mfma_f32_16x16x32_bf16 v[98:101], v[78:81], v[82:85], v[98:101]
	v_mul_f32_e64 v160, v106, v106
	v_mul_f32_e64 v161, v107, v107
	v_mul_f32_e64 v228, v108, v108
	v_mul_f32_e64 v229, v109, v109
	v_add_f32_e32 v0, v160, v161
	v_mfma_f32_16x16x32_bf16 v[94:97], v[170:173], v[82:85], v[94:97]
	ds_read2_b64 v[82:85], v221 offset0:88 offset1:92
	v_add_f32_e64 v102, v102, v230
	v_add_f32_e64 v103, v103, v231
	v_add_f32_e32 v0, v228, v0
	s_waitcnt lgkmcnt(0)
	v_mfma_f32_16x16x32_bf16 v[86:89], v[170:173], v[82:85], v[162:165]
	v_add_f32_e64 v104, v104, v158
	v_add_f32_e64 v105, v105, v159
	s_nop 0
	ds_read2_b64 v[162:165], v222 offset0:120 offset1:124
	v_mul_f32_e64 v158, v102, v102
	v_mul_f32_e64 v159, v103, v103
	v_mfma_f32_16x16x32_bf16 v[90:93], v[78:81], v[82:85], v[166:169]
	v_add_f32_e32 v0, v229, v0
	v_add_f32_e32 v0, v158, v0
	v_mul_f32_e64 v230, v104, v104
	v_mul_f32_e64 v231, v105, v105
	s_waitcnt lgkmcnt(0)
	v_mfma_f32_16x16x32_bf16 v[82:85], v[78:81], v[162:165], v[70:73]
	v_add_f32_e32 v0, v159, v0
	v_add_f32_e32 v0, v230, v0
	v_add_f32_e32 v0, v231, v0
	v_lshl_add_u64 v[70:71], s[60:61], 0, v[120:121]
	v_add_co_u32_e32 v72, vcc, s81, v70
	v_mfma_f32_16x16x32_bf16 v[78:81], v[170:173], v[162:165], v[74:77]
	s_nop 0
	v_addc_co_u32_e32 v73, vcc, 0, v71, vcc
	global_load_dwordx2 v[172:173], v[70:71], off
	global_load_dwordx2 v[170:171], v[70:71], off offset:32
	global_load_dwordx2 v[168:169], v[72:73], off
	global_load_dwordx2 v[166:167], v[72:73], off offset:32
	v_add_co_u32_e32 v72, vcc, s72, v70
	v_mov_b32_e32 v135, v0
	s_nop 1
	v_permlane16_swap_b32_e32 v135, v0
	s_nop 0
	v_addc_co_u32_e32 v73, vcc, 0, v71, vcc
	v_add_co_u32_e32 v70, vcc, s73, v70
	global_load_dwordx2 v[164:165], v[72:73], off
	global_load_dwordx2 v[162:163], v[72:73], off offset:32
	v_addc_co_u32_e32 v71, vcc, 0, v71, vcc
	global_load_dwordx2 v[156:157], v[70:71], off
	global_load_dwordx2 v[144:145], v[70:71], off offset:32
	global_load_dwordx4 v[74:77], v[138:139], off
	s_nop 0
	global_load_dwordx4 v[70:73], v[138:139], off offset:64
	s_waitcnt lgkmcnt(0)
	v_add_f32_e32 v0, v0, v135
	v_mov_b32_e32 v135, v0
	s_nop 1
	v_permlane32_swap_b32_e32 v135, v0
	s_and_saveexec_b64 s[60:61], s[4:5]
	s_cbranch_execz .LBB0_2294
	s_waitcnt lgkmcnt(0)
	v_add_f32_e32 v0, v0, v135
	ds_write_b32 v189, v0
.LBB0_2294:
	s_or_b64 exec, exec, s[60:61]
	s_waitcnt vmcnt(15)
	v_lshlrev_b32_e32 v158, 16, v152
	v_and_b32_e32 v159, 0xffff0000, v152
	v_add_f32_e64 v158, v98, v158
	v_add_f32_e64 v159, v99, v159
	v_lshlrev_b32_e32 v98, 16, v153
	v_and_b32_e32 v99, 0xffff0000, v153
	v_add_f32_e64 v100, v100, v98
	v_add_f32_e64 v101, v101, v99
	v_mul_f32_e64 v152, v158, v158
	v_mul_f32_e64 v153, v159, v159
	v_mul_f32_e64 v160, v100, v100
	v_mul_f32_e64 v161, v101, v101
	s_waitcnt vmcnt(14)
	v_lshlrev_b32_e32 v98, 16, v150
	v_and_b32_e32 v99, 0xffff0000, v150
	v_add_f32_e32 v0, v152, v153
	v_add_f32_e64 v98, v94, v98
	v_add_f32_e64 v99, v95, v99
	v_lshlrev_b32_e32 v94, 16, v151
	v_and_b32_e32 v95, 0xffff0000, v151
	v_add_f32_e32 v0, v160, v0
	v_add_f32_e64 v96, v96, v94
	v_add_f32_e64 v97, v97, v95
	v_mul_f32_e64 v94, v98, v98
	v_mul_f32_e64 v95, v99, v99
	v_add_f32_e32 v0, v161, v0
	v_add_f32_e32 v0, v94, v0
	v_mul_f32_e64 v150, v96, v96
	v_mul_f32_e64 v151, v97, v97
	v_add_f32_e32 v0, v95, v0
	v_add_f32_e32 v0, v150, v0
	v_add_f32_e32 v0, v151, v0
	v_mov_b32_e32 v94, v0
	s_nop 1
	v_permlane16_swap_b32_e32 v94, v0
	s_waitcnt lgkmcnt(0)
	v_add_f32_e32 v0, v0, v94
	v_mov_b32_e32 v94, v0
	s_nop 1
	v_permlane32_swap_b32_e32 v94, v0
	s_and_saveexec_b64 s[60:61], s[4:5]
	s_cbranch_execz .LBB0_2296
	s_waitcnt lgkmcnt(0)
	v_add_f32_e32 v0, v0, v94
	ds_write_b32 v189, v0 offset:512
.LBB0_2296:
	s_or_b64 exec, exec, s[60:61]
	s_waitcnt vmcnt(13) lgkmcnt(0)
	v_lshlrev_b32_e32 v94, 16, v148
	v_and_b32_e32 v95, 0xffff0000, v148
	v_add_f32_e64 v90, v90, v94
	v_add_f32_e64 v91, v91, v95
	v_lshlrev_b32_e32 v94, 16, v149
	v_and_b32_e32 v95, 0xffff0000, v149
	v_add_f32_e64 v94, v92, v94
	v_add_f32_e64 v95, v93, v95
	v_mul_f32_e64 v148, v90, v90
	v_mul_f32_e64 v149, v91, v91
	v_mul_f32_e64 v150, v94, v94
	v_mul_f32_e64 v151, v95, v95
	s_waitcnt vmcnt(12)
	v_lshlrev_b32_e32 v92, 16, v146
	v_and_b32_e32 v93, 0xffff0000, v146
	v_add_f32_e32 v0, v148, v149
	v_add_f32_e64 v92, v86, v92
	v_add_f32_e64 v93, v87, v93
	v_lshlrev_b32_e32 v86, 16, v147
	v_and_b32_e32 v87, 0xffff0000, v147
	v_add_f32_e32 v0, v150, v0
	v_add_f32_e64 v88, v88, v86
	v_add_f32_e64 v89, v89, v87
	v_mul_f32_e64 v86, v92, v92
	v_mul_f32_e64 v87, v93, v93
	v_add_f32_e32 v0, v151, v0
	v_add_f32_e32 v0, v86, v0
	v_mul_f32_e64 v146, v88, v88
	v_mul_f32_e64 v147, v89, v89
	v_add_f32_e32 v0, v87, v0
	v_add_f32_e32 v0, v146, v0
	v_add_f32_e32 v0, v147, v0
	v_mov_b32_e32 v86, v0
	s_nop 1
	v_permlane16_swap_b32_e32 v86, v0
	s_waitcnt lgkmcnt(0)
	v_add_f32_e32 v0, v0, v86
	v_mov_b32_e32 v86, v0
	s_nop 1
	v_permlane32_swap_b32_e32 v86, v0
	s_and_saveexec_b64 s[60:61], s[4:5]
	s_cbranch_execz .LBB0_2298
	s_waitcnt lgkmcnt(0)
	v_add_f32_e32 v0, v0, v86
	ds_write_b32 v189, v0 offset:1024
.LBB0_2298:
	s_or_b64 exec, exec, s[60:61]
	s_waitcnt vmcnt(11) lgkmcnt(0)
	v_lshlrev_b32_e32 v86, 16, v142
	v_and_b32_e32 v87, 0xffff0000, v142
	v_add_f32_e64 v86, v82, v86
	v_add_f32_e64 v87, v83, v87
	v_lshlrev_b32_e32 v82, 16, v143
	v_and_b32_e32 v83, 0xffff0000, v143
	v_add_f32_e64 v84, v84, v82
	v_add_f32_e64 v85, v85, v83
	v_mul_f32_e64 v142, v86, v86
	v_mul_f32_e64 v143, v87, v87
	v_mul_f32_e64 v146, v84, v84
	v_mul_f32_e64 v147, v85, v85
	s_waitcnt vmcnt(10)
	v_lshlrev_b32_e32 v82, 16, v140
	v_and_b32_e32 v83, 0xffff0000, v140
	v_add_f32_e32 v0, v142, v143
	v_add_f32_e64 v82, v78, v82
	v_add_f32_e64 v83, v79, v83
	v_lshlrev_b32_e32 v78, 16, v141
	v_and_b32_e32 v79, 0xffff0000, v141
	v_add_f32_e32 v0, v146, v0
	v_add_f32_e64 v78, v80, v78
	v_add_f32_e64 v79, v81, v79
	v_mul_f32_e64 v80, v82, v82
	v_mul_f32_e64 v81, v83, v83
	v_add_f32_e32 v0, v147, v0
	v_add_f32_e32 v0, v80, v0
	v_mul_f32_e64 v140, v78, v78
	v_mul_f32_e64 v141, v79, v79
	v_add_f32_e32 v0, v81, v0
	v_add_f32_e32 v0, v140, v0
	v_add_f32_e32 v0, v141, v0
	v_mov_b32_e32 v80, v0
	s_nop 1
	v_permlane16_swap_b32_e32 v80, v0
	s_waitcnt lgkmcnt(0)
	v_add_f32_e32 v0, v0, v80
	v_mov_b32_e32 v80, v0
	s_nop 1
	v_permlane32_swap_b32_e32 v80, v0
	s_and_saveexec_b64 s[60:61], s[4:5]
	s_cbranch_execz .LBB0_2282
	s_waitcnt lgkmcnt(0)
	v_add_f32_e32 v0, v0, v80
	ds_write_b32 v189, v0 offset:1536
	s_branch .LBB0_2282
